# K-loop: s_setprio moved outside the barrier->MFMA->barrier path, redundant lgkmcnt wait and mid-block prio flip dropped
# speedup vs baseline: 1.0035x; 1.0035x over previous
.LBB0_553:
	ds_read_b128 v[152:155], v149
	ds_read_b128 v[156:159], v149 offset:1024
	ds_read_b128 v[160:163], v149 offset:2048
	ds_read_b128 v[164:167], v149 offset:3072
	ds_read_b128 v[168:171], v150
	ds_read_b128 v[172:175], v150 offset:1024
	ds_read_b128 v[176:179], v150 offset:2048
	ds_read_b128 v[180:183], v150 offset:3072
	s_add_u32 s26, s24, 0x3fc000
	s_addc_u32 s27, s25, 0
	s_cmp_eq_u32 s62, 28
	s_cselect_b32 s30, s54, s26
	s_cselect_b32 s31, s17, s27
	s_cselect_b32 s28, s55, s56
	s_cselect_b32 s29, s19, s57
	s_add_u32 s26, s30, 0x400000
	s_addc_u32 s27, s31, 0
	s_add_i32 m0, s15, 0xc000
	ds_read_b128 v[184:187], v151
	ds_read_b128 v[188:191], v151 offset:1024
	ds_read_b128 v[192:195], v151 offset:2048
	ds_read_b128 v[196:199], v151 offset:3072
	ds_read_b128 v[200:203], v151 offset:4096
	ds_read_b128 v[204:207], v151 offset:5120
	ds_read_b128 v[208:211], v151 offset:6144
	ds_read_b128 v[212:215], v151 offset:7168
	global_load_lds_dwordx4 v136, s[24:25]
	s_add_i32 m0, s15, 0xe000
	s_nop 0
	global_load_lds_dwordx4 v138, s[24:25]
	s_waitcnt vmcnt(8)
	s_waitcnt lgkmcnt(0)
	s_setprio 1
	s_barrier
	v_mfma_f32_16x16x32_bf16 v[124:127], v[152:155], v[184:187], v[124:127]
	v_mfma_f32_16x16x32_bf16 v[120:123], v[160:163], v[184:187], v[120:123]
	v_mfma_f32_16x16x32_bf16 v[108:111], v[152:155], v[192:195], v[108:111]
	v_mfma_f32_16x16x32_bf16 v[104:107], v[160:163], v[192:195], v[104:107]
	v_mfma_f32_16x16x32_bf16 v[92:95], v[152:155], v[200:203], v[92:95]
	v_mfma_f32_16x16x32_bf16 v[88:91], v[160:163], v[200:203], v[88:91]
	v_mfma_f32_16x16x32_bf16 v[76:79], v[152:155], v[208:211], v[76:79]
	v_mfma_f32_16x16x32_bf16 v[72:75], v[160:163], v[208:211], v[72:75]
	v_mfma_f32_16x16x32_bf16 v[124:127], v[156:159], v[188:191], v[124:127]
	v_mfma_f32_16x16x32_bf16 v[120:123], v[164:167], v[188:191], v[120:123]
	v_mfma_f32_16x16x32_bf16 v[108:111], v[156:159], v[196:199], v[108:111]
	v_mfma_f32_16x16x32_bf16 v[104:107], v[164:167], v[196:199], v[104:107]
	v_mfma_f32_16x16x32_bf16 v[92:95], v[156:159], v[204:207], v[92:95]
	v_mfma_f32_16x16x32_bf16 v[88:91], v[164:167], v[204:207], v[88:91]
	v_mfma_f32_16x16x32_bf16 v[76:79], v[156:159], v[212:215], v[76:79]
	v_mfma_f32_16x16x32_bf16 v[72:75], v[164:167], v[212:215], v[72:75]
	v_mfma_f32_16x16x32_bf16 v[116:119], v[168:171], v[184:187], v[116:119]
	v_mfma_f32_16x16x32_bf16 v[112:115], v[176:179], v[184:187], v[112:115]
	v_mfma_f32_16x16x32_bf16 v[100:103], v[168:171], v[192:195], v[100:103]
	v_mfma_f32_16x16x32_bf16 v[96:99], v[176:179], v[192:195], v[96:99]
	v_mfma_f32_16x16x32_bf16 v[84:87], v[168:171], v[200:203], v[84:87]
	v_mfma_f32_16x16x32_bf16 v[80:83], v[176:179], v[200:203], v[80:83]
	v_mfma_f32_16x16x32_bf16 v[68:71], v[168:171], v[208:211], v[68:71]
	v_mfma_f32_16x16x32_bf16 v[64:67], v[176:179], v[208:211], v[64:67]
	v_mfma_f32_16x16x32_bf16 v[116:119], v[172:175], v[188:191], v[116:119]
	v_mfma_f32_16x16x32_bf16 v[112:115], v[180:183], v[188:191], v[112:115]
	v_mfma_f32_16x16x32_bf16 v[100:103], v[172:175], v[196:199], v[100:103]
	v_mfma_f32_16x16x32_bf16 v[96:99], v[180:183], v[196:199], v[96:99]
	v_mfma_f32_16x16x32_bf16 v[84:87], v[172:175], v[204:207], v[84:87]
	v_mfma_f32_16x16x32_bf16 v[80:83], v[180:183], v[204:207], v[80:83]
	v_mfma_f32_16x16x32_bf16 v[68:71], v[172:175], v[212:215], v[68:71]
	v_mfma_f32_16x16x32_bf16 v[64:67], v[180:183], v[212:215], v[64:67]
	s_barrier
	s_setprio 0
	s_add_i32 s63, s42, s5
	s_mov_b32 m0, s63
	ds_read_b128 v[184:187], v151 offset:16384
	ds_read_b128 v[188:191], v151 offset:17408
	ds_read_b128 v[192:195], v151 offset:18432
	ds_read_b128 v[196:199], v151 offset:19456
	ds_read_b128 v[200:203], v151 offset:20480
	ds_read_b128 v[204:207], v151 offset:21504
	ds_read_b128 v[208:211], v151 offset:22528
	ds_read_b128 v[212:215], v151 offset:23552
	global_load_lds_dwordx4 v132, s[28:29]
	s_add_i32 m0, s63, 0x2000
	s_add_u32 s66, s28, 0x4000
	s_addc_u32 s67, s29, 0
	s_add_i32 s63, s43, s5
	global_load_lds_dwordx4 v128, s[28:29]
	s_mov_b32 m0, s63
	s_nop 0
	global_load_lds_dwordx4 v132, s[66:67]
	s_add_i32 m0, s63, 0x2000
	s_nop 0
	global_load_lds_dwordx4 v128, s[66:67]
	s_mov_b32 m0, s15
	s_nop 0
	global_load_lds_dwordx4 v134, s[30:31]
	s_mov_b32 m0, s33
	s_nop 0
	global_load_lds_dwordx4 v130, s[30:31]
	s_waitcnt vmcnt(8)
	s_waitcnt lgkmcnt(0)
	s_setprio 1
	s_barrier
	v_mfma_f32_16x16x32_bf16 v[60:63], v[152:155], v[184:187], v[60:63]
	v_mfma_f32_16x16x32_bf16 v[56:59], v[160:163], v[184:187], v[56:59]
	v_mfma_f32_16x16x32_bf16 v[44:47], v[152:155], v[192:195], v[44:47]
	v_mfma_f32_16x16x32_bf16 v[40:43], v[160:163], v[192:195], v[40:43]
	v_mfma_f32_16x16x32_bf16 v[28:31], v[152:155], v[200:203], v[28:31]
	v_mfma_f32_16x16x32_bf16 v[24:27], v[160:163], v[200:203], v[24:27]
	v_mfma_f32_16x16x32_bf16 v[12:15], v[152:155], v[208:211], v[12:15]
	v_mfma_f32_16x16x32_bf16 v[8:11], v[160:163], v[208:211], v[8:11]
	v_mfma_f32_16x16x32_bf16 v[60:63], v[156:159], v[188:191], v[60:63]
	v_mfma_f32_16x16x32_bf16 v[56:59], v[164:167], v[188:191], v[56:59]
	v_mfma_f32_16x16x32_bf16 v[44:47], v[156:159], v[196:199], v[44:47]
	v_mfma_f32_16x16x32_bf16 v[40:43], v[164:167], v[196:199], v[40:43]
	v_mfma_f32_16x16x32_bf16 v[28:31], v[156:159], v[204:207], v[28:31]
	v_mfma_f32_16x16x32_bf16 v[24:27], v[164:167], v[204:207], v[24:27]
	v_mfma_f32_16x16x32_bf16 v[12:15], v[156:159], v[212:215], v[12:15]
	v_mfma_f32_16x16x32_bf16 v[8:11], v[164:167], v[212:215], v[8:11]
	v_mfma_f32_16x16x32_bf16 v[52:55], v[168:171], v[184:187], v[52:55]
	v_mfma_f32_16x16x32_bf16 v[48:51], v[176:179], v[184:187], v[48:51]
	v_mfma_f32_16x16x32_bf16 v[36:39], v[168:171], v[192:195], v[36:39]
	v_mfma_f32_16x16x32_bf16 v[32:35], v[176:179], v[192:195], v[32:35]
	v_mfma_f32_16x16x32_bf16 v[20:23], v[168:171], v[200:203], v[20:23]
	v_mfma_f32_16x16x32_bf16 v[16:19], v[176:179], v[200:203], v[16:19]
	v_mfma_f32_16x16x32_bf16 v[4:7], v[168:171], v[208:211], v[4:7]
	v_mfma_f32_16x16x32_bf16 v[0:3], v[176:179], v[208:211], v[0:3]
	v_mfma_f32_16x16x32_bf16 v[52:55], v[172:175], v[188:191], v[52:55]
	v_mfma_f32_16x16x32_bf16 v[48:51], v[180:183], v[188:191], v[48:51]
	v_mfma_f32_16x16x32_bf16 v[36:39], v[172:175], v[196:199], v[36:39]
	v_mfma_f32_16x16x32_bf16 v[32:35], v[180:183], v[196:199], v[32:35]
	v_mfma_f32_16x16x32_bf16 v[20:23], v[172:175], v[204:207], v[20:23]
	v_mfma_f32_16x16x32_bf16 v[16:19], v[180:183], v[204:207], v[16:19]
	v_mfma_f32_16x16x32_bf16 v[4:7], v[172:175], v[212:215], v[4:7]
	v_mfma_f32_16x16x32_bf16 v[0:3], v[180:183], v[212:215], v[0:3]
	s_barrier
	s_setprio 0
	s_add_i32 s63, 0, 0x18000
	v_add_u32_e32 v144, s63, v148
	s_add_i32 s66, 0, 0x1c000
	ds_read_b128 v[152:155], v144
	ds_read_b128 v[156:159], v144 offset:1024
	ds_read_b128 v[160:163], v144 offset:2048
	ds_read_b128 v[164:167], v144 offset:3072
	v_add_u32_e32 v144, s66, v148
	ds_read_b128 v[168:171], v144
	ds_read_b128 v[172:175], v144 offset:1024
	ds_read_b128 v[176:179], v144 offset:2048
	ds_read_b128 v[180:183], v144 offset:3072
	s_add_u32 s30, s30, 0x4000
	s_addc_u32 s31, s31, 0
	s_mov_b32 m0, s34
	ds_read_b128 v[184:187], v151 offset:32768
	ds_read_b128 v[188:191], v151 offset:33792
	ds_read_b128 v[192:195], v151 offset:34816
	ds_read_b128 v[196:199], v151 offset:35840
	ds_read_b128 v[200:203], v151 offset:36864
	ds_read_b128 v[204:207], v151 offset:37888
	ds_read_b128 v[208:211], v151 offset:38912
	ds_read_b128 v[212:215], v151 offset:39936
	global_load_lds_dwordx4 v134, s[30:31]
	s_mov_b32 m0, s35
	s_nop 0
	global_load_lds_dwordx4 v130, s[30:31]
	s_waitcnt vmcnt(8)
	s_waitcnt lgkmcnt(0)
	s_setprio 1
	s_barrier
	v_mfma_f32_16x16x32_bf16 v[124:127], v[152:155], v[184:187], v[124:127]
	v_mfma_f32_16x16x32_bf16 v[120:123], v[160:163], v[184:187], v[120:123]
	v_mfma_f32_16x16x32_bf16 v[108:111], v[152:155], v[192:195], v[108:111]
	v_mfma_f32_16x16x32_bf16 v[104:107], v[160:163], v[192:195], v[104:107]
	v_mfma_f32_16x16x32_bf16 v[92:95], v[152:155], v[200:203], v[92:95]
	v_mfma_f32_16x16x32_bf16 v[88:91], v[160:163], v[200:203], v[88:91]
	v_mfma_f32_16x16x32_bf16 v[76:79], v[152:155], v[208:211], v[76:79]
	v_mfma_f32_16x16x32_bf16 v[72:75], v[160:163], v[208:211], v[72:75]
	v_mfma_f32_16x16x32_bf16 v[124:127], v[156:159], v[188:191], v[124:127]
	v_mfma_f32_16x16x32_bf16 v[120:123], v[164:167], v[188:191], v[120:123]
	v_mfma_f32_16x16x32_bf16 v[108:111], v[156:159], v[196:199], v[108:111]
	v_mfma_f32_16x16x32_bf16 v[104:107], v[164:167], v[196:199], v[104:107]
	v_mfma_f32_16x16x32_bf16 v[92:95], v[156:159], v[204:207], v[92:95]
	v_mfma_f32_16x16x32_bf16 v[88:91], v[164:167], v[204:207], v[88:91]
	v_mfma_f32_16x16x32_bf16 v[76:79], v[156:159], v[212:215], v[76:79]
	v_mfma_f32_16x16x32_bf16 v[72:75], v[164:167], v[212:215], v[72:75]
	v_mfma_f32_16x16x32_bf16 v[116:119], v[168:171], v[184:187], v[116:119]
	v_mfma_f32_16x16x32_bf16 v[112:115], v[176:179], v[184:187], v[112:115]
	v_mfma_f32_16x16x32_bf16 v[100:103], v[168:171], v[192:195], v[100:103]
	v_mfma_f32_16x16x32_bf16 v[96:99], v[176:179], v[192:195], v[96:99]
	v_mfma_f32_16x16x32_bf16 v[84:87], v[168:171], v[200:203], v[84:87]
	v_mfma_f32_16x16x32_bf16 v[80:83], v[176:179], v[200:203], v[80:83]
	v_mfma_f32_16x16x32_bf16 v[68:71], v[168:171], v[208:211], v[68:71]
	v_mfma_f32_16x16x32_bf16 v[64:67], v[176:179], v[208:211], v[64:67]
	v_mfma_f32_16x16x32_bf16 v[116:119], v[172:175], v[188:191], v[116:119]
	v_mfma_f32_16x16x32_bf16 v[112:115], v[180:183], v[188:191], v[112:115]
	v_mfma_f32_16x16x32_bf16 v[100:103], v[172:175], v[196:199], v[100:103]
	v_mfma_f32_16x16x32_bf16 v[96:99], v[180:183], v[196:199], v[96:99]
	v_mfma_f32_16x16x32_bf16 v[84:87], v[172:175], v[204:207], v[84:87]
	v_mfma_f32_16x16x32_bf16 v[80:83], v[180:183], v[204:207], v[80:83]
	v_mfma_f32_16x16x32_bf16 v[68:71], v[172:175], v[212:215], v[68:71]
	v_mfma_f32_16x16x32_bf16 v[64:67], v[180:183], v[212:215], v[64:67]
	s_barrier
	s_setprio 0
	s_add_u32 s30, s28, 0x160000
	s_addc_u32 s31, s29, 0
	s_add_i32 s63, s63, s5
	s_mov_b32 m0, s63
	ds_read_b128 v[184:187], v151 offset:49152
	ds_read_b128 v[188:191], v151 offset:50176
	ds_read_b128 v[192:195], v151 offset:51200
	ds_read_b128 v[196:199], v151 offset:52224
	ds_read_b128 v[200:203], v151 offset:53248
	ds_read_b128 v[204:207], v151 offset:54272
	ds_read_b128 v[208:211], v151 offset:55296
	ds_read_b128 v[212:215], v151 offset:56320
	global_load_lds_dwordx4 v132, s[30:31]
	s_add_i32 m0, s63, 0x2000
	s_add_u32 s28, s28, 0x164000
	global_load_lds_dwordx4 v128, s[30:31]
	s_addc_u32 s29, s29, 0
	s_add_i32 s30, s66, s5
	s_mov_b32 m0, s30
	s_nop 0
	global_load_lds_dwordx4 v132, s[28:29]
	s_add_i32 m0, s30, 0x2000
	s_nop 0
	global_load_lds_dwordx4 v128, s[28:29]
	s_mov_b32 m0, s38
	s_nop 0
	global_load_lds_dwordx4 v134, s[26:27]
	s_mov_b32 m0, s39
	s_nop 0
	global_load_lds_dwordx4 v130, s[26:27]
	s_waitcnt vmcnt(8)
	s_waitcnt lgkmcnt(0)
	s_setprio 1
	s_barrier
	v_mfma_f32_16x16x32_bf16 v[60:63], v[152:155], v[184:187], v[60:63]
	v_mfma_f32_16x16x32_bf16 v[56:59], v[160:163], v[184:187], v[56:59]
	v_mfma_f32_16x16x32_bf16 v[44:47], v[152:155], v[192:195], v[44:47]
	v_mfma_f32_16x16x32_bf16 v[40:43], v[160:163], v[192:195], v[40:43]
	v_mfma_f32_16x16x32_bf16 v[28:31], v[152:155], v[200:203], v[28:31]
	v_mfma_f32_16x16x32_bf16 v[24:27], v[160:163], v[200:203], v[24:27]
	v_mfma_f32_16x16x32_bf16 v[12:15], v[152:155], v[208:211], v[12:15]
	v_mfma_f32_16x16x32_bf16 v[8:11], v[160:163], v[208:211], v[8:11]
	v_mfma_f32_16x16x32_bf16 v[60:63], v[156:159], v[188:191], v[60:63]
	v_mfma_f32_16x16x32_bf16 v[56:59], v[164:167], v[188:191], v[56:59]
	v_mfma_f32_16x16x32_bf16 v[44:47], v[156:159], v[196:199], v[44:47]
	v_mfma_f32_16x16x32_bf16 v[40:43], v[164:167], v[196:199], v[40:43]
	v_mfma_f32_16x16x32_bf16 v[28:31], v[156:159], v[204:207], v[28:31]
	v_mfma_f32_16x16x32_bf16 v[24:27], v[164:167], v[204:207], v[24:27]
	v_mfma_f32_16x16x32_bf16 v[12:15], v[156:159], v[212:215], v[12:15]
	v_mfma_f32_16x16x32_bf16 v[8:11], v[164:167], v[212:215], v[8:11]
	v_mfma_f32_16x16x32_bf16 v[52:55], v[168:171], v[184:187], v[52:55]
	v_mfma_f32_16x16x32_bf16 v[48:51], v[176:179], v[184:187], v[48:51]
	v_mfma_f32_16x16x32_bf16 v[36:39], v[168:171], v[192:195], v[36:39]
	v_mfma_f32_16x16x32_bf16 v[32:35], v[176:179], v[192:195], v[32:35]
	v_mfma_f32_16x16x32_bf16 v[20:23], v[168:171], v[200:203], v[20:23]
	v_mfma_f32_16x16x32_bf16 v[16:19], v[176:179], v[200:203], v[16:19]
	v_mfma_f32_16x16x32_bf16 v[4:7], v[168:171], v[208:211], v[4:7]
	v_mfma_f32_16x16x32_bf16 v[0:3], v[176:179], v[208:211], v[0:3]
	v_mfma_f32_16x16x32_bf16 v[52:55], v[172:175], v[188:191], v[52:55]
	v_mfma_f32_16x16x32_bf16 v[48:51], v[180:183], v[188:191], v[48:51]
	v_mfma_f32_16x16x32_bf16 v[36:39], v[172:175], v[196:199], v[36:39]
	v_mfma_f32_16x16x32_bf16 v[32:35], v[180:183], v[196:199], v[32:35]
	v_mfma_f32_16x16x32_bf16 v[20:23], v[172:175], v[204:207], v[20:23]
	v_mfma_f32_16x16x32_bf16 v[16:19], v[180:183], v[204:207], v[16:19]
	v_mfma_f32_16x16x32_bf16 v[4:7], v[172:175], v[212:215], v[4:7]
	v_mfma_f32_16x16x32_bf16 v[0:3], v[180:183], v[212:215], v[0:3]
	s_barrier
	s_setprio 0
	s_add_i32 s62, s62, 2
	s_add_u32 s56, s56, 0x2c0000
	s_addc_u32 s57, s57, 0
	s_add_u32 s24, s24, 0x800000
	s_addc_u32 s25, s25, 0
	s_cmp_gt_u32 s62, 29
	s_cbranch_scc0 .LBB0_553
	s_and_b64 vcc, exec, s[12:13]
	s_cbranch_vccz .LBB0_556
	s_barrier

.LBB0_631:
	ds_read_b128 v[128:131], v182
	ds_read_b128 v[132:135], v182 offset:1024
	ds_read_b128 v[136:139], v182 offset:2048
	ds_read_b128 v[140:143], v182 offset:3072
	ds_read_b128 v[144:147], v183
	ds_read_b128 v[148:151], v183 offset:1024
	ds_read_b128 v[152:155], v183 offset:2048
	ds_read_b128 v[156:159], v183 offset:3072
	s_add_u32 s8, s6, 0x3fc000
	s_addc_u32 s9, s7, 0
	s_cmpk_eq_i32 s42, 0x54
	s_cselect_b32 s36, s29, s8
	s_cselect_b32 s37, s17, s9
	s_cselect_b32 s10, s39, s40
	s_cselect_b32 s11, s38, s41
	s_add_u32 s8, s36, 0x400000
	s_addc_u32 s9, s37, 0
	s_add_i32 m0, s27, 0xc000
	ds_read_b128 v[174:177], v184
	ds_read_b128 v[188:191], v184 offset:1024
	ds_read_b128 v[192:195], v184 offset:2048
	ds_read_b128 v[196:199], v184 offset:3072
	ds_read_b128 v[200:203], v184 offset:4096
	ds_read_b128 v[204:207], v184 offset:5120
	ds_read_b128 v[208:211], v184 offset:6144
	ds_read_b128 v[212:215], v184 offset:7168
	global_load_lds_dwordx4 v168, s[6:7]
	s_add_i32 m0, s27, 0xe000
	s_nop 0
	global_load_lds_dwordx4 v170, s[6:7]
	s_waitcnt vmcnt(8)
	s_waitcnt lgkmcnt(0)
	s_setprio 1
	s_barrier
	v_mfma_f32_16x16x32_bf16 v[108:111], v[128:131], v[174:177], v[108:111]
	v_mfma_f32_16x16x32_bf16 v[104:107], v[136:139], v[174:177], v[104:107]
	v_mfma_f32_16x16x32_bf16 v[84:87], v[128:131], v[192:195], v[84:87]
	v_mfma_f32_16x16x32_bf16 v[80:83], v[136:139], v[192:195], v[80:83]
	v_mfma_f32_16x16x32_bf16 v[4:7], v[128:131], v[200:203], v[4:7]
	v_mfma_f32_16x16x32_bf16 v[0:3], v[136:139], v[200:203], v[0:3]
	v_mfma_f32_16x16x32_bf16 v[100:103], v[128:131], v[208:211], v[100:103]
	v_mfma_f32_16x16x32_bf16 v[96:99], v[136:139], v[208:211], v[96:99]
	v_mfma_f32_16x16x32_bf16 v[108:111], v[132:135], v[188:191], v[108:111]
	v_mfma_f32_16x16x32_bf16 v[104:107], v[140:143], v[188:191], v[104:107]
	v_mfma_f32_16x16x32_bf16 v[84:87], v[132:135], v[196:199], v[84:87]
	v_mfma_f32_16x16x32_bf16 v[80:83], v[140:143], v[196:199], v[80:83]
	v_mfma_f32_16x16x32_bf16 v[4:7], v[132:135], v[204:207], v[4:7]
	v_mfma_f32_16x16x32_bf16 v[0:3], v[140:143], v[204:207], v[0:3]
	v_mfma_f32_16x16x32_bf16 v[100:103], v[132:135], v[212:215], v[100:103]
	v_mfma_f32_16x16x32_bf16 v[96:99], v[140:143], v[212:215], v[96:99]
	v_mfma_f32_16x16x32_bf16 v[92:95], v[144:147], v[174:177], v[92:95]
	v_mfma_f32_16x16x32_bf16 v[88:91], v[152:155], v[174:177], v[88:91]
	v_mfma_f32_16x16x32_bf16 v[28:31], v[144:147], v[192:195], v[28:31]
	v_mfma_f32_16x16x32_bf16 v[24:27], v[152:155], v[192:195], v[24:27]
	v_mfma_f32_16x16x32_bf16 v[12:15], v[144:147], v[200:203], v[12:15]
	v_mfma_f32_16x16x32_bf16 v[8:11], v[152:155], v[200:203], v[8:11]
	v_mfma_f32_16x16x32_bf16 v[20:23], v[144:147], v[208:211], v[20:23]
	v_mfma_f32_16x16x32_bf16 v[16:19], v[152:155], v[208:211], v[16:19]
	v_mfma_f32_16x16x32_bf16 v[92:95], v[148:151], v[188:191], v[92:95]
	v_mfma_f32_16x16x32_bf16 v[88:91], v[156:159], v[188:191], v[88:91]
	v_mfma_f32_16x16x32_bf16 v[28:31], v[148:151], v[196:199], v[28:31]
	v_mfma_f32_16x16x32_bf16 v[24:27], v[156:159], v[196:199], v[24:27]
	v_mfma_f32_16x16x32_bf16 v[12:15], v[148:151], v[204:207], v[12:15]
	v_mfma_f32_16x16x32_bf16 v[8:11], v[156:159], v[204:207], v[8:11]
	v_mfma_f32_16x16x32_bf16 v[20:23], v[148:151], v[212:215], v[20:23]
	v_mfma_f32_16x16x32_bf16 v[16:19], v[156:159], v[212:215], v[16:19]
	s_barrier
	s_setprio 0
	s_add_i32 s43, s57, s4
	s_mov_b32 m0, s43
	ds_read_b128 v[174:177], v184 offset:16384
	ds_read_b128 v[188:191], v184 offset:17408
	ds_read_b128 v[192:195], v184 offset:18432
	ds_read_b128 v[196:199], v184 offset:19456
	ds_read_b128 v[200:203], v184 offset:20480
	ds_read_b128 v[204:207], v184 offset:21504
	ds_read_b128 v[208:211], v184 offset:22528
	ds_read_b128 v[212:215], v184 offset:23552
	global_load_lds_dwordx4 v162, s[10:11]
	s_add_i32 m0, s43, 0x2000
	s_add_u32 s44, s10, 0x4000
	s_addc_u32 s45, s11, 0
	s_add_i32 s43, s81, s4
	global_load_lds_dwordx4 v166, s[10:11]
	s_mov_b32 m0, s43
	s_nop 0
	global_load_lds_dwordx4 v162, s[44:45]
	s_add_i32 m0, s43, 0x2000
	s_nop 0
	global_load_lds_dwordx4 v166, s[44:45]
	s_mov_b32 m0, s27
	s_nop 0
	global_load_lds_dwordx4 v160, s[36:37]
	s_mov_b32 m0, s52
	s_nop 0
	global_load_lds_dwordx4 v164, s[36:37]
	s_waitcnt vmcnt(8)
	s_waitcnt lgkmcnt(0)
	s_setprio 1
	s_barrier
	v_mfma_f32_16x16x32_bf16 v[124:127], v[128:131], v[174:177], v[124:127]
	v_mfma_f32_16x16x32_bf16 v[120:123], v[136:139], v[174:177], v[120:123]
	v_mfma_f32_16x16x32_bf16 v[116:119], v[128:131], v[192:195], v[116:119]
	v_mfma_f32_16x16x32_bf16 v[112:115], v[136:139], v[192:195], v[112:115]
	v_mfma_f32_16x16x32_bf16 v[76:79], v[128:131], v[200:203], v[76:79]
	v_mfma_f32_16x16x32_bf16 v[72:75], v[136:139], v[200:203], v[72:75]
	v_mfma_f32_16x16x32_bf16 v[68:71], v[128:131], v[208:211], v[68:71]
	v_mfma_f32_16x16x32_bf16 v[64:67], v[136:139], v[208:211], v[64:67]
	v_mfma_f32_16x16x32_bf16 v[124:127], v[132:135], v[188:191], v[124:127]
	v_mfma_f32_16x16x32_bf16 v[120:123], v[140:143], v[188:191], v[120:123]
	v_mfma_f32_16x16x32_bf16 v[116:119], v[132:135], v[196:199], v[116:119]
	v_mfma_f32_16x16x32_bf16 v[112:115], v[140:143], v[196:199], v[112:115]
	v_mfma_f32_16x16x32_bf16 v[76:79], v[132:135], v[204:207], v[76:79]
	v_mfma_f32_16x16x32_bf16 v[72:75], v[140:143], v[204:207], v[72:75]
	v_mfma_f32_16x16x32_bf16 v[68:71], v[132:135], v[212:215], v[68:71]
	v_mfma_f32_16x16x32_bf16 v[64:67], v[140:143], v[212:215], v[64:67]
	v_mfma_f32_16x16x32_bf16 v[48:51], v[144:147], v[174:177], v[48:51]
	v_mfma_f32_16x16x32_bf16 v[36:39], v[152:155], v[174:177], v[36:39]
	v_mfma_f32_16x16x32_bf16 v[40:43], v[144:147], v[192:195], v[40:43]
	v_mfma_f32_16x16x32_bf16 v[32:35], v[152:155], v[192:195], v[32:35]
	v_mfma_f32_16x16x32_bf16 v[52:55], v[144:147], v[200:203], v[52:55]
	v_mfma_f32_16x16x32_bf16 v[44:47], v[152:155], v[200:203], v[44:47]
	v_mfma_f32_16x16x32_bf16 v[60:63], v[144:147], v[208:211], v[60:63]
	v_mfma_f32_16x16x32_bf16 v[56:59], v[152:155], v[208:211], v[56:59]
	v_mfma_f32_16x16x32_bf16 v[48:51], v[148:151], v[188:191], v[48:51]
	v_mfma_f32_16x16x32_bf16 v[36:39], v[156:159], v[188:191], v[36:39]
	v_mfma_f32_16x16x32_bf16 v[40:43], v[148:151], v[196:199], v[40:43]
	v_mfma_f32_16x16x32_bf16 v[32:35], v[156:159], v[196:199], v[32:35]
	v_mfma_f32_16x16x32_bf16 v[52:55], v[148:151], v[204:207], v[52:55]
	v_mfma_f32_16x16x32_bf16 v[44:47], v[156:159], v[204:207], v[44:47]
	v_mfma_f32_16x16x32_bf16 v[60:63], v[148:151], v[212:215], v[60:63]
	v_mfma_f32_16x16x32_bf16 v[56:59], v[156:159], v[212:215], v[56:59]
	s_barrier
	s_setprio 0
	s_add_i32 s82, 0, 0x18000
	s_add_i32 s83, 0, 0x1c000
	v_add_u32_e32 v140, s82, v181
	v_add_u32_e32 v156, s83, v181
	ds_read_b128 v[128:131], v140
	ds_read_b128 v[132:135], v140 offset:1024
	ds_read_b128 v[136:139], v140 offset:2048
	ds_read_b128 v[140:143], v140 offset:3072
	ds_read_b128 v[144:147], v156
	ds_read_b128 v[148:151], v156 offset:1024
	ds_read_b128 v[152:155], v156 offset:2048
	ds_read_b128 v[156:159], v156 offset:3072
	s_add_u32 s36, s36, 0x4000
	s_addc_u32 s37, s37, 0
	s_mov_b32 m0, s53
	ds_read_b128 v[174:177], v184 offset:32768
	ds_read_b128 v[188:191], v184 offset:33792
	ds_read_b128 v[192:195], v184 offset:34816
	ds_read_b128 v[196:199], v184 offset:35840
	ds_read_b128 v[200:203], v184 offset:36864
	ds_read_b128 v[204:207], v184 offset:37888
	ds_read_b128 v[208:211], v184 offset:38912
	ds_read_b128 v[212:215], v184 offset:39936
	global_load_lds_dwordx4 v160, s[36:37]
	s_mov_b32 m0, s54
	s_nop 0
	global_load_lds_dwordx4 v164, s[36:37]
	s_waitcnt vmcnt(8)
	s_waitcnt lgkmcnt(0)
	s_setprio 1
	s_barrier
	v_mfma_f32_16x16x32_bf16 v[108:111], v[128:131], v[174:177], v[108:111]
	v_mfma_f32_16x16x32_bf16 v[104:107], v[136:139], v[174:177], v[104:107]
	v_mfma_f32_16x16x32_bf16 v[84:87], v[128:131], v[192:195], v[84:87]
	v_mfma_f32_16x16x32_bf16 v[80:83], v[136:139], v[192:195], v[80:83]
	v_mfma_f32_16x16x32_bf16 v[4:7], v[128:131], v[200:203], v[4:7]
	v_mfma_f32_16x16x32_bf16 v[0:3], v[136:139], v[200:203], v[0:3]
	v_mfma_f32_16x16x32_bf16 v[100:103], v[128:131], v[208:211], v[100:103]
	v_mfma_f32_16x16x32_bf16 v[96:99], v[136:139], v[208:211], v[96:99]
	v_mfma_f32_16x16x32_bf16 v[108:111], v[132:135], v[188:191], v[108:111]
	v_mfma_f32_16x16x32_bf16 v[104:107], v[140:143], v[188:191], v[104:107]
	v_mfma_f32_16x16x32_bf16 v[84:87], v[132:135], v[196:199], v[84:87]
	v_mfma_f32_16x16x32_bf16 v[80:83], v[140:143], v[196:199], v[80:83]
	v_mfma_f32_16x16x32_bf16 v[4:7], v[132:135], v[204:207], v[4:7]
	v_mfma_f32_16x16x32_bf16 v[0:3], v[140:143], v[204:207], v[0:3]
	v_mfma_f32_16x16x32_bf16 v[100:103], v[132:135], v[212:215], v[100:103]
	v_mfma_f32_16x16x32_bf16 v[96:99], v[140:143], v[212:215], v[96:99]
	v_mfma_f32_16x16x32_bf16 v[92:95], v[144:147], v[174:177], v[92:95]
	v_mfma_f32_16x16x32_bf16 v[88:91], v[152:155], v[174:177], v[88:91]
	v_mfma_f32_16x16x32_bf16 v[28:31], v[144:147], v[192:195], v[28:31]
	v_mfma_f32_16x16x32_bf16 v[24:27], v[152:155], v[192:195], v[24:27]
	v_mfma_f32_16x16x32_bf16 v[12:15], v[144:147], v[200:203], v[12:15]
	v_mfma_f32_16x16x32_bf16 v[8:11], v[152:155], v[200:203], v[8:11]
	v_mfma_f32_16x16x32_bf16 v[20:23], v[144:147], v[208:211], v[20:23]
	v_mfma_f32_16x16x32_bf16 v[16:19], v[152:155], v[208:211], v[16:19]
	v_mfma_f32_16x16x32_bf16 v[92:95], v[148:151], v[188:191], v[92:95]
	v_mfma_f32_16x16x32_bf16 v[88:91], v[156:159], v[188:191], v[88:91]
	v_mfma_f32_16x16x32_bf16 v[28:31], v[148:151], v[196:199], v[28:31]
	v_mfma_f32_16x16x32_bf16 v[24:27], v[156:159], v[196:199], v[24:27]
	v_mfma_f32_16x16x32_bf16 v[12:15], v[148:151], v[204:207], v[12:15]
	v_mfma_f32_16x16x32_bf16 v[8:11], v[156:159], v[204:207], v[8:11]
	v_mfma_f32_16x16x32_bf16 v[20:23], v[148:151], v[212:215], v[20:23]
	v_mfma_f32_16x16x32_bf16 v[16:19], v[156:159], v[212:215], v[16:19]
	s_barrier
	s_setprio 0
	s_add_u32 s36, s10, 0x40000
	s_addc_u32 s37, s11, 0
	s_add_i32 s43, s82, s4
	s_mov_b32 m0, s43
	ds_read_b128 v[174:177], v184 offset:49152
	ds_read_b128 v[188:191], v184 offset:50176
	ds_read_b128 v[192:195], v184 offset:51200
	ds_read_b128 v[196:199], v184 offset:52224
	ds_read_b128 v[200:203], v184 offset:53248
	ds_read_b128 v[204:207], v184 offset:54272
	ds_read_b128 v[208:211], v184 offset:55296
	ds_read_b128 v[212:215], v184 offset:56320
	global_load_lds_dwordx4 v162, s[36:37]
	s_add_i32 m0, s43, 0x2000
	s_add_u32 s10, s10, 0x44000
	global_load_lds_dwordx4 v166, s[36:37]
	s_addc_u32 s11, s11, 0
	s_add_i32 s36, s83, s4
	s_mov_b32 m0, s36
	s_nop 0
	global_load_lds_dwordx4 v162, s[10:11]
	s_add_i32 m0, s36, 0x2000
	s_nop 0
	global_load_lds_dwordx4 v166, s[10:11]
	s_mov_b32 m0, s50
	s_nop 0
	global_load_lds_dwordx4 v160, s[8:9]
	s_mov_b32 m0, s51
	s_nop 0
	global_load_lds_dwordx4 v164, s[8:9]
	s_waitcnt vmcnt(8)
	s_waitcnt lgkmcnt(0)
	s_setprio 1
	s_barrier
	v_mfma_f32_16x16x32_bf16 v[124:127], v[128:131], v[174:177], v[124:127]
	v_mfma_f32_16x16x32_bf16 v[120:123], v[136:139], v[174:177], v[120:123]
	v_mfma_f32_16x16x32_bf16 v[116:119], v[128:131], v[192:195], v[116:119]
	v_mfma_f32_16x16x32_bf16 v[112:115], v[136:139], v[192:195], v[112:115]
	v_mfma_f32_16x16x32_bf16 v[76:79], v[128:131], v[200:203], v[76:79]
	v_mfma_f32_16x16x32_bf16 v[72:75], v[136:139], v[200:203], v[72:75]
	v_mfma_f32_16x16x32_bf16 v[68:71], v[128:131], v[208:211], v[68:71]
	v_mfma_f32_16x16x32_bf16 v[64:67], v[136:139], v[208:211], v[64:67]
	v_mfma_f32_16x16x32_bf16 v[124:127], v[132:135], v[188:191], v[124:127]
	v_mfma_f32_16x16x32_bf16 v[120:123], v[140:143], v[188:191], v[120:123]
	v_mfma_f32_16x16x32_bf16 v[116:119], v[132:135], v[196:199], v[116:119]
	v_mfma_f32_16x16x32_bf16 v[112:115], v[140:143], v[196:199], v[112:115]
	v_mfma_f32_16x16x32_bf16 v[76:79], v[132:135], v[204:207], v[76:79]
	v_mfma_f32_16x16x32_bf16 v[72:75], v[140:143], v[204:207], v[72:75]
	v_mfma_f32_16x16x32_bf16 v[68:71], v[132:135], v[212:215], v[68:71]
	v_mfma_f32_16x16x32_bf16 v[64:67], v[140:143], v[212:215], v[64:67]
	v_mfma_f32_16x16x32_bf16 v[48:51], v[144:147], v[174:177], v[48:51]
	v_mfma_f32_16x16x32_bf16 v[36:39], v[152:155], v[174:177], v[36:39]
	v_mfma_f32_16x16x32_bf16 v[40:43], v[144:147], v[192:195], v[40:43]
	v_mfma_f32_16x16x32_bf16 v[32:35], v[152:155], v[192:195], v[32:35]
	v_mfma_f32_16x16x32_bf16 v[52:55], v[144:147], v[200:203], v[52:55]
	v_mfma_f32_16x16x32_bf16 v[44:47], v[152:155], v[200:203], v[44:47]
	v_mfma_f32_16x16x32_bf16 v[60:63], v[144:147], v[208:211], v[60:63]
	v_mfma_f32_16x16x32_bf16 v[56:59], v[152:155], v[208:211], v[56:59]
	v_mfma_f32_16x16x32_bf16 v[48:51], v[148:151], v[188:191], v[48:51]
	v_mfma_f32_16x16x32_bf16 v[36:39], v[156:159], v[188:191], v[36:39]
	v_mfma_f32_16x16x32_bf16 v[40:43], v[148:151], v[196:199], v[40:43]
	v_mfma_f32_16x16x32_bf16 v[32:35], v[156:159], v[196:199], v[32:35]
	v_mfma_f32_16x16x32_bf16 v[52:55], v[148:151], v[204:207], v[52:55]
	v_mfma_f32_16x16x32_bf16 v[44:47], v[156:159], v[204:207], v[44:47]
	v_mfma_f32_16x16x32_bf16 v[60:63], v[148:151], v[212:215], v[60:63]
	v_mfma_f32_16x16x32_bf16 v[56:59], v[156:159], v[212:215], v[56:59]
	s_barrier
	s_setprio 0
	s_add_i32 s42, s42, 2
	s_add_u32 s40, s40, 0x80000
	s_addc_u32 s41, s41, 0
	s_add_u32 s6, s6, 0x800000
	s_addc_u32 s7, s7, 0
	s_cmpk_gt_u32 s42, 0x55
	s_cbranch_scc0 .LBB0_631
	s_and_b64 vcc, exec, s[24:25]
	s_cbranch_vccz .LBB0_634
	s_barrier

.LBB0_732:
	ds_read_b128 v[144:147], v153
	ds_read_b128 v[156:159], v153 offset:1024
	ds_read_b128 v[160:163], v153 offset:2048
	ds_read_b128 v[164:167], v153 offset:3072
	ds_read_b128 v[168:171], v154
	ds_read_b128 v[172:175], v154 offset:1024
	ds_read_b128 v[176:179], v154 offset:2048
	ds_read_b128 v[180:183], v154 offset:3072
	s_add_u32 s26, s24, 0x3fc000
	s_addc_u32 s27, s25, 0
	s_cmp_eq_u32 s75, 28
	s_cselect_b32 s30, s54, s26
	s_cselect_b32 s31, s17, s27
	s_cselect_b32 s28, s55, s56
	s_cselect_b32 s29, s19, s74
	s_add_u32 s26, s30, 0x400000
	s_addc_u32 s27, s31, 0
	s_add_i32 m0, s33, 0xc000
	ds_read_b128 v[184:187], v155
	ds_read_b128 v[188:191], v155 offset:1024
	ds_read_b128 v[192:195], v155 offset:2048
	ds_read_b128 v[196:199], v155 offset:3072
	ds_read_b128 v[200:203], v155 offset:4096
	ds_read_b128 v[204:207], v155 offset:5120
	ds_read_b128 v[208:211], v155 offset:6144
	ds_read_b128 v[212:215], v155 offset:7168
	global_load_lds_dwordx4 v136, s[24:25]
	s_add_i32 m0, s33, 0xe000
	s_nop 0
	global_load_lds_dwordx4 v138, s[24:25]
	s_waitcnt vmcnt(8)
	s_waitcnt lgkmcnt(0)
	s_setprio 1
	s_barrier
	v_mfma_f32_16x16x32_bf16 v[76:79], v[144:147], v[184:187], v[76:79]
	v_mfma_f32_16x16x32_bf16 v[72:75], v[160:163], v[184:187], v[72:75]
	v_mfma_f32_16x16x32_bf16 v[68:71], v[144:147], v[192:195], v[68:71]
	v_mfma_f32_16x16x32_bf16 v[64:67], v[160:163], v[192:195], v[64:67]
	v_mfma_f32_16x16x32_bf16 v[56:59], v[144:147], v[200:203], v[56:59]
	v_mfma_f32_16x16x32_bf16 v[52:55], v[160:163], v[200:203], v[52:55]
	v_mfma_f32_16x16x32_bf16 v[44:47], v[144:147], v[208:211], v[44:47]
	v_mfma_f32_16x16x32_bf16 v[40:43], v[160:163], v[208:211], v[40:43]
	v_mfma_f32_16x16x32_bf16 v[76:79], v[156:159], v[188:191], v[76:79]
	v_mfma_f32_16x16x32_bf16 v[72:75], v[164:167], v[188:191], v[72:75]
	v_mfma_f32_16x16x32_bf16 v[68:71], v[156:159], v[196:199], v[68:71]
	v_mfma_f32_16x16x32_bf16 v[64:67], v[164:167], v[196:199], v[64:67]
	v_mfma_f32_16x16x32_bf16 v[56:59], v[156:159], v[204:207], v[56:59]
	v_mfma_f32_16x16x32_bf16 v[52:55], v[164:167], v[204:207], v[52:55]
	v_mfma_f32_16x16x32_bf16 v[44:47], v[156:159], v[212:215], v[44:47]
	v_mfma_f32_16x16x32_bf16 v[40:43], v[164:167], v[212:215], v[40:43]
	v_mfma_f32_16x16x32_bf16 v[124:127], v[168:171], v[184:187], v[124:127]
	v_mfma_f32_16x16x32_bf16 v[120:123], v[176:179], v[184:187], v[120:123]
	v_mfma_f32_16x16x32_bf16 v[116:119], v[168:171], v[192:195], v[116:119]
	v_mfma_f32_16x16x32_bf16 v[112:115], v[176:179], v[192:195], v[112:115]
	v_mfma_f32_16x16x32_bf16 v[108:111], v[168:171], v[200:203], v[108:111]
	v_mfma_f32_16x16x32_bf16 v[104:107], v[176:179], v[200:203], v[104:107]
	v_mfma_f32_16x16x32_bf16 v[100:103], v[168:171], v[208:211], v[100:103]
	v_mfma_f32_16x16x32_bf16 v[96:99], v[176:179], v[208:211], v[96:99]
	v_mfma_f32_16x16x32_bf16 v[124:127], v[172:175], v[188:191], v[124:127]
	v_mfma_f32_16x16x32_bf16 v[120:123], v[180:183], v[188:191], v[120:123]
	v_mfma_f32_16x16x32_bf16 v[116:119], v[172:175], v[196:199], v[116:119]
	v_mfma_f32_16x16x32_bf16 v[112:115], v[180:183], v[196:199], v[112:115]
	v_mfma_f32_16x16x32_bf16 v[108:111], v[172:175], v[204:207], v[108:111]
	v_mfma_f32_16x16x32_bf16 v[104:107], v[180:183], v[204:207], v[104:107]
	v_mfma_f32_16x16x32_bf16 v[100:103], v[172:175], v[212:215], v[100:103]
	v_mfma_f32_16x16x32_bf16 v[96:99], v[180:183], v[212:215], v[96:99]
	s_barrier
	s_setprio 0
	s_add_i32 s78, s57, s5
	s_mov_b32 m0, s78
	ds_read_b128 v[184:187], v155 offset:16384
	ds_read_b128 v[188:191], v155 offset:17408
	ds_read_b128 v[192:195], v155 offset:18432
	ds_read_b128 v[196:199], v155 offset:19456
	ds_read_b128 v[200:203], v155 offset:20480
	ds_read_b128 v[204:207], v155 offset:21504
	ds_read_b128 v[208:211], v155 offset:22528
	ds_read_b128 v[212:215], v155 offset:23552
	global_load_lds_dwordx4 v132, s[28:29]
	s_add_i32 m0, s78, 0x2000
	s_add_u32 s78, s28, 0x4000
	s_addc_u32 s79, s29, 0
	s_add_i32 s80, s81, s5
	global_load_lds_dwordx4 v128, s[28:29]
	s_mov_b32 m0, s80
	s_nop 0
	global_load_lds_dwordx4 v132, s[78:79]
	s_add_i32 m0, s80, 0x2000
	s_nop 0
	global_load_lds_dwordx4 v128, s[78:79]
	s_mov_b32 m0, s33
	s_nop 0
	global_load_lds_dwordx4 v134, s[30:31]
	s_mov_b32 m0, s34
	s_nop 0
	global_load_lds_dwordx4 v130, s[30:31]
	s_waitcnt vmcnt(8)
	s_waitcnt lgkmcnt(0)
	s_setprio 1
	s_barrier
	v_mfma_f32_16x16x32_bf16 v[28:31], v[144:147], v[184:187], v[28:31]
	v_mfma_f32_16x16x32_bf16 v[24:27], v[160:163], v[184:187], v[24:27]
	v_mfma_f32_16x16x32_bf16 v[20:23], v[144:147], v[192:195], v[20:23]
	v_mfma_f32_16x16x32_bf16 v[16:19], v[160:163], v[192:195], v[16:19]
	v_mfma_f32_16x16x32_bf16 v[12:15], v[144:147], v[200:203], v[12:15]
	v_mfma_f32_16x16x32_bf16 v[8:11], v[160:163], v[200:203], v[8:11]
	v_mfma_f32_16x16x32_bf16 v[4:7], v[144:147], v[208:211], v[4:7]
	v_mfma_f32_16x16x32_bf16 v[0:3], v[160:163], v[208:211], v[0:3]
	v_mfma_f32_16x16x32_bf16 v[28:31], v[156:159], v[188:191], v[28:31]
	v_mfma_f32_16x16x32_bf16 v[24:27], v[164:167], v[188:191], v[24:27]
	v_mfma_f32_16x16x32_bf16 v[20:23], v[156:159], v[196:199], v[20:23]
	v_mfma_f32_16x16x32_bf16 v[16:19], v[164:167], v[196:199], v[16:19]
	v_mfma_f32_16x16x32_bf16 v[12:15], v[156:159], v[204:207], v[12:15]
	v_mfma_f32_16x16x32_bf16 v[8:11], v[164:167], v[204:207], v[8:11]
	v_mfma_f32_16x16x32_bf16 v[4:7], v[156:159], v[212:215], v[4:7]
	v_mfma_f32_16x16x32_bf16 v[0:3], v[164:167], v[212:215], v[0:3]
	v_mfma_f32_16x16x32_bf16 v[92:95], v[168:171], v[184:187], v[92:95]
	v_mfma_f32_16x16x32_bf16 v[88:91], v[176:179], v[184:187], v[88:91]
	v_mfma_f32_16x16x32_bf16 v[84:87], v[168:171], v[192:195], v[84:87]
	v_mfma_f32_16x16x32_bf16 v[80:83], v[176:179], v[192:195], v[80:83]
	v_mfma_f32_16x16x32_bf16 v[60:63], v[168:171], v[200:203], v[60:63]
	v_mfma_f32_16x16x32_bf16 v[48:51], v[176:179], v[200:203], v[48:51]
	v_mfma_f32_16x16x32_bf16 v[36:39], v[168:171], v[208:211], v[36:39]
	v_mfma_f32_16x16x32_bf16 v[32:35], v[176:179], v[208:211], v[32:35]
	v_mfma_f32_16x16x32_bf16 v[92:95], v[172:175], v[188:191], v[92:95]
	v_mfma_f32_16x16x32_bf16 v[88:91], v[180:183], v[188:191], v[88:91]
	v_mfma_f32_16x16x32_bf16 v[84:87], v[172:175], v[196:199], v[84:87]
	v_mfma_f32_16x16x32_bf16 v[80:83], v[180:183], v[196:199], v[80:83]
	v_mfma_f32_16x16x32_bf16 v[60:63], v[172:175], v[204:207], v[60:63]
	v_mfma_f32_16x16x32_bf16 v[48:51], v[180:183], v[204:207], v[48:51]
	v_mfma_f32_16x16x32_bf16 v[36:39], v[172:175], v[212:215], v[36:39]
	v_mfma_f32_16x16x32_bf16 v[32:35], v[180:183], v[212:215], v[32:35]
	s_barrier
	s_setprio 0
	v_add_u32_e32 v148, s82, v152
	ds_read_b128 v[144:147], v148
	ds_read_b128 v[156:159], v148 offset:1024
	ds_read_b128 v[160:163], v148 offset:2048
	ds_read_b128 v[164:167], v148 offset:3072
	v_add_u32_e32 v148, s83, v152
	ds_read_b128 v[168:171], v148
	ds_read_b128 v[172:175], v148 offset:1024
	ds_read_b128 v[176:179], v148 offset:2048
	ds_read_b128 v[180:183], v148 offset:3072
	s_add_u32 s30, s30, 0x4000
	s_addc_u32 s31, s31, 0
	s_mov_b32 m0, s35
	ds_read_b128 v[184:187], v155 offset:32768
	ds_read_b128 v[188:191], v155 offset:33792
	ds_read_b128 v[192:195], v155 offset:34816
	ds_read_b128 v[196:199], v155 offset:35840
	ds_read_b128 v[200:203], v155 offset:36864
	ds_read_b128 v[204:207], v155 offset:37888
	ds_read_b128 v[208:211], v155 offset:38912
	ds_read_b128 v[212:215], v155 offset:39936
	global_load_lds_dwordx4 v134, s[30:31]
	s_mov_b32 m0, s36
	s_nop 0
	global_load_lds_dwordx4 v130, s[30:31]
	s_waitcnt vmcnt(8)
	s_waitcnt lgkmcnt(0)
	s_setprio 1
	s_barrier
	v_mfma_f32_16x16x32_bf16 v[76:79], v[144:147], v[184:187], v[76:79]
	v_mfma_f32_16x16x32_bf16 v[72:75], v[160:163], v[184:187], v[72:75]
	v_mfma_f32_16x16x32_bf16 v[68:71], v[144:147], v[192:195], v[68:71]
	v_mfma_f32_16x16x32_bf16 v[64:67], v[160:163], v[192:195], v[64:67]
	v_mfma_f32_16x16x32_bf16 v[56:59], v[144:147], v[200:203], v[56:59]
	v_mfma_f32_16x16x32_bf16 v[52:55], v[160:163], v[200:203], v[52:55]
	v_mfma_f32_16x16x32_bf16 v[44:47], v[144:147], v[208:211], v[44:47]
	v_mfma_f32_16x16x32_bf16 v[40:43], v[160:163], v[208:211], v[40:43]
	v_mfma_f32_16x16x32_bf16 v[76:79], v[156:159], v[188:191], v[76:79]
	v_mfma_f32_16x16x32_bf16 v[72:75], v[164:167], v[188:191], v[72:75]
	v_mfma_f32_16x16x32_bf16 v[68:71], v[156:159], v[196:199], v[68:71]
	v_mfma_f32_16x16x32_bf16 v[64:67], v[164:167], v[196:199], v[64:67]
	v_mfma_f32_16x16x32_bf16 v[56:59], v[156:159], v[204:207], v[56:59]
	v_mfma_f32_16x16x32_bf16 v[52:55], v[164:167], v[204:207], v[52:55]
	v_mfma_f32_16x16x32_bf16 v[44:47], v[156:159], v[212:215], v[44:47]
	v_mfma_f32_16x16x32_bf16 v[40:43], v[164:167], v[212:215], v[40:43]
	v_mfma_f32_16x16x32_bf16 v[124:127], v[168:171], v[184:187], v[124:127]
	v_mfma_f32_16x16x32_bf16 v[120:123], v[176:179], v[184:187], v[120:123]
	v_mfma_f32_16x16x32_bf16 v[116:119], v[168:171], v[192:195], v[116:119]
	v_mfma_f32_16x16x32_bf16 v[112:115], v[176:179], v[192:195], v[112:115]
	v_mfma_f32_16x16x32_bf16 v[108:111], v[168:171], v[200:203], v[108:111]
	v_mfma_f32_16x16x32_bf16 v[104:107], v[176:179], v[200:203], v[104:107]
	v_mfma_f32_16x16x32_bf16 v[100:103], v[168:171], v[208:211], v[100:103]
	v_mfma_f32_16x16x32_bf16 v[96:99], v[176:179], v[208:211], v[96:99]
	v_mfma_f32_16x16x32_bf16 v[124:127], v[172:175], v[188:191], v[124:127]
	v_mfma_f32_16x16x32_bf16 v[120:123], v[180:183], v[188:191], v[120:123]
	v_mfma_f32_16x16x32_bf16 v[116:119], v[172:175], v[196:199], v[116:119]
	v_mfma_f32_16x16x32_bf16 v[112:115], v[180:183], v[196:199], v[112:115]
	v_mfma_f32_16x16x32_bf16 v[108:111], v[172:175], v[204:207], v[108:111]
	v_mfma_f32_16x16x32_bf16 v[104:107], v[180:183], v[204:207], v[104:107]
	v_mfma_f32_16x16x32_bf16 v[100:103], v[172:175], v[212:215], v[100:103]
	v_mfma_f32_16x16x32_bf16 v[96:99], v[180:183], v[212:215], v[96:99]
	s_barrier
	s_setprio 0
	s_add_u32 s30, s28, 0xd8000
	s_addc_u32 s31, s29, 0
	s_add_i32 s78, s82, s5
	s_mov_b32 m0, s78
	ds_read_b128 v[184:187], v155 offset:49152
	ds_read_b128 v[188:191], v155 offset:50176
	ds_read_b128 v[192:195], v155 offset:51200
	ds_read_b128 v[196:199], v155 offset:52224
	ds_read_b128 v[200:203], v155 offset:53248
	ds_read_b128 v[204:207], v155 offset:54272
	ds_read_b128 v[208:211], v155 offset:55296
	ds_read_b128 v[212:215], v155 offset:56320
	global_load_lds_dwordx4 v132, s[30:31]
	s_add_i32 m0, s78, 0x2000
	s_add_u32 s28, s28, 0xdc000
	global_load_lds_dwordx4 v128, s[30:31]
	s_addc_u32 s29, s29, 0
	s_add_i32 s30, s83, s5
	s_mov_b32 m0, s30
	s_nop 0
	global_load_lds_dwordx4 v132, s[28:29]
	s_add_i32 m0, s30, 0x2000
	s_nop 0
	global_load_lds_dwordx4 v128, s[28:29]
	s_mov_b32 m0, s44
	s_nop 0
	global_load_lds_dwordx4 v134, s[26:27]
	s_mov_b32 m0, s45
	s_nop 0
	global_load_lds_dwordx4 v130, s[26:27]
	s_waitcnt vmcnt(8)
	s_waitcnt lgkmcnt(0)
	s_setprio 1
	s_barrier
	v_mfma_f32_16x16x32_bf16 v[28:31], v[144:147], v[184:187], v[28:31]
	v_mfma_f32_16x16x32_bf16 v[24:27], v[160:163], v[184:187], v[24:27]
	v_mfma_f32_16x16x32_bf16 v[20:23], v[144:147], v[192:195], v[20:23]
	v_mfma_f32_16x16x32_bf16 v[16:19], v[160:163], v[192:195], v[16:19]
	v_mfma_f32_16x16x32_bf16 v[12:15], v[144:147], v[200:203], v[12:15]
	v_mfma_f32_16x16x32_bf16 v[8:11], v[160:163], v[200:203], v[8:11]
	v_mfma_f32_16x16x32_bf16 v[4:7], v[144:147], v[208:211], v[4:7]
	v_mfma_f32_16x16x32_bf16 v[0:3], v[160:163], v[208:211], v[0:3]
	v_mfma_f32_16x16x32_bf16 v[28:31], v[156:159], v[188:191], v[28:31]
	v_mfma_f32_16x16x32_bf16 v[24:27], v[164:167], v[188:191], v[24:27]
	v_mfma_f32_16x16x32_bf16 v[20:23], v[156:159], v[196:199], v[20:23]
	v_mfma_f32_16x16x32_bf16 v[16:19], v[164:167], v[196:199], v[16:19]
	v_mfma_f32_16x16x32_bf16 v[12:15], v[156:159], v[204:207], v[12:15]
	v_mfma_f32_16x16x32_bf16 v[8:11], v[164:167], v[204:207], v[8:11]
	v_mfma_f32_16x16x32_bf16 v[4:7], v[156:159], v[212:215], v[4:7]
	v_mfma_f32_16x16x32_bf16 v[0:3], v[164:167], v[212:215], v[0:3]
	v_mfma_f32_16x16x32_bf16 v[92:95], v[168:171], v[184:187], v[92:95]
	v_mfma_f32_16x16x32_bf16 v[88:91], v[176:179], v[184:187], v[88:91]
	v_mfma_f32_16x16x32_bf16 v[84:87], v[168:171], v[192:195], v[84:87]
	v_mfma_f32_16x16x32_bf16 v[80:83], v[176:179], v[192:195], v[80:83]
	v_mfma_f32_16x16x32_bf16 v[60:63], v[168:171], v[200:203], v[60:63]
	v_mfma_f32_16x16x32_bf16 v[48:51], v[176:179], v[200:203], v[48:51]
	v_mfma_f32_16x16x32_bf16 v[36:39], v[168:171], v[208:211], v[36:39]
	v_mfma_f32_16x16x32_bf16 v[32:35], v[176:179], v[208:211], v[32:35]
	v_mfma_f32_16x16x32_bf16 v[92:95], v[172:175], v[188:191], v[92:95]
	v_mfma_f32_16x16x32_bf16 v[88:91], v[180:183], v[188:191], v[88:91]
	v_mfma_f32_16x16x32_bf16 v[84:87], v[172:175], v[196:199], v[84:87]
	v_mfma_f32_16x16x32_bf16 v[80:83], v[180:183], v[196:199], v[80:83]
	v_mfma_f32_16x16x32_bf16 v[60:63], v[172:175], v[204:207], v[60:63]
	v_mfma_f32_16x16x32_bf16 v[48:51], v[180:183], v[204:207], v[48:51]
	v_mfma_f32_16x16x32_bf16 v[36:39], v[172:175], v[212:215], v[36:39]
	v_mfma_f32_16x16x32_bf16 v[32:35], v[180:183], v[212:215], v[32:35]
	s_barrier
	s_setprio 0
	s_add_i32 s75, s75, 2
	s_add_u32 s56, s56, 0x1b0000
	s_addc_u32 s74, s74, 0
	s_add_u32 s24, s24, 0x800000
	s_addc_u32 s25, s25, 0
	s_cmp_gt_u32 s75, 29
	s_cbranch_scc0 .LBB0_732
	s_and_b64 vcc, exec, s[12:13]
	s_cbranch_vccz .LBB0_735
	s_barrier

.LBB0_746:
	ds_read_b128 v[148:151], v142
	ds_read_b128 v[152:155], v142 offset:1024
	ds_read_b128 v[156:159], v142 offset:2048
	ds_read_b128 v[160:163], v142 offset:3072
	ds_read_b128 v[164:167], v143
	ds_read_b128 v[168:171], v143 offset:1024
	ds_read_b128 v[172:175], v143 offset:2048
	ds_read_b128 v[176:179], v143 offset:3072
	s_add_u32 s16, s12, s14
	s_addc_u32 s17, s13, s15
	s_add_u32 s16, s16, 0x21000100
	s_addc_u32 s17, s17, 0
	s_add_u32 s42, s28, s14
	s_addc_u32 s43, s29, s15
	s_cmpk_eq_i32 s14, 0xf00
	s_cselect_b32 s19, s9, s17
	s_cselect_b32 s18, s8, s16
	s_cselect_b32 s17, s7, s43
	s_cselect_b32 s16, s6, s42
	s_mov_b32 m0, s31
	v_lshl_add_u64 v[212:213], v[136:137], 0, s[14:15]
	ds_read_b128 v[180:183], v144
	ds_read_b128 v[184:187], v144 offset:1024
	ds_read_b128 v[188:191], v144 offset:2048
	ds_read_b128 v[192:195], v144 offset:3072
	ds_read_b128 v[196:199], v144 offset:4096
	ds_read_b128 v[200:203], v144 offset:5120
	ds_read_b128 v[204:207], v144 offset:6144
	ds_read_b128 v[208:211], v144 offset:7168
	global_load_lds_dwordx4 v[212:213], off
	v_lshl_add_u64 v[212:213], v[138:139], 0, s[14:15]
	s_mov_b32 m0, s33
	s_nop 0
	global_load_lds_dwordx4 v[212:213], off
	s_waitcnt vmcnt(8)
	s_waitcnt lgkmcnt(0)
	s_setprio 1
	s_barrier
	v_mfma_f32_16x16x32_bf16 v[124:127], v[148:151], v[180:183], v[124:127]
	v_mfma_f32_16x16x32_bf16 v[120:123], v[156:159], v[180:183], v[120:123]
	v_mfma_f32_16x16x32_bf16 v[116:119], v[148:151], v[188:191], v[116:119]
	v_mfma_f32_16x16x32_bf16 v[108:111], v[156:159], v[188:191], v[108:111]
	v_mfma_f32_16x16x32_bf16 v[100:103], v[148:151], v[196:199], v[100:103]
	v_mfma_f32_16x16x32_bf16 v[92:95], v[156:159], v[196:199], v[92:95]
	v_mfma_f32_16x16x32_bf16 v[84:87], v[148:151], v[204:207], v[84:87]
	v_mfma_f32_16x16x32_bf16 v[76:79], v[156:159], v[204:207], v[76:79]
	v_mfma_f32_16x16x32_bf16 v[124:127], v[152:155], v[184:187], v[124:127]
	v_mfma_f32_16x16x32_bf16 v[120:123], v[160:163], v[184:187], v[120:123]
	v_mfma_f32_16x16x32_bf16 v[116:119], v[152:155], v[192:195], v[116:119]
	v_mfma_f32_16x16x32_bf16 v[108:111], v[160:163], v[192:195], v[108:111]
	v_mfma_f32_16x16x32_bf16 v[100:103], v[152:155], v[200:203], v[100:103]
	v_mfma_f32_16x16x32_bf16 v[92:95], v[160:163], v[200:203], v[92:95]
	v_mfma_f32_16x16x32_bf16 v[84:87], v[152:155], v[208:211], v[84:87]
	v_mfma_f32_16x16x32_bf16 v[76:79], v[160:163], v[208:211], v[76:79]
	v_mfma_f32_16x16x32_bf16 v[112:115], v[164:167], v[180:183], v[112:115]
	v_mfma_f32_16x16x32_bf16 v[104:107], v[172:175], v[180:183], v[104:107]
	v_mfma_f32_16x16x32_bf16 v[96:99], v[164:167], v[188:191], v[96:99]
	v_mfma_f32_16x16x32_bf16 v[88:91], v[172:175], v[188:191], v[88:91]
	v_mfma_f32_16x16x32_bf16 v[80:83], v[164:167], v[196:199], v[80:83]
	v_mfma_f32_16x16x32_bf16 v[72:75], v[172:175], v[196:199], v[72:75]
	v_mfma_f32_16x16x32_bf16 v[68:71], v[164:167], v[204:207], v[68:71]
	v_mfma_f32_16x16x32_bf16 v[64:67], v[172:175], v[204:207], v[64:67]
	v_mfma_f32_16x16x32_bf16 v[112:115], v[168:171], v[184:187], v[112:115]
	v_mfma_f32_16x16x32_bf16 v[104:107], v[176:179], v[184:187], v[104:107]
	v_mfma_f32_16x16x32_bf16 v[96:99], v[168:171], v[192:195], v[96:99]
	v_mfma_f32_16x16x32_bf16 v[88:91], v[176:179], v[192:195], v[88:91]
	v_mfma_f32_16x16x32_bf16 v[80:83], v[168:171], v[200:203], v[80:83]
	v_mfma_f32_16x16x32_bf16 v[72:75], v[176:179], v[200:203], v[72:75]
	v_mfma_f32_16x16x32_bf16 v[68:71], v[168:171], v[208:211], v[68:71]
	v_mfma_f32_16x16x32_bf16 v[64:67], v[176:179], v[208:211], v[64:67]
	s_barrier
	s_setprio 0
	s_mov_b32 m0, s34
	v_lshl_add_u64 v[212:213], s[16:17], 0, v[132:133]
	s_add_u32 s42, s16, 0x80000
	ds_read_b128 v[180:183], v144 offset:16384
	ds_read_b128 v[184:187], v144 offset:17408
	ds_read_b128 v[188:191], v144 offset:18432
	ds_read_b128 v[192:195], v144 offset:19456
	ds_read_b128 v[196:199], v144 offset:20480
	ds_read_b128 v[200:203], v144 offset:21504
	ds_read_b128 v[204:207], v144 offset:22528
	ds_read_b128 v[208:211], v144 offset:23552
	global_load_lds_dwordx4 v[212:213], off
	v_lshl_add_u64 v[214:215], s[16:17], 0, v[128:129]
	s_mov_b32 m0, s35
	s_addc_u32 s43, s17, 0
	global_load_lds_dwordx4 v[214:215], off
	s_mov_b32 m0, s36
	v_lshl_add_u64 v[218:219], s[18:19], 0, v[130:131]
	global_load_lds_dwordx4 v132, s[42:43]
	s_mov_b32 m0, s37
	s_nop 0
	global_load_lds_dwordx4 v128, s[42:43]
	v_lshl_add_u64 v[216:217], s[18:19], 0, v[134:135]
	s_mov_b32 m0, s21
	s_nop 0
	global_load_lds_dwordx4 v[216:217], off
	s_mov_b32 m0, s23
	s_nop 0
	global_load_lds_dwordx4 v[218:219], off
	s_waitcnt vmcnt(8)
	s_waitcnt lgkmcnt(0)
	s_setprio 1
	s_barrier
	v_mfma_f32_16x16x32_bf16 v[60:63], v[148:151], v[180:183], v[60:63]
	v_mfma_f32_16x16x32_bf16 v[56:59], v[156:159], v[180:183], v[56:59]
	v_mfma_f32_16x16x32_bf16 v[52:55], v[148:151], v[188:191], v[52:55]
	v_mfma_f32_16x16x32_bf16 v[44:47], v[156:159], v[188:191], v[44:47]
	v_mfma_f32_16x16x32_bf16 v[36:39], v[148:151], v[196:199], v[36:39]
	v_mfma_f32_16x16x32_bf16 v[28:31], v[156:159], v[196:199], v[28:31]
	v_mfma_f32_16x16x32_bf16 v[20:23], v[148:151], v[204:207], v[20:23]
	v_mfma_f32_16x16x32_bf16 v[12:15], v[156:159], v[204:207], v[12:15]
	v_mfma_f32_16x16x32_bf16 v[60:63], v[152:155], v[184:187], v[60:63]
	v_mfma_f32_16x16x32_bf16 v[56:59], v[160:163], v[184:187], v[56:59]
	v_mfma_f32_16x16x32_bf16 v[52:55], v[152:155], v[192:195], v[52:55]
	v_mfma_f32_16x16x32_bf16 v[44:47], v[160:163], v[192:195], v[44:47]
	v_mfma_f32_16x16x32_bf16 v[36:39], v[152:155], v[200:203], v[36:39]
	v_mfma_f32_16x16x32_bf16 v[28:31], v[160:163], v[200:203], v[28:31]
	v_mfma_f32_16x16x32_bf16 v[20:23], v[152:155], v[208:211], v[20:23]
	v_mfma_f32_16x16x32_bf16 v[12:15], v[160:163], v[208:211], v[12:15]
	v_mfma_f32_16x16x32_bf16 v[48:51], v[164:167], v[180:183], v[48:51]
	v_mfma_f32_16x16x32_bf16 v[40:43], v[172:175], v[180:183], v[40:43]
	v_mfma_f32_16x16x32_bf16 v[32:35], v[164:167], v[188:191], v[32:35]
	v_mfma_f32_16x16x32_bf16 v[24:27], v[172:175], v[188:191], v[24:27]
	v_mfma_f32_16x16x32_bf16 v[16:19], v[164:167], v[196:199], v[16:19]
	v_mfma_f32_16x16x32_bf16 v[8:11], v[172:175], v[196:199], v[8:11]
	v_mfma_f32_16x16x32_bf16 v[4:7], v[164:167], v[204:207], v[4:7]
	v_mfma_f32_16x16x32_bf16 v[0:3], v[172:175], v[204:207], v[0:3]
	v_mfma_f32_16x16x32_bf16 v[48:51], v[168:171], v[184:187], v[48:51]
	v_mfma_f32_16x16x32_bf16 v[40:43], v[176:179], v[184:187], v[40:43]
	v_mfma_f32_16x16x32_bf16 v[32:35], v[168:171], v[192:195], v[32:35]
	v_mfma_f32_16x16x32_bf16 v[24:27], v[176:179], v[192:195], v[24:27]
	v_mfma_f32_16x16x32_bf16 v[16:19], v[168:171], v[200:203], v[16:19]
	v_mfma_f32_16x16x32_bf16 v[8:11], v[176:179], v[200:203], v[8:11]
	v_mfma_f32_16x16x32_bf16 v[4:7], v[168:171], v[208:211], v[4:7]
	v_mfma_f32_16x16x32_bf16 v[0:3], v[176:179], v[208:211], v[0:3]
	s_barrier
	s_setprio 0
	ds_read_b128 v[148:151], v145
	ds_read_b128 v[152:155], v145 offset:1024
	ds_read_b128 v[156:159], v145 offset:2048
	ds_read_b128 v[160:163], v145 offset:3072
	ds_read_b128 v[164:167], v146
	ds_read_b128 v[168:171], v146 offset:1024
	ds_read_b128 v[172:175], v146 offset:2048
	ds_read_b128 v[176:179], v146 offset:3072
	s_add_u32 s18, s18, 0x80000
	s_addc_u32 s19, s19, 0
	s_mov_b32 m0, s24
	ds_read_b128 v[180:183], v144 offset:32768
	ds_read_b128 v[184:187], v144 offset:33792
	ds_read_b128 v[188:191], v144 offset:34816
	ds_read_b128 v[192:195], v144 offset:35840
	ds_read_b128 v[196:199], v144 offset:36864
	ds_read_b128 v[200:203], v144 offset:37888
	ds_read_b128 v[204:207], v144 offset:38912
	ds_read_b128 v[208:211], v144 offset:39936
	global_load_lds_dwordx4 v134, s[18:19]
	v_lshl_add_u64 v[220:221], s[18:19], 0, v[130:131]
	s_mov_b32 m0, s25
	s_nop 0
	global_load_lds_dwordx4 v[220:221], off
	s_waitcnt vmcnt(8)
	s_waitcnt lgkmcnt(0)
	s_setprio 1
	s_barrier
	v_mfma_f32_16x16x32_bf16 v[124:127], v[148:151], v[180:183], v[124:127]
	v_mfma_f32_16x16x32_bf16 v[120:123], v[156:159], v[180:183], v[120:123]
	v_mfma_f32_16x16x32_bf16 v[116:119], v[148:151], v[188:191], v[116:119]
	v_mfma_f32_16x16x32_bf16 v[108:111], v[156:159], v[188:191], v[108:111]
	v_mfma_f32_16x16x32_bf16 v[100:103], v[148:151], v[196:199], v[100:103]
	v_mfma_f32_16x16x32_bf16 v[92:95], v[156:159], v[196:199], v[92:95]
	v_mfma_f32_16x16x32_bf16 v[84:87], v[148:151], v[204:207], v[84:87]
	v_mfma_f32_16x16x32_bf16 v[76:79], v[156:159], v[204:207], v[76:79]
	v_mfma_f32_16x16x32_bf16 v[124:127], v[152:155], v[184:187], v[124:127]
	v_mfma_f32_16x16x32_bf16 v[120:123], v[160:163], v[184:187], v[120:123]
	v_mfma_f32_16x16x32_bf16 v[116:119], v[152:155], v[192:195], v[116:119]
	v_mfma_f32_16x16x32_bf16 v[108:111], v[160:163], v[192:195], v[108:111]
	v_mfma_f32_16x16x32_bf16 v[100:103], v[152:155], v[200:203], v[100:103]
	v_mfma_f32_16x16x32_bf16 v[92:95], v[160:163], v[200:203], v[92:95]
	v_mfma_f32_16x16x32_bf16 v[84:87], v[152:155], v[208:211], v[84:87]
	v_mfma_f32_16x16x32_bf16 v[76:79], v[160:163], v[208:211], v[76:79]
	v_mfma_f32_16x16x32_bf16 v[112:115], v[164:167], v[180:183], v[112:115]
	v_mfma_f32_16x16x32_bf16 v[104:107], v[172:175], v[180:183], v[104:107]
	v_mfma_f32_16x16x32_bf16 v[96:99], v[164:167], v[188:191], v[96:99]
	v_mfma_f32_16x16x32_bf16 v[88:91], v[172:175], v[188:191], v[88:91]
	v_mfma_f32_16x16x32_bf16 v[80:83], v[164:167], v[196:199], v[80:83]
	v_mfma_f32_16x16x32_bf16 v[72:75], v[172:175], v[196:199], v[72:75]
	v_mfma_f32_16x16x32_bf16 v[68:71], v[164:167], v[204:207], v[68:71]
	v_mfma_f32_16x16x32_bf16 v[64:67], v[172:175], v[204:207], v[64:67]
	v_mfma_f32_16x16x32_bf16 v[112:115], v[168:171], v[184:187], v[112:115]
	v_mfma_f32_16x16x32_bf16 v[104:107], v[176:179], v[184:187], v[104:107]
	v_mfma_f32_16x16x32_bf16 v[96:99], v[168:171], v[192:195], v[96:99]
	v_mfma_f32_16x16x32_bf16 v[88:91], v[176:179], v[192:195], v[88:91]
	v_mfma_f32_16x16x32_bf16 v[80:83], v[168:171], v[200:203], v[80:83]
	v_mfma_f32_16x16x32_bf16 v[72:75], v[176:179], v[200:203], v[72:75]
	v_mfma_f32_16x16x32_bf16 v[68:71], v[168:171], v[208:211], v[68:71]
	v_mfma_f32_16x16x32_bf16 v[64:67], v[176:179], v[208:211], v[64:67]
	s_barrier
	s_setprio 0
	s_mov_b32 m0, s38
	v_lshl_add_u64 v[212:213], v[212:213], 0, s[10:11]
	s_add_u32 s16, s16, 0x80080
	ds_read_b128 v[180:183], v144 offset:49152
	ds_read_b128 v[184:187], v144 offset:50176
	ds_read_b128 v[188:191], v144 offset:51200
	ds_read_b128 v[192:195], v144 offset:52224
	ds_read_b128 v[196:199], v144 offset:53248
	ds_read_b128 v[200:203], v144 offset:54272
	ds_read_b128 v[204:207], v144 offset:55296
	ds_read_b128 v[208:211], v144 offset:56320
	global_load_lds_dwordx4 v[212:213], off
	v_lshl_add_u64 v[212:213], v[214:215], 0, s[10:11]
	s_mov_b32 m0, s39
	s_addc_u32 s17, s17, 0
	global_load_lds_dwordx4 v[212:213], off
	s_mov_b32 m0, s40
	s_nop 0
	global_load_lds_dwordx4 v132, s[16:17]
	s_mov_b32 m0, s41
	s_nop 0
	global_load_lds_dwordx4 v128, s[16:17]
	v_lshl_add_u64 v[212:213], v[216:217], 0, s[10:11]
	s_mov_b32 m0, s26
	s_nop 0
	global_load_lds_dwordx4 v[212:213], off
	v_lshl_add_u64 v[212:213], v[218:219], 0, s[10:11]
	s_mov_b32 m0, s27
	s_nop 0
	global_load_lds_dwordx4 v[212:213], off
	s_waitcnt vmcnt(8)
	s_waitcnt lgkmcnt(0)
	s_setprio 1
	s_barrier
	v_mfma_f32_16x16x32_bf16 v[60:63], v[148:151], v[180:183], v[60:63]
	v_mfma_f32_16x16x32_bf16 v[56:59], v[156:159], v[180:183], v[56:59]
	v_mfma_f32_16x16x32_bf16 v[52:55], v[148:151], v[188:191], v[52:55]
	v_mfma_f32_16x16x32_bf16 v[44:47], v[156:159], v[188:191], v[44:47]
	v_mfma_f32_16x16x32_bf16 v[36:39], v[148:151], v[196:199], v[36:39]
	v_mfma_f32_16x16x32_bf16 v[28:31], v[156:159], v[196:199], v[28:31]
	v_mfma_f32_16x16x32_bf16 v[20:23], v[148:151], v[204:207], v[20:23]
	v_mfma_f32_16x16x32_bf16 v[12:15], v[156:159], v[204:207], v[12:15]
	v_mfma_f32_16x16x32_bf16 v[60:63], v[152:155], v[184:187], v[60:63]
	v_mfma_f32_16x16x32_bf16 v[56:59], v[160:163], v[184:187], v[56:59]
	v_mfma_f32_16x16x32_bf16 v[52:55], v[152:155], v[192:195], v[52:55]
	v_mfma_f32_16x16x32_bf16 v[44:47], v[160:163], v[192:195], v[44:47]
	v_mfma_f32_16x16x32_bf16 v[36:39], v[152:155], v[200:203], v[36:39]
	v_mfma_f32_16x16x32_bf16 v[28:31], v[160:163], v[200:203], v[28:31]
	v_mfma_f32_16x16x32_bf16 v[20:23], v[152:155], v[208:211], v[20:23]
	v_mfma_f32_16x16x32_bf16 v[12:15], v[160:163], v[208:211], v[12:15]
	v_mfma_f32_16x16x32_bf16 v[48:51], v[164:167], v[180:183], v[48:51]
	v_mfma_f32_16x16x32_bf16 v[40:43], v[172:175], v[180:183], v[40:43]
	v_mfma_f32_16x16x32_bf16 v[32:35], v[164:167], v[188:191], v[32:35]
	v_mfma_f32_16x16x32_bf16 v[24:27], v[172:175], v[188:191], v[24:27]
	v_mfma_f32_16x16x32_bf16 v[16:19], v[164:167], v[196:199], v[16:19]
	v_mfma_f32_16x16x32_bf16 v[8:11], v[172:175], v[196:199], v[8:11]
	v_mfma_f32_16x16x32_bf16 v[4:7], v[164:167], v[204:207], v[4:7]
	v_mfma_f32_16x16x32_bf16 v[0:3], v[172:175], v[204:207], v[0:3]
	v_mfma_f32_16x16x32_bf16 v[48:51], v[168:171], v[184:187], v[48:51]
	v_mfma_f32_16x16x32_bf16 v[40:43], v[176:179], v[184:187], v[40:43]
	v_mfma_f32_16x16x32_bf16 v[32:35], v[168:171], v[192:195], v[32:35]
	v_mfma_f32_16x16x32_bf16 v[24:27], v[176:179], v[192:195], v[24:27]
	v_mfma_f32_16x16x32_bf16 v[16:19], v[168:171], v[200:203], v[16:19]
	v_mfma_f32_16x16x32_bf16 v[8:11], v[176:179], v[200:203], v[8:11]
	v_mfma_f32_16x16x32_bf16 v[4:7], v[168:171], v[208:211], v[4:7]
	v_mfma_f32_16x16x32_bf16 v[0:3], v[176:179], v[208:211], v[0:3]
	s_barrier
	s_setprio 0
	s_add_i32 s30, s30, 2
	s_add_u32 s14, s14, 0x100
	s_addc_u32 s15, s15, 0
	s_cmp_gt_u32 s30, 29
	s_cbranch_scc0 .LBB0_746
	s_cmp_lt_u32 s4, 4
	s_cbranch_scc0 .LBB0_749
	s_barrier

.LBB0_896:
	ds_read_b128 v[148:151], v142
	ds_read_b128 v[152:155], v142 offset:1024
	ds_read_b128 v[156:159], v142 offset:2048
	ds_read_b128 v[160:163], v142 offset:3072
	ds_read_b128 v[164:167], v143
	ds_read_b128 v[168:171], v143 offset:1024
	ds_read_b128 v[172:175], v143 offset:2048
	ds_read_b128 v[176:179], v143 offset:3072
	s_add_u32 s16, s12, s14
	s_addc_u32 s17, s13, s15
	s_add_u32 s16, s16, 0x21400100
	s_addc_u32 s17, s17, 0
	s_add_u32 s42, s28, s14
	s_addc_u32 s43, s29, s15
	s_cmpk_eq_i32 s14, 0x300
	s_cselect_b32 s19, s9, s17
	s_cselect_b32 s18, s8, s16
	s_cselect_b32 s17, s7, s43
	s_cselect_b32 s16, s6, s42
	s_mov_b32 m0, s31
	v_lshl_add_u64 v[212:213], v[136:137], 0, s[14:15]
	ds_read_b128 v[180:183], v144
	ds_read_b128 v[184:187], v144 offset:1024
	ds_read_b128 v[188:191], v144 offset:2048
	ds_read_b128 v[192:195], v144 offset:3072
	ds_read_b128 v[196:199], v144 offset:4096
	ds_read_b128 v[200:203], v144 offset:5120
	ds_read_b128 v[204:207], v144 offset:6144
	ds_read_b128 v[208:211], v144 offset:7168
	global_load_lds_dwordx4 v[212:213], off
	v_lshl_add_u64 v[212:213], v[138:139], 0, s[14:15]
	s_mov_b32 m0, s33
	s_nop 0
	global_load_lds_dwordx4 v[212:213], off
	s_waitcnt vmcnt(8)
	s_waitcnt lgkmcnt(0)
	s_setprio 1
	s_barrier
	v_mfma_f32_16x16x32_bf16 v[124:127], v[148:151], v[180:183], v[124:127]
	v_mfma_f32_16x16x32_bf16 v[120:123], v[156:159], v[180:183], v[120:123]
	v_mfma_f32_16x16x32_bf16 v[112:115], v[148:151], v[188:191], v[112:115]
	v_mfma_f32_16x16x32_bf16 v[104:107], v[156:159], v[188:191], v[104:107]
	v_mfma_f32_16x16x32_bf16 v[96:99], v[148:151], v[196:199], v[96:99]
	v_mfma_f32_16x16x32_bf16 v[88:91], v[156:159], v[196:199], v[88:91]
	v_mfma_f32_16x16x32_bf16 v[80:83], v[148:151], v[204:207], v[80:83]
	v_mfma_f32_16x16x32_bf16 v[72:75], v[156:159], v[204:207], v[72:75]
	v_mfma_f32_16x16x32_bf16 v[124:127], v[152:155], v[184:187], v[124:127]
	v_mfma_f32_16x16x32_bf16 v[120:123], v[160:163], v[184:187], v[120:123]
	v_mfma_f32_16x16x32_bf16 v[112:115], v[152:155], v[192:195], v[112:115]
	v_mfma_f32_16x16x32_bf16 v[104:107], v[160:163], v[192:195], v[104:107]
	v_mfma_f32_16x16x32_bf16 v[96:99], v[152:155], v[200:203], v[96:99]
	v_mfma_f32_16x16x32_bf16 v[88:91], v[160:163], v[200:203], v[88:91]
	v_mfma_f32_16x16x32_bf16 v[80:83], v[152:155], v[208:211], v[80:83]
	v_mfma_f32_16x16x32_bf16 v[72:75], v[160:163], v[208:211], v[72:75]
	v_mfma_f32_16x16x32_bf16 v[116:119], v[164:167], v[180:183], v[116:119]
	v_mfma_f32_16x16x32_bf16 v[108:111], v[172:175], v[180:183], v[108:111]
	v_mfma_f32_16x16x32_bf16 v[100:103], v[164:167], v[188:191], v[100:103]
	v_mfma_f32_16x16x32_bf16 v[92:95], v[172:175], v[188:191], v[92:95]
	v_mfma_f32_16x16x32_bf16 v[84:87], v[164:167], v[196:199], v[84:87]
	v_mfma_f32_16x16x32_bf16 v[76:79], v[172:175], v[196:199], v[76:79]
	v_mfma_f32_16x16x32_bf16 v[68:71], v[164:167], v[204:207], v[68:71]
	v_mfma_f32_16x16x32_bf16 v[64:67], v[172:175], v[204:207], v[64:67]
	v_mfma_f32_16x16x32_bf16 v[116:119], v[168:171], v[184:187], v[116:119]
	v_mfma_f32_16x16x32_bf16 v[108:111], v[176:179], v[184:187], v[108:111]
	v_mfma_f32_16x16x32_bf16 v[100:103], v[168:171], v[192:195], v[100:103]
	v_mfma_f32_16x16x32_bf16 v[92:95], v[176:179], v[192:195], v[92:95]
	v_mfma_f32_16x16x32_bf16 v[84:87], v[168:171], v[200:203], v[84:87]
	v_mfma_f32_16x16x32_bf16 v[76:79], v[176:179], v[200:203], v[76:79]
	v_mfma_f32_16x16x32_bf16 v[68:71], v[168:171], v[208:211], v[68:71]
	v_mfma_f32_16x16x32_bf16 v[64:67], v[176:179], v[208:211], v[64:67]
	s_barrier
	s_setprio 0
	s_mov_b32 m0, s34
	v_lshl_add_u64 v[212:213], s[16:17], 0, v[132:133]
	s_add_u32 s42, s16, 0x80000
	ds_read_b128 v[180:183], v144 offset:16384
	ds_read_b128 v[184:187], v144 offset:17408
	ds_read_b128 v[188:191], v144 offset:18432
	ds_read_b128 v[192:195], v144 offset:19456
	ds_read_b128 v[196:199], v144 offset:20480
	ds_read_b128 v[200:203], v144 offset:21504
	ds_read_b128 v[204:207], v144 offset:22528
	ds_read_b128 v[208:211], v144 offset:23552
	global_load_lds_dwordx4 v[212:213], off
	v_lshl_add_u64 v[214:215], s[16:17], 0, v[128:129]
	s_mov_b32 m0, s35
	s_addc_u32 s43, s17, 0
	global_load_lds_dwordx4 v[214:215], off
	s_mov_b32 m0, s36
	v_lshl_add_u64 v[218:219], s[18:19], 0, v[130:131]
	global_load_lds_dwordx4 v132, s[42:43]
	s_mov_b32 m0, s37
	s_nop 0
	global_load_lds_dwordx4 v128, s[42:43]
	v_lshl_add_u64 v[216:217], s[18:19], 0, v[134:135]
	s_mov_b32 m0, s21
	s_nop 0
	global_load_lds_dwordx4 v[216:217], off
	s_mov_b32 m0, s23
	s_nop 0
	global_load_lds_dwordx4 v[218:219], off
	s_waitcnt vmcnt(8)
	s_waitcnt lgkmcnt(0)
	s_setprio 1
	s_barrier
	v_mfma_f32_16x16x32_bf16 v[60:63], v[148:151], v[180:183], v[60:63]
	v_mfma_f32_16x16x32_bf16 v[56:59], v[156:159], v[180:183], v[56:59]
	v_mfma_f32_16x16x32_bf16 v[48:51], v[148:151], v[188:191], v[48:51]
	v_mfma_f32_16x16x32_bf16 v[40:43], v[156:159], v[188:191], v[40:43]
	v_mfma_f32_16x16x32_bf16 v[32:35], v[148:151], v[196:199], v[32:35]
	v_mfma_f32_16x16x32_bf16 v[24:27], v[156:159], v[196:199], v[24:27]
	v_mfma_f32_16x16x32_bf16 v[16:19], v[148:151], v[204:207], v[16:19]
	v_mfma_f32_16x16x32_bf16 v[8:11], v[156:159], v[204:207], v[8:11]
	v_mfma_f32_16x16x32_bf16 v[60:63], v[152:155], v[184:187], v[60:63]
	v_mfma_f32_16x16x32_bf16 v[56:59], v[160:163], v[184:187], v[56:59]
	v_mfma_f32_16x16x32_bf16 v[48:51], v[152:155], v[192:195], v[48:51]
	v_mfma_f32_16x16x32_bf16 v[40:43], v[160:163], v[192:195], v[40:43]
	v_mfma_f32_16x16x32_bf16 v[32:35], v[152:155], v[200:203], v[32:35]
	v_mfma_f32_16x16x32_bf16 v[24:27], v[160:163], v[200:203], v[24:27]
	v_mfma_f32_16x16x32_bf16 v[16:19], v[152:155], v[208:211], v[16:19]
	v_mfma_f32_16x16x32_bf16 v[8:11], v[160:163], v[208:211], v[8:11]
	v_mfma_f32_16x16x32_bf16 v[52:55], v[164:167], v[180:183], v[52:55]
	v_mfma_f32_16x16x32_bf16 v[44:47], v[172:175], v[180:183], v[44:47]
	v_mfma_f32_16x16x32_bf16 v[36:39], v[164:167], v[188:191], v[36:39]
	v_mfma_f32_16x16x32_bf16 v[28:31], v[172:175], v[188:191], v[28:31]
	v_mfma_f32_16x16x32_bf16 v[20:23], v[164:167], v[196:199], v[20:23]
	v_mfma_f32_16x16x32_bf16 v[12:15], v[172:175], v[196:199], v[12:15]
	v_mfma_f32_16x16x32_bf16 v[4:7], v[164:167], v[204:207], v[4:7]
	v_mfma_f32_16x16x32_bf16 v[0:3], v[172:175], v[204:207], v[0:3]
	v_mfma_f32_16x16x32_bf16 v[52:55], v[168:171], v[184:187], v[52:55]
	v_mfma_f32_16x16x32_bf16 v[44:47], v[176:179], v[184:187], v[44:47]
	v_mfma_f32_16x16x32_bf16 v[36:39], v[168:171], v[192:195], v[36:39]
	v_mfma_f32_16x16x32_bf16 v[28:31], v[176:179], v[192:195], v[28:31]
	v_mfma_f32_16x16x32_bf16 v[20:23], v[168:171], v[200:203], v[20:23]
	v_mfma_f32_16x16x32_bf16 v[12:15], v[176:179], v[200:203], v[12:15]
	v_mfma_f32_16x16x32_bf16 v[4:7], v[168:171], v[208:211], v[4:7]
	v_mfma_f32_16x16x32_bf16 v[0:3], v[176:179], v[208:211], v[0:3]
	s_barrier
	s_setprio 0
	ds_read_b128 v[148:151], v145
	ds_read_b128 v[152:155], v145 offset:1024
	ds_read_b128 v[156:159], v145 offset:2048
	ds_read_b128 v[160:163], v145 offset:3072
	ds_read_b128 v[164:167], v146
	ds_read_b128 v[168:171], v146 offset:1024
	ds_read_b128 v[172:175], v146 offset:2048
	ds_read_b128 v[176:179], v146 offset:3072
	s_add_u32 s18, s18, 0x100000
	s_addc_u32 s19, s19, 0
	s_mov_b32 m0, s24
	ds_read_b128 v[180:183], v144 offset:32768
	ds_read_b128 v[184:187], v144 offset:33792
	ds_read_b128 v[188:191], v144 offset:34816
	ds_read_b128 v[192:195], v144 offset:35840
	ds_read_b128 v[196:199], v144 offset:36864
	ds_read_b128 v[200:203], v144 offset:37888
	ds_read_b128 v[204:207], v144 offset:38912
	ds_read_b128 v[208:211], v144 offset:39936
	global_load_lds_dwordx4 v134, s[18:19]
	s_mov_b32 m0, s25
	s_nop 0
	global_load_lds_dwordx4 v130, s[18:19]
	s_waitcnt vmcnt(8)
	s_waitcnt lgkmcnt(0)
	s_setprio 1
	s_barrier
	v_mfma_f32_16x16x32_bf16 v[124:127], v[148:151], v[180:183], v[124:127]
	v_mfma_f32_16x16x32_bf16 v[120:123], v[156:159], v[180:183], v[120:123]
	v_mfma_f32_16x16x32_bf16 v[112:115], v[148:151], v[188:191], v[112:115]
	v_mfma_f32_16x16x32_bf16 v[104:107], v[156:159], v[188:191], v[104:107]
	v_mfma_f32_16x16x32_bf16 v[96:99], v[148:151], v[196:199], v[96:99]
	v_mfma_f32_16x16x32_bf16 v[88:91], v[156:159], v[196:199], v[88:91]
	v_mfma_f32_16x16x32_bf16 v[80:83], v[148:151], v[204:207], v[80:83]
	v_mfma_f32_16x16x32_bf16 v[72:75], v[156:159], v[204:207], v[72:75]
	v_mfma_f32_16x16x32_bf16 v[124:127], v[152:155], v[184:187], v[124:127]
	v_mfma_f32_16x16x32_bf16 v[120:123], v[160:163], v[184:187], v[120:123]
	v_mfma_f32_16x16x32_bf16 v[112:115], v[152:155], v[192:195], v[112:115]
	v_mfma_f32_16x16x32_bf16 v[104:107], v[160:163], v[192:195], v[104:107]
	v_mfma_f32_16x16x32_bf16 v[96:99], v[152:155], v[200:203], v[96:99]
	v_mfma_f32_16x16x32_bf16 v[88:91], v[160:163], v[200:203], v[88:91]
	v_mfma_f32_16x16x32_bf16 v[80:83], v[152:155], v[208:211], v[80:83]
	v_mfma_f32_16x16x32_bf16 v[72:75], v[160:163], v[208:211], v[72:75]
	v_mfma_f32_16x16x32_bf16 v[116:119], v[164:167], v[180:183], v[116:119]
	v_mfma_f32_16x16x32_bf16 v[108:111], v[172:175], v[180:183], v[108:111]
	v_mfma_f32_16x16x32_bf16 v[100:103], v[164:167], v[188:191], v[100:103]
	v_mfma_f32_16x16x32_bf16 v[92:95], v[172:175], v[188:191], v[92:95]
	v_mfma_f32_16x16x32_bf16 v[84:87], v[164:167], v[196:199], v[84:87]
	v_mfma_f32_16x16x32_bf16 v[76:79], v[172:175], v[196:199], v[76:79]
	v_mfma_f32_16x16x32_bf16 v[68:71], v[164:167], v[204:207], v[68:71]
	v_mfma_f32_16x16x32_bf16 v[64:67], v[172:175], v[204:207], v[64:67]
	v_mfma_f32_16x16x32_bf16 v[116:119], v[168:171], v[184:187], v[116:119]
	v_mfma_f32_16x16x32_bf16 v[108:111], v[176:179], v[184:187], v[108:111]
	v_mfma_f32_16x16x32_bf16 v[100:103], v[168:171], v[192:195], v[100:103]
	v_mfma_f32_16x16x32_bf16 v[92:95], v[176:179], v[192:195], v[92:95]
	v_mfma_f32_16x16x32_bf16 v[84:87], v[168:171], v[200:203], v[84:87]
	v_mfma_f32_16x16x32_bf16 v[76:79], v[176:179], v[200:203], v[76:79]
	v_mfma_f32_16x16x32_bf16 v[68:71], v[168:171], v[208:211], v[68:71]
	v_mfma_f32_16x16x32_bf16 v[64:67], v[176:179], v[208:211], v[64:67]
	s_barrier
	s_setprio 0
	s_mov_b32 m0, s38
	v_lshl_add_u64 v[212:213], v[212:213], 0, s[10:11]
	s_add_u32 s16, s16, 0x80080
	ds_read_b128 v[180:183], v144 offset:49152
	ds_read_b128 v[184:187], v144 offset:50176
	ds_read_b128 v[188:191], v144 offset:51200
	ds_read_b128 v[192:195], v144 offset:52224
	ds_read_b128 v[196:199], v144 offset:53248
	ds_read_b128 v[200:203], v144 offset:54272
	ds_read_b128 v[204:207], v144 offset:55296
	ds_read_b128 v[208:211], v144 offset:56320
	global_load_lds_dwordx4 v[212:213], off
	v_lshl_add_u64 v[212:213], v[214:215], 0, s[10:11]
	s_mov_b32 m0, s39
	s_addc_u32 s17, s17, 0
	global_load_lds_dwordx4 v[212:213], off
	s_mov_b32 m0, s40
	s_nop 0
	global_load_lds_dwordx4 v132, s[16:17]
	s_mov_b32 m0, s41
	s_nop 0
	global_load_lds_dwordx4 v128, s[16:17]
	v_lshl_add_u64 v[212:213], v[216:217], 0, s[10:11]
	s_mov_b32 m0, s26
	s_nop 0
	global_load_lds_dwordx4 v[212:213], off
	v_lshl_add_u64 v[212:213], v[218:219], 0, s[10:11]
	s_mov_b32 m0, s27
	s_nop 0
	global_load_lds_dwordx4 v[212:213], off
	s_waitcnt vmcnt(8)
	s_waitcnt lgkmcnt(0)
	s_setprio 1
	s_barrier
	v_mfma_f32_16x16x32_bf16 v[60:63], v[148:151], v[180:183], v[60:63]
	v_mfma_f32_16x16x32_bf16 v[56:59], v[156:159], v[180:183], v[56:59]
	v_mfma_f32_16x16x32_bf16 v[48:51], v[148:151], v[188:191], v[48:51]
	v_mfma_f32_16x16x32_bf16 v[40:43], v[156:159], v[188:191], v[40:43]
	v_mfma_f32_16x16x32_bf16 v[32:35], v[148:151], v[196:199], v[32:35]
	v_mfma_f32_16x16x32_bf16 v[24:27], v[156:159], v[196:199], v[24:27]
	v_mfma_f32_16x16x32_bf16 v[16:19], v[148:151], v[204:207], v[16:19]
	v_mfma_f32_16x16x32_bf16 v[8:11], v[156:159], v[204:207], v[8:11]
	v_mfma_f32_16x16x32_bf16 v[60:63], v[152:155], v[184:187], v[60:63]
	v_mfma_f32_16x16x32_bf16 v[56:59], v[160:163], v[184:187], v[56:59]
	v_mfma_f32_16x16x32_bf16 v[48:51], v[152:155], v[192:195], v[48:51]
	v_mfma_f32_16x16x32_bf16 v[40:43], v[160:163], v[192:195], v[40:43]
	v_mfma_f32_16x16x32_bf16 v[32:35], v[152:155], v[200:203], v[32:35]
	v_mfma_f32_16x16x32_bf16 v[24:27], v[160:163], v[200:203], v[24:27]
	v_mfma_f32_16x16x32_bf16 v[16:19], v[152:155], v[208:211], v[16:19]
	v_mfma_f32_16x16x32_bf16 v[8:11], v[160:163], v[208:211], v[8:11]
	v_mfma_f32_16x16x32_bf16 v[52:55], v[164:167], v[180:183], v[52:55]
	v_mfma_f32_16x16x32_bf16 v[44:47], v[172:175], v[180:183], v[44:47]
	v_mfma_f32_16x16x32_bf16 v[36:39], v[164:167], v[188:191], v[36:39]
	v_mfma_f32_16x16x32_bf16 v[28:31], v[172:175], v[188:191], v[28:31]
	v_mfma_f32_16x16x32_bf16 v[20:23], v[164:167], v[196:199], v[20:23]
	v_mfma_f32_16x16x32_bf16 v[12:15], v[172:175], v[196:199], v[12:15]
	v_mfma_f32_16x16x32_bf16 v[4:7], v[164:167], v[204:207], v[4:7]
	v_mfma_f32_16x16x32_bf16 v[0:3], v[172:175], v[204:207], v[0:3]
	v_mfma_f32_16x16x32_bf16 v[52:55], v[168:171], v[184:187], v[52:55]
	v_mfma_f32_16x16x32_bf16 v[44:47], v[176:179], v[184:187], v[44:47]
	v_mfma_f32_16x16x32_bf16 v[36:39], v[168:171], v[192:195], v[36:39]
	v_mfma_f32_16x16x32_bf16 v[28:31], v[176:179], v[192:195], v[28:31]
	v_mfma_f32_16x16x32_bf16 v[20:23], v[168:171], v[200:203], v[20:23]
	v_mfma_f32_16x16x32_bf16 v[12:15], v[176:179], v[200:203], v[12:15]
	v_mfma_f32_16x16x32_bf16 v[4:7], v[168:171], v[208:211], v[4:7]
	v_mfma_f32_16x16x32_bf16 v[0:3], v[176:179], v[208:211], v[0:3]
	s_barrier
	s_setprio 0
	s_add_i32 s30, s30, 2
	s_add_u32 s14, s14, 0x100
	s_addc_u32 s15, s15, 0
	s_cmp_gt_u32 s30, 5
	s_cbranch_scc0 .LBB0_896
	s_cmp_lt_u32 s3, 4
	s_cbranch_scc0 .LBB0_899
	s_barrier

.LBB0_904:
	ds_read_b128 v[148:151], v142
	ds_read_b128 v[152:155], v142 offset:1024
	ds_read_b128 v[156:159], v142 offset:2048
	ds_read_b128 v[160:163], v142 offset:3072
	ds_read_b128 v[164:167], v143
	ds_read_b128 v[168:171], v143 offset:1024
	ds_read_b128 v[172:175], v143 offset:2048
	ds_read_b128 v[176:179], v143 offset:3072
	s_add_u32 s16, s12, s14
	s_addc_u32 s17, s13, s15
	s_add_u32 s16, s16, 0x18000100
	s_addc_u32 s17, s17, 0
	s_add_u32 s42, s28, s14
	s_addc_u32 s43, s29, s15
	s_cmpk_eq_i32 s14, 0x300
	s_cselect_b32 s19, s9, s17
	s_cselect_b32 s18, s8, s16
	s_cselect_b32 s17, s7, s43
	s_cselect_b32 s16, s6, s42
	s_mov_b32 m0, s31
	v_lshl_add_u64 v[212:213], v[136:137], 0, s[14:15]
	ds_read_b128 v[180:183], v144
	ds_read_b128 v[184:187], v144 offset:1024
	ds_read_b128 v[188:191], v144 offset:2048
	ds_read_b128 v[192:195], v144 offset:3072
	ds_read_b128 v[196:199], v144 offset:4096
	ds_read_b128 v[200:203], v144 offset:5120
	ds_read_b128 v[204:207], v144 offset:6144
	ds_read_b128 v[208:211], v144 offset:7168
	global_load_lds_dwordx4 v[212:213], off
	v_lshl_add_u64 v[212:213], v[138:139], 0, s[14:15]
	s_mov_b32 m0, s33
	s_nop 0
	global_load_lds_dwordx4 v[212:213], off
	s_waitcnt vmcnt(8)
	s_waitcnt lgkmcnt(0)
	s_setprio 1
	s_barrier
	v_mfma_f32_16x16x32_bf16 v[124:127], v[148:151], v[180:183], v[124:127]
	v_mfma_f32_16x16x32_bf16 v[120:123], v[156:159], v[180:183], v[120:123]
	v_mfma_f32_16x16x32_bf16 v[116:119], v[148:151], v[188:191], v[116:119]
	v_mfma_f32_16x16x32_bf16 v[108:111], v[156:159], v[188:191], v[108:111]
	v_mfma_f32_16x16x32_bf16 v[100:103], v[148:151], v[196:199], v[100:103]
	v_mfma_f32_16x16x32_bf16 v[92:95], v[156:159], v[196:199], v[92:95]
	v_mfma_f32_16x16x32_bf16 v[84:87], v[148:151], v[204:207], v[84:87]
	v_mfma_f32_16x16x32_bf16 v[76:79], v[156:159], v[204:207], v[76:79]
	v_mfma_f32_16x16x32_bf16 v[124:127], v[152:155], v[184:187], v[124:127]
	v_mfma_f32_16x16x32_bf16 v[120:123], v[160:163], v[184:187], v[120:123]
	v_mfma_f32_16x16x32_bf16 v[116:119], v[152:155], v[192:195], v[116:119]
	v_mfma_f32_16x16x32_bf16 v[108:111], v[160:163], v[192:195], v[108:111]
	v_mfma_f32_16x16x32_bf16 v[100:103], v[152:155], v[200:203], v[100:103]
	v_mfma_f32_16x16x32_bf16 v[92:95], v[160:163], v[200:203], v[92:95]
	v_mfma_f32_16x16x32_bf16 v[84:87], v[152:155], v[208:211], v[84:87]
	v_mfma_f32_16x16x32_bf16 v[76:79], v[160:163], v[208:211], v[76:79]
	v_mfma_f32_16x16x32_bf16 v[112:115], v[164:167], v[180:183], v[112:115]
	v_mfma_f32_16x16x32_bf16 v[104:107], v[172:175], v[180:183], v[104:107]
	v_mfma_f32_16x16x32_bf16 v[96:99], v[164:167], v[188:191], v[96:99]
	v_mfma_f32_16x16x32_bf16 v[88:91], v[172:175], v[188:191], v[88:91]
	v_mfma_f32_16x16x32_bf16 v[80:83], v[164:167], v[196:199], v[80:83]
	v_mfma_f32_16x16x32_bf16 v[72:75], v[172:175], v[196:199], v[72:75]
	v_mfma_f32_16x16x32_bf16 v[68:71], v[164:167], v[204:207], v[68:71]
	v_mfma_f32_16x16x32_bf16 v[64:67], v[172:175], v[204:207], v[64:67]
	v_mfma_f32_16x16x32_bf16 v[112:115], v[168:171], v[184:187], v[112:115]
	v_mfma_f32_16x16x32_bf16 v[104:107], v[176:179], v[184:187], v[104:107]
	v_mfma_f32_16x16x32_bf16 v[96:99], v[168:171], v[192:195], v[96:99]
	v_mfma_f32_16x16x32_bf16 v[88:91], v[176:179], v[192:195], v[88:91]
	v_mfma_f32_16x16x32_bf16 v[80:83], v[168:171], v[200:203], v[80:83]
	v_mfma_f32_16x16x32_bf16 v[72:75], v[176:179], v[200:203], v[72:75]
	v_mfma_f32_16x16x32_bf16 v[68:71], v[168:171], v[208:211], v[68:71]
	v_mfma_f32_16x16x32_bf16 v[64:67], v[176:179], v[208:211], v[64:67]
	s_barrier
	s_setprio 0
	s_mov_b32 m0, s34
	v_lshl_add_u64 v[212:213], s[16:17], 0, v[132:133]
	s_add_u32 s42, s16, 0x100000
	ds_read_b128 v[180:183], v144 offset:16384
	ds_read_b128 v[184:187], v144 offset:17408
	ds_read_b128 v[188:191], v144 offset:18432
	ds_read_b128 v[192:195], v144 offset:19456
	ds_read_b128 v[196:199], v144 offset:20480
	ds_read_b128 v[200:203], v144 offset:21504
	ds_read_b128 v[204:207], v144 offset:22528
	ds_read_b128 v[208:211], v144 offset:23552
	global_load_lds_dwordx4 v[212:213], off
	v_lshl_add_u64 v[214:215], s[16:17], 0, v[128:129]
	s_mov_b32 m0, s35
	s_addc_u32 s43, s17, 0
	global_load_lds_dwordx4 v[214:215], off
	s_mov_b32 m0, s36
	v_lshl_add_u64 v[218:219], s[18:19], 0, v[130:131]
	global_load_lds_dwordx4 v132, s[42:43]
	s_mov_b32 m0, s37
	s_nop 0
	global_load_lds_dwordx4 v128, s[42:43]
	v_lshl_add_u64 v[216:217], s[18:19], 0, v[134:135]
	s_mov_b32 m0, s21
	s_nop 0
	global_load_lds_dwordx4 v[216:217], off
	s_mov_b32 m0, s23
	s_nop 0
	global_load_lds_dwordx4 v[218:219], off
	s_waitcnt vmcnt(8)
	s_waitcnt lgkmcnt(0)
	s_setprio 1
	s_barrier
	v_mfma_f32_16x16x32_bf16 v[60:63], v[148:151], v[180:183], v[60:63]
	v_mfma_f32_16x16x32_bf16 v[56:59], v[156:159], v[180:183], v[56:59]
	v_mfma_f32_16x16x32_bf16 v[52:55], v[148:151], v[188:191], v[52:55]
	v_mfma_f32_16x16x32_bf16 v[44:47], v[156:159], v[188:191], v[44:47]
	v_mfma_f32_16x16x32_bf16 v[36:39], v[148:151], v[196:199], v[36:39]
	v_mfma_f32_16x16x32_bf16 v[28:31], v[156:159], v[196:199], v[28:31]
	v_mfma_f32_16x16x32_bf16 v[20:23], v[148:151], v[204:207], v[20:23]
	v_mfma_f32_16x16x32_bf16 v[12:15], v[156:159], v[204:207], v[12:15]
	v_mfma_f32_16x16x32_bf16 v[60:63], v[152:155], v[184:187], v[60:63]
	v_mfma_f32_16x16x32_bf16 v[56:59], v[160:163], v[184:187], v[56:59]
	v_mfma_f32_16x16x32_bf16 v[52:55], v[152:155], v[192:195], v[52:55]
	v_mfma_f32_16x16x32_bf16 v[44:47], v[160:163], v[192:195], v[44:47]
	v_mfma_f32_16x16x32_bf16 v[36:39], v[152:155], v[200:203], v[36:39]
	v_mfma_f32_16x16x32_bf16 v[28:31], v[160:163], v[200:203], v[28:31]
	v_mfma_f32_16x16x32_bf16 v[20:23], v[152:155], v[208:211], v[20:23]
	v_mfma_f32_16x16x32_bf16 v[12:15], v[160:163], v[208:211], v[12:15]
	v_mfma_f32_16x16x32_bf16 v[48:51], v[164:167], v[180:183], v[48:51]
	v_mfma_f32_16x16x32_bf16 v[40:43], v[172:175], v[180:183], v[40:43]
	v_mfma_f32_16x16x32_bf16 v[32:35], v[164:167], v[188:191], v[32:35]
	v_mfma_f32_16x16x32_bf16 v[24:27], v[172:175], v[188:191], v[24:27]
	v_mfma_f32_16x16x32_bf16 v[16:19], v[164:167], v[196:199], v[16:19]
	v_mfma_f32_16x16x32_bf16 v[8:11], v[172:175], v[196:199], v[8:11]
	v_mfma_f32_16x16x32_bf16 v[4:7], v[164:167], v[204:207], v[4:7]
	v_mfma_f32_16x16x32_bf16 v[0:3], v[172:175], v[204:207], v[0:3]
	v_mfma_f32_16x16x32_bf16 v[48:51], v[168:171], v[184:187], v[48:51]
	v_mfma_f32_16x16x32_bf16 v[40:43], v[176:179], v[184:187], v[40:43]
	v_mfma_f32_16x16x32_bf16 v[32:35], v[168:171], v[192:195], v[32:35]
	v_mfma_f32_16x16x32_bf16 v[24:27], v[176:179], v[192:195], v[24:27]
	v_mfma_f32_16x16x32_bf16 v[16:19], v[168:171], v[200:203], v[16:19]
	v_mfma_f32_16x16x32_bf16 v[8:11], v[176:179], v[200:203], v[8:11]
	v_mfma_f32_16x16x32_bf16 v[4:7], v[168:171], v[208:211], v[4:7]
	v_mfma_f32_16x16x32_bf16 v[0:3], v[176:179], v[208:211], v[0:3]
	s_barrier
	s_setprio 0
	ds_read_b128 v[148:151], v145
	ds_read_b128 v[152:155], v145 offset:1024
	ds_read_b128 v[156:159], v145 offset:2048
	ds_read_b128 v[160:163], v145 offset:3072
	ds_read_b128 v[164:167], v146
	ds_read_b128 v[168:171], v146 offset:1024
	ds_read_b128 v[172:175], v146 offset:2048
	ds_read_b128 v[176:179], v146 offset:3072
	s_add_u32 s18, s18, 0x80000
	s_addc_u32 s19, s19, 0
	s_mov_b32 m0, s24
	ds_read_b128 v[180:183], v144 offset:32768
	ds_read_b128 v[184:187], v144 offset:33792
	ds_read_b128 v[188:191], v144 offset:34816
	ds_read_b128 v[192:195], v144 offset:35840
	ds_read_b128 v[196:199], v144 offset:36864
	ds_read_b128 v[200:203], v144 offset:37888
	ds_read_b128 v[204:207], v144 offset:38912
	ds_read_b128 v[208:211], v144 offset:39936
	global_load_lds_dwordx4 v134, s[18:19]
	s_mov_b32 m0, s25
	s_nop 0
	global_load_lds_dwordx4 v130, s[18:19]
	s_waitcnt vmcnt(8)
	s_waitcnt lgkmcnt(0)
	s_setprio 1
	s_barrier
	v_mfma_f32_16x16x32_bf16 v[124:127], v[148:151], v[180:183], v[124:127]
	v_mfma_f32_16x16x32_bf16 v[120:123], v[156:159], v[180:183], v[120:123]
	v_mfma_f32_16x16x32_bf16 v[116:119], v[148:151], v[188:191], v[116:119]
	v_mfma_f32_16x16x32_bf16 v[108:111], v[156:159], v[188:191], v[108:111]
	v_mfma_f32_16x16x32_bf16 v[100:103], v[148:151], v[196:199], v[100:103]
	v_mfma_f32_16x16x32_bf16 v[92:95], v[156:159], v[196:199], v[92:95]
	v_mfma_f32_16x16x32_bf16 v[84:87], v[148:151], v[204:207], v[84:87]
	v_mfma_f32_16x16x32_bf16 v[76:79], v[156:159], v[204:207], v[76:79]
	v_mfma_f32_16x16x32_bf16 v[124:127], v[152:155], v[184:187], v[124:127]
	v_mfma_f32_16x16x32_bf16 v[120:123], v[160:163], v[184:187], v[120:123]
	v_mfma_f32_16x16x32_bf16 v[116:119], v[152:155], v[192:195], v[116:119]
	v_mfma_f32_16x16x32_bf16 v[108:111], v[160:163], v[192:195], v[108:111]
	v_mfma_f32_16x16x32_bf16 v[100:103], v[152:155], v[200:203], v[100:103]
	v_mfma_f32_16x16x32_bf16 v[92:95], v[160:163], v[200:203], v[92:95]
	v_mfma_f32_16x16x32_bf16 v[84:87], v[152:155], v[208:211], v[84:87]
	v_mfma_f32_16x16x32_bf16 v[76:79], v[160:163], v[208:211], v[76:79]
	v_mfma_f32_16x16x32_bf16 v[112:115], v[164:167], v[180:183], v[112:115]
	v_mfma_f32_16x16x32_bf16 v[104:107], v[172:175], v[180:183], v[104:107]
	v_mfma_f32_16x16x32_bf16 v[96:99], v[164:167], v[188:191], v[96:99]
	v_mfma_f32_16x16x32_bf16 v[88:91], v[172:175], v[188:191], v[88:91]
	v_mfma_f32_16x16x32_bf16 v[80:83], v[164:167], v[196:199], v[80:83]
	v_mfma_f32_16x16x32_bf16 v[72:75], v[172:175], v[196:199], v[72:75]
	v_mfma_f32_16x16x32_bf16 v[68:71], v[164:167], v[204:207], v[68:71]
	v_mfma_f32_16x16x32_bf16 v[64:67], v[172:175], v[204:207], v[64:67]
	v_mfma_f32_16x16x32_bf16 v[112:115], v[168:171], v[184:187], v[112:115]
	v_mfma_f32_16x16x32_bf16 v[104:107], v[176:179], v[184:187], v[104:107]
	v_mfma_f32_16x16x32_bf16 v[96:99], v[168:171], v[192:195], v[96:99]
	v_mfma_f32_16x16x32_bf16 v[88:91], v[176:179], v[192:195], v[88:91]
	v_mfma_f32_16x16x32_bf16 v[80:83], v[168:171], v[200:203], v[80:83]
	v_mfma_f32_16x16x32_bf16 v[72:75], v[176:179], v[200:203], v[72:75]
	v_mfma_f32_16x16x32_bf16 v[68:71], v[168:171], v[208:211], v[68:71]
	v_mfma_f32_16x16x32_bf16 v[64:67], v[176:179], v[208:211], v[64:67]
	s_barrier
	s_setprio 0
	s_mov_b32 m0, s38
	v_lshl_add_u64 v[212:213], v[212:213], 0, s[10:11]
	s_add_u32 s16, s16, 0x100080
	ds_read_b128 v[180:183], v144 offset:49152
	ds_read_b128 v[184:187], v144 offset:50176
	ds_read_b128 v[188:191], v144 offset:51200
	ds_read_b128 v[192:195], v144 offset:52224
	ds_read_b128 v[196:199], v144 offset:53248
	ds_read_b128 v[200:203], v144 offset:54272
	ds_read_b128 v[204:207], v144 offset:55296
	ds_read_b128 v[208:211], v144 offset:56320
	global_load_lds_dwordx4 v[212:213], off
	v_lshl_add_u64 v[212:213], v[214:215], 0, s[10:11]
	s_mov_b32 m0, s39
	s_addc_u32 s17, s17, 0
	global_load_lds_dwordx4 v[212:213], off
	s_mov_b32 m0, s40
	s_nop 0
	global_load_lds_dwordx4 v132, s[16:17]
	s_mov_b32 m0, s41
	s_nop 0
	global_load_lds_dwordx4 v128, s[16:17]
	v_lshl_add_u64 v[212:213], v[216:217], 0, s[10:11]
	s_mov_b32 m0, s26
	s_nop 0
	global_load_lds_dwordx4 v[212:213], off
	v_lshl_add_u64 v[212:213], v[218:219], 0, s[10:11]
	s_mov_b32 m0, s27
	s_nop 0
	global_load_lds_dwordx4 v[212:213], off
	s_waitcnt vmcnt(8)
	s_waitcnt lgkmcnt(0)
	s_setprio 1
	s_barrier
	v_mfma_f32_16x16x32_bf16 v[60:63], v[148:151], v[180:183], v[60:63]
	v_mfma_f32_16x16x32_bf16 v[56:59], v[156:159], v[180:183], v[56:59]
	v_mfma_f32_16x16x32_bf16 v[52:55], v[148:151], v[188:191], v[52:55]
	v_mfma_f32_16x16x32_bf16 v[44:47], v[156:159], v[188:191], v[44:47]
	v_mfma_f32_16x16x32_bf16 v[36:39], v[148:151], v[196:199], v[36:39]
	v_mfma_f32_16x16x32_bf16 v[28:31], v[156:159], v[196:199], v[28:31]
	v_mfma_f32_16x16x32_bf16 v[20:23], v[148:151], v[204:207], v[20:23]
	v_mfma_f32_16x16x32_bf16 v[12:15], v[156:159], v[204:207], v[12:15]
	v_mfma_f32_16x16x32_bf16 v[60:63], v[152:155], v[184:187], v[60:63]
	v_mfma_f32_16x16x32_bf16 v[56:59], v[160:163], v[184:187], v[56:59]
	v_mfma_f32_16x16x32_bf16 v[52:55], v[152:155], v[192:195], v[52:55]
	v_mfma_f32_16x16x32_bf16 v[44:47], v[160:163], v[192:195], v[44:47]
	v_mfma_f32_16x16x32_bf16 v[36:39], v[152:155], v[200:203], v[36:39]
	v_mfma_f32_16x16x32_bf16 v[28:31], v[160:163], v[200:203], v[28:31]
	v_mfma_f32_16x16x32_bf16 v[20:23], v[152:155], v[208:211], v[20:23]
	v_mfma_f32_16x16x32_bf16 v[12:15], v[160:163], v[208:211], v[12:15]
	v_mfma_f32_16x16x32_bf16 v[48:51], v[164:167], v[180:183], v[48:51]
	v_mfma_f32_16x16x32_bf16 v[40:43], v[172:175], v[180:183], v[40:43]
	v_mfma_f32_16x16x32_bf16 v[32:35], v[164:167], v[188:191], v[32:35]
	v_mfma_f32_16x16x32_bf16 v[24:27], v[172:175], v[188:191], v[24:27]
	v_mfma_f32_16x16x32_bf16 v[16:19], v[164:167], v[196:199], v[16:19]
	v_mfma_f32_16x16x32_bf16 v[8:11], v[172:175], v[196:199], v[8:11]
	v_mfma_f32_16x16x32_bf16 v[4:7], v[164:167], v[204:207], v[4:7]
	v_mfma_f32_16x16x32_bf16 v[0:3], v[172:175], v[204:207], v[0:3]
	v_mfma_f32_16x16x32_bf16 v[48:51], v[168:171], v[184:187], v[48:51]
	v_mfma_f32_16x16x32_bf16 v[40:43], v[176:179], v[184:187], v[40:43]
	v_mfma_f32_16x16x32_bf16 v[32:35], v[168:171], v[192:195], v[32:35]
	v_mfma_f32_16x16x32_bf16 v[24:27], v[176:179], v[192:195], v[24:27]
	v_mfma_f32_16x16x32_bf16 v[16:19], v[168:171], v[200:203], v[16:19]
	v_mfma_f32_16x16x32_bf16 v[8:11], v[176:179], v[200:203], v[8:11]
	v_mfma_f32_16x16x32_bf16 v[4:7], v[168:171], v[208:211], v[4:7]
	v_mfma_f32_16x16x32_bf16 v[0:3], v[176:179], v[208:211], v[0:3]
	s_barrier
	s_setprio 0
	s_add_i32 s30, s30, 2
	s_add_u32 s14, s14, 0x100
	s_addc_u32 s15, s15, 0
	s_cmp_gt_u32 s30, 5
	s_cbranch_scc0 .LBB0_904
	s_cmp_lt_u32 s3, 4
	s_cbranch_scc0 .LBB0_907
	s_barrier

.LBB0_1282:
	ds_read_b128 v[128:131], v180
	ds_read_b128 v[132:135], v180 offset:1024
	ds_read_b128 v[136:139], v180 offset:2048
	ds_read_b128 v[140:143], v180 offset:3072
	ds_read_b128 v[144:147], v181
	ds_read_b128 v[148:151], v181 offset:1024
	ds_read_b128 v[152:155], v181 offset:2048
	ds_read_b128 v[156:159], v181 offset:3072
	s_add_u32 s8, s6, 0x3fc000
	s_addc_u32 s9, s7, 0
	s_cmp_eq_u32 s44, 28
	s_cselect_b32 s38, s15, s8
	s_cselect_b32 s39, s12, s9
	s_cselect_b32 s10, s41, s42
	s_cselect_b32 s11, s31, s43
	s_add_u32 s8, s38, 0x400000
	s_addc_u32 s9, s39, 0
	s_add_i32 m0, s29, 0xc000
	ds_read_b128 v[186:189], v182
	ds_read_b128 v[190:193], v182 offset:1024
	ds_read_b128 v[194:197], v182 offset:2048
	ds_read_b128 v[198:201], v182 offset:3072
	ds_read_b128 v[202:205], v182 offset:4096
	ds_read_b128 v[206:209], v182 offset:5120
	ds_read_b128 v[210:213], v182 offset:6144
	ds_read_b128 v[214:217], v182 offset:7168
	global_load_lds_dwordx4 v168, s[6:7]
	s_add_i32 m0, s29, 0xe000
	s_nop 0
	global_load_lds_dwordx4 v170, s[6:7]
	s_waitcnt vmcnt(8)
	s_waitcnt lgkmcnt(0)
	s_setprio 1
	s_barrier
	v_mfma_f32_16x16x32_bf16 v[100:103], v[128:131], v[186:189], v[100:103]
	v_mfma_f32_16x16x32_bf16 v[88:91], v[136:139], v[186:189], v[88:91]
	v_mfma_f32_16x16x32_bf16 v[84:87], v[128:131], v[194:197], v[84:87]
	v_mfma_f32_16x16x32_bf16 v[80:83], v[136:139], v[194:197], v[80:83]
	v_mfma_f32_16x16x32_bf16 v[96:99], v[128:131], v[202:205], v[96:99]
	v_mfma_f32_16x16x32_bf16 v[92:95], v[136:139], v[202:205], v[92:95]
	v_mfma_f32_16x16x32_bf16 v[108:111], v[128:131], v[210:213], v[108:111]
	v_mfma_f32_16x16x32_bf16 v[104:107], v[136:139], v[210:213], v[104:107]
	v_mfma_f32_16x16x32_bf16 v[100:103], v[132:135], v[190:193], v[100:103]
	v_mfma_f32_16x16x32_bf16 v[88:91], v[140:143], v[190:193], v[88:91]
	v_mfma_f32_16x16x32_bf16 v[84:87], v[132:135], v[198:201], v[84:87]
	v_mfma_f32_16x16x32_bf16 v[80:83], v[140:143], v[198:201], v[80:83]
	v_mfma_f32_16x16x32_bf16 v[96:99], v[132:135], v[206:209], v[96:99]
	v_mfma_f32_16x16x32_bf16 v[92:95], v[140:143], v[206:209], v[92:95]
	v_mfma_f32_16x16x32_bf16 v[108:111], v[132:135], v[214:217], v[108:111]
	v_mfma_f32_16x16x32_bf16 v[104:107], v[140:143], v[214:217], v[104:107]
	v_mfma_f32_16x16x32_bf16 v[28:31], v[144:147], v[186:189], v[28:31]
	v_mfma_f32_16x16x32_bf16 v[16:19], v[152:155], v[186:189], v[16:19]
	v_mfma_f32_16x16x32_bf16 v[4:7], v[144:147], v[194:197], v[4:7]
	v_mfma_f32_16x16x32_bf16 v[0:3], v[152:155], v[194:197], v[0:3]
	v_mfma_f32_16x16x32_bf16 v[12:15], v[144:147], v[202:205], v[12:15]
	v_mfma_f32_16x16x32_bf16 v[8:11], v[152:155], v[202:205], v[8:11]
	v_mfma_f32_16x16x32_bf16 v[24:27], v[144:147], v[210:213], v[24:27]
	v_mfma_f32_16x16x32_bf16 v[20:23], v[152:155], v[210:213], v[20:23]
	v_mfma_f32_16x16x32_bf16 v[28:31], v[148:151], v[190:193], v[28:31]
	v_mfma_f32_16x16x32_bf16 v[16:19], v[156:159], v[190:193], v[16:19]
	v_mfma_f32_16x16x32_bf16 v[4:7], v[148:151], v[198:201], v[4:7]
	v_mfma_f32_16x16x32_bf16 v[0:3], v[156:159], v[198:201], v[0:3]
	v_mfma_f32_16x16x32_bf16 v[12:15], v[148:151], v[206:209], v[12:15]
	v_mfma_f32_16x16x32_bf16 v[8:11], v[156:159], v[206:209], v[8:11]
	v_mfma_f32_16x16x32_bf16 v[24:27], v[148:151], v[214:217], v[24:27]
	v_mfma_f32_16x16x32_bf16 v[20:23], v[156:159], v[214:217], v[20:23]
	s_barrier
	s_setprio 0
	s_add_i32 s45, s57, s4
	s_mov_b32 m0, s45
	ds_read_b128 v[186:189], v182 offset:16384
	ds_read_b128 v[190:193], v182 offset:17408
	ds_read_b128 v[194:197], v182 offset:18432
	ds_read_b128 v[198:201], v182 offset:19456
	ds_read_b128 v[202:205], v182 offset:20480
	ds_read_b128 v[206:209], v182 offset:21504
	ds_read_b128 v[210:213], v182 offset:22528
	ds_read_b128 v[214:217], v182 offset:23552
	global_load_lds_dwordx4 v162, s[10:11]
	s_add_i32 m0, s45, 0x2000
	s_add_u32 s46, s10, 0x4000
	s_addc_u32 s47, s11, 0
	s_add_i32 s45, s81, s4
	global_load_lds_dwordx4 v166, s[10:11]
	s_mov_b32 m0, s45
	s_nop 0
	global_load_lds_dwordx4 v162, s[46:47]
	s_add_i32 m0, s45, 0x2000
	s_nop 0
	global_load_lds_dwordx4 v166, s[46:47]
	s_mov_b32 m0, s29
	s_nop 0
	global_load_lds_dwordx4 v160, s[38:39]
	s_mov_b32 m0, s52
	s_nop 0
	global_load_lds_dwordx4 v164, s[38:39]
	s_waitcnt vmcnt(8)
	s_waitcnt lgkmcnt(0)
	s_setprio 1
	s_barrier
	v_mfma_f32_16x16x32_bf16 v[116:119], v[128:131], v[186:189], v[116:119]
	v_mfma_f32_16x16x32_bf16 v[112:115], v[136:139], v[186:189], v[112:115]
	v_mfma_f32_16x16x32_bf16 v[124:127], v[128:131], v[194:197], v[124:127]
	v_mfma_f32_16x16x32_bf16 v[120:123], v[136:139], v[194:197], v[120:123]
	v_mfma_f32_16x16x32_bf16 v[76:79], v[128:131], v[202:205], v[76:79]
	v_mfma_f32_16x16x32_bf16 v[72:75], v[136:139], v[202:205], v[72:75]
	v_mfma_f32_16x16x32_bf16 v[68:71], v[128:131], v[210:213], v[68:71]
	v_mfma_f32_16x16x32_bf16 v[64:67], v[136:139], v[210:213], v[64:67]
	v_mfma_f32_16x16x32_bf16 v[116:119], v[132:135], v[190:193], v[116:119]
	v_mfma_f32_16x16x32_bf16 v[112:115], v[140:143], v[190:193], v[112:115]
	v_mfma_f32_16x16x32_bf16 v[124:127], v[132:135], v[198:201], v[124:127]
	v_mfma_f32_16x16x32_bf16 v[120:123], v[140:143], v[198:201], v[120:123]
	v_mfma_f32_16x16x32_bf16 v[76:79], v[132:135], v[206:209], v[76:79]
	v_mfma_f32_16x16x32_bf16 v[72:75], v[140:143], v[206:209], v[72:75]
	v_mfma_f32_16x16x32_bf16 v[68:71], v[132:135], v[214:217], v[68:71]
	v_mfma_f32_16x16x32_bf16 v[64:67], v[140:143], v[214:217], v[64:67]
	v_mfma_f32_16x16x32_bf16 v[36:39], v[144:147], v[186:189], v[36:39]
	v_mfma_f32_16x16x32_bf16 v[32:35], v[152:155], v[186:189], v[32:35]
	v_mfma_f32_16x16x32_bf16 v[44:47], v[144:147], v[194:197], v[44:47]
	v_mfma_f32_16x16x32_bf16 v[40:43], v[152:155], v[194:197], v[40:43]
	v_mfma_f32_16x16x32_bf16 v[52:55], v[144:147], v[202:205], v[52:55]
	v_mfma_f32_16x16x32_bf16 v[48:51], v[152:155], v[202:205], v[48:51]
	v_mfma_f32_16x16x32_bf16 v[60:63], v[144:147], v[210:213], v[60:63]
	v_mfma_f32_16x16x32_bf16 v[56:59], v[152:155], v[210:213], v[56:59]
	v_mfma_f32_16x16x32_bf16 v[36:39], v[148:151], v[190:193], v[36:39]
	v_mfma_f32_16x16x32_bf16 v[32:35], v[156:159], v[190:193], v[32:35]
	v_mfma_f32_16x16x32_bf16 v[44:47], v[148:151], v[198:201], v[44:47]
	v_mfma_f32_16x16x32_bf16 v[40:43], v[156:159], v[198:201], v[40:43]
	v_mfma_f32_16x16x32_bf16 v[52:55], v[148:151], v[206:209], v[52:55]
	v_mfma_f32_16x16x32_bf16 v[48:51], v[156:159], v[206:209], v[48:51]
	v_mfma_f32_16x16x32_bf16 v[60:63], v[148:151], v[214:217], v[60:63]
	v_mfma_f32_16x16x32_bf16 v[56:59], v[156:159], v[214:217], v[56:59]
	s_barrier
	s_setprio 0
	v_add_u32_e32 v140, s82, v179
	v_add_u32_e32 v156, s83, v179
	ds_read_b128 v[128:131], v140
	ds_read_b128 v[132:135], v140 offset:1024
	ds_read_b128 v[136:139], v140 offset:2048
	ds_read_b128 v[140:143], v140 offset:3072
	ds_read_b128 v[144:147], v156
	ds_read_b128 v[148:151], v156 offset:1024
	ds_read_b128 v[152:155], v156 offset:2048
	ds_read_b128 v[156:159], v156 offset:3072
	s_add_u32 s38, s38, 0x4000
	s_addc_u32 s39, s39, 0
	s_mov_b32 m0, s53
	ds_read_b128 v[186:189], v182 offset:32768
	ds_read_b128 v[190:193], v182 offset:33792
	ds_read_b128 v[194:197], v182 offset:34816
	ds_read_b128 v[198:201], v182 offset:35840
	ds_read_b128 v[202:205], v182 offset:36864
	ds_read_b128 v[206:209], v182 offset:37888
	ds_read_b128 v[210:213], v182 offset:38912
	ds_read_b128 v[214:217], v182 offset:39936
	global_load_lds_dwordx4 v160, s[38:39]
	s_mov_b32 m0, s54
	s_nop 0
	global_load_lds_dwordx4 v164, s[38:39]
	s_waitcnt vmcnt(8)
	s_waitcnt lgkmcnt(0)
	s_setprio 1
	s_barrier
	v_mfma_f32_16x16x32_bf16 v[100:103], v[128:131], v[186:189], v[100:103]
	v_mfma_f32_16x16x32_bf16 v[88:91], v[136:139], v[186:189], v[88:91]
	v_mfma_f32_16x16x32_bf16 v[84:87], v[128:131], v[194:197], v[84:87]
	v_mfma_f32_16x16x32_bf16 v[80:83], v[136:139], v[194:197], v[80:83]
	v_mfma_f32_16x16x32_bf16 v[96:99], v[128:131], v[202:205], v[96:99]
	v_mfma_f32_16x16x32_bf16 v[92:95], v[136:139], v[202:205], v[92:95]
	v_mfma_f32_16x16x32_bf16 v[108:111], v[128:131], v[210:213], v[108:111]
	v_mfma_f32_16x16x32_bf16 v[104:107], v[136:139], v[210:213], v[104:107]
	v_mfma_f32_16x16x32_bf16 v[100:103], v[132:135], v[190:193], v[100:103]
	v_mfma_f32_16x16x32_bf16 v[88:91], v[140:143], v[190:193], v[88:91]
	v_mfma_f32_16x16x32_bf16 v[84:87], v[132:135], v[198:201], v[84:87]
	v_mfma_f32_16x16x32_bf16 v[80:83], v[140:143], v[198:201], v[80:83]
	v_mfma_f32_16x16x32_bf16 v[96:99], v[132:135], v[206:209], v[96:99]
	v_mfma_f32_16x16x32_bf16 v[92:95], v[140:143], v[206:209], v[92:95]
	v_mfma_f32_16x16x32_bf16 v[108:111], v[132:135], v[214:217], v[108:111]
	v_mfma_f32_16x16x32_bf16 v[104:107], v[140:143], v[214:217], v[104:107]
	v_mfma_f32_16x16x32_bf16 v[28:31], v[144:147], v[186:189], v[28:31]
	v_mfma_f32_16x16x32_bf16 v[16:19], v[152:155], v[186:189], v[16:19]
	v_mfma_f32_16x16x32_bf16 v[4:7], v[144:147], v[194:197], v[4:7]
	v_mfma_f32_16x16x32_bf16 v[0:3], v[152:155], v[194:197], v[0:3]
	v_mfma_f32_16x16x32_bf16 v[12:15], v[144:147], v[202:205], v[12:15]
	v_mfma_f32_16x16x32_bf16 v[8:11], v[152:155], v[202:205], v[8:11]
	v_mfma_f32_16x16x32_bf16 v[24:27], v[144:147], v[210:213], v[24:27]
	v_mfma_f32_16x16x32_bf16 v[20:23], v[152:155], v[210:213], v[20:23]
	v_mfma_f32_16x16x32_bf16 v[28:31], v[148:151], v[190:193], v[28:31]
	v_mfma_f32_16x16x32_bf16 v[16:19], v[156:159], v[190:193], v[16:19]
	v_mfma_f32_16x16x32_bf16 v[4:7], v[148:151], v[198:201], v[4:7]
	v_mfma_f32_16x16x32_bf16 v[0:3], v[156:159], v[198:201], v[0:3]
	v_mfma_f32_16x16x32_bf16 v[12:15], v[148:151], v[206:209], v[12:15]
	v_mfma_f32_16x16x32_bf16 v[8:11], v[156:159], v[206:209], v[8:11]
	v_mfma_f32_16x16x32_bf16 v[24:27], v[148:151], v[214:217], v[24:27]
	v_mfma_f32_16x16x32_bf16 v[20:23], v[156:159], v[214:217], v[20:23]
	s_barrier
	s_setprio 0
	s_add_u32 s38, s10, 0x40000
	s_addc_u32 s39, s11, 0
	s_add_i32 s45, s82, s4
	s_mov_b32 m0, s45
	ds_read_b128 v[186:189], v182 offset:49152
	ds_read_b128 v[190:193], v182 offset:50176
	ds_read_b128 v[194:197], v182 offset:51200
	ds_read_b128 v[198:201], v182 offset:52224
	ds_read_b128 v[202:205], v182 offset:53248
	ds_read_b128 v[206:209], v182 offset:54272
	ds_read_b128 v[210:213], v182 offset:55296
	ds_read_b128 v[214:217], v182 offset:56320
	global_load_lds_dwordx4 v162, s[38:39]
	s_add_i32 m0, s45, 0x2000
	s_add_u32 s10, s10, 0x44000
	global_load_lds_dwordx4 v166, s[38:39]
	s_addc_u32 s11, s11, 0
	s_add_i32 s38, s83, s4
	s_mov_b32 m0, s38
	s_nop 0
	global_load_lds_dwordx4 v162, s[10:11]
	s_add_i32 m0, s38, 0x2000
	s_nop 0
	global_load_lds_dwordx4 v166, s[10:11]
	s_mov_b32 m0, s2
	s_nop 0
	global_load_lds_dwordx4 v160, s[8:9]
	s_mov_b32 m0, s50
	s_nop 0
	global_load_lds_dwordx4 v164, s[8:9]
	s_waitcnt vmcnt(8)
	s_waitcnt lgkmcnt(0)
	s_setprio 1
	s_barrier
	v_mfma_f32_16x16x32_bf16 v[116:119], v[128:131], v[186:189], v[116:119]
	v_mfma_f32_16x16x32_bf16 v[112:115], v[136:139], v[186:189], v[112:115]
	v_mfma_f32_16x16x32_bf16 v[124:127], v[128:131], v[194:197], v[124:127]
	v_mfma_f32_16x16x32_bf16 v[120:123], v[136:139], v[194:197], v[120:123]
	v_mfma_f32_16x16x32_bf16 v[76:79], v[128:131], v[202:205], v[76:79]
	v_mfma_f32_16x16x32_bf16 v[72:75], v[136:139], v[202:205], v[72:75]
	v_mfma_f32_16x16x32_bf16 v[68:71], v[128:131], v[210:213], v[68:71]
	v_mfma_f32_16x16x32_bf16 v[64:67], v[136:139], v[210:213], v[64:67]
	v_mfma_f32_16x16x32_bf16 v[116:119], v[132:135], v[190:193], v[116:119]
	v_mfma_f32_16x16x32_bf16 v[112:115], v[140:143], v[190:193], v[112:115]
	v_mfma_f32_16x16x32_bf16 v[124:127], v[132:135], v[198:201], v[124:127]
	v_mfma_f32_16x16x32_bf16 v[120:123], v[140:143], v[198:201], v[120:123]
	v_mfma_f32_16x16x32_bf16 v[76:79], v[132:135], v[206:209], v[76:79]
	v_mfma_f32_16x16x32_bf16 v[72:75], v[140:143], v[206:209], v[72:75]
	v_mfma_f32_16x16x32_bf16 v[68:71], v[132:135], v[214:217], v[68:71]
	v_mfma_f32_16x16x32_bf16 v[64:67], v[140:143], v[214:217], v[64:67]
	v_mfma_f32_16x16x32_bf16 v[36:39], v[144:147], v[186:189], v[36:39]
	v_mfma_f32_16x16x32_bf16 v[32:35], v[152:155], v[186:189], v[32:35]
	v_mfma_f32_16x16x32_bf16 v[44:47], v[144:147], v[194:197], v[44:47]
	v_mfma_f32_16x16x32_bf16 v[40:43], v[152:155], v[194:197], v[40:43]
	v_mfma_f32_16x16x32_bf16 v[52:55], v[144:147], v[202:205], v[52:55]
	v_mfma_f32_16x16x32_bf16 v[48:51], v[152:155], v[202:205], v[48:51]
	v_mfma_f32_16x16x32_bf16 v[60:63], v[144:147], v[210:213], v[60:63]
	v_mfma_f32_16x16x32_bf16 v[56:59], v[152:155], v[210:213], v[56:59]
	v_mfma_f32_16x16x32_bf16 v[36:39], v[148:151], v[190:193], v[36:39]
	v_mfma_f32_16x16x32_bf16 v[32:35], v[156:159], v[190:193], v[32:35]
	v_mfma_f32_16x16x32_bf16 v[44:47], v[148:151], v[198:201], v[44:47]
	v_mfma_f32_16x16x32_bf16 v[40:43], v[156:159], v[198:201], v[40:43]
	v_mfma_f32_16x16x32_bf16 v[52:55], v[148:151], v[206:209], v[52:55]
	v_mfma_f32_16x16x32_bf16 v[48:51], v[156:159], v[206:209], v[48:51]
	v_mfma_f32_16x16x32_bf16 v[60:63], v[148:151], v[214:217], v[60:63]
	v_mfma_f32_16x16x32_bf16 v[56:59], v[156:159], v[214:217], v[56:59]
	s_barrier
	s_setprio 0
	s_add_i32 s44, s44, 2
	s_add_u32 s42, s42, 0x80000
	s_addc_u32 s43, s43, 0
	s_add_u32 s6, s6, 0x800000
	s_addc_u32 s7, s7, 0
	s_cmp_gt_u32 s44, 29
	s_cbranch_scc0 .LBB0_1282
	s_and_b64 vcc, exec, s[26:27]
	s_cbranch_vccz .LBB0_1285
	s_barrier

.LBB0_1404:
	ds_read_b128 v[152:155], v149
	ds_read_b128 v[156:159], v149 offset:1024
	ds_read_b128 v[160:163], v149 offset:2048
	ds_read_b128 v[164:167], v149 offset:3072
	ds_read_b128 v[168:171], v150
	ds_read_b128 v[172:175], v150 offset:1024
	ds_read_b128 v[176:179], v150 offset:2048
	ds_read_b128 v[180:183], v150 offset:3072
	s_add_u32 s26, s24, 0x3fc000
	s_addc_u32 s27, s25, 0
	s_cmp_eq_u32 s52, 28
	s_cselect_b32 s30, s17, s26
	s_cselect_b32 s31, s8, s27
	s_cselect_b32 s28, s47, s50
	s_cselect_b32 s29, s19, s51
	s_add_u32 s26, s30, 0x400000
	s_addc_u32 s27, s31, 0
	s_add_i32 m0, s33, 0xc000
	ds_read_b128 v[184:187], v151
	ds_read_b128 v[188:191], v151 offset:1024
	ds_read_b128 v[192:195], v151 offset:2048
	ds_read_b128 v[196:199], v151 offset:3072
	ds_read_b128 v[200:203], v151 offset:4096
	ds_read_b128 v[204:207], v151 offset:5120
	ds_read_b128 v[208:211], v151 offset:6144
	ds_read_b128 v[212:215], v151 offset:7168
	global_load_lds_dwordx4 v136, s[24:25]
	s_add_i32 m0, s33, 0xe000
	s_nop 0
	global_load_lds_dwordx4 v138, s[24:25]
	s_waitcnt vmcnt(8)
	s_waitcnt lgkmcnt(0)
	s_setprio 1
	s_barrier
	v_mfma_f32_16x16x32_bf16 v[124:127], v[152:155], v[184:187], v[124:127]
	v_mfma_f32_16x16x32_bf16 v[120:123], v[160:163], v[184:187], v[120:123]
	v_mfma_f32_16x16x32_bf16 v[108:111], v[152:155], v[192:195], v[108:111]
	v_mfma_f32_16x16x32_bf16 v[104:107], v[160:163], v[192:195], v[104:107]
	v_mfma_f32_16x16x32_bf16 v[92:95], v[152:155], v[200:203], v[92:95]
	v_mfma_f32_16x16x32_bf16 v[88:91], v[160:163], v[200:203], v[88:91]
	v_mfma_f32_16x16x32_bf16 v[76:79], v[152:155], v[208:211], v[76:79]
	v_mfma_f32_16x16x32_bf16 v[72:75], v[160:163], v[208:211], v[72:75]
	v_mfma_f32_16x16x32_bf16 v[124:127], v[156:159], v[188:191], v[124:127]
	v_mfma_f32_16x16x32_bf16 v[120:123], v[164:167], v[188:191], v[120:123]
	v_mfma_f32_16x16x32_bf16 v[108:111], v[156:159], v[196:199], v[108:111]
	v_mfma_f32_16x16x32_bf16 v[104:107], v[164:167], v[196:199], v[104:107]
	v_mfma_f32_16x16x32_bf16 v[92:95], v[156:159], v[204:207], v[92:95]
	v_mfma_f32_16x16x32_bf16 v[88:91], v[164:167], v[204:207], v[88:91]
	v_mfma_f32_16x16x32_bf16 v[76:79], v[156:159], v[212:215], v[76:79]
	v_mfma_f32_16x16x32_bf16 v[72:75], v[164:167], v[212:215], v[72:75]
	v_mfma_f32_16x16x32_bf16 v[116:119], v[168:171], v[184:187], v[116:119]
	v_mfma_f32_16x16x32_bf16 v[112:115], v[176:179], v[184:187], v[112:115]
	v_mfma_f32_16x16x32_bf16 v[100:103], v[168:171], v[192:195], v[100:103]
	v_mfma_f32_16x16x32_bf16 v[96:99], v[176:179], v[192:195], v[96:99]
	v_mfma_f32_16x16x32_bf16 v[84:87], v[168:171], v[200:203], v[84:87]
	v_mfma_f32_16x16x32_bf16 v[80:83], v[176:179], v[200:203], v[80:83]
	v_mfma_f32_16x16x32_bf16 v[68:71], v[168:171], v[208:211], v[68:71]
	v_mfma_f32_16x16x32_bf16 v[64:67], v[176:179], v[208:211], v[64:67]
	v_mfma_f32_16x16x32_bf16 v[116:119], v[172:175], v[188:191], v[116:119]
	v_mfma_f32_16x16x32_bf16 v[112:115], v[180:183], v[188:191], v[112:115]
	v_mfma_f32_16x16x32_bf16 v[100:103], v[172:175], v[196:199], v[100:103]
	v_mfma_f32_16x16x32_bf16 v[96:99], v[180:183], v[196:199], v[96:99]
	v_mfma_f32_16x16x32_bf16 v[84:87], v[172:175], v[204:207], v[84:87]
	v_mfma_f32_16x16x32_bf16 v[80:83], v[180:183], v[204:207], v[80:83]
	v_mfma_f32_16x16x32_bf16 v[68:71], v[172:175], v[212:215], v[68:71]
	v_mfma_f32_16x16x32_bf16 v[64:67], v[180:183], v[212:215], v[64:67]
	s_barrier
	s_setprio 0
	s_add_i32 s53, s57, s5
	v_lshl_add_u64 v[144:145], s[28:29], 0, v[130:131]
	s_mov_b32 m0, s53
	ds_read_b128 v[184:187], v151 offset:16384
	ds_read_b128 v[188:191], v151 offset:17408
	ds_read_b128 v[192:195], v151 offset:18432
	ds_read_b128 v[196:199], v151 offset:19456
	ds_read_b128 v[200:203], v151 offset:20480
	ds_read_b128 v[204:207], v151 offset:21504
	ds_read_b128 v[208:211], v151 offset:22528
	ds_read_b128 v[212:215], v151 offset:23552
	global_load_lds_dwordx4 v[144:145], off
	s_add_i32 m0, s53, 0x2000
	s_add_u32 s54, s28, 0x80000
	v_lshl_add_u64 v[216:217], s[28:29], 0, v[134:135]
	s_addc_u32 s55, s29, 0
	s_add_i32 s53, s81, s5
	global_load_lds_dwordx4 v[216:217], off
	s_mov_b32 m0, s53
	s_nop 0
	global_load_lds_dwordx4 v130, s[54:55]
	s_add_i32 m0, s53, 0x2000
	s_nop 0
	global_load_lds_dwordx4 v134, s[54:55]
	s_mov_b32 m0, s33
	s_nop 0
	global_load_lds_dwordx4 v128, s[30:31]
	s_mov_b32 m0, s34
	s_nop 0
	global_load_lds_dwordx4 v132, s[30:31]
	s_waitcnt vmcnt(8)
	s_waitcnt lgkmcnt(0)
	s_setprio 1
	s_barrier
	v_mfma_f32_16x16x32_bf16 v[60:63], v[152:155], v[184:187], v[60:63]
	v_mfma_f32_16x16x32_bf16 v[56:59], v[160:163], v[184:187], v[56:59]
	v_mfma_f32_16x16x32_bf16 v[44:47], v[152:155], v[192:195], v[44:47]
	v_mfma_f32_16x16x32_bf16 v[40:43], v[160:163], v[192:195], v[40:43]
	v_mfma_f32_16x16x32_bf16 v[28:31], v[152:155], v[200:203], v[28:31]
	v_mfma_f32_16x16x32_bf16 v[24:27], v[160:163], v[200:203], v[24:27]
	v_mfma_f32_16x16x32_bf16 v[12:15], v[152:155], v[208:211], v[12:15]
	v_mfma_f32_16x16x32_bf16 v[8:11], v[160:163], v[208:211], v[8:11]
	v_mfma_f32_16x16x32_bf16 v[60:63], v[156:159], v[188:191], v[60:63]
	v_mfma_f32_16x16x32_bf16 v[56:59], v[164:167], v[188:191], v[56:59]
	v_mfma_f32_16x16x32_bf16 v[44:47], v[156:159], v[196:199], v[44:47]
	v_mfma_f32_16x16x32_bf16 v[40:43], v[164:167], v[196:199], v[40:43]
	v_mfma_f32_16x16x32_bf16 v[28:31], v[156:159], v[204:207], v[28:31]
	v_mfma_f32_16x16x32_bf16 v[24:27], v[164:167], v[204:207], v[24:27]
	v_mfma_f32_16x16x32_bf16 v[12:15], v[156:159], v[212:215], v[12:15]
	v_mfma_f32_16x16x32_bf16 v[8:11], v[164:167], v[212:215], v[8:11]
	v_mfma_f32_16x16x32_bf16 v[52:55], v[168:171], v[184:187], v[52:55]
	v_mfma_f32_16x16x32_bf16 v[48:51], v[176:179], v[184:187], v[48:51]
	v_mfma_f32_16x16x32_bf16 v[36:39], v[168:171], v[192:195], v[36:39]
	v_mfma_f32_16x16x32_bf16 v[32:35], v[176:179], v[192:195], v[32:35]
	v_mfma_f32_16x16x32_bf16 v[20:23], v[168:171], v[200:203], v[20:23]
	v_mfma_f32_16x16x32_bf16 v[16:19], v[176:179], v[200:203], v[16:19]
	v_mfma_f32_16x16x32_bf16 v[4:7], v[168:171], v[208:211], v[4:7]
	v_mfma_f32_16x16x32_bf16 v[0:3], v[176:179], v[208:211], v[0:3]
	v_mfma_f32_16x16x32_bf16 v[52:55], v[172:175], v[188:191], v[52:55]
	v_mfma_f32_16x16x32_bf16 v[48:51], v[180:183], v[188:191], v[48:51]
	v_mfma_f32_16x16x32_bf16 v[36:39], v[172:175], v[196:199], v[36:39]
	v_mfma_f32_16x16x32_bf16 v[32:35], v[180:183], v[196:199], v[32:35]
	v_mfma_f32_16x16x32_bf16 v[20:23], v[172:175], v[204:207], v[20:23]
	v_mfma_f32_16x16x32_bf16 v[16:19], v[180:183], v[204:207], v[16:19]
	v_mfma_f32_16x16x32_bf16 v[4:7], v[172:175], v[212:215], v[4:7]
	v_mfma_f32_16x16x32_bf16 v[0:3], v[180:183], v[212:215], v[0:3]
	s_barrier
	s_setprio 0
	v_add_u32_e32 v164, s82, v148
	v_add_u32_e32 v180, s83, v148
	ds_read_b128 v[152:155], v164
	ds_read_b128 v[156:159], v164 offset:1024
	ds_read_b128 v[160:163], v164 offset:2048
	ds_read_b128 v[164:167], v164 offset:3072
	ds_read_b128 v[168:171], v180
	ds_read_b128 v[172:175], v180 offset:1024
	ds_read_b128 v[176:179], v180 offset:2048
	ds_read_b128 v[180:183], v180 offset:3072
	s_add_u32 s30, s30, 0x4000
	s_addc_u32 s31, s31, 0
	s_mov_b32 m0, s35
	ds_read_b128 v[184:187], v151 offset:32768
	ds_read_b128 v[188:191], v151 offset:33792
	ds_read_b128 v[192:195], v151 offset:34816
	ds_read_b128 v[196:199], v151 offset:35840
	ds_read_b128 v[200:203], v151 offset:36864
	ds_read_b128 v[204:207], v151 offset:37888
	ds_read_b128 v[208:211], v151 offset:38912
	ds_read_b128 v[212:215], v151 offset:39936
	global_load_lds_dwordx4 v128, s[30:31]
	v_lshl_add_u64 v[218:219], s[30:31], 0, v[132:133]
	s_mov_b32 m0, s36
	s_nop 0
	global_load_lds_dwordx4 v[218:219], off
	s_waitcnt vmcnt(8)
	s_waitcnt lgkmcnt(0)
	s_setprio 1
	s_barrier
	v_mfma_f32_16x16x32_bf16 v[124:127], v[152:155], v[184:187], v[124:127]
	v_mfma_f32_16x16x32_bf16 v[120:123], v[160:163], v[184:187], v[120:123]
	v_mfma_f32_16x16x32_bf16 v[108:111], v[152:155], v[192:195], v[108:111]
	v_mfma_f32_16x16x32_bf16 v[104:107], v[160:163], v[192:195], v[104:107]
	v_mfma_f32_16x16x32_bf16 v[92:95], v[152:155], v[200:203], v[92:95]
	v_mfma_f32_16x16x32_bf16 v[88:91], v[160:163], v[200:203], v[88:91]
	v_mfma_f32_16x16x32_bf16 v[76:79], v[152:155], v[208:211], v[76:79]
	v_mfma_f32_16x16x32_bf16 v[72:75], v[160:163], v[208:211], v[72:75]
	v_mfma_f32_16x16x32_bf16 v[124:127], v[156:159], v[188:191], v[124:127]
	v_mfma_f32_16x16x32_bf16 v[120:123], v[164:167], v[188:191], v[120:123]
	v_mfma_f32_16x16x32_bf16 v[108:111], v[156:159], v[196:199], v[108:111]
	v_mfma_f32_16x16x32_bf16 v[104:107], v[164:167], v[196:199], v[104:107]
	v_mfma_f32_16x16x32_bf16 v[92:95], v[156:159], v[204:207], v[92:95]
	v_mfma_f32_16x16x32_bf16 v[88:91], v[164:167], v[204:207], v[88:91]
	v_mfma_f32_16x16x32_bf16 v[76:79], v[156:159], v[212:215], v[76:79]
	v_mfma_f32_16x16x32_bf16 v[72:75], v[164:167], v[212:215], v[72:75]
	v_mfma_f32_16x16x32_bf16 v[116:119], v[168:171], v[184:187], v[116:119]
	v_mfma_f32_16x16x32_bf16 v[112:115], v[176:179], v[184:187], v[112:115]
	v_mfma_f32_16x16x32_bf16 v[100:103], v[168:171], v[192:195], v[100:103]
	v_mfma_f32_16x16x32_bf16 v[96:99], v[176:179], v[192:195], v[96:99]
	v_mfma_f32_16x16x32_bf16 v[84:87], v[168:171], v[200:203], v[84:87]
	v_mfma_f32_16x16x32_bf16 v[80:83], v[176:179], v[200:203], v[80:83]
	v_mfma_f32_16x16x32_bf16 v[68:71], v[168:171], v[208:211], v[68:71]
	v_mfma_f32_16x16x32_bf16 v[64:67], v[176:179], v[208:211], v[64:67]
	v_mfma_f32_16x16x32_bf16 v[116:119], v[172:175], v[188:191], v[116:119]
	v_mfma_f32_16x16x32_bf16 v[112:115], v[180:183], v[188:191], v[112:115]
	v_mfma_f32_16x16x32_bf16 v[100:103], v[172:175], v[196:199], v[100:103]
	v_mfma_f32_16x16x32_bf16 v[96:99], v[180:183], v[196:199], v[96:99]
	v_mfma_f32_16x16x32_bf16 v[84:87], v[172:175], v[204:207], v[84:87]
	v_mfma_f32_16x16x32_bf16 v[80:83], v[180:183], v[204:207], v[80:83]
	v_mfma_f32_16x16x32_bf16 v[68:71], v[172:175], v[212:215], v[68:71]
	v_mfma_f32_16x16x32_bf16 v[64:67], v[180:183], v[212:215], v[64:67]
	s_barrier
	s_setprio 0
	s_add_i32 s30, s82, s5
	v_lshl_add_u64 v[144:145], v[144:145], 0, s[12:13]
	s_mov_b32 m0, s30
	ds_read_b128 v[184:187], v151 offset:49152
	ds_read_b128 v[188:191], v151 offset:50176
	ds_read_b128 v[192:195], v151 offset:51200
	ds_read_b128 v[196:199], v151 offset:52224
	ds_read_b128 v[200:203], v151 offset:53248
	ds_read_b128 v[204:207], v151 offset:54272
	ds_read_b128 v[208:211], v151 offset:55296
	ds_read_b128 v[212:215], v151 offset:56320
	global_load_lds_dwordx4 v[144:145], off
	s_add_i32 m0, s30, 0x2000
	s_add_u32 s28, s28, 0x80080
	v_lshl_add_u64 v[144:145], v[216:217], 0, s[12:13]
	s_addc_u32 s29, s29, 0
	s_add_i32 s30, s83, s5
	global_load_lds_dwordx4 v[144:145], off
	s_mov_b32 m0, s30
	s_nop 0
	global_load_lds_dwordx4 v130, s[28:29]
	s_add_i32 m0, s30, 0x2000
	s_nop 0
	global_load_lds_dwordx4 v134, s[28:29]
	s_mov_b32 m0, s38
	s_nop 0
	global_load_lds_dwordx4 v128, s[26:27]
	s_mov_b32 m0, s39
	s_nop 0
	global_load_lds_dwordx4 v132, s[26:27]
	s_waitcnt vmcnt(8)
	s_waitcnt lgkmcnt(0)
	s_setprio 1
	s_barrier
	v_mfma_f32_16x16x32_bf16 v[60:63], v[152:155], v[184:187], v[60:63]
	v_mfma_f32_16x16x32_bf16 v[56:59], v[160:163], v[184:187], v[56:59]
	v_mfma_f32_16x16x32_bf16 v[44:47], v[152:155], v[192:195], v[44:47]
	v_mfma_f32_16x16x32_bf16 v[40:43], v[160:163], v[192:195], v[40:43]
	v_mfma_f32_16x16x32_bf16 v[28:31], v[152:155], v[200:203], v[28:31]
	v_mfma_f32_16x16x32_bf16 v[24:27], v[160:163], v[200:203], v[24:27]
	v_mfma_f32_16x16x32_bf16 v[12:15], v[152:155], v[208:211], v[12:15]
	v_mfma_f32_16x16x32_bf16 v[8:11], v[160:163], v[208:211], v[8:11]
	v_mfma_f32_16x16x32_bf16 v[60:63], v[156:159], v[188:191], v[60:63]
	v_mfma_f32_16x16x32_bf16 v[56:59], v[164:167], v[188:191], v[56:59]
	v_mfma_f32_16x16x32_bf16 v[44:47], v[156:159], v[196:199], v[44:47]
	v_mfma_f32_16x16x32_bf16 v[40:43], v[164:167], v[196:199], v[40:43]
	v_mfma_f32_16x16x32_bf16 v[28:31], v[156:159], v[204:207], v[28:31]
	v_mfma_f32_16x16x32_bf16 v[24:27], v[164:167], v[204:207], v[24:27]
	v_mfma_f32_16x16x32_bf16 v[12:15], v[156:159], v[212:215], v[12:15]
	v_mfma_f32_16x16x32_bf16 v[8:11], v[164:167], v[212:215], v[8:11]
	v_mfma_f32_16x16x32_bf16 v[52:55], v[168:171], v[184:187], v[52:55]
	v_mfma_f32_16x16x32_bf16 v[48:51], v[176:179], v[184:187], v[48:51]
	v_mfma_f32_16x16x32_bf16 v[36:39], v[168:171], v[192:195], v[36:39]
	v_mfma_f32_16x16x32_bf16 v[32:35], v[176:179], v[192:195], v[32:35]
	v_mfma_f32_16x16x32_bf16 v[20:23], v[168:171], v[200:203], v[20:23]
	v_mfma_f32_16x16x32_bf16 v[16:19], v[176:179], v[200:203], v[16:19]
	v_mfma_f32_16x16x32_bf16 v[4:7], v[168:171], v[208:211], v[4:7]
	v_mfma_f32_16x16x32_bf16 v[0:3], v[176:179], v[208:211], v[0:3]
	v_mfma_f32_16x16x32_bf16 v[52:55], v[172:175], v[188:191], v[52:55]
	v_mfma_f32_16x16x32_bf16 v[48:51], v[180:183], v[188:191], v[48:51]
	v_mfma_f32_16x16x32_bf16 v[36:39], v[172:175], v[196:199], v[36:39]
	v_mfma_f32_16x16x32_bf16 v[32:35], v[180:183], v[196:199], v[32:35]
	v_mfma_f32_16x16x32_bf16 v[20:23], v[172:175], v[204:207], v[20:23]
	v_mfma_f32_16x16x32_bf16 v[16:19], v[180:183], v[204:207], v[16:19]
	v_mfma_f32_16x16x32_bf16 v[4:7], v[172:175], v[212:215], v[4:7]
	v_mfma_f32_16x16x32_bf16 v[0:3], v[180:183], v[212:215], v[0:3]
	s_barrier
	s_setprio 0
	s_add_i32 s52, s52, 2
	s_add_u32 s50, s50, 0x100
	s_addc_u32 s51, s51, 0
	s_add_u32 s24, s24, 0x800000
	s_addc_u32 s25, s25, 0
	s_cmp_gt_u32 s52, 29
	s_cbranch_scc0 .LBB0_1404
	s_and_b64 vcc, exec, s[14:15]
	s_cbranch_vccz .LBB0_1407
	s_barrier

.LBB0_1512:
	ds_read_b128 v[128:131], v180
	ds_read_b128 v[132:135], v180 offset:1024
	ds_read_b128 v[136:139], v180 offset:2048
	ds_read_b128 v[140:143], v180 offset:3072
	ds_read_b128 v[144:147], v181
	ds_read_b128 v[148:151], v181 offset:1024
	ds_read_b128 v[152:155], v181 offset:2048
	ds_read_b128 v[156:159], v181 offset:3072
	s_add_u32 s8, s6, 0x3fc000
	s_addc_u32 s9, s7, 0
	s_cmp_eq_u32 s43, 12
	s_cselect_b32 s38, s15, s8
	s_cselect_b32 s39, s12, s9
	s_cselect_b32 s10, s31, s41
	s_cselect_b32 s11, s29, s42
	s_add_u32 s8, s38, 0x400000
	s_addc_u32 s9, s39, 0
	s_add_i32 m0, s52, 0xc000
	ds_read_b128 v[186:189], v182
	ds_read_b128 v[190:193], v182 offset:1024
	ds_read_b128 v[194:197], v182 offset:2048
	ds_read_b128 v[198:201], v182 offset:3072
	ds_read_b128 v[202:205], v182 offset:4096
	ds_read_b128 v[206:209], v182 offset:5120
	ds_read_b128 v[210:213], v182 offset:6144
	ds_read_b128 v[214:217], v182 offset:7168
	global_load_lds_dwordx4 v168, s[6:7]
	s_add_i32 m0, s52, 0xe000
	s_nop 0
	global_load_lds_dwordx4 v170, s[6:7]
	s_waitcnt vmcnt(8)
	s_waitcnt lgkmcnt(0)
	s_setprio 1
	s_barrier
	v_mfma_f32_16x16x32_bf16 v[100:103], v[128:131], v[186:189], v[100:103]
	v_mfma_f32_16x16x32_bf16 v[88:91], v[136:139], v[186:189], v[88:91]
	v_mfma_f32_16x16x32_bf16 v[84:87], v[128:131], v[194:197], v[84:87]
	v_mfma_f32_16x16x32_bf16 v[80:83], v[136:139], v[194:197], v[80:83]
	v_mfma_f32_16x16x32_bf16 v[96:99], v[128:131], v[202:205], v[96:99]
	v_mfma_f32_16x16x32_bf16 v[92:95], v[136:139], v[202:205], v[92:95]
	v_mfma_f32_16x16x32_bf16 v[108:111], v[128:131], v[210:213], v[108:111]
	v_mfma_f32_16x16x32_bf16 v[104:107], v[136:139], v[210:213], v[104:107]
	v_mfma_f32_16x16x32_bf16 v[100:103], v[132:135], v[190:193], v[100:103]
	v_mfma_f32_16x16x32_bf16 v[88:91], v[140:143], v[190:193], v[88:91]
	v_mfma_f32_16x16x32_bf16 v[84:87], v[132:135], v[198:201], v[84:87]
	v_mfma_f32_16x16x32_bf16 v[80:83], v[140:143], v[198:201], v[80:83]
	v_mfma_f32_16x16x32_bf16 v[96:99], v[132:135], v[206:209], v[96:99]
	v_mfma_f32_16x16x32_bf16 v[92:95], v[140:143], v[206:209], v[92:95]
	v_mfma_f32_16x16x32_bf16 v[108:111], v[132:135], v[214:217], v[108:111]
	v_mfma_f32_16x16x32_bf16 v[104:107], v[140:143], v[214:217], v[104:107]
	v_mfma_f32_16x16x32_bf16 v[28:31], v[144:147], v[186:189], v[28:31]
	v_mfma_f32_16x16x32_bf16 v[16:19], v[152:155], v[186:189], v[16:19]
	v_mfma_f32_16x16x32_bf16 v[4:7], v[144:147], v[194:197], v[4:7]
	v_mfma_f32_16x16x32_bf16 v[0:3], v[152:155], v[194:197], v[0:3]
	v_mfma_f32_16x16x32_bf16 v[12:15], v[144:147], v[202:205], v[12:15]
	v_mfma_f32_16x16x32_bf16 v[8:11], v[152:155], v[202:205], v[8:11]
	v_mfma_f32_16x16x32_bf16 v[24:27], v[144:147], v[210:213], v[24:27]
	v_mfma_f32_16x16x32_bf16 v[20:23], v[152:155], v[210:213], v[20:23]
	v_mfma_f32_16x16x32_bf16 v[28:31], v[148:151], v[190:193], v[28:31]
	v_mfma_f32_16x16x32_bf16 v[16:19], v[156:159], v[190:193], v[16:19]
	v_mfma_f32_16x16x32_bf16 v[4:7], v[148:151], v[198:201], v[4:7]
	v_mfma_f32_16x16x32_bf16 v[0:3], v[156:159], v[198:201], v[0:3]
	v_mfma_f32_16x16x32_bf16 v[12:15], v[148:151], v[206:209], v[12:15]
	v_mfma_f32_16x16x32_bf16 v[8:11], v[156:159], v[206:209], v[8:11]
	v_mfma_f32_16x16x32_bf16 v[24:27], v[148:151], v[214:217], v[24:27]
	v_mfma_f32_16x16x32_bf16 v[20:23], v[156:159], v[214:217], v[20:23]
	s_barrier
	s_setprio 0
	s_add_i32 s44, s57, s4
	v_lshl_add_u64 v[174:175], s[10:11], 0, v[162:163]
	s_mov_b32 m0, s44
	ds_read_b128 v[186:189], v182 offset:16384
	ds_read_b128 v[190:193], v182 offset:17408
	ds_read_b128 v[194:197], v182 offset:18432
	ds_read_b128 v[198:201], v182 offset:19456
	ds_read_b128 v[202:205], v182 offset:20480
	ds_read_b128 v[206:209], v182 offset:21504
	ds_read_b128 v[210:213], v182 offset:22528
	ds_read_b128 v[214:217], v182 offset:23552
	global_load_lds_dwordx4 v[174:175], off
	s_add_i32 m0, s44, 0x2000
	s_add_u32 s44, s10, 0x40000
	v_lshl_add_u64 v[218:219], s[10:11], 0, v[166:167]
	s_addc_u32 s45, s11, 0
	s_add_i32 s46, s81, s4
	global_load_lds_dwordx4 v[218:219], off
	s_mov_b32 m0, s46
	s_nop 0
	global_load_lds_dwordx4 v162, s[44:45]
	s_add_i32 m0, s46, 0x2000
	s_nop 0
	global_load_lds_dwordx4 v166, s[44:45]
	s_mov_b32 m0, s52
	s_nop 0
	global_load_lds_dwordx4 v160, s[38:39]
	s_mov_b32 m0, s33
	s_nop 0
	global_load_lds_dwordx4 v164, s[38:39]
	s_waitcnt vmcnt(8)
	s_waitcnt lgkmcnt(0)
	s_setprio 1
	s_barrier
	v_mfma_f32_16x16x32_bf16 v[116:119], v[128:131], v[186:189], v[116:119]
	v_mfma_f32_16x16x32_bf16 v[112:115], v[136:139], v[186:189], v[112:115]
	v_mfma_f32_16x16x32_bf16 v[124:127], v[128:131], v[194:197], v[124:127]
	v_mfma_f32_16x16x32_bf16 v[120:123], v[136:139], v[194:197], v[120:123]
	v_mfma_f32_16x16x32_bf16 v[76:79], v[128:131], v[202:205], v[76:79]
	v_mfma_f32_16x16x32_bf16 v[72:75], v[136:139], v[202:205], v[72:75]
	v_mfma_f32_16x16x32_bf16 v[68:71], v[128:131], v[210:213], v[68:71]
	v_mfma_f32_16x16x32_bf16 v[64:67], v[136:139], v[210:213], v[64:67]
	v_mfma_f32_16x16x32_bf16 v[116:119], v[132:135], v[190:193], v[116:119]
	v_mfma_f32_16x16x32_bf16 v[112:115], v[140:143], v[190:193], v[112:115]
	v_mfma_f32_16x16x32_bf16 v[124:127], v[132:135], v[198:201], v[124:127]
	v_mfma_f32_16x16x32_bf16 v[120:123], v[140:143], v[198:201], v[120:123]
	v_mfma_f32_16x16x32_bf16 v[76:79], v[132:135], v[206:209], v[76:79]
	v_mfma_f32_16x16x32_bf16 v[72:75], v[140:143], v[206:209], v[72:75]
	v_mfma_f32_16x16x32_bf16 v[68:71], v[132:135], v[214:217], v[68:71]
	v_mfma_f32_16x16x32_bf16 v[64:67], v[140:143], v[214:217], v[64:67]
	v_mfma_f32_16x16x32_bf16 v[36:39], v[144:147], v[186:189], v[36:39]
	v_mfma_f32_16x16x32_bf16 v[32:35], v[152:155], v[186:189], v[32:35]
	v_mfma_f32_16x16x32_bf16 v[44:47], v[144:147], v[194:197], v[44:47]
	v_mfma_f32_16x16x32_bf16 v[40:43], v[152:155], v[194:197], v[40:43]
	v_mfma_f32_16x16x32_bf16 v[52:55], v[144:147], v[202:205], v[52:55]
	v_mfma_f32_16x16x32_bf16 v[48:51], v[152:155], v[202:205], v[48:51]
	v_mfma_f32_16x16x32_bf16 v[60:63], v[144:147], v[210:213], v[60:63]
	v_mfma_f32_16x16x32_bf16 v[56:59], v[152:155], v[210:213], v[56:59]
	v_mfma_f32_16x16x32_bf16 v[36:39], v[148:151], v[190:193], v[36:39]
	v_mfma_f32_16x16x32_bf16 v[32:35], v[156:159], v[190:193], v[32:35]
	v_mfma_f32_16x16x32_bf16 v[44:47], v[148:151], v[198:201], v[44:47]
	v_mfma_f32_16x16x32_bf16 v[40:43], v[156:159], v[198:201], v[40:43]
	v_mfma_f32_16x16x32_bf16 v[52:55], v[148:151], v[206:209], v[52:55]
	v_mfma_f32_16x16x32_bf16 v[48:51], v[156:159], v[206:209], v[48:51]
	v_mfma_f32_16x16x32_bf16 v[60:63], v[148:151], v[214:217], v[60:63]
	v_mfma_f32_16x16x32_bf16 v[56:59], v[156:159], v[214:217], v[56:59]
	s_barrier
	s_setprio 0
	v_add_u32_e32 v140, s82, v179
	v_add_u32_e32 v156, s83, v179
	ds_read_b128 v[128:131], v140
	ds_read_b128 v[132:135], v140 offset:1024
	ds_read_b128 v[136:139], v140 offset:2048
	ds_read_b128 v[140:143], v140 offset:3072
	ds_read_b128 v[144:147], v156
	ds_read_b128 v[148:151], v156 offset:1024
	ds_read_b128 v[152:155], v156 offset:2048
	ds_read_b128 v[156:159], v156 offset:3072
	s_add_u32 s38, s38, 0x4000
	s_addc_u32 s39, s39, 0
	s_mov_b32 m0, s53
	ds_read_b128 v[186:189], v182 offset:32768
	ds_read_b128 v[190:193], v182 offset:33792
	ds_read_b128 v[194:197], v182 offset:34816
	ds_read_b128 v[198:201], v182 offset:35840
	ds_read_b128 v[202:205], v182 offset:36864
	ds_read_b128 v[206:209], v182 offset:37888
	ds_read_b128 v[210:213], v182 offset:38912
	ds_read_b128 v[214:217], v182 offset:39936
	global_load_lds_dwordx4 v160, s[38:39]
	v_lshl_add_u64 v[220:221], s[38:39], 0, v[164:165]
	s_mov_b32 m0, s54
	s_nop 0
	global_load_lds_dwordx4 v[220:221], off
	s_waitcnt vmcnt(8)
	s_waitcnt lgkmcnt(0)
	s_setprio 1
	s_barrier
	v_mfma_f32_16x16x32_bf16 v[100:103], v[128:131], v[186:189], v[100:103]
	v_mfma_f32_16x16x32_bf16 v[88:91], v[136:139], v[186:189], v[88:91]
	v_mfma_f32_16x16x32_bf16 v[84:87], v[128:131], v[194:197], v[84:87]
	v_mfma_f32_16x16x32_bf16 v[80:83], v[136:139], v[194:197], v[80:83]
	v_mfma_f32_16x16x32_bf16 v[96:99], v[128:131], v[202:205], v[96:99]
	v_mfma_f32_16x16x32_bf16 v[92:95], v[136:139], v[202:205], v[92:95]
	v_mfma_f32_16x16x32_bf16 v[108:111], v[128:131], v[210:213], v[108:111]
	v_mfma_f32_16x16x32_bf16 v[104:107], v[136:139], v[210:213], v[104:107]
	v_mfma_f32_16x16x32_bf16 v[100:103], v[132:135], v[190:193], v[100:103]
	v_mfma_f32_16x16x32_bf16 v[88:91], v[140:143], v[190:193], v[88:91]
	v_mfma_f32_16x16x32_bf16 v[84:87], v[132:135], v[198:201], v[84:87]
	v_mfma_f32_16x16x32_bf16 v[80:83], v[140:143], v[198:201], v[80:83]
	v_mfma_f32_16x16x32_bf16 v[96:99], v[132:135], v[206:209], v[96:99]
	v_mfma_f32_16x16x32_bf16 v[92:95], v[140:143], v[206:209], v[92:95]
	v_mfma_f32_16x16x32_bf16 v[108:111], v[132:135], v[214:217], v[108:111]
	v_mfma_f32_16x16x32_bf16 v[104:107], v[140:143], v[214:217], v[104:107]
	v_mfma_f32_16x16x32_bf16 v[28:31], v[144:147], v[186:189], v[28:31]
	v_mfma_f32_16x16x32_bf16 v[16:19], v[152:155], v[186:189], v[16:19]
	v_mfma_f32_16x16x32_bf16 v[4:7], v[144:147], v[194:197], v[4:7]
	v_mfma_f32_16x16x32_bf16 v[0:3], v[152:155], v[194:197], v[0:3]
	v_mfma_f32_16x16x32_bf16 v[12:15], v[144:147], v[202:205], v[12:15]
	v_mfma_f32_16x16x32_bf16 v[8:11], v[152:155], v[202:205], v[8:11]
	v_mfma_f32_16x16x32_bf16 v[24:27], v[144:147], v[210:213], v[24:27]
	v_mfma_f32_16x16x32_bf16 v[20:23], v[152:155], v[210:213], v[20:23]
	v_mfma_f32_16x16x32_bf16 v[28:31], v[148:151], v[190:193], v[28:31]
	v_mfma_f32_16x16x32_bf16 v[16:19], v[156:159], v[190:193], v[16:19]
	v_mfma_f32_16x16x32_bf16 v[4:7], v[148:151], v[198:201], v[4:7]
	v_mfma_f32_16x16x32_bf16 v[0:3], v[156:159], v[198:201], v[0:3]
	v_mfma_f32_16x16x32_bf16 v[12:15], v[148:151], v[206:209], v[12:15]
	v_mfma_f32_16x16x32_bf16 v[8:11], v[156:159], v[206:209], v[8:11]
	v_mfma_f32_16x16x32_bf16 v[24:27], v[148:151], v[214:217], v[24:27]
	v_mfma_f32_16x16x32_bf16 v[20:23], v[156:159], v[214:217], v[20:23]
	s_barrier
	s_setprio 0
	s_add_i32 s38, s82, s4
	v_lshl_add_u64 v[174:175], v[174:175], 0, s[22:23]
	s_mov_b32 m0, s38
	ds_read_b128 v[186:189], v182 offset:49152
	ds_read_b128 v[190:193], v182 offset:50176
	ds_read_b128 v[194:197], v182 offset:51200
	ds_read_b128 v[198:201], v182 offset:52224
	ds_read_b128 v[202:205], v182 offset:53248
	ds_read_b128 v[206:209], v182 offset:54272
	ds_read_b128 v[210:213], v182 offset:55296
	ds_read_b128 v[214:217], v182 offset:56320
	global_load_lds_dwordx4 v[174:175], off
	s_add_i32 m0, s38, 0x2000
	s_add_u32 s10, s10, 0x40080
	v_lshl_add_u64 v[174:175], v[218:219], 0, s[22:23]
	s_addc_u32 s11, s11, 0
	s_add_i32 s38, s83, s4
	global_load_lds_dwordx4 v[174:175], off
	s_mov_b32 m0, s38
	s_nop 0
	global_load_lds_dwordx4 v162, s[10:11]
	s_add_i32 m0, s38, 0x2000
	s_nop 0
	global_load_lds_dwordx4 v166, s[10:11]
	s_mov_b32 m0, s50
	s_nop 0
	global_load_lds_dwordx4 v160, s[8:9]
	s_mov_b32 m0, s51
	s_nop 0
	global_load_lds_dwordx4 v164, s[8:9]
	s_waitcnt vmcnt(8)
	s_waitcnt lgkmcnt(0)
	s_setprio 1
	s_barrier
	v_mfma_f32_16x16x32_bf16 v[116:119], v[128:131], v[186:189], v[116:119]
	v_mfma_f32_16x16x32_bf16 v[112:115], v[136:139], v[186:189], v[112:115]
	v_mfma_f32_16x16x32_bf16 v[124:127], v[128:131], v[194:197], v[124:127]
	v_mfma_f32_16x16x32_bf16 v[120:123], v[136:139], v[194:197], v[120:123]
	v_mfma_f32_16x16x32_bf16 v[76:79], v[128:131], v[202:205], v[76:79]
	v_mfma_f32_16x16x32_bf16 v[72:75], v[136:139], v[202:205], v[72:75]
	v_mfma_f32_16x16x32_bf16 v[68:71], v[128:131], v[210:213], v[68:71]
	v_mfma_f32_16x16x32_bf16 v[64:67], v[136:139], v[210:213], v[64:67]
	v_mfma_f32_16x16x32_bf16 v[116:119], v[132:135], v[190:193], v[116:119]
	v_mfma_f32_16x16x32_bf16 v[112:115], v[140:143], v[190:193], v[112:115]
	v_mfma_f32_16x16x32_bf16 v[124:127], v[132:135], v[198:201], v[124:127]
	v_mfma_f32_16x16x32_bf16 v[120:123], v[140:143], v[198:201], v[120:123]
	v_mfma_f32_16x16x32_bf16 v[76:79], v[132:135], v[206:209], v[76:79]
	v_mfma_f32_16x16x32_bf16 v[72:75], v[140:143], v[206:209], v[72:75]
	v_mfma_f32_16x16x32_bf16 v[68:71], v[132:135], v[214:217], v[68:71]
	v_mfma_f32_16x16x32_bf16 v[64:67], v[140:143], v[214:217], v[64:67]
	v_mfma_f32_16x16x32_bf16 v[36:39], v[144:147], v[186:189], v[36:39]
	v_mfma_f32_16x16x32_bf16 v[32:35], v[152:155], v[186:189], v[32:35]
	v_mfma_f32_16x16x32_bf16 v[44:47], v[144:147], v[194:197], v[44:47]
	v_mfma_f32_16x16x32_bf16 v[40:43], v[152:155], v[194:197], v[40:43]
	v_mfma_f32_16x16x32_bf16 v[52:55], v[144:147], v[202:205], v[52:55]
	v_mfma_f32_16x16x32_bf16 v[48:51], v[152:155], v[202:205], v[48:51]
	v_mfma_f32_16x16x32_bf16 v[60:63], v[144:147], v[210:213], v[60:63]
	v_mfma_f32_16x16x32_bf16 v[56:59], v[152:155], v[210:213], v[56:59]
	v_mfma_f32_16x16x32_bf16 v[36:39], v[148:151], v[190:193], v[36:39]
	v_mfma_f32_16x16x32_bf16 v[32:35], v[156:159], v[190:193], v[32:35]
	v_mfma_f32_16x16x32_bf16 v[44:47], v[148:151], v[198:201], v[44:47]
	v_mfma_f32_16x16x32_bf16 v[40:43], v[156:159], v[198:201], v[40:43]
	v_mfma_f32_16x16x32_bf16 v[52:55], v[148:151], v[206:209], v[52:55]
	v_mfma_f32_16x16x32_bf16 v[48:51], v[156:159], v[206:209], v[48:51]
	v_mfma_f32_16x16x32_bf16 v[60:63], v[148:151], v[214:217], v[60:63]
	v_mfma_f32_16x16x32_bf16 v[56:59], v[156:159], v[214:217], v[56:59]
	s_barrier
	s_setprio 0
	s_add_i32 s43, s43, 2
	s_add_u32 s41, s41, 0x100
	s_addc_u32 s42, s42, 0
	s_add_u32 s6, s6, 0x800000
	s_addc_u32 s7, s7, 0
	s_cmp_gt_u32 s43, 13
	s_cbranch_scc0 .LBB0_1512
	s_and_b64 vcc, exec, s[24:25]
	s_cbranch_vccz .LBB0_1515
	s_barrier

.LBB0_1628:
	ds_read_b128 v[152:155], v149
	ds_read_b128 v[156:159], v149 offset:1024
	ds_read_b128 v[160:163], v149 offset:2048
	ds_read_b128 v[164:167], v149 offset:3072
	ds_read_b128 v[168:171], v150
	ds_read_b128 v[172:175], v150 offset:1024
	ds_read_b128 v[176:179], v150 offset:2048
	ds_read_b128 v[180:183], v150 offset:3072
	s_add_u32 s26, s24, 0x3fc000
	s_addc_u32 s27, s25, 0
	s_cmp_eq_u32 s52, 28
	s_cselect_b32 s30, s46, s26
	s_cselect_b32 s31, s17, s27
	s_cselect_b32 s28, s47, s50
	s_cselect_b32 s29, s19, s51
	s_add_u32 s26, s30, 0x400000
	s_addc_u32 s27, s31, 0
	s_add_i32 m0, s34, 0xc000
	ds_read_b128 v[184:187], v151
	ds_read_b128 v[188:191], v151 offset:1024
	ds_read_b128 v[192:195], v151 offset:2048
	ds_read_b128 v[196:199], v151 offset:3072
	ds_read_b128 v[200:203], v151 offset:4096
	ds_read_b128 v[204:207], v151 offset:5120
	ds_read_b128 v[208:211], v151 offset:6144
	ds_read_b128 v[212:215], v151 offset:7168
	global_load_lds_dwordx4 v136, s[24:25]
	s_add_i32 m0, s34, 0xe000
	s_nop 0
	global_load_lds_dwordx4 v138, s[24:25]
	s_waitcnt vmcnt(8)
	s_waitcnt lgkmcnt(0)
	s_setprio 1
	s_barrier
	v_mfma_f32_16x16x32_bf16 v[124:127], v[152:155], v[184:187], v[124:127]
	v_mfma_f32_16x16x32_bf16 v[120:123], v[160:163], v[184:187], v[120:123]
	v_mfma_f32_16x16x32_bf16 v[108:111], v[152:155], v[192:195], v[108:111]
	v_mfma_f32_16x16x32_bf16 v[104:107], v[160:163], v[192:195], v[104:107]
	v_mfma_f32_16x16x32_bf16 v[92:95], v[152:155], v[200:203], v[92:95]
	v_mfma_f32_16x16x32_bf16 v[88:91], v[160:163], v[200:203], v[88:91]
	v_mfma_f32_16x16x32_bf16 v[76:79], v[152:155], v[208:211], v[76:79]
	v_mfma_f32_16x16x32_bf16 v[72:75], v[160:163], v[208:211], v[72:75]
	v_mfma_f32_16x16x32_bf16 v[124:127], v[156:159], v[188:191], v[124:127]
	v_mfma_f32_16x16x32_bf16 v[120:123], v[164:167], v[188:191], v[120:123]
	v_mfma_f32_16x16x32_bf16 v[108:111], v[156:159], v[196:199], v[108:111]
	v_mfma_f32_16x16x32_bf16 v[104:107], v[164:167], v[196:199], v[104:107]
	v_mfma_f32_16x16x32_bf16 v[92:95], v[156:159], v[204:207], v[92:95]
	v_mfma_f32_16x16x32_bf16 v[88:91], v[164:167], v[204:207], v[88:91]
	v_mfma_f32_16x16x32_bf16 v[76:79], v[156:159], v[212:215], v[76:79]
	v_mfma_f32_16x16x32_bf16 v[72:75], v[164:167], v[212:215], v[72:75]
	v_mfma_f32_16x16x32_bf16 v[116:119], v[168:171], v[184:187], v[116:119]
	v_mfma_f32_16x16x32_bf16 v[112:115], v[176:179], v[184:187], v[112:115]
	v_mfma_f32_16x16x32_bf16 v[100:103], v[168:171], v[192:195], v[100:103]
	v_mfma_f32_16x16x32_bf16 v[96:99], v[176:179], v[192:195], v[96:99]
	v_mfma_f32_16x16x32_bf16 v[84:87], v[168:171], v[200:203], v[84:87]
	v_mfma_f32_16x16x32_bf16 v[80:83], v[176:179], v[200:203], v[80:83]
	v_mfma_f32_16x16x32_bf16 v[68:71], v[168:171], v[208:211], v[68:71]
	v_mfma_f32_16x16x32_bf16 v[64:67], v[176:179], v[208:211], v[64:67]
	v_mfma_f32_16x16x32_bf16 v[116:119], v[172:175], v[188:191], v[116:119]
	v_mfma_f32_16x16x32_bf16 v[112:115], v[180:183], v[188:191], v[112:115]
	v_mfma_f32_16x16x32_bf16 v[100:103], v[172:175], v[196:199], v[100:103]
	v_mfma_f32_16x16x32_bf16 v[96:99], v[180:183], v[196:199], v[96:99]
	v_mfma_f32_16x16x32_bf16 v[84:87], v[172:175], v[204:207], v[84:87]
	v_mfma_f32_16x16x32_bf16 v[80:83], v[180:183], v[204:207], v[80:83]
	v_mfma_f32_16x16x32_bf16 v[68:71], v[172:175], v[212:215], v[68:71]
	v_mfma_f32_16x16x32_bf16 v[64:67], v[180:183], v[212:215], v[64:67]
	s_barrier
	s_setprio 0
	s_add_i32 s53, s57, s33
	s_mov_b32 m0, s53
	ds_read_b128 v[184:187], v151 offset:16384
	ds_read_b128 v[188:191], v151 offset:17408
	ds_read_b128 v[192:195], v151 offset:18432
	ds_read_b128 v[196:199], v151 offset:19456
	ds_read_b128 v[200:203], v151 offset:20480
	ds_read_b128 v[204:207], v151 offset:21504
	ds_read_b128 v[208:211], v151 offset:22528
	ds_read_b128 v[212:215], v151 offset:23552
	global_load_lds_dwordx4 v132, s[28:29]
	s_add_i32 m0, s53, 0x2000
	s_add_u32 s54, s28, 0x4000
	s_addc_u32 s55, s29, 0
	s_add_i32 s53, s81, s33
	global_load_lds_dwordx4 v128, s[28:29]
	s_mov_b32 m0, s53
	s_nop 0
	global_load_lds_dwordx4 v132, s[54:55]
	s_add_i32 m0, s53, 0x2000
	s_nop 0
	global_load_lds_dwordx4 v128, s[54:55]
	s_mov_b32 m0, s34
	s_nop 0
	global_load_lds_dwordx4 v134, s[30:31]
	s_mov_b32 m0, s35
	s_nop 0
	global_load_lds_dwordx4 v130, s[30:31]
	s_waitcnt vmcnt(8)
	s_waitcnt lgkmcnt(0)
	s_setprio 1
	s_barrier
	v_mfma_f32_16x16x32_bf16 v[60:63], v[152:155], v[184:187], v[60:63]
	v_mfma_f32_16x16x32_bf16 v[56:59], v[160:163], v[184:187], v[56:59]
	v_mfma_f32_16x16x32_bf16 v[44:47], v[152:155], v[192:195], v[44:47]
	v_mfma_f32_16x16x32_bf16 v[40:43], v[160:163], v[192:195], v[40:43]
	v_mfma_f32_16x16x32_bf16 v[28:31], v[152:155], v[200:203], v[28:31]
	v_mfma_f32_16x16x32_bf16 v[24:27], v[160:163], v[200:203], v[24:27]
	v_mfma_f32_16x16x32_bf16 v[12:15], v[152:155], v[208:211], v[12:15]
	v_mfma_f32_16x16x32_bf16 v[8:11], v[160:163], v[208:211], v[8:11]
	v_mfma_f32_16x16x32_bf16 v[60:63], v[156:159], v[188:191], v[60:63]
	v_mfma_f32_16x16x32_bf16 v[56:59], v[164:167], v[188:191], v[56:59]
	v_mfma_f32_16x16x32_bf16 v[44:47], v[156:159], v[196:199], v[44:47]
	v_mfma_f32_16x16x32_bf16 v[40:43], v[164:167], v[196:199], v[40:43]
	v_mfma_f32_16x16x32_bf16 v[28:31], v[156:159], v[204:207], v[28:31]
	v_mfma_f32_16x16x32_bf16 v[24:27], v[164:167], v[204:207], v[24:27]
	v_mfma_f32_16x16x32_bf16 v[12:15], v[156:159], v[212:215], v[12:15]
	v_mfma_f32_16x16x32_bf16 v[8:11], v[164:167], v[212:215], v[8:11]
	v_mfma_f32_16x16x32_bf16 v[52:55], v[168:171], v[184:187], v[52:55]
	v_mfma_f32_16x16x32_bf16 v[48:51], v[176:179], v[184:187], v[48:51]
	v_mfma_f32_16x16x32_bf16 v[36:39], v[168:171], v[192:195], v[36:39]
	v_mfma_f32_16x16x32_bf16 v[32:35], v[176:179], v[192:195], v[32:35]
	v_mfma_f32_16x16x32_bf16 v[20:23], v[168:171], v[200:203], v[20:23]
	v_mfma_f32_16x16x32_bf16 v[16:19], v[176:179], v[200:203], v[16:19]
	v_mfma_f32_16x16x32_bf16 v[4:7], v[168:171], v[208:211], v[4:7]
	v_mfma_f32_16x16x32_bf16 v[0:3], v[176:179], v[208:211], v[0:3]
	v_mfma_f32_16x16x32_bf16 v[52:55], v[172:175], v[188:191], v[52:55]
	v_mfma_f32_16x16x32_bf16 v[48:51], v[180:183], v[188:191], v[48:51]
	v_mfma_f32_16x16x32_bf16 v[36:39], v[172:175], v[196:199], v[36:39]
	v_mfma_f32_16x16x32_bf16 v[32:35], v[180:183], v[196:199], v[32:35]
	v_mfma_f32_16x16x32_bf16 v[20:23], v[172:175], v[204:207], v[20:23]
	v_mfma_f32_16x16x32_bf16 v[16:19], v[180:183], v[204:207], v[16:19]
	v_mfma_f32_16x16x32_bf16 v[4:7], v[172:175], v[212:215], v[4:7]
	v_mfma_f32_16x16x32_bf16 v[0:3], v[180:183], v[212:215], v[0:3]
	s_barrier
	s_setprio 0
	v_add_u32_e32 v144, s82, v148
	ds_read_b128 v[152:155], v144
	ds_read_b128 v[156:159], v144 offset:1024
	ds_read_b128 v[160:163], v144 offset:2048
	ds_read_b128 v[164:167], v144 offset:3072
	v_add_u32_e32 v144, s83, v148
	ds_read_b128 v[168:171], v144
	ds_read_b128 v[172:175], v144 offset:1024
	ds_read_b128 v[176:179], v144 offset:2048
	ds_read_b128 v[180:183], v144 offset:3072
	s_add_u32 s30, s30, 0x4000
	s_addc_u32 s31, s31, 0
	s_mov_b32 m0, s36
	ds_read_b128 v[184:187], v151 offset:32768
	ds_read_b128 v[188:191], v151 offset:33792
	ds_read_b128 v[192:195], v151 offset:34816
	ds_read_b128 v[196:199], v151 offset:35840
	ds_read_b128 v[200:203], v151 offset:36864
	ds_read_b128 v[204:207], v151 offset:37888
	ds_read_b128 v[208:211], v151 offset:38912
	ds_read_b128 v[212:215], v151 offset:39936
	global_load_lds_dwordx4 v134, s[30:31]
	s_mov_b32 m0, s37
	s_nop 0
	global_load_lds_dwordx4 v130, s[30:31]
	s_waitcnt vmcnt(8)
	s_waitcnt lgkmcnt(0)
	s_setprio 1
	s_barrier
	v_mfma_f32_16x16x32_bf16 v[124:127], v[152:155], v[184:187], v[124:127]
	v_mfma_f32_16x16x32_bf16 v[120:123], v[160:163], v[184:187], v[120:123]
	v_mfma_f32_16x16x32_bf16 v[108:111], v[152:155], v[192:195], v[108:111]
	v_mfma_f32_16x16x32_bf16 v[104:107], v[160:163], v[192:195], v[104:107]
	v_mfma_f32_16x16x32_bf16 v[92:95], v[152:155], v[200:203], v[92:95]
	v_mfma_f32_16x16x32_bf16 v[88:91], v[160:163], v[200:203], v[88:91]
	v_mfma_f32_16x16x32_bf16 v[76:79], v[152:155], v[208:211], v[76:79]
	v_mfma_f32_16x16x32_bf16 v[72:75], v[160:163], v[208:211], v[72:75]
	v_mfma_f32_16x16x32_bf16 v[124:127], v[156:159], v[188:191], v[124:127]
	v_mfma_f32_16x16x32_bf16 v[120:123], v[164:167], v[188:191], v[120:123]
	v_mfma_f32_16x16x32_bf16 v[108:111], v[156:159], v[196:199], v[108:111]
	v_mfma_f32_16x16x32_bf16 v[104:107], v[164:167], v[196:199], v[104:107]
	v_mfma_f32_16x16x32_bf16 v[92:95], v[156:159], v[204:207], v[92:95]
	v_mfma_f32_16x16x32_bf16 v[88:91], v[164:167], v[204:207], v[88:91]
	v_mfma_f32_16x16x32_bf16 v[76:79], v[156:159], v[212:215], v[76:79]
	v_mfma_f32_16x16x32_bf16 v[72:75], v[164:167], v[212:215], v[72:75]
	v_mfma_f32_16x16x32_bf16 v[116:119], v[168:171], v[184:187], v[116:119]
	v_mfma_f32_16x16x32_bf16 v[112:115], v[176:179], v[184:187], v[112:115]
	v_mfma_f32_16x16x32_bf16 v[100:103], v[168:171], v[192:195], v[100:103]
	v_mfma_f32_16x16x32_bf16 v[96:99], v[176:179], v[192:195], v[96:99]
	v_mfma_f32_16x16x32_bf16 v[84:87], v[168:171], v[200:203], v[84:87]
	v_mfma_f32_16x16x32_bf16 v[80:83], v[176:179], v[200:203], v[80:83]
	v_mfma_f32_16x16x32_bf16 v[68:71], v[168:171], v[208:211], v[68:71]
	v_mfma_f32_16x16x32_bf16 v[64:67], v[176:179], v[208:211], v[64:67]
	v_mfma_f32_16x16x32_bf16 v[116:119], v[172:175], v[188:191], v[116:119]
	v_mfma_f32_16x16x32_bf16 v[112:115], v[180:183], v[188:191], v[112:115]
	v_mfma_f32_16x16x32_bf16 v[100:103], v[172:175], v[196:199], v[100:103]
	v_mfma_f32_16x16x32_bf16 v[96:99], v[180:183], v[196:199], v[96:99]
	v_mfma_f32_16x16x32_bf16 v[84:87], v[172:175], v[204:207], v[84:87]
	v_mfma_f32_16x16x32_bf16 v[80:83], v[180:183], v[204:207], v[80:83]
	v_mfma_f32_16x16x32_bf16 v[68:71], v[172:175], v[212:215], v[68:71]
	v_mfma_f32_16x16x32_bf16 v[64:67], v[180:183], v[212:215], v[64:67]
	s_barrier
	s_setprio 0
	s_add_u32 s30, s28, 0x160000
	s_addc_u32 s31, s29, 0
	s_add_i32 s53, s82, s33
	s_mov_b32 m0, s53
	ds_read_b128 v[184:187], v151 offset:49152
	ds_read_b128 v[188:191], v151 offset:50176
	ds_read_b128 v[192:195], v151 offset:51200
	ds_read_b128 v[196:199], v151 offset:52224
	ds_read_b128 v[200:203], v151 offset:53248
	ds_read_b128 v[204:207], v151 offset:54272
	ds_read_b128 v[208:211], v151 offset:55296
	ds_read_b128 v[212:215], v151 offset:56320
	global_load_lds_dwordx4 v132, s[30:31]
	s_add_i32 m0, s53, 0x2000
	s_add_u32 s28, s28, 0x164000
	global_load_lds_dwordx4 v128, s[30:31]
	s_addc_u32 s29, s29, 0
	s_add_i32 s30, s83, s33
	s_mov_b32 m0, s30
	s_nop 0
	global_load_lds_dwordx4 v132, s[28:29]
	s_add_i32 m0, s30, 0x2000
	s_nop 0
	global_load_lds_dwordx4 v128, s[28:29]
	s_mov_b32 m0, s39
	s_nop 0
	global_load_lds_dwordx4 v134, s[26:27]
	s_mov_b32 m0, s40
	s_nop 0
	global_load_lds_dwordx4 v130, s[26:27]
	s_waitcnt vmcnt(8)
	s_waitcnt lgkmcnt(0)
	s_setprio 1
	s_barrier
	v_mfma_f32_16x16x32_bf16 v[60:63], v[152:155], v[184:187], v[60:63]
	v_mfma_f32_16x16x32_bf16 v[56:59], v[160:163], v[184:187], v[56:59]
	v_mfma_f32_16x16x32_bf16 v[44:47], v[152:155], v[192:195], v[44:47]
	v_mfma_f32_16x16x32_bf16 v[40:43], v[160:163], v[192:195], v[40:43]
	v_mfma_f32_16x16x32_bf16 v[28:31], v[152:155], v[200:203], v[28:31]
	v_mfma_f32_16x16x32_bf16 v[24:27], v[160:163], v[200:203], v[24:27]
	v_mfma_f32_16x16x32_bf16 v[12:15], v[152:155], v[208:211], v[12:15]
	v_mfma_f32_16x16x32_bf16 v[8:11], v[160:163], v[208:211], v[8:11]
	v_mfma_f32_16x16x32_bf16 v[60:63], v[156:159], v[188:191], v[60:63]
	v_mfma_f32_16x16x32_bf16 v[56:59], v[164:167], v[188:191], v[56:59]
	v_mfma_f32_16x16x32_bf16 v[44:47], v[156:159], v[196:199], v[44:47]
	v_mfma_f32_16x16x32_bf16 v[40:43], v[164:167], v[196:199], v[40:43]
	v_mfma_f32_16x16x32_bf16 v[28:31], v[156:159], v[204:207], v[28:31]
	v_mfma_f32_16x16x32_bf16 v[24:27], v[164:167], v[204:207], v[24:27]
	v_mfma_f32_16x16x32_bf16 v[12:15], v[156:159], v[212:215], v[12:15]
	v_mfma_f32_16x16x32_bf16 v[8:11], v[164:167], v[212:215], v[8:11]
	v_mfma_f32_16x16x32_bf16 v[52:55], v[168:171], v[184:187], v[52:55]
	v_mfma_f32_16x16x32_bf16 v[48:51], v[176:179], v[184:187], v[48:51]
	v_mfma_f32_16x16x32_bf16 v[36:39], v[168:171], v[192:195], v[36:39]
	v_mfma_f32_16x16x32_bf16 v[32:35], v[176:179], v[192:195], v[32:35]
	v_mfma_f32_16x16x32_bf16 v[20:23], v[168:171], v[200:203], v[20:23]
	v_mfma_f32_16x16x32_bf16 v[16:19], v[176:179], v[200:203], v[16:19]
	v_mfma_f32_16x16x32_bf16 v[4:7], v[168:171], v[208:211], v[4:7]
	v_mfma_f32_16x16x32_bf16 v[0:3], v[176:179], v[208:211], v[0:3]
	v_mfma_f32_16x16x32_bf16 v[52:55], v[172:175], v[188:191], v[52:55]
	v_mfma_f32_16x16x32_bf16 v[48:51], v[180:183], v[188:191], v[48:51]
	v_mfma_f32_16x16x32_bf16 v[36:39], v[172:175], v[196:199], v[36:39]
	v_mfma_f32_16x16x32_bf16 v[32:35], v[180:183], v[196:199], v[32:35]
	v_mfma_f32_16x16x32_bf16 v[20:23], v[172:175], v[204:207], v[20:23]
	v_mfma_f32_16x16x32_bf16 v[16:19], v[180:183], v[204:207], v[16:19]
	v_mfma_f32_16x16x32_bf16 v[4:7], v[172:175], v[212:215], v[4:7]
	v_mfma_f32_16x16x32_bf16 v[0:3], v[180:183], v[212:215], v[0:3]
	s_barrier
	s_setprio 0
	s_add_i32 s52, s52, 2
	s_add_u32 s50, s50, 0x2c0000
	s_addc_u32 s51, s51, 0
	s_add_u32 s24, s24, 0x800000
	s_addc_u32 s25, s25, 0
	s_cmp_gt_u32 s52, 29
	s_cbranch_scc0 .LBB0_1628
	s_and_b64 vcc, exec, s[12:13]
	s_cbranch_vccz .LBB0_1631
	s_barrier

.LBB0_1706:
	ds_read_b128 v[128:131], v180
	ds_read_b128 v[132:135], v180 offset:1024
	ds_read_b128 v[136:139], v180 offset:2048
	ds_read_b128 v[140:143], v180 offset:3072
	ds_read_b128 v[144:147], v181
	ds_read_b128 v[148:151], v181 offset:1024
	ds_read_b128 v[152:155], v181 offset:2048
	ds_read_b128 v[156:159], v181 offset:3072
	s_add_u32 s8, s6, 0x3fc000
	s_addc_u32 s9, s7, 0
	s_cmpk_eq_i32 s44, 0x54
	s_cselect_b32 s38, s15, s8
	s_cselect_b32 s39, s12, s9
	s_cselect_b32 s10, s41, s42
	s_cselect_b32 s11, s31, s43
	s_add_u32 s8, s38, 0x400000
	s_addc_u32 s9, s39, 0
	s_add_i32 m0, s74, 0xc000
	ds_read_b128 v[186:189], v182
	ds_read_b128 v[190:193], v182 offset:1024
	ds_read_b128 v[194:197], v182 offset:2048
	ds_read_b128 v[198:201], v182 offset:3072
	ds_read_b128 v[202:205], v182 offset:4096
	ds_read_b128 v[206:209], v182 offset:5120
	ds_read_b128 v[210:213], v182 offset:6144
	ds_read_b128 v[214:217], v182 offset:7168
	global_load_lds_dwordx4 v168, s[6:7]
	s_add_i32 m0, s74, 0xe000
	s_nop 0
	global_load_lds_dwordx4 v170, s[6:7]
	s_waitcnt vmcnt(8)
	s_waitcnt lgkmcnt(0)
	s_setprio 1
	s_barrier
	v_mfma_f32_16x16x32_bf16 v[92:95], v[128:131], v[186:189], v[92:95]
	v_mfma_f32_16x16x32_bf16 v[88:91], v[136:139], v[186:189], v[88:91]
	v_mfma_f32_16x16x32_bf16 v[12:15], v[128:131], v[194:197], v[12:15]
	v_mfma_f32_16x16x32_bf16 v[8:11], v[136:139], v[194:197], v[8:11]
	v_mfma_f32_16x16x32_bf16 v[100:103], v[128:131], v[202:205], v[100:103]
	v_mfma_f32_16x16x32_bf16 v[96:99], v[136:139], v[202:205], v[96:99]
	v_mfma_f32_16x16x32_bf16 v[108:111], v[128:131], v[210:213], v[108:111]
	v_mfma_f32_16x16x32_bf16 v[104:107], v[136:139], v[210:213], v[104:107]
	v_mfma_f32_16x16x32_bf16 v[92:95], v[132:135], v[190:193], v[92:95]
	v_mfma_f32_16x16x32_bf16 v[88:91], v[140:143], v[190:193], v[88:91]
	v_mfma_f32_16x16x32_bf16 v[12:15], v[132:135], v[198:201], v[12:15]
	v_mfma_f32_16x16x32_bf16 v[8:11], v[140:143], v[198:201], v[8:11]
	v_mfma_f32_16x16x32_bf16 v[100:103], v[132:135], v[206:209], v[100:103]
	v_mfma_f32_16x16x32_bf16 v[96:99], v[140:143], v[206:209], v[96:99]
	v_mfma_f32_16x16x32_bf16 v[108:111], v[132:135], v[214:217], v[108:111]
	v_mfma_f32_16x16x32_bf16 v[104:107], v[140:143], v[214:217], v[104:107]
	v_mfma_f32_16x16x32_bf16 v[84:87], v[144:147], v[186:189], v[84:87]
	v_mfma_f32_16x16x32_bf16 v[80:83], v[152:155], v[186:189], v[80:83]
	v_mfma_f32_16x16x32_bf16 v[4:7], v[144:147], v[194:197], v[4:7]
	v_mfma_f32_16x16x32_bf16 v[0:3], v[152:155], v[194:197], v[0:3]
	v_mfma_f32_16x16x32_bf16 v[20:23], v[144:147], v[202:205], v[20:23]
	v_mfma_f32_16x16x32_bf16 v[16:19], v[152:155], v[202:205], v[16:19]
	v_mfma_f32_16x16x32_bf16 v[28:31], v[144:147], v[210:213], v[28:31]
	v_mfma_f32_16x16x32_bf16 v[24:27], v[152:155], v[210:213], v[24:27]
	v_mfma_f32_16x16x32_bf16 v[84:87], v[148:151], v[190:193], v[84:87]
	v_mfma_f32_16x16x32_bf16 v[80:83], v[156:159], v[190:193], v[80:83]
	v_mfma_f32_16x16x32_bf16 v[4:7], v[148:151], v[198:201], v[4:7]
	v_mfma_f32_16x16x32_bf16 v[0:3], v[156:159], v[198:201], v[0:3]
	v_mfma_f32_16x16x32_bf16 v[20:23], v[148:151], v[206:209], v[20:23]
	v_mfma_f32_16x16x32_bf16 v[16:19], v[156:159], v[206:209], v[16:19]
	v_mfma_f32_16x16x32_bf16 v[28:31], v[148:151], v[214:217], v[28:31]
	v_mfma_f32_16x16x32_bf16 v[24:27], v[156:159], v[214:217], v[24:27]
	s_barrier
	s_setprio 0
	s_add_i32 s45, s57, s72
	s_mov_b32 m0, s45
	ds_read_b128 v[186:189], v182 offset:16384
	ds_read_b128 v[190:193], v182 offset:17408
	ds_read_b128 v[194:197], v182 offset:18432
	ds_read_b128 v[198:201], v182 offset:19456
	ds_read_b128 v[202:205], v182 offset:20480
	ds_read_b128 v[206:209], v182 offset:21504
	ds_read_b128 v[210:213], v182 offset:22528
	ds_read_b128 v[214:217], v182 offset:23552
	global_load_lds_dwordx4 v162, s[10:11]
	s_add_i32 m0, s45, 0x2000
	s_add_u32 s46, s10, 0x4000
	s_addc_u32 s47, s11, 0
	s_add_i32 s45, s81, s72
	global_load_lds_dwordx4 v166, s[10:11]
	s_mov_b32 m0, s45
	s_nop 0
	global_load_lds_dwordx4 v162, s[46:47]
	s_add_i32 m0, s45, 0x2000
	s_nop 0
	global_load_lds_dwordx4 v166, s[46:47]
	s_mov_b32 m0, s74
	s_nop 0
	global_load_lds_dwordx4 v160, s[38:39]
	s_mov_b32 m0, s75
	s_nop 0
	global_load_lds_dwordx4 v164, s[38:39]
	s_waitcnt vmcnt(8)
	s_waitcnt lgkmcnt(0)
	s_setprio 1
	s_barrier
	v_mfma_f32_16x16x32_bf16 v[116:119], v[128:131], v[186:189], v[116:119]
	v_mfma_f32_16x16x32_bf16 v[112:115], v[136:139], v[186:189], v[112:115]
	v_mfma_f32_16x16x32_bf16 v[124:127], v[128:131], v[194:197], v[124:127]
	v_mfma_f32_16x16x32_bf16 v[120:123], v[136:139], v[194:197], v[120:123]
	v_mfma_f32_16x16x32_bf16 v[76:79], v[128:131], v[202:205], v[76:79]
	v_mfma_f32_16x16x32_bf16 v[72:75], v[136:139], v[202:205], v[72:75]
	v_mfma_f32_16x16x32_bf16 v[68:71], v[128:131], v[210:213], v[68:71]
	v_mfma_f32_16x16x32_bf16 v[64:67], v[136:139], v[210:213], v[64:67]
	v_mfma_f32_16x16x32_bf16 v[116:119], v[132:135], v[190:193], v[116:119]
	v_mfma_f32_16x16x32_bf16 v[112:115], v[140:143], v[190:193], v[112:115]
	v_mfma_f32_16x16x32_bf16 v[124:127], v[132:135], v[198:201], v[124:127]
	v_mfma_f32_16x16x32_bf16 v[120:123], v[140:143], v[198:201], v[120:123]
	v_mfma_f32_16x16x32_bf16 v[76:79], v[132:135], v[206:209], v[76:79]
	v_mfma_f32_16x16x32_bf16 v[72:75], v[140:143], v[206:209], v[72:75]
	v_mfma_f32_16x16x32_bf16 v[68:71], v[132:135], v[214:217], v[68:71]
	v_mfma_f32_16x16x32_bf16 v[64:67], v[140:143], v[214:217], v[64:67]
	v_mfma_f32_16x16x32_bf16 v[36:39], v[144:147], v[186:189], v[36:39]
	v_mfma_f32_16x16x32_bf16 v[32:35], v[152:155], v[186:189], v[32:35]
	v_mfma_f32_16x16x32_bf16 v[44:47], v[144:147], v[194:197], v[44:47]
	v_mfma_f32_16x16x32_bf16 v[40:43], v[152:155], v[194:197], v[40:43]
	v_mfma_f32_16x16x32_bf16 v[52:55], v[144:147], v[202:205], v[52:55]
	v_mfma_f32_16x16x32_bf16 v[48:51], v[152:155], v[202:205], v[48:51]
	v_mfma_f32_16x16x32_bf16 v[60:63], v[144:147], v[210:213], v[60:63]
	v_mfma_f32_16x16x32_bf16 v[56:59], v[152:155], v[210:213], v[56:59]
	v_mfma_f32_16x16x32_bf16 v[36:39], v[148:151], v[190:193], v[36:39]
	v_mfma_f32_16x16x32_bf16 v[32:35], v[156:159], v[190:193], v[32:35]
	v_mfma_f32_16x16x32_bf16 v[44:47], v[148:151], v[198:201], v[44:47]
	v_mfma_f32_16x16x32_bf16 v[40:43], v[156:159], v[198:201], v[40:43]
	v_mfma_f32_16x16x32_bf16 v[52:55], v[148:151], v[206:209], v[52:55]
	v_mfma_f32_16x16x32_bf16 v[48:51], v[156:159], v[206:209], v[48:51]
	v_mfma_f32_16x16x32_bf16 v[60:63], v[148:151], v[214:217], v[60:63]
	v_mfma_f32_16x16x32_bf16 v[56:59], v[156:159], v[214:217], v[56:59]
	s_barrier
	s_setprio 0
	v_add_u32_e32 v140, s82, v179
	v_add_u32_e32 v156, s83, v179
	ds_read_b128 v[128:131], v140
	ds_read_b128 v[132:135], v140 offset:1024
	ds_read_b128 v[136:139], v140 offset:2048
	ds_read_b128 v[140:143], v140 offset:3072
	ds_read_b128 v[144:147], v156
	ds_read_b128 v[148:151], v156 offset:1024
	ds_read_b128 v[152:155], v156 offset:2048
	ds_read_b128 v[156:159], v156 offset:3072
	s_add_u32 s38, s38, 0x4000
	s_addc_u32 s39, s39, 0
	s_mov_b32 m0, s96
	ds_read_b128 v[186:189], v182 offset:32768
	ds_read_b128 v[190:193], v182 offset:33792
	ds_read_b128 v[194:197], v182 offset:34816
	ds_read_b128 v[198:201], v182 offset:35840
	ds_read_b128 v[202:205], v182 offset:36864
	ds_read_b128 v[206:209], v182 offset:37888
	ds_read_b128 v[210:213], v182 offset:38912
	ds_read_b128 v[214:217], v182 offset:39936
	global_load_lds_dwordx4 v160, s[38:39]
	s_mov_b32 m0, s97
	s_nop 0
	global_load_lds_dwordx4 v164, s[38:39]
	s_waitcnt vmcnt(8)
	s_waitcnt lgkmcnt(0)
	s_setprio 1
	s_barrier
	v_mfma_f32_16x16x32_bf16 v[92:95], v[128:131], v[186:189], v[92:95]
	v_mfma_f32_16x16x32_bf16 v[88:91], v[136:139], v[186:189], v[88:91]
	v_mfma_f32_16x16x32_bf16 v[12:15], v[128:131], v[194:197], v[12:15]
	v_mfma_f32_16x16x32_bf16 v[8:11], v[136:139], v[194:197], v[8:11]
	v_mfma_f32_16x16x32_bf16 v[100:103], v[128:131], v[202:205], v[100:103]
	v_mfma_f32_16x16x32_bf16 v[96:99], v[136:139], v[202:205], v[96:99]
	v_mfma_f32_16x16x32_bf16 v[108:111], v[128:131], v[210:213], v[108:111]
	v_mfma_f32_16x16x32_bf16 v[104:107], v[136:139], v[210:213], v[104:107]
	v_mfma_f32_16x16x32_bf16 v[92:95], v[132:135], v[190:193], v[92:95]
	v_mfma_f32_16x16x32_bf16 v[88:91], v[140:143], v[190:193], v[88:91]
	v_mfma_f32_16x16x32_bf16 v[12:15], v[132:135], v[198:201], v[12:15]
	v_mfma_f32_16x16x32_bf16 v[8:11], v[140:143], v[198:201], v[8:11]
	v_mfma_f32_16x16x32_bf16 v[100:103], v[132:135], v[206:209], v[100:103]
	v_mfma_f32_16x16x32_bf16 v[96:99], v[140:143], v[206:209], v[96:99]
	v_mfma_f32_16x16x32_bf16 v[108:111], v[132:135], v[214:217], v[108:111]
	v_mfma_f32_16x16x32_bf16 v[104:107], v[140:143], v[214:217], v[104:107]
	v_mfma_f32_16x16x32_bf16 v[84:87], v[144:147], v[186:189], v[84:87]
	v_mfma_f32_16x16x32_bf16 v[80:83], v[152:155], v[186:189], v[80:83]
	v_mfma_f32_16x16x32_bf16 v[4:7], v[144:147], v[194:197], v[4:7]
	v_mfma_f32_16x16x32_bf16 v[0:3], v[152:155], v[194:197], v[0:3]
	v_mfma_f32_16x16x32_bf16 v[20:23], v[144:147], v[202:205], v[20:23]
	v_mfma_f32_16x16x32_bf16 v[16:19], v[152:155], v[202:205], v[16:19]
	v_mfma_f32_16x16x32_bf16 v[28:31], v[144:147], v[210:213], v[28:31]
	v_mfma_f32_16x16x32_bf16 v[24:27], v[152:155], v[210:213], v[24:27]
	v_mfma_f32_16x16x32_bf16 v[84:87], v[148:151], v[190:193], v[84:87]
	v_mfma_f32_16x16x32_bf16 v[80:83], v[156:159], v[190:193], v[80:83]
	v_mfma_f32_16x16x32_bf16 v[4:7], v[148:151], v[198:201], v[4:7]
	v_mfma_f32_16x16x32_bf16 v[0:3], v[156:159], v[198:201], v[0:3]
	v_mfma_f32_16x16x32_bf16 v[20:23], v[148:151], v[206:209], v[20:23]
	v_mfma_f32_16x16x32_bf16 v[16:19], v[156:159], v[206:209], v[16:19]
	v_mfma_f32_16x16x32_bf16 v[28:31], v[148:151], v[214:217], v[28:31]
	v_mfma_f32_16x16x32_bf16 v[24:27], v[156:159], v[214:217], v[24:27]
	s_barrier
	s_setprio 0
	s_add_u32 s38, s10, 0x40000
	s_addc_u32 s39, s11, 0
	s_add_i32 s45, s82, s72
	s_mov_b32 m0, s45
	ds_read_b128 v[186:189], v182 offset:49152
	ds_read_b128 v[190:193], v182 offset:50176
	ds_read_b128 v[194:197], v182 offset:51200
	ds_read_b128 v[198:201], v182 offset:52224
	ds_read_b128 v[202:205], v182 offset:53248
	ds_read_b128 v[206:209], v182 offset:54272
	ds_read_b128 v[210:213], v182 offset:55296
	ds_read_b128 v[214:217], v182 offset:56320
	global_load_lds_dwordx4 v162, s[38:39]
	s_add_i32 m0, s45, 0x2000
	s_add_u32 s10, s10, 0x44000
	global_load_lds_dwordx4 v166, s[38:39]
	s_addc_u32 s11, s11, 0
	s_add_i32 s38, s83, s72
	s_mov_b32 m0, s38
	s_nop 0
	global_load_lds_dwordx4 v162, s[10:11]
	s_add_i32 m0, s38, 0x2000
	s_nop 0
	global_load_lds_dwordx4 v166, s[10:11]
	s_mov_b32 m0, s5
	s_nop 0
	global_load_lds_dwordx4 v160, s[8:9]
	s_mov_b32 m0, s68
	s_nop 0
	global_load_lds_dwordx4 v164, s[8:9]
	s_waitcnt vmcnt(8)
	s_waitcnt lgkmcnt(0)
	s_setprio 1
	s_barrier
	v_mfma_f32_16x16x32_bf16 v[116:119], v[128:131], v[186:189], v[116:119]
	v_mfma_f32_16x16x32_bf16 v[112:115], v[136:139], v[186:189], v[112:115]
	v_mfma_f32_16x16x32_bf16 v[124:127], v[128:131], v[194:197], v[124:127]
	v_mfma_f32_16x16x32_bf16 v[120:123], v[136:139], v[194:197], v[120:123]
	v_mfma_f32_16x16x32_bf16 v[76:79], v[128:131], v[202:205], v[76:79]
	v_mfma_f32_16x16x32_bf16 v[72:75], v[136:139], v[202:205], v[72:75]
	v_mfma_f32_16x16x32_bf16 v[68:71], v[128:131], v[210:213], v[68:71]
	v_mfma_f32_16x16x32_bf16 v[64:67], v[136:139], v[210:213], v[64:67]
	v_mfma_f32_16x16x32_bf16 v[116:119], v[132:135], v[190:193], v[116:119]
	v_mfma_f32_16x16x32_bf16 v[112:115], v[140:143], v[190:193], v[112:115]
	v_mfma_f32_16x16x32_bf16 v[124:127], v[132:135], v[198:201], v[124:127]
	v_mfma_f32_16x16x32_bf16 v[120:123], v[140:143], v[198:201], v[120:123]
	v_mfma_f32_16x16x32_bf16 v[76:79], v[132:135], v[206:209], v[76:79]
	v_mfma_f32_16x16x32_bf16 v[72:75], v[140:143], v[206:209], v[72:75]
	v_mfma_f32_16x16x32_bf16 v[68:71], v[132:135], v[214:217], v[68:71]
	v_mfma_f32_16x16x32_bf16 v[64:67], v[140:143], v[214:217], v[64:67]
	v_mfma_f32_16x16x32_bf16 v[36:39], v[144:147], v[186:189], v[36:39]
	v_mfma_f32_16x16x32_bf16 v[32:35], v[152:155], v[186:189], v[32:35]
	v_mfma_f32_16x16x32_bf16 v[44:47], v[144:147], v[194:197], v[44:47]
	v_mfma_f32_16x16x32_bf16 v[40:43], v[152:155], v[194:197], v[40:43]
	v_mfma_f32_16x16x32_bf16 v[52:55], v[144:147], v[202:205], v[52:55]
	v_mfma_f32_16x16x32_bf16 v[48:51], v[152:155], v[202:205], v[48:51]
	v_mfma_f32_16x16x32_bf16 v[60:63], v[144:147], v[210:213], v[60:63]
	v_mfma_f32_16x16x32_bf16 v[56:59], v[152:155], v[210:213], v[56:59]
	v_mfma_f32_16x16x32_bf16 v[36:39], v[148:151], v[190:193], v[36:39]
	v_mfma_f32_16x16x32_bf16 v[32:35], v[156:159], v[190:193], v[32:35]
	v_mfma_f32_16x16x32_bf16 v[44:47], v[148:151], v[198:201], v[44:47]
	v_mfma_f32_16x16x32_bf16 v[40:43], v[156:159], v[198:201], v[40:43]
	v_mfma_f32_16x16x32_bf16 v[52:55], v[148:151], v[206:209], v[52:55]
	v_mfma_f32_16x16x32_bf16 v[48:51], v[156:159], v[206:209], v[48:51]
	v_mfma_f32_16x16x32_bf16 v[60:63], v[148:151], v[214:217], v[60:63]
	v_mfma_f32_16x16x32_bf16 v[56:59], v[156:159], v[214:217], v[56:59]
	s_barrier
	s_setprio 0
	s_add_i32 s44, s44, 2
	s_add_u32 s42, s42, 0x80000
	s_addc_u32 s43, s43, 0
	s_add_u32 s6, s6, 0x800000
	s_addc_u32 s7, s7, 0
	s_cmpk_gt_u32 s44, 0x55
	s_cbranch_scc0 .LBB0_1706
	s_and_b64 vcc, exec, s[26:27]
	s_cbranch_vccz .LBB0_1709
	s_barrier

.LBB0_1900:
	ds_read_b128 v[128:131], v180
	ds_read_b128 v[132:135], v180 offset:1024
	ds_read_b128 v[136:139], v180 offset:2048
	ds_read_b128 v[140:143], v180 offset:3072
	ds_read_b128 v[144:147], v181
	ds_read_b128 v[148:151], v181 offset:1024
	ds_read_b128 v[152:155], v181 offset:2048
	ds_read_b128 v[156:159], v181 offset:3072
	s_add_u32 s8, s6, 0x3fc000
	s_addc_u32 s9, s7, 0
	s_cmpk_eq_i32 s44, 0x54
	s_cselect_b32 s38, s15, s8
	s_cselect_b32 s39, s12, s9
	s_cselect_b32 s10, s41, s42
	s_cselect_b32 s11, s31, s43
	s_add_u32 s8, s38, 0x400000
	s_addc_u32 s9, s39, 0
	s_add_i32 m0, s74, 0xc000
	ds_read_b128 v[186:189], v182
	ds_read_b128 v[190:193], v182 offset:1024
	ds_read_b128 v[194:197], v182 offset:2048
	ds_read_b128 v[198:201], v182 offset:3072
	ds_read_b128 v[202:205], v182 offset:4096
	ds_read_b128 v[206:209], v182 offset:5120
	ds_read_b128 v[210:213], v182 offset:6144
	ds_read_b128 v[214:217], v182 offset:7168
	global_load_lds_dwordx4 v168, s[6:7]
	s_add_i32 m0, s74, 0xe000
	s_nop 0
	global_load_lds_dwordx4 v170, s[6:7]
	s_waitcnt vmcnt(8)
	s_waitcnt lgkmcnt(0)
	s_setprio 1
	s_barrier
	v_mfma_f32_16x16x32_bf16 v[92:95], v[128:131], v[186:189], v[92:95]
	v_mfma_f32_16x16x32_bf16 v[88:91], v[136:139], v[186:189], v[88:91]
	v_mfma_f32_16x16x32_bf16 v[12:15], v[128:131], v[194:197], v[12:15]
	v_mfma_f32_16x16x32_bf16 v[8:11], v[136:139], v[194:197], v[8:11]
	v_mfma_f32_16x16x32_bf16 v[100:103], v[128:131], v[202:205], v[100:103]
	v_mfma_f32_16x16x32_bf16 v[96:99], v[136:139], v[202:205], v[96:99]
	v_mfma_f32_16x16x32_bf16 v[108:111], v[128:131], v[210:213], v[108:111]
	v_mfma_f32_16x16x32_bf16 v[104:107], v[136:139], v[210:213], v[104:107]
	v_mfma_f32_16x16x32_bf16 v[92:95], v[132:135], v[190:193], v[92:95]
	v_mfma_f32_16x16x32_bf16 v[88:91], v[140:143], v[190:193], v[88:91]
	v_mfma_f32_16x16x32_bf16 v[12:15], v[132:135], v[198:201], v[12:15]
	v_mfma_f32_16x16x32_bf16 v[8:11], v[140:143], v[198:201], v[8:11]
	v_mfma_f32_16x16x32_bf16 v[100:103], v[132:135], v[206:209], v[100:103]
	v_mfma_f32_16x16x32_bf16 v[96:99], v[140:143], v[206:209], v[96:99]
	v_mfma_f32_16x16x32_bf16 v[108:111], v[132:135], v[214:217], v[108:111]
	v_mfma_f32_16x16x32_bf16 v[104:107], v[140:143], v[214:217], v[104:107]
	v_mfma_f32_16x16x32_bf16 v[84:87], v[144:147], v[186:189], v[84:87]
	v_mfma_f32_16x16x32_bf16 v[80:83], v[152:155], v[186:189], v[80:83]
	v_mfma_f32_16x16x32_bf16 v[4:7], v[144:147], v[194:197], v[4:7]
	v_mfma_f32_16x16x32_bf16 v[0:3], v[152:155], v[194:197], v[0:3]
	v_mfma_f32_16x16x32_bf16 v[20:23], v[144:147], v[202:205], v[20:23]
	v_mfma_f32_16x16x32_bf16 v[16:19], v[152:155], v[202:205], v[16:19]
	v_mfma_f32_16x16x32_bf16 v[28:31], v[144:147], v[210:213], v[28:31]
	v_mfma_f32_16x16x32_bf16 v[24:27], v[152:155], v[210:213], v[24:27]
	v_mfma_f32_16x16x32_bf16 v[84:87], v[148:151], v[190:193], v[84:87]
	v_mfma_f32_16x16x32_bf16 v[80:83], v[156:159], v[190:193], v[80:83]
	v_mfma_f32_16x16x32_bf16 v[4:7], v[148:151], v[198:201], v[4:7]
	v_mfma_f32_16x16x32_bf16 v[0:3], v[156:159], v[198:201], v[0:3]
	v_mfma_f32_16x16x32_bf16 v[20:23], v[148:151], v[206:209], v[20:23]
	v_mfma_f32_16x16x32_bf16 v[16:19], v[156:159], v[206:209], v[16:19]
	v_mfma_f32_16x16x32_bf16 v[28:31], v[148:151], v[214:217], v[28:31]
	v_mfma_f32_16x16x32_bf16 v[24:27], v[156:159], v[214:217], v[24:27]
	s_barrier
	s_setprio 0
	s_add_i32 s45, s57, s72
	s_mov_b32 m0, s45
	ds_read_b128 v[186:189], v182 offset:16384
	ds_read_b128 v[190:193], v182 offset:17408
	ds_read_b128 v[194:197], v182 offset:18432
	ds_read_b128 v[198:201], v182 offset:19456
	ds_read_b128 v[202:205], v182 offset:20480
	ds_read_b128 v[206:209], v182 offset:21504
	ds_read_b128 v[210:213], v182 offset:22528
	ds_read_b128 v[214:217], v182 offset:23552
	global_load_lds_dwordx4 v162, s[10:11]
	s_add_i32 m0, s45, 0x2000
	s_add_u32 s46, s10, 0x4000
	s_addc_u32 s47, s11, 0
	s_add_i32 s45, s81, s72
	global_load_lds_dwordx4 v166, s[10:11]
	s_mov_b32 m0, s45
	s_nop 0
	global_load_lds_dwordx4 v162, s[46:47]
	s_add_i32 m0, s45, 0x2000
	s_nop 0
	global_load_lds_dwordx4 v166, s[46:47]
	s_mov_b32 m0, s74
	s_nop 0
	global_load_lds_dwordx4 v160, s[38:39]
	s_mov_b32 m0, s75
	s_nop 0
	global_load_lds_dwordx4 v164, s[38:39]
	s_waitcnt vmcnt(8)
	s_waitcnt lgkmcnt(0)
	s_setprio 1
	s_barrier
	v_mfma_f32_16x16x32_bf16 v[116:119], v[128:131], v[186:189], v[116:119]
	v_mfma_f32_16x16x32_bf16 v[112:115], v[136:139], v[186:189], v[112:115]
	v_mfma_f32_16x16x32_bf16 v[124:127], v[128:131], v[194:197], v[124:127]
	v_mfma_f32_16x16x32_bf16 v[120:123], v[136:139], v[194:197], v[120:123]
	v_mfma_f32_16x16x32_bf16 v[76:79], v[128:131], v[202:205], v[76:79]
	v_mfma_f32_16x16x32_bf16 v[72:75], v[136:139], v[202:205], v[72:75]
	v_mfma_f32_16x16x32_bf16 v[68:71], v[128:131], v[210:213], v[68:71]
	v_mfma_f32_16x16x32_bf16 v[64:67], v[136:139], v[210:213], v[64:67]
	v_mfma_f32_16x16x32_bf16 v[116:119], v[132:135], v[190:193], v[116:119]
	v_mfma_f32_16x16x32_bf16 v[112:115], v[140:143], v[190:193], v[112:115]
	v_mfma_f32_16x16x32_bf16 v[124:127], v[132:135], v[198:201], v[124:127]
	v_mfma_f32_16x16x32_bf16 v[120:123], v[140:143], v[198:201], v[120:123]
	v_mfma_f32_16x16x32_bf16 v[76:79], v[132:135], v[206:209], v[76:79]
	v_mfma_f32_16x16x32_bf16 v[72:75], v[140:143], v[206:209], v[72:75]
	v_mfma_f32_16x16x32_bf16 v[68:71], v[132:135], v[214:217], v[68:71]
	v_mfma_f32_16x16x32_bf16 v[64:67], v[140:143], v[214:217], v[64:67]
	v_mfma_f32_16x16x32_bf16 v[36:39], v[144:147], v[186:189], v[36:39]
	v_mfma_f32_16x16x32_bf16 v[32:35], v[152:155], v[186:189], v[32:35]
	v_mfma_f32_16x16x32_bf16 v[44:47], v[144:147], v[194:197], v[44:47]
	v_mfma_f32_16x16x32_bf16 v[40:43], v[152:155], v[194:197], v[40:43]
	v_mfma_f32_16x16x32_bf16 v[52:55], v[144:147], v[202:205], v[52:55]
	v_mfma_f32_16x16x32_bf16 v[48:51], v[152:155], v[202:205], v[48:51]
	v_mfma_f32_16x16x32_bf16 v[60:63], v[144:147], v[210:213], v[60:63]
	v_mfma_f32_16x16x32_bf16 v[56:59], v[152:155], v[210:213], v[56:59]
	v_mfma_f32_16x16x32_bf16 v[36:39], v[148:151], v[190:193], v[36:39]
	v_mfma_f32_16x16x32_bf16 v[32:35], v[156:159], v[190:193], v[32:35]
	v_mfma_f32_16x16x32_bf16 v[44:47], v[148:151], v[198:201], v[44:47]
	v_mfma_f32_16x16x32_bf16 v[40:43], v[156:159], v[198:201], v[40:43]
	v_mfma_f32_16x16x32_bf16 v[52:55], v[148:151], v[206:209], v[52:55]
	v_mfma_f32_16x16x32_bf16 v[48:51], v[156:159], v[206:209], v[48:51]
	v_mfma_f32_16x16x32_bf16 v[60:63], v[148:151], v[214:217], v[60:63]
	v_mfma_f32_16x16x32_bf16 v[56:59], v[156:159], v[214:217], v[56:59]
	s_barrier
	s_setprio 0
	v_add_u32_e32 v140, s82, v179
	v_add_u32_e32 v156, s83, v179
	ds_read_b128 v[128:131], v140
	ds_read_b128 v[132:135], v140 offset:1024
	ds_read_b128 v[136:139], v140 offset:2048
	ds_read_b128 v[140:143], v140 offset:3072
	ds_read_b128 v[144:147], v156
	ds_read_b128 v[148:151], v156 offset:1024
	ds_read_b128 v[152:155], v156 offset:2048
	ds_read_b128 v[156:159], v156 offset:3072
	s_add_u32 s38, s38, 0x4000
	s_addc_u32 s39, s39, 0
	s_mov_b32 m0, s96
	ds_read_b128 v[186:189], v182 offset:32768
	ds_read_b128 v[190:193], v182 offset:33792
	ds_read_b128 v[194:197], v182 offset:34816
	ds_read_b128 v[198:201], v182 offset:35840
	ds_read_b128 v[202:205], v182 offset:36864
	ds_read_b128 v[206:209], v182 offset:37888
	ds_read_b128 v[210:213], v182 offset:38912
	ds_read_b128 v[214:217], v182 offset:39936
	global_load_lds_dwordx4 v160, s[38:39]
	s_mov_b32 m0, s97
	s_nop 0
	global_load_lds_dwordx4 v164, s[38:39]
	s_waitcnt vmcnt(8)
	s_waitcnt lgkmcnt(0)
	s_setprio 1
	s_barrier
	v_mfma_f32_16x16x32_bf16 v[92:95], v[128:131], v[186:189], v[92:95]
	v_mfma_f32_16x16x32_bf16 v[88:91], v[136:139], v[186:189], v[88:91]
	v_mfma_f32_16x16x32_bf16 v[12:15], v[128:131], v[194:197], v[12:15]
	v_mfma_f32_16x16x32_bf16 v[8:11], v[136:139], v[194:197], v[8:11]
	v_mfma_f32_16x16x32_bf16 v[100:103], v[128:131], v[202:205], v[100:103]
	v_mfma_f32_16x16x32_bf16 v[96:99], v[136:139], v[202:205], v[96:99]
	v_mfma_f32_16x16x32_bf16 v[108:111], v[128:131], v[210:213], v[108:111]
	v_mfma_f32_16x16x32_bf16 v[104:107], v[136:139], v[210:213], v[104:107]
	v_mfma_f32_16x16x32_bf16 v[92:95], v[132:135], v[190:193], v[92:95]
	v_mfma_f32_16x16x32_bf16 v[88:91], v[140:143], v[190:193], v[88:91]
	v_mfma_f32_16x16x32_bf16 v[12:15], v[132:135], v[198:201], v[12:15]
	v_mfma_f32_16x16x32_bf16 v[8:11], v[140:143], v[198:201], v[8:11]
	v_mfma_f32_16x16x32_bf16 v[100:103], v[132:135], v[206:209], v[100:103]
	v_mfma_f32_16x16x32_bf16 v[96:99], v[140:143], v[206:209], v[96:99]
	v_mfma_f32_16x16x32_bf16 v[108:111], v[132:135], v[214:217], v[108:111]
	v_mfma_f32_16x16x32_bf16 v[104:107], v[140:143], v[214:217], v[104:107]
	v_mfma_f32_16x16x32_bf16 v[84:87], v[144:147], v[186:189], v[84:87]
	v_mfma_f32_16x16x32_bf16 v[80:83], v[152:155], v[186:189], v[80:83]
	v_mfma_f32_16x16x32_bf16 v[4:7], v[144:147], v[194:197], v[4:7]
	v_mfma_f32_16x16x32_bf16 v[0:3], v[152:155], v[194:197], v[0:3]
	v_mfma_f32_16x16x32_bf16 v[20:23], v[144:147], v[202:205], v[20:23]
	v_mfma_f32_16x16x32_bf16 v[16:19], v[152:155], v[202:205], v[16:19]
	v_mfma_f32_16x16x32_bf16 v[28:31], v[144:147], v[210:213], v[28:31]
	v_mfma_f32_16x16x32_bf16 v[24:27], v[152:155], v[210:213], v[24:27]
	v_mfma_f32_16x16x32_bf16 v[84:87], v[148:151], v[190:193], v[84:87]
	v_mfma_f32_16x16x32_bf16 v[80:83], v[156:159], v[190:193], v[80:83]
	v_mfma_f32_16x16x32_bf16 v[4:7], v[148:151], v[198:201], v[4:7]
	v_mfma_f32_16x16x32_bf16 v[0:3], v[156:159], v[198:201], v[0:3]
	v_mfma_f32_16x16x32_bf16 v[20:23], v[148:151], v[206:209], v[20:23]
	v_mfma_f32_16x16x32_bf16 v[16:19], v[156:159], v[206:209], v[16:19]
	v_mfma_f32_16x16x32_bf16 v[28:31], v[148:151], v[214:217], v[28:31]
	v_mfma_f32_16x16x32_bf16 v[24:27], v[156:159], v[214:217], v[24:27]
	s_barrier
	s_setprio 0
	s_add_u32 s38, s10, 0x40000
	s_addc_u32 s39, s11, 0
	s_add_i32 s45, s82, s72
	s_mov_b32 m0, s45
	ds_read_b128 v[186:189], v182 offset:49152
	ds_read_b128 v[190:193], v182 offset:50176
	ds_read_b128 v[194:197], v182 offset:51200
	ds_read_b128 v[198:201], v182 offset:52224
	ds_read_b128 v[202:205], v182 offset:53248
	ds_read_b128 v[206:209], v182 offset:54272
	ds_read_b128 v[210:213], v182 offset:55296
	ds_read_b128 v[214:217], v182 offset:56320
	global_load_lds_dwordx4 v162, s[38:39]
	s_add_i32 m0, s45, 0x2000
	s_add_u32 s10, s10, 0x44000
	global_load_lds_dwordx4 v166, s[38:39]
	s_addc_u32 s11, s11, 0
	s_add_i32 s38, s83, s72
	s_mov_b32 m0, s38
	s_nop 0
	global_load_lds_dwordx4 v162, s[10:11]
	s_add_i32 m0, s38, 0x2000
	s_nop 0
	global_load_lds_dwordx4 v166, s[10:11]
	s_mov_b32 m0, s4
	s_nop 0
	global_load_lds_dwordx4 v160, s[8:9]
	s_mov_b32 m0, s5
	s_nop 0
	global_load_lds_dwordx4 v164, s[8:9]
	s_waitcnt vmcnt(8)
	s_waitcnt lgkmcnt(0)
	s_setprio 1
	s_barrier
	v_mfma_f32_16x16x32_bf16 v[116:119], v[128:131], v[186:189], v[116:119]
	v_mfma_f32_16x16x32_bf16 v[112:115], v[136:139], v[186:189], v[112:115]
	v_mfma_f32_16x16x32_bf16 v[124:127], v[128:131], v[194:197], v[124:127]
	v_mfma_f32_16x16x32_bf16 v[120:123], v[136:139], v[194:197], v[120:123]
	v_mfma_f32_16x16x32_bf16 v[76:79], v[128:131], v[202:205], v[76:79]
	v_mfma_f32_16x16x32_bf16 v[72:75], v[136:139], v[202:205], v[72:75]
	v_mfma_f32_16x16x32_bf16 v[68:71], v[128:131], v[210:213], v[68:71]
	v_mfma_f32_16x16x32_bf16 v[64:67], v[136:139], v[210:213], v[64:67]
	v_mfma_f32_16x16x32_bf16 v[116:119], v[132:135], v[190:193], v[116:119]
	v_mfma_f32_16x16x32_bf16 v[112:115], v[140:143], v[190:193], v[112:115]
	v_mfma_f32_16x16x32_bf16 v[124:127], v[132:135], v[198:201], v[124:127]
	v_mfma_f32_16x16x32_bf16 v[120:123], v[140:143], v[198:201], v[120:123]
	v_mfma_f32_16x16x32_bf16 v[76:79], v[132:135], v[206:209], v[76:79]
	v_mfma_f32_16x16x32_bf16 v[72:75], v[140:143], v[206:209], v[72:75]
	v_mfma_f32_16x16x32_bf16 v[68:71], v[132:135], v[214:217], v[68:71]
	v_mfma_f32_16x16x32_bf16 v[64:67], v[140:143], v[214:217], v[64:67]
	v_mfma_f32_16x16x32_bf16 v[36:39], v[144:147], v[186:189], v[36:39]
	v_mfma_f32_16x16x32_bf16 v[32:35], v[152:155], v[186:189], v[32:35]
	v_mfma_f32_16x16x32_bf16 v[44:47], v[144:147], v[194:197], v[44:47]
	v_mfma_f32_16x16x32_bf16 v[40:43], v[152:155], v[194:197], v[40:43]
	v_mfma_f32_16x16x32_bf16 v[52:55], v[144:147], v[202:205], v[52:55]
	v_mfma_f32_16x16x32_bf16 v[48:51], v[152:155], v[202:205], v[48:51]
	v_mfma_f32_16x16x32_bf16 v[60:63], v[144:147], v[210:213], v[60:63]
	v_mfma_f32_16x16x32_bf16 v[56:59], v[152:155], v[210:213], v[56:59]
	v_mfma_f32_16x16x32_bf16 v[36:39], v[148:151], v[190:193], v[36:39]
	v_mfma_f32_16x16x32_bf16 v[32:35], v[156:159], v[190:193], v[32:35]
	v_mfma_f32_16x16x32_bf16 v[44:47], v[148:151], v[198:201], v[44:47]
	v_mfma_f32_16x16x32_bf16 v[40:43], v[156:159], v[198:201], v[40:43]
	v_mfma_f32_16x16x32_bf16 v[52:55], v[148:151], v[206:209], v[52:55]
	v_mfma_f32_16x16x32_bf16 v[48:51], v[156:159], v[206:209], v[48:51]
	v_mfma_f32_16x16x32_bf16 v[60:63], v[148:151], v[214:217], v[60:63]
	v_mfma_f32_16x16x32_bf16 v[56:59], v[156:159], v[214:217], v[56:59]
	s_barrier
	s_setprio 0
	s_add_i32 s44, s44, 2
	s_add_u32 s42, s42, 0x80000
	s_addc_u32 s43, s43, 0
	s_add_u32 s6, s6, 0x800000
	s_addc_u32 s7, s7, 0
	s_cmpk_gt_u32 s44, 0x55
	s_cbranch_scc0 .LBB0_1900
	s_and_b64 vcc, exec, s[26:27]
	s_cbranch_vccz .LBB0_1903
	s_barrier

.LBB0_1999:
	ds_read_b128 v[144:147], v153
	ds_read_b128 v[156:159], v153 offset:1024
	ds_read_b128 v[160:163], v153 offset:2048
	ds_read_b128 v[164:167], v153 offset:3072
	ds_read_b128 v[168:171], v154
	ds_read_b128 v[172:175], v154 offset:1024
	ds_read_b128 v[176:179], v154 offset:2048
	ds_read_b128 v[180:183], v154 offset:3072
	s_add_u32 s26, s24, 0x3fc000
	s_addc_u32 s27, s25, 0
	s_cmp_eq_u32 s55, 28
	s_cselect_b32 s30, s51, s26
	s_cselect_b32 s31, s17, s27
	s_cselect_b32 s28, s52, s53
	s_cselect_b32 s29, s19, s54
	s_add_u32 s26, s30, 0x400000
	s_addc_u32 s27, s31, 0
	s_add_i32 m0, s35, 0xc000
	ds_read_b128 v[184:187], v155
	ds_read_b128 v[188:191], v155 offset:1024
	ds_read_b128 v[192:195], v155 offset:2048
	ds_read_b128 v[196:199], v155 offset:3072
	ds_read_b128 v[200:203], v155 offset:4096
	ds_read_b128 v[204:207], v155 offset:5120
	ds_read_b128 v[208:211], v155 offset:6144
	ds_read_b128 v[212:215], v155 offset:7168
	global_load_lds_dwordx4 v136, s[24:25]
	s_add_i32 m0, s35, 0xe000
	s_nop 0
	global_load_lds_dwordx4 v138, s[24:25]
	s_waitcnt vmcnt(8)
	s_waitcnt lgkmcnt(0)
	s_setprio 1
	s_barrier
	v_mfma_f32_16x16x32_bf16 v[76:79], v[144:147], v[184:187], v[76:79]
	v_mfma_f32_16x16x32_bf16 v[72:75], v[160:163], v[184:187], v[72:75]
	v_mfma_f32_16x16x32_bf16 v[68:71], v[144:147], v[192:195], v[68:71]
	v_mfma_f32_16x16x32_bf16 v[64:67], v[160:163], v[192:195], v[64:67]
	v_mfma_f32_16x16x32_bf16 v[56:59], v[144:147], v[200:203], v[56:59]
	v_mfma_f32_16x16x32_bf16 v[52:55], v[160:163], v[200:203], v[52:55]
	v_mfma_f32_16x16x32_bf16 v[44:47], v[144:147], v[208:211], v[44:47]
	v_mfma_f32_16x16x32_bf16 v[40:43], v[160:163], v[208:211], v[40:43]
	v_mfma_f32_16x16x32_bf16 v[76:79], v[156:159], v[188:191], v[76:79]
	v_mfma_f32_16x16x32_bf16 v[72:75], v[164:167], v[188:191], v[72:75]
	v_mfma_f32_16x16x32_bf16 v[68:71], v[156:159], v[196:199], v[68:71]
	v_mfma_f32_16x16x32_bf16 v[64:67], v[164:167], v[196:199], v[64:67]
	v_mfma_f32_16x16x32_bf16 v[56:59], v[156:159], v[204:207], v[56:59]
	v_mfma_f32_16x16x32_bf16 v[52:55], v[164:167], v[204:207], v[52:55]
	v_mfma_f32_16x16x32_bf16 v[44:47], v[156:159], v[212:215], v[44:47]
	v_mfma_f32_16x16x32_bf16 v[40:43], v[164:167], v[212:215], v[40:43]
	v_mfma_f32_16x16x32_bf16 v[124:127], v[168:171], v[184:187], v[124:127]
	v_mfma_f32_16x16x32_bf16 v[120:123], v[176:179], v[184:187], v[120:123]
	v_mfma_f32_16x16x32_bf16 v[116:119], v[168:171], v[192:195], v[116:119]
	v_mfma_f32_16x16x32_bf16 v[112:115], v[176:179], v[192:195], v[112:115]
	v_mfma_f32_16x16x32_bf16 v[108:111], v[168:171], v[200:203], v[108:111]
	v_mfma_f32_16x16x32_bf16 v[104:107], v[176:179], v[200:203], v[104:107]
	v_mfma_f32_16x16x32_bf16 v[100:103], v[168:171], v[208:211], v[100:103]
	v_mfma_f32_16x16x32_bf16 v[96:99], v[176:179], v[208:211], v[96:99]
	v_mfma_f32_16x16x32_bf16 v[124:127], v[172:175], v[188:191], v[124:127]
	v_mfma_f32_16x16x32_bf16 v[120:123], v[180:183], v[188:191], v[120:123]
	v_mfma_f32_16x16x32_bf16 v[116:119], v[172:175], v[196:199], v[116:119]
	v_mfma_f32_16x16x32_bf16 v[112:115], v[180:183], v[196:199], v[112:115]
	v_mfma_f32_16x16x32_bf16 v[108:111], v[172:175], v[204:207], v[108:111]
	v_mfma_f32_16x16x32_bf16 v[104:107], v[180:183], v[204:207], v[104:107]
	v_mfma_f32_16x16x32_bf16 v[100:103], v[172:175], v[212:215], v[100:103]
	v_mfma_f32_16x16x32_bf16 v[96:99], v[180:183], v[212:215], v[96:99]
	s_barrier
	s_setprio 0
	s_add_i32 s56, s57, s34
	s_mov_b32 m0, s56
	ds_read_b128 v[184:187], v155 offset:16384
	ds_read_b128 v[188:191], v155 offset:17408
	ds_read_b128 v[192:195], v155 offset:18432
	ds_read_b128 v[196:199], v155 offset:19456
	ds_read_b128 v[200:203], v155 offset:20480
	ds_read_b128 v[204:207], v155 offset:21504
	ds_read_b128 v[208:211], v155 offset:22528
	ds_read_b128 v[212:215], v155 offset:23552
	global_load_lds_dwordx4 v132, s[28:29]
	s_add_i32 m0, s56, 0x2000
	s_add_u32 s68, s28, 0x4000
	s_addc_u32 s69, s29, 0
	s_add_i32 s56, s81, s34
	global_load_lds_dwordx4 v128, s[28:29]
	s_mov_b32 m0, s56
	s_nop 0
	global_load_lds_dwordx4 v132, s[68:69]
	s_add_i32 m0, s56, 0x2000
	s_nop 0
	global_load_lds_dwordx4 v128, s[68:69]
	s_mov_b32 m0, s35
	s_nop 0
	global_load_lds_dwordx4 v134, s[30:31]
	s_mov_b32 m0, s36
	s_nop 0
	global_load_lds_dwordx4 v130, s[30:31]
	s_waitcnt vmcnt(8)
	s_waitcnt lgkmcnt(0)
	s_setprio 1
	s_barrier
	v_mfma_f32_16x16x32_bf16 v[28:31], v[144:147], v[184:187], v[28:31]
	v_mfma_f32_16x16x32_bf16 v[24:27], v[160:163], v[184:187], v[24:27]
	v_mfma_f32_16x16x32_bf16 v[20:23], v[144:147], v[192:195], v[20:23]
	v_mfma_f32_16x16x32_bf16 v[16:19], v[160:163], v[192:195], v[16:19]
	v_mfma_f32_16x16x32_bf16 v[12:15], v[144:147], v[200:203], v[12:15]
	v_mfma_f32_16x16x32_bf16 v[8:11], v[160:163], v[200:203], v[8:11]
	v_mfma_f32_16x16x32_bf16 v[4:7], v[144:147], v[208:211], v[4:7]
	v_mfma_f32_16x16x32_bf16 v[0:3], v[160:163], v[208:211], v[0:3]
	v_mfma_f32_16x16x32_bf16 v[28:31], v[156:159], v[188:191], v[28:31]
	v_mfma_f32_16x16x32_bf16 v[24:27], v[164:167], v[188:191], v[24:27]
	v_mfma_f32_16x16x32_bf16 v[20:23], v[156:159], v[196:199], v[20:23]
	v_mfma_f32_16x16x32_bf16 v[16:19], v[164:167], v[196:199], v[16:19]
	v_mfma_f32_16x16x32_bf16 v[12:15], v[156:159], v[204:207], v[12:15]
	v_mfma_f32_16x16x32_bf16 v[8:11], v[164:167], v[204:207], v[8:11]
	v_mfma_f32_16x16x32_bf16 v[4:7], v[156:159], v[212:215], v[4:7]
	v_mfma_f32_16x16x32_bf16 v[0:3], v[164:167], v[212:215], v[0:3]
	v_mfma_f32_16x16x32_bf16 v[92:95], v[168:171], v[184:187], v[92:95]
	v_mfma_f32_16x16x32_bf16 v[88:91], v[176:179], v[184:187], v[88:91]
	v_mfma_f32_16x16x32_bf16 v[84:87], v[168:171], v[192:195], v[84:87]
	v_mfma_f32_16x16x32_bf16 v[80:83], v[176:179], v[192:195], v[80:83]
	v_mfma_f32_16x16x32_bf16 v[60:63], v[168:171], v[200:203], v[60:63]
	v_mfma_f32_16x16x32_bf16 v[48:51], v[176:179], v[200:203], v[48:51]
	v_mfma_f32_16x16x32_bf16 v[36:39], v[168:171], v[208:211], v[36:39]
	v_mfma_f32_16x16x32_bf16 v[32:35], v[176:179], v[208:211], v[32:35]
	v_mfma_f32_16x16x32_bf16 v[92:95], v[172:175], v[188:191], v[92:95]
	v_mfma_f32_16x16x32_bf16 v[88:91], v[180:183], v[188:191], v[88:91]
	v_mfma_f32_16x16x32_bf16 v[84:87], v[172:175], v[196:199], v[84:87]
	v_mfma_f32_16x16x32_bf16 v[80:83], v[180:183], v[196:199], v[80:83]
	v_mfma_f32_16x16x32_bf16 v[60:63], v[172:175], v[204:207], v[60:63]
	v_mfma_f32_16x16x32_bf16 v[48:51], v[180:183], v[204:207], v[48:51]
	v_mfma_f32_16x16x32_bf16 v[36:39], v[172:175], v[212:215], v[36:39]
	v_mfma_f32_16x16x32_bf16 v[32:35], v[180:183], v[212:215], v[32:35]
	s_barrier
	s_setprio 0
	v_add_u32_e32 v148, s82, v152
	ds_read_b128 v[144:147], v148
	ds_read_b128 v[156:159], v148 offset:1024
	ds_read_b128 v[160:163], v148 offset:2048
	ds_read_b128 v[164:167], v148 offset:3072
	v_add_u32_e32 v148, s83, v152
	ds_read_b128 v[168:171], v148
	ds_read_b128 v[172:175], v148 offset:1024
	ds_read_b128 v[176:179], v148 offset:2048
	ds_read_b128 v[180:183], v148 offset:3072
	s_add_u32 s30, s30, 0x4000
	s_addc_u32 s31, s31, 0
	s_mov_b32 m0, s37
	ds_read_b128 v[184:187], v155 offset:32768
	ds_read_b128 v[188:191], v155 offset:33792
	ds_read_b128 v[192:195], v155 offset:34816
	ds_read_b128 v[196:199], v155 offset:35840
	ds_read_b128 v[200:203], v155 offset:36864
	ds_read_b128 v[204:207], v155 offset:37888
	ds_read_b128 v[208:211], v155 offset:38912
	ds_read_b128 v[212:215], v155 offset:39936
	global_load_lds_dwordx4 v134, s[30:31]
	s_mov_b32 m0, s38
	s_nop 0
	global_load_lds_dwordx4 v130, s[30:31]
	s_waitcnt vmcnt(8)
	s_waitcnt lgkmcnt(0)
	s_setprio 1
	s_barrier
	v_mfma_f32_16x16x32_bf16 v[76:79], v[144:147], v[184:187], v[76:79]
	v_mfma_f32_16x16x32_bf16 v[72:75], v[160:163], v[184:187], v[72:75]
	v_mfma_f32_16x16x32_bf16 v[68:71], v[144:147], v[192:195], v[68:71]
	v_mfma_f32_16x16x32_bf16 v[64:67], v[160:163], v[192:195], v[64:67]
	v_mfma_f32_16x16x32_bf16 v[56:59], v[144:147], v[200:203], v[56:59]
	v_mfma_f32_16x16x32_bf16 v[52:55], v[160:163], v[200:203], v[52:55]
	v_mfma_f32_16x16x32_bf16 v[44:47], v[144:147], v[208:211], v[44:47]
	v_mfma_f32_16x16x32_bf16 v[40:43], v[160:163], v[208:211], v[40:43]
	v_mfma_f32_16x16x32_bf16 v[76:79], v[156:159], v[188:191], v[76:79]
	v_mfma_f32_16x16x32_bf16 v[72:75], v[164:167], v[188:191], v[72:75]
	v_mfma_f32_16x16x32_bf16 v[68:71], v[156:159], v[196:199], v[68:71]
	v_mfma_f32_16x16x32_bf16 v[64:67], v[164:167], v[196:199], v[64:67]
	v_mfma_f32_16x16x32_bf16 v[56:59], v[156:159], v[204:207], v[56:59]
	v_mfma_f32_16x16x32_bf16 v[52:55], v[164:167], v[204:207], v[52:55]
	v_mfma_f32_16x16x32_bf16 v[44:47], v[156:159], v[212:215], v[44:47]
	v_mfma_f32_16x16x32_bf16 v[40:43], v[164:167], v[212:215], v[40:43]
	v_mfma_f32_16x16x32_bf16 v[124:127], v[168:171], v[184:187], v[124:127]
	v_mfma_f32_16x16x32_bf16 v[120:123], v[176:179], v[184:187], v[120:123]
	v_mfma_f32_16x16x32_bf16 v[116:119], v[168:171], v[192:195], v[116:119]
	v_mfma_f32_16x16x32_bf16 v[112:115], v[176:179], v[192:195], v[112:115]
	v_mfma_f32_16x16x32_bf16 v[108:111], v[168:171], v[200:203], v[108:111]
	v_mfma_f32_16x16x32_bf16 v[104:107], v[176:179], v[200:203], v[104:107]
	v_mfma_f32_16x16x32_bf16 v[100:103], v[168:171], v[208:211], v[100:103]
	v_mfma_f32_16x16x32_bf16 v[96:99], v[176:179], v[208:211], v[96:99]
	v_mfma_f32_16x16x32_bf16 v[124:127], v[172:175], v[188:191], v[124:127]
	v_mfma_f32_16x16x32_bf16 v[120:123], v[180:183], v[188:191], v[120:123]
	v_mfma_f32_16x16x32_bf16 v[116:119], v[172:175], v[196:199], v[116:119]
	v_mfma_f32_16x16x32_bf16 v[112:115], v[180:183], v[196:199], v[112:115]
	v_mfma_f32_16x16x32_bf16 v[108:111], v[172:175], v[204:207], v[108:111]
	v_mfma_f32_16x16x32_bf16 v[104:107], v[180:183], v[204:207], v[104:107]
	v_mfma_f32_16x16x32_bf16 v[100:103], v[172:175], v[212:215], v[100:103]
	v_mfma_f32_16x16x32_bf16 v[96:99], v[180:183], v[212:215], v[96:99]
	s_barrier
	s_setprio 0
	s_add_u32 s30, s28, 0xd8000
	s_addc_u32 s31, s29, 0
	s_add_i32 s56, s82, s34
	s_mov_b32 m0, s56
	ds_read_b128 v[184:187], v155 offset:49152
	ds_read_b128 v[188:191], v155 offset:50176
	ds_read_b128 v[192:195], v155 offset:51200
	ds_read_b128 v[196:199], v155 offset:52224
	ds_read_b128 v[200:203], v155 offset:53248
	ds_read_b128 v[204:207], v155 offset:54272
	ds_read_b128 v[208:211], v155 offset:55296
	ds_read_b128 v[212:215], v155 offset:56320
	global_load_lds_dwordx4 v132, s[30:31]
	s_add_i32 m0, s56, 0x2000
	s_add_u32 s28, s28, 0xdc000
	global_load_lds_dwordx4 v128, s[30:31]
	s_addc_u32 s29, s29, 0
	s_add_i32 s30, s83, s34
	s_mov_b32 m0, s30
	s_nop 0
	global_load_lds_dwordx4 v132, s[28:29]
	s_add_i32 m0, s30, 0x2000
	s_nop 0
	global_load_lds_dwordx4 v128, s[28:29]
	s_mov_b32 m0, s42
	s_nop 0
	global_load_lds_dwordx4 v134, s[26:27]
	s_mov_b32 m0, s43
	s_nop 0
	global_load_lds_dwordx4 v130, s[26:27]
	s_waitcnt vmcnt(8)
	s_waitcnt lgkmcnt(0)
	s_setprio 1
	s_barrier
	v_mfma_f32_16x16x32_bf16 v[28:31], v[144:147], v[184:187], v[28:31]
	v_mfma_f32_16x16x32_bf16 v[24:27], v[160:163], v[184:187], v[24:27]
	v_mfma_f32_16x16x32_bf16 v[20:23], v[144:147], v[192:195], v[20:23]
	v_mfma_f32_16x16x32_bf16 v[16:19], v[160:163], v[192:195], v[16:19]
	v_mfma_f32_16x16x32_bf16 v[12:15], v[144:147], v[200:203], v[12:15]
	v_mfma_f32_16x16x32_bf16 v[8:11], v[160:163], v[200:203], v[8:11]
	v_mfma_f32_16x16x32_bf16 v[4:7], v[144:147], v[208:211], v[4:7]
	v_mfma_f32_16x16x32_bf16 v[0:3], v[160:163], v[208:211], v[0:3]
	v_mfma_f32_16x16x32_bf16 v[28:31], v[156:159], v[188:191], v[28:31]
	v_mfma_f32_16x16x32_bf16 v[24:27], v[164:167], v[188:191], v[24:27]
	v_mfma_f32_16x16x32_bf16 v[20:23], v[156:159], v[196:199], v[20:23]
	v_mfma_f32_16x16x32_bf16 v[16:19], v[164:167], v[196:199], v[16:19]
	v_mfma_f32_16x16x32_bf16 v[12:15], v[156:159], v[204:207], v[12:15]
	v_mfma_f32_16x16x32_bf16 v[8:11], v[164:167], v[204:207], v[8:11]
	v_mfma_f32_16x16x32_bf16 v[4:7], v[156:159], v[212:215], v[4:7]
	v_mfma_f32_16x16x32_bf16 v[0:3], v[164:167], v[212:215], v[0:3]
	v_mfma_f32_16x16x32_bf16 v[92:95], v[168:171], v[184:187], v[92:95]
	v_mfma_f32_16x16x32_bf16 v[88:91], v[176:179], v[184:187], v[88:91]
	v_mfma_f32_16x16x32_bf16 v[84:87], v[168:171], v[192:195], v[84:87]
	v_mfma_f32_16x16x32_bf16 v[80:83], v[176:179], v[192:195], v[80:83]
	v_mfma_f32_16x16x32_bf16 v[60:63], v[168:171], v[200:203], v[60:63]
	v_mfma_f32_16x16x32_bf16 v[48:51], v[176:179], v[200:203], v[48:51]
	v_mfma_f32_16x16x32_bf16 v[36:39], v[168:171], v[208:211], v[36:39]
	v_mfma_f32_16x16x32_bf16 v[32:35], v[176:179], v[208:211], v[32:35]
	v_mfma_f32_16x16x32_bf16 v[92:95], v[172:175], v[188:191], v[92:95]
	v_mfma_f32_16x16x32_bf16 v[88:91], v[180:183], v[188:191], v[88:91]
	v_mfma_f32_16x16x32_bf16 v[84:87], v[172:175], v[196:199], v[84:87]
	v_mfma_f32_16x16x32_bf16 v[80:83], v[180:183], v[196:199], v[80:83]
	v_mfma_f32_16x16x32_bf16 v[60:63], v[172:175], v[204:207], v[60:63]
	v_mfma_f32_16x16x32_bf16 v[48:51], v[180:183], v[204:207], v[48:51]
	v_mfma_f32_16x16x32_bf16 v[36:39], v[172:175], v[212:215], v[36:39]
	v_mfma_f32_16x16x32_bf16 v[32:35], v[180:183], v[212:215], v[32:35]
	s_barrier
	s_setprio 0
	s_add_i32 s55, s55, 2
	s_add_u32 s53, s53, 0x1b0000
	s_addc_u32 s54, s54, 0
	s_add_u32 s24, s24, 0x800000
	s_addc_u32 s25, s25, 0
	s_cmp_gt_u32 s55, 29
	s_cbranch_scc0 .LBB0_1999
	s_and_b64 vcc, exec, s[12:13]
	s_cbranch_vccz .LBB0_2002
	s_barrier

.LBB0_2013:
	ds_read_b128 v[148:151], v142
	ds_read_b128 v[152:155], v142 offset:1024
	ds_read_b128 v[156:159], v142 offset:2048
	ds_read_b128 v[160:163], v142 offset:3072
	ds_read_b128 v[164:167], v143
	ds_read_b128 v[168:171], v143 offset:1024
	ds_read_b128 v[172:175], v143 offset:2048
	ds_read_b128 v[176:179], v143 offset:3072
	s_add_u32 s16, s12, s14
	s_addc_u32 s17, s13, s15
	s_add_u32 s16, s16, 0x21c00100
	s_addc_u32 s17, s17, 0
	s_add_u32 s44, s30, s14
	s_addc_u32 s45, s31, s15
	s_cmpk_eq_i32 s14, 0x300
	s_cselect_b32 s19, s9, s17
	s_cselect_b32 s18, s8, s16
	s_cselect_b32 s17, s7, s45
	s_cselect_b32 s16, s6, s44
	s_mov_b32 m0, s34
	v_lshl_add_u64 v[212:213], v[136:137], 0, s[14:15]
	ds_read_b128 v[180:183], v144
	ds_read_b128 v[184:187], v144 offset:1024
	ds_read_b128 v[188:191], v144 offset:2048
	ds_read_b128 v[192:195], v144 offset:3072
	ds_read_b128 v[196:199], v144 offset:4096
	ds_read_b128 v[200:203], v144 offset:5120
	ds_read_b128 v[204:207], v144 offset:6144
	ds_read_b128 v[208:211], v144 offset:7168
	global_load_lds_dwordx4 v[212:213], off
	v_lshl_add_u64 v[212:213], v[138:139], 0, s[14:15]
	s_mov_b32 m0, s35
	s_nop 0
	global_load_lds_dwordx4 v[212:213], off
	s_waitcnt vmcnt(8)
	s_waitcnt lgkmcnt(0)
	s_setprio 1
	s_barrier
	v_mfma_f32_16x16x32_bf16 v[124:127], v[148:151], v[180:183], v[124:127]
	v_mfma_f32_16x16x32_bf16 v[120:123], v[156:159], v[180:183], v[120:123]
	v_mfma_f32_16x16x32_bf16 v[112:115], v[148:151], v[188:191], v[112:115]
	v_mfma_f32_16x16x32_bf16 v[104:107], v[156:159], v[188:191], v[104:107]
	v_mfma_f32_16x16x32_bf16 v[96:99], v[148:151], v[196:199], v[96:99]
	v_mfma_f32_16x16x32_bf16 v[88:91], v[156:159], v[196:199], v[88:91]
	v_mfma_f32_16x16x32_bf16 v[80:83], v[148:151], v[204:207], v[80:83]
	v_mfma_f32_16x16x32_bf16 v[72:75], v[156:159], v[204:207], v[72:75]
	v_mfma_f32_16x16x32_bf16 v[124:127], v[152:155], v[184:187], v[124:127]
	v_mfma_f32_16x16x32_bf16 v[120:123], v[160:163], v[184:187], v[120:123]
	v_mfma_f32_16x16x32_bf16 v[112:115], v[152:155], v[192:195], v[112:115]
	v_mfma_f32_16x16x32_bf16 v[104:107], v[160:163], v[192:195], v[104:107]
	v_mfma_f32_16x16x32_bf16 v[96:99], v[152:155], v[200:203], v[96:99]
	v_mfma_f32_16x16x32_bf16 v[88:91], v[160:163], v[200:203], v[88:91]
	v_mfma_f32_16x16x32_bf16 v[80:83], v[152:155], v[208:211], v[80:83]
	v_mfma_f32_16x16x32_bf16 v[72:75], v[160:163], v[208:211], v[72:75]
	v_mfma_f32_16x16x32_bf16 v[116:119], v[164:167], v[180:183], v[116:119]
	v_mfma_f32_16x16x32_bf16 v[108:111], v[172:175], v[180:183], v[108:111]
	v_mfma_f32_16x16x32_bf16 v[100:103], v[164:167], v[188:191], v[100:103]
	v_mfma_f32_16x16x32_bf16 v[92:95], v[172:175], v[188:191], v[92:95]
	v_mfma_f32_16x16x32_bf16 v[84:87], v[164:167], v[196:199], v[84:87]
	v_mfma_f32_16x16x32_bf16 v[76:79], v[172:175], v[196:199], v[76:79]
	v_mfma_f32_16x16x32_bf16 v[68:71], v[164:167], v[204:207], v[68:71]
	v_mfma_f32_16x16x32_bf16 v[64:67], v[172:175], v[204:207], v[64:67]
	v_mfma_f32_16x16x32_bf16 v[116:119], v[168:171], v[184:187], v[116:119]
	v_mfma_f32_16x16x32_bf16 v[108:111], v[176:179], v[184:187], v[108:111]
	v_mfma_f32_16x16x32_bf16 v[100:103], v[168:171], v[192:195], v[100:103]
	v_mfma_f32_16x16x32_bf16 v[92:95], v[176:179], v[192:195], v[92:95]
	v_mfma_f32_16x16x32_bf16 v[84:87], v[168:171], v[200:203], v[84:87]
	v_mfma_f32_16x16x32_bf16 v[76:79], v[176:179], v[200:203], v[76:79]
	v_mfma_f32_16x16x32_bf16 v[68:71], v[168:171], v[208:211], v[68:71]
	v_mfma_f32_16x16x32_bf16 v[64:67], v[176:179], v[208:211], v[64:67]
	s_barrier
	s_setprio 0
	s_mov_b32 m0, s36
	v_lshl_add_u64 v[212:213], s[16:17], 0, v[132:133]
	s_add_u32 s44, s16, 0x80000
	ds_read_b128 v[180:183], v144 offset:16384
	ds_read_b128 v[184:187], v144 offset:17408
	ds_read_b128 v[188:191], v144 offset:18432
	ds_read_b128 v[192:195], v144 offset:19456
	ds_read_b128 v[196:199], v144 offset:20480
	ds_read_b128 v[200:203], v144 offset:21504
	ds_read_b128 v[204:207], v144 offset:22528
	ds_read_b128 v[208:211], v144 offset:23552
	global_load_lds_dwordx4 v[212:213], off
	v_lshl_add_u64 v[214:215], s[16:17], 0, v[128:129]
	s_mov_b32 m0, s37
	s_addc_u32 s45, s17, 0
	global_load_lds_dwordx4 v[214:215], off
	s_mov_b32 m0, s38
	v_lshl_add_u64 v[218:219], s[18:19], 0, v[130:131]
	global_load_lds_dwordx4 v132, s[44:45]
	s_mov_b32 m0, s39
	s_nop 0
	global_load_lds_dwordx4 v128, s[44:45]
	v_lshl_add_u64 v[216:217], s[18:19], 0, v[134:135]
	s_mov_b32 m0, s23
	s_nop 0
	global_load_lds_dwordx4 v[216:217], off
	s_mov_b32 m0, s25
	s_nop 0
	global_load_lds_dwordx4 v[218:219], off
	s_waitcnt vmcnt(8)
	s_waitcnt lgkmcnt(0)
	s_setprio 1
	s_barrier
	v_mfma_f32_16x16x32_bf16 v[60:63], v[148:151], v[180:183], v[60:63]
	v_mfma_f32_16x16x32_bf16 v[56:59], v[156:159], v[180:183], v[56:59]
	v_mfma_f32_16x16x32_bf16 v[48:51], v[148:151], v[188:191], v[48:51]
	v_mfma_f32_16x16x32_bf16 v[40:43], v[156:159], v[188:191], v[40:43]
	v_mfma_f32_16x16x32_bf16 v[32:35], v[148:151], v[196:199], v[32:35]
	v_mfma_f32_16x16x32_bf16 v[24:27], v[156:159], v[196:199], v[24:27]
	v_mfma_f32_16x16x32_bf16 v[16:19], v[148:151], v[204:207], v[16:19]
	v_mfma_f32_16x16x32_bf16 v[8:11], v[156:159], v[204:207], v[8:11]
	v_mfma_f32_16x16x32_bf16 v[60:63], v[152:155], v[184:187], v[60:63]
	v_mfma_f32_16x16x32_bf16 v[56:59], v[160:163], v[184:187], v[56:59]
	v_mfma_f32_16x16x32_bf16 v[48:51], v[152:155], v[192:195], v[48:51]
	v_mfma_f32_16x16x32_bf16 v[40:43], v[160:163], v[192:195], v[40:43]
	v_mfma_f32_16x16x32_bf16 v[32:35], v[152:155], v[200:203], v[32:35]
	v_mfma_f32_16x16x32_bf16 v[24:27], v[160:163], v[200:203], v[24:27]
	v_mfma_f32_16x16x32_bf16 v[16:19], v[152:155], v[208:211], v[16:19]
	v_mfma_f32_16x16x32_bf16 v[8:11], v[160:163], v[208:211], v[8:11]
	v_mfma_f32_16x16x32_bf16 v[52:55], v[164:167], v[180:183], v[52:55]
	v_mfma_f32_16x16x32_bf16 v[44:47], v[172:175], v[180:183], v[44:47]
	v_mfma_f32_16x16x32_bf16 v[36:39], v[164:167], v[188:191], v[36:39]
	v_mfma_f32_16x16x32_bf16 v[28:31], v[172:175], v[188:191], v[28:31]
	v_mfma_f32_16x16x32_bf16 v[20:23], v[164:167], v[196:199], v[20:23]
	v_mfma_f32_16x16x32_bf16 v[12:15], v[172:175], v[196:199], v[12:15]
	v_mfma_f32_16x16x32_bf16 v[4:7], v[164:167], v[204:207], v[4:7]
	v_mfma_f32_16x16x32_bf16 v[0:3], v[172:175], v[204:207], v[0:3]
	v_mfma_f32_16x16x32_bf16 v[52:55], v[168:171], v[184:187], v[52:55]
	v_mfma_f32_16x16x32_bf16 v[44:47], v[176:179], v[184:187], v[44:47]
	v_mfma_f32_16x16x32_bf16 v[36:39], v[168:171], v[192:195], v[36:39]
	v_mfma_f32_16x16x32_bf16 v[28:31], v[176:179], v[192:195], v[28:31]
	v_mfma_f32_16x16x32_bf16 v[20:23], v[168:171], v[200:203], v[20:23]
	v_mfma_f32_16x16x32_bf16 v[12:15], v[176:179], v[200:203], v[12:15]
	v_mfma_f32_16x16x32_bf16 v[4:7], v[168:171], v[208:211], v[4:7]
	v_mfma_f32_16x16x32_bf16 v[0:3], v[176:179], v[208:211], v[0:3]
	s_barrier
	s_setprio 0
	ds_read_b128 v[148:151], v145
	ds_read_b128 v[152:155], v145 offset:1024
	ds_read_b128 v[156:159], v145 offset:2048
	ds_read_b128 v[160:163], v145 offset:3072
	ds_read_b128 v[164:167], v146
	ds_read_b128 v[168:171], v146 offset:1024
	ds_read_b128 v[172:175], v146 offset:2048
	ds_read_b128 v[176:179], v146 offset:3072
	s_add_u32 s18, s18, 0x100000
	s_addc_u32 s19, s19, 0
	s_mov_b32 m0, s26
	ds_read_b128 v[180:183], v144 offset:32768
	ds_read_b128 v[184:187], v144 offset:33792
	ds_read_b128 v[188:191], v144 offset:34816
	ds_read_b128 v[192:195], v144 offset:35840
	ds_read_b128 v[196:199], v144 offset:36864
	ds_read_b128 v[200:203], v144 offset:37888
	ds_read_b128 v[204:207], v144 offset:38912
	ds_read_b128 v[208:211], v144 offset:39936
	global_load_lds_dwordx4 v134, s[18:19]
	s_mov_b32 m0, s27
	s_nop 0
	global_load_lds_dwordx4 v130, s[18:19]
	s_waitcnt vmcnt(8)
	s_waitcnt lgkmcnt(0)
	s_setprio 1
	s_barrier
	v_mfma_f32_16x16x32_bf16 v[124:127], v[148:151], v[180:183], v[124:127]
	v_mfma_f32_16x16x32_bf16 v[120:123], v[156:159], v[180:183], v[120:123]
	v_mfma_f32_16x16x32_bf16 v[112:115], v[148:151], v[188:191], v[112:115]
	v_mfma_f32_16x16x32_bf16 v[104:107], v[156:159], v[188:191], v[104:107]
	v_mfma_f32_16x16x32_bf16 v[96:99], v[148:151], v[196:199], v[96:99]
	v_mfma_f32_16x16x32_bf16 v[88:91], v[156:159], v[196:199], v[88:91]
	v_mfma_f32_16x16x32_bf16 v[80:83], v[148:151], v[204:207], v[80:83]
	v_mfma_f32_16x16x32_bf16 v[72:75], v[156:159], v[204:207], v[72:75]
	v_mfma_f32_16x16x32_bf16 v[124:127], v[152:155], v[184:187], v[124:127]
	v_mfma_f32_16x16x32_bf16 v[120:123], v[160:163], v[184:187], v[120:123]
	v_mfma_f32_16x16x32_bf16 v[112:115], v[152:155], v[192:195], v[112:115]
	v_mfma_f32_16x16x32_bf16 v[104:107], v[160:163], v[192:195], v[104:107]
	v_mfma_f32_16x16x32_bf16 v[96:99], v[152:155], v[200:203], v[96:99]
	v_mfma_f32_16x16x32_bf16 v[88:91], v[160:163], v[200:203], v[88:91]
	v_mfma_f32_16x16x32_bf16 v[80:83], v[152:155], v[208:211], v[80:83]
	v_mfma_f32_16x16x32_bf16 v[72:75], v[160:163], v[208:211], v[72:75]
	v_mfma_f32_16x16x32_bf16 v[116:119], v[164:167], v[180:183], v[116:119]
	v_mfma_f32_16x16x32_bf16 v[108:111], v[172:175], v[180:183], v[108:111]
	v_mfma_f32_16x16x32_bf16 v[100:103], v[164:167], v[188:191], v[100:103]
	v_mfma_f32_16x16x32_bf16 v[92:95], v[172:175], v[188:191], v[92:95]
	v_mfma_f32_16x16x32_bf16 v[84:87], v[164:167], v[196:199], v[84:87]
	v_mfma_f32_16x16x32_bf16 v[76:79], v[172:175], v[196:199], v[76:79]
	v_mfma_f32_16x16x32_bf16 v[68:71], v[164:167], v[204:207], v[68:71]
	v_mfma_f32_16x16x32_bf16 v[64:67], v[172:175], v[204:207], v[64:67]
	v_mfma_f32_16x16x32_bf16 v[116:119], v[168:171], v[184:187], v[116:119]
	v_mfma_f32_16x16x32_bf16 v[108:111], v[176:179], v[184:187], v[108:111]
	v_mfma_f32_16x16x32_bf16 v[100:103], v[168:171], v[192:195], v[100:103]
	v_mfma_f32_16x16x32_bf16 v[92:95], v[176:179], v[192:195], v[92:95]
	v_mfma_f32_16x16x32_bf16 v[84:87], v[168:171], v[200:203], v[84:87]
	v_mfma_f32_16x16x32_bf16 v[76:79], v[176:179], v[200:203], v[76:79]
	v_mfma_f32_16x16x32_bf16 v[68:71], v[168:171], v[208:211], v[68:71]
	v_mfma_f32_16x16x32_bf16 v[64:67], v[176:179], v[208:211], v[64:67]
	s_barrier
	s_setprio 0
	s_mov_b32 m0, s40
	v_lshl_add_u64 v[212:213], v[212:213], 0, s[10:11]
	s_add_u32 s16, s16, 0x80080
	ds_read_b128 v[180:183], v144 offset:49152
	ds_read_b128 v[184:187], v144 offset:50176
	ds_read_b128 v[188:191], v144 offset:51200
	ds_read_b128 v[192:195], v144 offset:52224
	ds_read_b128 v[196:199], v144 offset:53248
	ds_read_b128 v[200:203], v144 offset:54272
	ds_read_b128 v[204:207], v144 offset:55296
	ds_read_b128 v[208:211], v144 offset:56320
	global_load_lds_dwordx4 v[212:213], off
	v_lshl_add_u64 v[212:213], v[214:215], 0, s[10:11]
	s_mov_b32 m0, s41
	s_addc_u32 s17, s17, 0
	global_load_lds_dwordx4 v[212:213], off
	s_mov_b32 m0, s42
	s_nop 0
	global_load_lds_dwordx4 v132, s[16:17]
	s_mov_b32 m0, s43
	s_nop 0
	global_load_lds_dwordx4 v128, s[16:17]
	v_lshl_add_u64 v[212:213], v[216:217], 0, s[10:11]
	s_mov_b32 m0, s28
	s_nop 0
	global_load_lds_dwordx4 v[212:213], off
	v_lshl_add_u64 v[212:213], v[218:219], 0, s[10:11]
	s_mov_b32 m0, s29
	s_nop 0
	global_load_lds_dwordx4 v[212:213], off
	s_waitcnt vmcnt(8)
	s_waitcnt lgkmcnt(0)
	s_setprio 1
	s_barrier
	v_mfma_f32_16x16x32_bf16 v[60:63], v[148:151], v[180:183], v[60:63]
	v_mfma_f32_16x16x32_bf16 v[56:59], v[156:159], v[180:183], v[56:59]
	v_mfma_f32_16x16x32_bf16 v[48:51], v[148:151], v[188:191], v[48:51]
	v_mfma_f32_16x16x32_bf16 v[40:43], v[156:159], v[188:191], v[40:43]
	v_mfma_f32_16x16x32_bf16 v[32:35], v[148:151], v[196:199], v[32:35]
	v_mfma_f32_16x16x32_bf16 v[24:27], v[156:159], v[196:199], v[24:27]
	v_mfma_f32_16x16x32_bf16 v[16:19], v[148:151], v[204:207], v[16:19]
	v_mfma_f32_16x16x32_bf16 v[8:11], v[156:159], v[204:207], v[8:11]
	v_mfma_f32_16x16x32_bf16 v[60:63], v[152:155], v[184:187], v[60:63]
	v_mfma_f32_16x16x32_bf16 v[56:59], v[160:163], v[184:187], v[56:59]
	v_mfma_f32_16x16x32_bf16 v[48:51], v[152:155], v[192:195], v[48:51]
	v_mfma_f32_16x16x32_bf16 v[40:43], v[160:163], v[192:195], v[40:43]
	v_mfma_f32_16x16x32_bf16 v[32:35], v[152:155], v[200:203], v[32:35]
	v_mfma_f32_16x16x32_bf16 v[24:27], v[160:163], v[200:203], v[24:27]
	v_mfma_f32_16x16x32_bf16 v[16:19], v[152:155], v[208:211], v[16:19]
	v_mfma_f32_16x16x32_bf16 v[8:11], v[160:163], v[208:211], v[8:11]
	v_mfma_f32_16x16x32_bf16 v[52:55], v[164:167], v[180:183], v[52:55]
	v_mfma_f32_16x16x32_bf16 v[44:47], v[172:175], v[180:183], v[44:47]
	v_mfma_f32_16x16x32_bf16 v[36:39], v[164:167], v[188:191], v[36:39]
	v_mfma_f32_16x16x32_bf16 v[28:31], v[172:175], v[188:191], v[28:31]
	v_mfma_f32_16x16x32_bf16 v[20:23], v[164:167], v[196:199], v[20:23]
	v_mfma_f32_16x16x32_bf16 v[12:15], v[172:175], v[196:199], v[12:15]
	v_mfma_f32_16x16x32_bf16 v[4:7], v[164:167], v[204:207], v[4:7]
	v_mfma_f32_16x16x32_bf16 v[0:3], v[172:175], v[204:207], v[0:3]
	v_mfma_f32_16x16x32_bf16 v[52:55], v[168:171], v[184:187], v[52:55]
	v_mfma_f32_16x16x32_bf16 v[44:47], v[176:179], v[184:187], v[44:47]
	v_mfma_f32_16x16x32_bf16 v[36:39], v[168:171], v[192:195], v[36:39]
	v_mfma_f32_16x16x32_bf16 v[28:31], v[176:179], v[192:195], v[28:31]
	v_mfma_f32_16x16x32_bf16 v[20:23], v[168:171], v[200:203], v[20:23]
	v_mfma_f32_16x16x32_bf16 v[12:15], v[176:179], v[200:203], v[12:15]
	v_mfma_f32_16x16x32_bf16 v[4:7], v[168:171], v[208:211], v[4:7]
	v_mfma_f32_16x16x32_bf16 v[0:3], v[176:179], v[208:211], v[0:3]
	s_barrier
	s_setprio 0
	s_add_i32 s33, s33, 2
	s_add_u32 s14, s14, 0x100
	s_addc_u32 s15, s15, 0
	s_cmp_gt_u32 s33, 5
	s_cbranch_scc0 .LBB0_2013
	s_cmp_lt_u32 s5, 4
	s_cbranch_scc0 .LBB0_2016
	s_barrier

.LBB0_2021:
	ds_read_b128 v[148:151], v142
	ds_read_b128 v[152:155], v142 offset:1024
	ds_read_b128 v[156:159], v142 offset:2048
	ds_read_b128 v[160:163], v142 offset:3072
	ds_read_b128 v[164:167], v143
	ds_read_b128 v[168:171], v143 offset:1024
	ds_read_b128 v[172:175], v143 offset:2048
	ds_read_b128 v[176:179], v143 offset:3072
	s_add_u32 s16, s12, s14
	s_addc_u32 s17, s13, s15
	s_add_u32 s16, s16, 0x18800100
	s_addc_u32 s17, s17, 0
	s_add_u32 s42, s28, s14
	s_addc_u32 s43, s29, s15
	s_cmpk_eq_i32 s14, 0x300
	s_cselect_b32 s19, s9, s17
	s_cselect_b32 s18, s8, s16
	s_cselect_b32 s17, s7, s43
	s_cselect_b32 s16, s6, s42
	s_mov_b32 m0, s31
	v_lshl_add_u64 v[212:213], v[136:137], 0, s[14:15]
	ds_read_b128 v[180:183], v144
	ds_read_b128 v[184:187], v144 offset:1024
	ds_read_b128 v[188:191], v144 offset:2048
	ds_read_b128 v[192:195], v144 offset:3072
	ds_read_b128 v[196:199], v144 offset:4096
	ds_read_b128 v[200:203], v144 offset:5120
	ds_read_b128 v[204:207], v144 offset:6144
	ds_read_b128 v[208:211], v144 offset:7168
	global_load_lds_dwordx4 v[212:213], off
	v_lshl_add_u64 v[212:213], v[138:139], 0, s[14:15]
	s_mov_b32 m0, s33
	s_nop 0
	global_load_lds_dwordx4 v[212:213], off
	s_waitcnt vmcnt(8)
	s_waitcnt lgkmcnt(0)
	s_setprio 1
	s_barrier
	v_mfma_f32_16x16x32_bf16 v[124:127], v[148:151], v[180:183], v[124:127]
	v_mfma_f32_16x16x32_bf16 v[120:123], v[156:159], v[180:183], v[120:123]
	v_mfma_f32_16x16x32_bf16 v[116:119], v[148:151], v[188:191], v[116:119]
	v_mfma_f32_16x16x32_bf16 v[108:111], v[156:159], v[188:191], v[108:111]
	v_mfma_f32_16x16x32_bf16 v[100:103], v[148:151], v[196:199], v[100:103]
	v_mfma_f32_16x16x32_bf16 v[92:95], v[156:159], v[196:199], v[92:95]
	v_mfma_f32_16x16x32_bf16 v[84:87], v[148:151], v[204:207], v[84:87]
	v_mfma_f32_16x16x32_bf16 v[76:79], v[156:159], v[204:207], v[76:79]
	v_mfma_f32_16x16x32_bf16 v[124:127], v[152:155], v[184:187], v[124:127]
	v_mfma_f32_16x16x32_bf16 v[120:123], v[160:163], v[184:187], v[120:123]
	v_mfma_f32_16x16x32_bf16 v[116:119], v[152:155], v[192:195], v[116:119]
	v_mfma_f32_16x16x32_bf16 v[108:111], v[160:163], v[192:195], v[108:111]
	v_mfma_f32_16x16x32_bf16 v[100:103], v[152:155], v[200:203], v[100:103]
	v_mfma_f32_16x16x32_bf16 v[92:95], v[160:163], v[200:203], v[92:95]
	v_mfma_f32_16x16x32_bf16 v[84:87], v[152:155], v[208:211], v[84:87]
	v_mfma_f32_16x16x32_bf16 v[76:79], v[160:163], v[208:211], v[76:79]
	v_mfma_f32_16x16x32_bf16 v[112:115], v[164:167], v[180:183], v[112:115]
	v_mfma_f32_16x16x32_bf16 v[104:107], v[172:175], v[180:183], v[104:107]
	v_mfma_f32_16x16x32_bf16 v[96:99], v[164:167], v[188:191], v[96:99]
	v_mfma_f32_16x16x32_bf16 v[88:91], v[172:175], v[188:191], v[88:91]
	v_mfma_f32_16x16x32_bf16 v[80:83], v[164:167], v[196:199], v[80:83]
	v_mfma_f32_16x16x32_bf16 v[72:75], v[172:175], v[196:199], v[72:75]
	v_mfma_f32_16x16x32_bf16 v[68:71], v[164:167], v[204:207], v[68:71]
	v_mfma_f32_16x16x32_bf16 v[64:67], v[172:175], v[204:207], v[64:67]
	v_mfma_f32_16x16x32_bf16 v[112:115], v[168:171], v[184:187], v[112:115]
	v_mfma_f32_16x16x32_bf16 v[104:107], v[176:179], v[184:187], v[104:107]
	v_mfma_f32_16x16x32_bf16 v[96:99], v[168:171], v[192:195], v[96:99]
	v_mfma_f32_16x16x32_bf16 v[88:91], v[176:179], v[192:195], v[88:91]
	v_mfma_f32_16x16x32_bf16 v[80:83], v[168:171], v[200:203], v[80:83]
	v_mfma_f32_16x16x32_bf16 v[72:75], v[176:179], v[200:203], v[72:75]
	v_mfma_f32_16x16x32_bf16 v[68:71], v[168:171], v[208:211], v[68:71]
	v_mfma_f32_16x16x32_bf16 v[64:67], v[176:179], v[208:211], v[64:67]
	s_barrier
	s_setprio 0
	s_mov_b32 m0, s34
	v_lshl_add_u64 v[212:213], s[16:17], 0, v[132:133]
	s_add_u32 s42, s16, 0x100000
	ds_read_b128 v[180:183], v144 offset:16384
	ds_read_b128 v[184:187], v144 offset:17408
	ds_read_b128 v[188:191], v144 offset:18432
	ds_read_b128 v[192:195], v144 offset:19456
	ds_read_b128 v[196:199], v144 offset:20480
	ds_read_b128 v[200:203], v144 offset:21504
	ds_read_b128 v[204:207], v144 offset:22528
	ds_read_b128 v[208:211], v144 offset:23552
	global_load_lds_dwordx4 v[212:213], off
	v_lshl_add_u64 v[214:215], s[16:17], 0, v[128:129]
	s_mov_b32 m0, s35
	s_addc_u32 s43, s17, 0
	global_load_lds_dwordx4 v[214:215], off
	s_mov_b32 m0, s36
	v_lshl_add_u64 v[218:219], s[18:19], 0, v[130:131]
	global_load_lds_dwordx4 v132, s[42:43]
	s_mov_b32 m0, s37
	s_nop 0
	global_load_lds_dwordx4 v128, s[42:43]
	v_lshl_add_u64 v[216:217], s[18:19], 0, v[134:135]
	s_mov_b32 m0, s2
	s_nop 0
	global_load_lds_dwordx4 v[216:217], off
	s_mov_b32 m0, s23
	s_nop 0
	global_load_lds_dwordx4 v[218:219], off
	s_waitcnt vmcnt(8)
	s_waitcnt lgkmcnt(0)
	s_setprio 1
	s_barrier
	v_mfma_f32_16x16x32_bf16 v[60:63], v[148:151], v[180:183], v[60:63]
	v_mfma_f32_16x16x32_bf16 v[56:59], v[156:159], v[180:183], v[56:59]
	v_mfma_f32_16x16x32_bf16 v[52:55], v[148:151], v[188:191], v[52:55]
	v_mfma_f32_16x16x32_bf16 v[44:47], v[156:159], v[188:191], v[44:47]
	v_mfma_f32_16x16x32_bf16 v[36:39], v[148:151], v[196:199], v[36:39]
	v_mfma_f32_16x16x32_bf16 v[28:31], v[156:159], v[196:199], v[28:31]
	v_mfma_f32_16x16x32_bf16 v[20:23], v[148:151], v[204:207], v[20:23]
	v_mfma_f32_16x16x32_bf16 v[12:15], v[156:159], v[204:207], v[12:15]
	v_mfma_f32_16x16x32_bf16 v[60:63], v[152:155], v[184:187], v[60:63]
	v_mfma_f32_16x16x32_bf16 v[56:59], v[160:163], v[184:187], v[56:59]
	v_mfma_f32_16x16x32_bf16 v[52:55], v[152:155], v[192:195], v[52:55]
	v_mfma_f32_16x16x32_bf16 v[44:47], v[160:163], v[192:195], v[44:47]
	v_mfma_f32_16x16x32_bf16 v[36:39], v[152:155], v[200:203], v[36:39]
	v_mfma_f32_16x16x32_bf16 v[28:31], v[160:163], v[200:203], v[28:31]
	v_mfma_f32_16x16x32_bf16 v[20:23], v[152:155], v[208:211], v[20:23]
	v_mfma_f32_16x16x32_bf16 v[12:15], v[160:163], v[208:211], v[12:15]
	v_mfma_f32_16x16x32_bf16 v[48:51], v[164:167], v[180:183], v[48:51]
	v_mfma_f32_16x16x32_bf16 v[40:43], v[172:175], v[180:183], v[40:43]
	v_mfma_f32_16x16x32_bf16 v[32:35], v[164:167], v[188:191], v[32:35]
	v_mfma_f32_16x16x32_bf16 v[24:27], v[172:175], v[188:191], v[24:27]
	v_mfma_f32_16x16x32_bf16 v[16:19], v[164:167], v[196:199], v[16:19]
	v_mfma_f32_16x16x32_bf16 v[8:11], v[172:175], v[196:199], v[8:11]
	v_mfma_f32_16x16x32_bf16 v[4:7], v[164:167], v[204:207], v[4:7]
	v_mfma_f32_16x16x32_bf16 v[0:3], v[172:175], v[204:207], v[0:3]
	v_mfma_f32_16x16x32_bf16 v[48:51], v[168:171], v[184:187], v[48:51]
	v_mfma_f32_16x16x32_bf16 v[40:43], v[176:179], v[184:187], v[40:43]
	v_mfma_f32_16x16x32_bf16 v[32:35], v[168:171], v[192:195], v[32:35]
	v_mfma_f32_16x16x32_bf16 v[24:27], v[176:179], v[192:195], v[24:27]
	v_mfma_f32_16x16x32_bf16 v[16:19], v[168:171], v[200:203], v[16:19]
	v_mfma_f32_16x16x32_bf16 v[8:11], v[176:179], v[200:203], v[8:11]
	v_mfma_f32_16x16x32_bf16 v[4:7], v[168:171], v[208:211], v[4:7]
	v_mfma_f32_16x16x32_bf16 v[0:3], v[176:179], v[208:211], v[0:3]
	s_barrier
	s_setprio 0
	ds_read_b128 v[148:151], v145
	ds_read_b128 v[152:155], v145 offset:1024
	ds_read_b128 v[156:159], v145 offset:2048
	ds_read_b128 v[160:163], v145 offset:3072
	ds_read_b128 v[164:167], v146
	ds_read_b128 v[168:171], v146 offset:1024
	ds_read_b128 v[172:175], v146 offset:2048
	ds_read_b128 v[176:179], v146 offset:3072
	s_add_u32 s18, s18, 0x80000
	s_addc_u32 s19, s19, 0
	s_mov_b32 m0, s24
	ds_read_b128 v[180:183], v144 offset:32768
	ds_read_b128 v[184:187], v144 offset:33792
	ds_read_b128 v[188:191], v144 offset:34816
	ds_read_b128 v[192:195], v144 offset:35840
	ds_read_b128 v[196:199], v144 offset:36864
	ds_read_b128 v[200:203], v144 offset:37888
	ds_read_b128 v[204:207], v144 offset:38912
	ds_read_b128 v[208:211], v144 offset:39936
	global_load_lds_dwordx4 v134, s[18:19]
	v_lshl_add_u64 v[220:221], s[18:19], 0, v[130:131]
	s_mov_b32 m0, s25
	s_nop 0
	global_load_lds_dwordx4 v[220:221], off
	s_waitcnt vmcnt(8)
	s_waitcnt lgkmcnt(0)
	s_setprio 1
	s_barrier
	v_mfma_f32_16x16x32_bf16 v[124:127], v[148:151], v[180:183], v[124:127]
	v_mfma_f32_16x16x32_bf16 v[120:123], v[156:159], v[180:183], v[120:123]
	v_mfma_f32_16x16x32_bf16 v[116:119], v[148:151], v[188:191], v[116:119]
	v_mfma_f32_16x16x32_bf16 v[108:111], v[156:159], v[188:191], v[108:111]
	v_mfma_f32_16x16x32_bf16 v[100:103], v[148:151], v[196:199], v[100:103]
	v_mfma_f32_16x16x32_bf16 v[92:95], v[156:159], v[196:199], v[92:95]
	v_mfma_f32_16x16x32_bf16 v[84:87], v[148:151], v[204:207], v[84:87]
	v_mfma_f32_16x16x32_bf16 v[76:79], v[156:159], v[204:207], v[76:79]
	v_mfma_f32_16x16x32_bf16 v[124:127], v[152:155], v[184:187], v[124:127]
	v_mfma_f32_16x16x32_bf16 v[120:123], v[160:163], v[184:187], v[120:123]
	v_mfma_f32_16x16x32_bf16 v[116:119], v[152:155], v[192:195], v[116:119]
	v_mfma_f32_16x16x32_bf16 v[108:111], v[160:163], v[192:195], v[108:111]
	v_mfma_f32_16x16x32_bf16 v[100:103], v[152:155], v[200:203], v[100:103]
	v_mfma_f32_16x16x32_bf16 v[92:95], v[160:163], v[200:203], v[92:95]
	v_mfma_f32_16x16x32_bf16 v[84:87], v[152:155], v[208:211], v[84:87]
	v_mfma_f32_16x16x32_bf16 v[76:79], v[160:163], v[208:211], v[76:79]
	v_mfma_f32_16x16x32_bf16 v[112:115], v[164:167], v[180:183], v[112:115]
	v_mfma_f32_16x16x32_bf16 v[104:107], v[172:175], v[180:183], v[104:107]
	v_mfma_f32_16x16x32_bf16 v[96:99], v[164:167], v[188:191], v[96:99]
	v_mfma_f32_16x16x32_bf16 v[88:91], v[172:175], v[188:191], v[88:91]
	v_mfma_f32_16x16x32_bf16 v[80:83], v[164:167], v[196:199], v[80:83]
	v_mfma_f32_16x16x32_bf16 v[72:75], v[172:175], v[196:199], v[72:75]
	v_mfma_f32_16x16x32_bf16 v[68:71], v[164:167], v[204:207], v[68:71]
	v_mfma_f32_16x16x32_bf16 v[64:67], v[172:175], v[204:207], v[64:67]
	v_mfma_f32_16x16x32_bf16 v[112:115], v[168:171], v[184:187], v[112:115]
	v_mfma_f32_16x16x32_bf16 v[104:107], v[176:179], v[184:187], v[104:107]
	v_mfma_f32_16x16x32_bf16 v[96:99], v[168:171], v[192:195], v[96:99]
	v_mfma_f32_16x16x32_bf16 v[88:91], v[176:179], v[192:195], v[88:91]
	v_mfma_f32_16x16x32_bf16 v[80:83], v[168:171], v[200:203], v[80:83]
	v_mfma_f32_16x16x32_bf16 v[72:75], v[176:179], v[200:203], v[72:75]
	v_mfma_f32_16x16x32_bf16 v[68:71], v[168:171], v[208:211], v[68:71]
	v_mfma_f32_16x16x32_bf16 v[64:67], v[176:179], v[208:211], v[64:67]
	s_barrier
	s_setprio 0
	s_mov_b32 m0, s38
	v_lshl_add_u64 v[212:213], v[212:213], 0, s[10:11]
	s_add_u32 s16, s16, 0x100080
	ds_read_b128 v[180:183], v144 offset:49152
	ds_read_b128 v[184:187], v144 offset:50176
	ds_read_b128 v[188:191], v144 offset:51200
	ds_read_b128 v[192:195], v144 offset:52224
	ds_read_b128 v[196:199], v144 offset:53248
	ds_read_b128 v[200:203], v144 offset:54272
	ds_read_b128 v[204:207], v144 offset:55296
	ds_read_b128 v[208:211], v144 offset:56320
	global_load_lds_dwordx4 v[212:213], off
	v_lshl_add_u64 v[212:213], v[214:215], 0, s[10:11]
	s_mov_b32 m0, s39
	s_addc_u32 s17, s17, 0
	global_load_lds_dwordx4 v[212:213], off
	s_mov_b32 m0, s40
	s_nop 0
	global_load_lds_dwordx4 v132, s[16:17]
	s_mov_b32 m0, s41
	s_nop 0
	global_load_lds_dwordx4 v128, s[16:17]
	v_lshl_add_u64 v[212:213], v[216:217], 0, s[10:11]
	s_mov_b32 m0, s26
	s_nop 0
	global_load_lds_dwordx4 v[212:213], off
	v_lshl_add_u64 v[212:213], v[218:219], 0, s[10:11]
	s_mov_b32 m0, s27
	s_nop 0
	global_load_lds_dwordx4 v[212:213], off
	s_waitcnt vmcnt(8)
	s_waitcnt lgkmcnt(0)
	s_setprio 1
	s_barrier
	v_mfma_f32_16x16x32_bf16 v[60:63], v[148:151], v[180:183], v[60:63]
	v_mfma_f32_16x16x32_bf16 v[56:59], v[156:159], v[180:183], v[56:59]
	v_mfma_f32_16x16x32_bf16 v[52:55], v[148:151], v[188:191], v[52:55]
	v_mfma_f32_16x16x32_bf16 v[44:47], v[156:159], v[188:191], v[44:47]
	v_mfma_f32_16x16x32_bf16 v[36:39], v[148:151], v[196:199], v[36:39]
	v_mfma_f32_16x16x32_bf16 v[28:31], v[156:159], v[196:199], v[28:31]
	v_mfma_f32_16x16x32_bf16 v[20:23], v[148:151], v[204:207], v[20:23]
	v_mfma_f32_16x16x32_bf16 v[12:15], v[156:159], v[204:207], v[12:15]
	v_mfma_f32_16x16x32_bf16 v[60:63], v[152:155], v[184:187], v[60:63]
	v_mfma_f32_16x16x32_bf16 v[56:59], v[160:163], v[184:187], v[56:59]
	v_mfma_f32_16x16x32_bf16 v[52:55], v[152:155], v[192:195], v[52:55]
	v_mfma_f32_16x16x32_bf16 v[44:47], v[160:163], v[192:195], v[44:47]
	v_mfma_f32_16x16x32_bf16 v[36:39], v[152:155], v[200:203], v[36:39]
	v_mfma_f32_16x16x32_bf16 v[28:31], v[160:163], v[200:203], v[28:31]
	v_mfma_f32_16x16x32_bf16 v[20:23], v[152:155], v[208:211], v[20:23]
	v_mfma_f32_16x16x32_bf16 v[12:15], v[160:163], v[208:211], v[12:15]
	v_mfma_f32_16x16x32_bf16 v[48:51], v[164:167], v[180:183], v[48:51]
	v_mfma_f32_16x16x32_bf16 v[40:43], v[172:175], v[180:183], v[40:43]
	v_mfma_f32_16x16x32_bf16 v[32:35], v[164:167], v[188:191], v[32:35]
	v_mfma_f32_16x16x32_bf16 v[24:27], v[172:175], v[188:191], v[24:27]
	v_mfma_f32_16x16x32_bf16 v[16:19], v[164:167], v[196:199], v[16:19]
	v_mfma_f32_16x16x32_bf16 v[8:11], v[172:175], v[196:199], v[8:11]
	v_mfma_f32_16x16x32_bf16 v[4:7], v[164:167], v[204:207], v[4:7]
	v_mfma_f32_16x16x32_bf16 v[0:3], v[172:175], v[204:207], v[0:3]
	v_mfma_f32_16x16x32_bf16 v[48:51], v[168:171], v[184:187], v[48:51]
	v_mfma_f32_16x16x32_bf16 v[40:43], v[176:179], v[184:187], v[40:43]
	v_mfma_f32_16x16x32_bf16 v[32:35], v[168:171], v[192:195], v[32:35]
	v_mfma_f32_16x16x32_bf16 v[24:27], v[176:179], v[192:195], v[24:27]
	v_mfma_f32_16x16x32_bf16 v[16:19], v[168:171], v[200:203], v[16:19]
	v_mfma_f32_16x16x32_bf16 v[8:11], v[176:179], v[200:203], v[8:11]
	v_mfma_f32_16x16x32_bf16 v[4:7], v[168:171], v[208:211], v[4:7]
	v_mfma_f32_16x16x32_bf16 v[0:3], v[176:179], v[208:211], v[0:3]
	s_barrier
	s_setprio 0
	s_add_i32 s30, s30, 2
	s_add_u32 s14, s14, 0x100
	s_addc_u32 s15, s15, 0
	s_cmp_gt_u32 s30, 5
	s_cbranch_scc0 .LBB0_2021
	s_cmp_lt_u32 s5, 4
	s_cbranch_scc0 .LBB0_2024
	s_barrier

.LBB0_2542:
	ds_read_b128 v[128:131], v180
	ds_read_b128 v[132:135], v180 offset:1024
	ds_read_b128 v[136:139], v180 offset:2048
	ds_read_b128 v[140:143], v180 offset:3072
	ds_read_b128 v[144:147], v181
	ds_read_b128 v[148:151], v181 offset:1024
	ds_read_b128 v[152:155], v181 offset:2048
	ds_read_b128 v[156:159], v181 offset:3072
	s_add_u32 s6, s0, 0x3fc000
	s_addc_u32 s7, s1, 0
	s_cmp_eq_u32 s42, 28
	s_cselect_b32 s36, s13, s6
	s_cselect_b32 s37, s10, s7
	s_cselect_b32 s8, s39, s40
	s_cselect_b32 s9, s29, s41
	s_add_u32 s6, s36, 0x400000
	s_addc_u32 s7, s37, 0
	s_add_i32 m0, s33, 0xc000
	ds_read_b128 v[186:189], v182
	ds_read_b128 v[190:193], v182 offset:1024
	ds_read_b128 v[194:197], v182 offset:2048
	ds_read_b128 v[198:201], v182 offset:3072
	ds_read_b128 v[202:205], v182 offset:4096
	ds_read_b128 v[206:209], v182 offset:5120
	ds_read_b128 v[210:213], v182 offset:6144
	ds_read_b128 v[214:217], v182 offset:7168
	global_load_lds_dwordx4 v168, s[0:1]
	s_add_i32 m0, s33, 0xe000
	s_nop 0
	global_load_lds_dwordx4 v170, s[0:1]
	s_waitcnt vmcnt(8)
	s_waitcnt lgkmcnt(0)
	s_setprio 1
	s_barrier
	v_mfma_f32_16x16x32_bf16 v[104:107], v[128:131], v[186:189], v[104:107]
	v_mfma_f32_16x16x32_bf16 v[96:99], v[136:139], v[186:189], v[96:99]
	v_mfma_f32_16x16x32_bf16 v[84:87], v[128:131], v[194:197], v[84:87]
	v_mfma_f32_16x16x32_bf16 v[80:83], v[136:139], v[194:197], v[80:83]
	v_mfma_f32_16x16x32_bf16 v[92:95], v[128:131], v[202:205], v[92:95]
	v_mfma_f32_16x16x32_bf16 v[88:91], v[136:139], v[202:205], v[88:91]
	v_mfma_f32_16x16x32_bf16 v[108:111], v[128:131], v[210:213], v[108:111]
	v_mfma_f32_16x16x32_bf16 v[100:103], v[136:139], v[210:213], v[100:103]
	v_mfma_f32_16x16x32_bf16 v[104:107], v[132:135], v[190:193], v[104:107]
	v_mfma_f32_16x16x32_bf16 v[96:99], v[140:143], v[190:193], v[96:99]
	v_mfma_f32_16x16x32_bf16 v[84:87], v[132:135], v[198:201], v[84:87]
	v_mfma_f32_16x16x32_bf16 v[80:83], v[140:143], v[198:201], v[80:83]
	v_mfma_f32_16x16x32_bf16 v[92:95], v[132:135], v[206:209], v[92:95]
	v_mfma_f32_16x16x32_bf16 v[88:91], v[140:143], v[206:209], v[88:91]
	v_mfma_f32_16x16x32_bf16 v[108:111], v[132:135], v[214:217], v[108:111]
	v_mfma_f32_16x16x32_bf16 v[100:103], v[140:143], v[214:217], v[100:103]
	v_mfma_f32_16x16x32_bf16 v[28:31], v[144:147], v[186:189], v[28:31]
	v_mfma_f32_16x16x32_bf16 v[16:19], v[152:155], v[186:189], v[16:19]
	v_mfma_f32_16x16x32_bf16 v[4:7], v[144:147], v[194:197], v[4:7]
	v_mfma_f32_16x16x32_bf16 v[0:3], v[152:155], v[194:197], v[0:3]
	v_mfma_f32_16x16x32_bf16 v[12:15], v[144:147], v[202:205], v[12:15]
	v_mfma_f32_16x16x32_bf16 v[8:11], v[152:155], v[202:205], v[8:11]
	v_mfma_f32_16x16x32_bf16 v[24:27], v[144:147], v[210:213], v[24:27]
	v_mfma_f32_16x16x32_bf16 v[20:23], v[152:155], v[210:213], v[20:23]
	v_mfma_f32_16x16x32_bf16 v[28:31], v[148:151], v[190:193], v[28:31]
	v_mfma_f32_16x16x32_bf16 v[16:19], v[156:159], v[190:193], v[16:19]
	v_mfma_f32_16x16x32_bf16 v[4:7], v[148:151], v[198:201], v[4:7]
	v_mfma_f32_16x16x32_bf16 v[0:3], v[156:159], v[198:201], v[0:3]
	v_mfma_f32_16x16x32_bf16 v[12:15], v[148:151], v[206:209], v[12:15]
	v_mfma_f32_16x16x32_bf16 v[8:11], v[156:159], v[206:209], v[8:11]
	v_mfma_f32_16x16x32_bf16 v[24:27], v[148:151], v[214:217], v[24:27]
	v_mfma_f32_16x16x32_bf16 v[20:23], v[156:159], v[214:217], v[20:23]
	s_barrier
	s_setprio 0
	s_add_i32 s43, s57, s5
	s_mov_b32 m0, s43
	ds_read_b128 v[186:189], v182 offset:16384
	ds_read_b128 v[190:193], v182 offset:17408
	ds_read_b128 v[194:197], v182 offset:18432
	ds_read_b128 v[198:201], v182 offset:19456
	ds_read_b128 v[202:205], v182 offset:20480
	ds_read_b128 v[206:209], v182 offset:21504
	ds_read_b128 v[210:213], v182 offset:22528
	ds_read_b128 v[214:217], v182 offset:23552
	global_load_lds_dwordx4 v162, s[8:9]
	s_add_i32 m0, s43, 0x2000
	s_add_u32 s44, s8, 0x4000
	s_addc_u32 s45, s9, 0
	s_add_i32 s43, s81, s5
	global_load_lds_dwordx4 v166, s[8:9]
	s_mov_b32 m0, s43
	s_nop 0
	global_load_lds_dwordx4 v162, s[44:45]
	s_add_i32 m0, s43, 0x2000
	s_nop 0
	global_load_lds_dwordx4 v166, s[44:45]
	s_mov_b32 m0, s33
	s_nop 0
	global_load_lds_dwordx4 v160, s[36:37]
	s_mov_b32 m0, s46
	s_nop 0
	global_load_lds_dwordx4 v164, s[36:37]
	s_waitcnt vmcnt(8)
	s_waitcnt lgkmcnt(0)
	s_setprio 1
	s_barrier
	v_mfma_f32_16x16x32_bf16 v[116:119], v[128:131], v[186:189], v[116:119]
	v_mfma_f32_16x16x32_bf16 v[112:115], v[136:139], v[186:189], v[112:115]
	v_mfma_f32_16x16x32_bf16 v[124:127], v[128:131], v[194:197], v[124:127]
	v_mfma_f32_16x16x32_bf16 v[120:123], v[136:139], v[194:197], v[120:123]
	v_mfma_f32_16x16x32_bf16 v[76:79], v[128:131], v[202:205], v[76:79]
	v_mfma_f32_16x16x32_bf16 v[72:75], v[136:139], v[202:205], v[72:75]
	v_mfma_f32_16x16x32_bf16 v[68:71], v[128:131], v[210:213], v[68:71]
	v_mfma_f32_16x16x32_bf16 v[64:67], v[136:139], v[210:213], v[64:67]
	v_mfma_f32_16x16x32_bf16 v[116:119], v[132:135], v[190:193], v[116:119]
	v_mfma_f32_16x16x32_bf16 v[112:115], v[140:143], v[190:193], v[112:115]
	v_mfma_f32_16x16x32_bf16 v[124:127], v[132:135], v[198:201], v[124:127]
	v_mfma_f32_16x16x32_bf16 v[120:123], v[140:143], v[198:201], v[120:123]
	v_mfma_f32_16x16x32_bf16 v[76:79], v[132:135], v[206:209], v[76:79]
	v_mfma_f32_16x16x32_bf16 v[72:75], v[140:143], v[206:209], v[72:75]
	v_mfma_f32_16x16x32_bf16 v[68:71], v[132:135], v[214:217], v[68:71]
	v_mfma_f32_16x16x32_bf16 v[64:67], v[140:143], v[214:217], v[64:67]
	v_mfma_f32_16x16x32_bf16 v[36:39], v[144:147], v[186:189], v[36:39]
	v_mfma_f32_16x16x32_bf16 v[32:35], v[152:155], v[186:189], v[32:35]
	v_mfma_f32_16x16x32_bf16 v[44:47], v[144:147], v[194:197], v[44:47]
	v_mfma_f32_16x16x32_bf16 v[40:43], v[152:155], v[194:197], v[40:43]
	v_mfma_f32_16x16x32_bf16 v[52:55], v[144:147], v[202:205], v[52:55]
	v_mfma_f32_16x16x32_bf16 v[48:51], v[152:155], v[202:205], v[48:51]
	v_mfma_f32_16x16x32_bf16 v[60:63], v[144:147], v[210:213], v[60:63]
	v_mfma_f32_16x16x32_bf16 v[56:59], v[152:155], v[210:213], v[56:59]
	v_mfma_f32_16x16x32_bf16 v[36:39], v[148:151], v[190:193], v[36:39]
	v_mfma_f32_16x16x32_bf16 v[32:35], v[156:159], v[190:193], v[32:35]
	v_mfma_f32_16x16x32_bf16 v[44:47], v[148:151], v[198:201], v[44:47]
	v_mfma_f32_16x16x32_bf16 v[40:43], v[156:159], v[198:201], v[40:43]
	v_mfma_f32_16x16x32_bf16 v[52:55], v[148:151], v[206:209], v[52:55]
	v_mfma_f32_16x16x32_bf16 v[48:51], v[156:159], v[206:209], v[48:51]
	v_mfma_f32_16x16x32_bf16 v[60:63], v[148:151], v[214:217], v[60:63]
	v_mfma_f32_16x16x32_bf16 v[56:59], v[156:159], v[214:217], v[56:59]
	s_barrier
	s_setprio 0
	v_add_u32_e32 v140, s82, v179
	v_add_u32_e32 v156, s83, v179
	ds_read_b128 v[128:131], v140
	ds_read_b128 v[132:135], v140 offset:1024
	ds_read_b128 v[136:139], v140 offset:2048
	ds_read_b128 v[140:143], v140 offset:3072
	ds_read_b128 v[144:147], v156
	ds_read_b128 v[148:151], v156 offset:1024
	ds_read_b128 v[152:155], v156 offset:2048
	ds_read_b128 v[156:159], v156 offset:3072
	s_add_u32 s36, s36, 0x4000
	s_addc_u32 s37, s37, 0
	s_mov_b32 m0, s47
	ds_read_b128 v[186:189], v182 offset:32768
	ds_read_b128 v[190:193], v182 offset:33792
	ds_read_b128 v[194:197], v182 offset:34816
	ds_read_b128 v[198:201], v182 offset:35840
	ds_read_b128 v[202:205], v182 offset:36864
	ds_read_b128 v[206:209], v182 offset:37888
	ds_read_b128 v[210:213], v182 offset:38912
	ds_read_b128 v[214:217], v182 offset:39936
	global_load_lds_dwordx4 v160, s[36:37]
	s_mov_b32 m0, s50
	s_nop 0
	global_load_lds_dwordx4 v164, s[36:37]
	s_waitcnt vmcnt(8)
	s_waitcnt lgkmcnt(0)
	s_setprio 1
	s_barrier
	v_mfma_f32_16x16x32_bf16 v[104:107], v[128:131], v[186:189], v[104:107]
	v_mfma_f32_16x16x32_bf16 v[96:99], v[136:139], v[186:189], v[96:99]
	v_mfma_f32_16x16x32_bf16 v[84:87], v[128:131], v[194:197], v[84:87]
	v_mfma_f32_16x16x32_bf16 v[80:83], v[136:139], v[194:197], v[80:83]
	v_mfma_f32_16x16x32_bf16 v[92:95], v[128:131], v[202:205], v[92:95]
	v_mfma_f32_16x16x32_bf16 v[88:91], v[136:139], v[202:205], v[88:91]
	v_mfma_f32_16x16x32_bf16 v[108:111], v[128:131], v[210:213], v[108:111]
	v_mfma_f32_16x16x32_bf16 v[100:103], v[136:139], v[210:213], v[100:103]
	v_mfma_f32_16x16x32_bf16 v[104:107], v[132:135], v[190:193], v[104:107]
	v_mfma_f32_16x16x32_bf16 v[96:99], v[140:143], v[190:193], v[96:99]
	v_mfma_f32_16x16x32_bf16 v[84:87], v[132:135], v[198:201], v[84:87]
	v_mfma_f32_16x16x32_bf16 v[80:83], v[140:143], v[198:201], v[80:83]
	v_mfma_f32_16x16x32_bf16 v[92:95], v[132:135], v[206:209], v[92:95]
	v_mfma_f32_16x16x32_bf16 v[88:91], v[140:143], v[206:209], v[88:91]
	v_mfma_f32_16x16x32_bf16 v[108:111], v[132:135], v[214:217], v[108:111]
	v_mfma_f32_16x16x32_bf16 v[100:103], v[140:143], v[214:217], v[100:103]
	v_mfma_f32_16x16x32_bf16 v[28:31], v[144:147], v[186:189], v[28:31]
	v_mfma_f32_16x16x32_bf16 v[16:19], v[152:155], v[186:189], v[16:19]
	v_mfma_f32_16x16x32_bf16 v[4:7], v[144:147], v[194:197], v[4:7]
	v_mfma_f32_16x16x32_bf16 v[0:3], v[152:155], v[194:197], v[0:3]
	v_mfma_f32_16x16x32_bf16 v[12:15], v[144:147], v[202:205], v[12:15]
	v_mfma_f32_16x16x32_bf16 v[8:11], v[152:155], v[202:205], v[8:11]
	v_mfma_f32_16x16x32_bf16 v[24:27], v[144:147], v[210:213], v[24:27]
	v_mfma_f32_16x16x32_bf16 v[20:23], v[152:155], v[210:213], v[20:23]
	v_mfma_f32_16x16x32_bf16 v[28:31], v[148:151], v[190:193], v[28:31]
	v_mfma_f32_16x16x32_bf16 v[16:19], v[156:159], v[190:193], v[16:19]
	v_mfma_f32_16x16x32_bf16 v[4:7], v[148:151], v[198:201], v[4:7]
	v_mfma_f32_16x16x32_bf16 v[0:3], v[156:159], v[198:201], v[0:3]
	v_mfma_f32_16x16x32_bf16 v[12:15], v[148:151], v[206:209], v[12:15]
	v_mfma_f32_16x16x32_bf16 v[8:11], v[156:159], v[206:209], v[8:11]
	v_mfma_f32_16x16x32_bf16 v[24:27], v[148:151], v[214:217], v[24:27]
	v_mfma_f32_16x16x32_bf16 v[20:23], v[156:159], v[214:217], v[20:23]
	s_barrier
	s_setprio 0
	s_add_u32 s36, s8, 0x40000
	s_addc_u32 s37, s9, 0
	s_add_i32 s43, s82, s5
	s_mov_b32 m0, s43
	ds_read_b128 v[186:189], v182 offset:49152
	ds_read_b128 v[190:193], v182 offset:50176
	ds_read_b128 v[194:197], v182 offset:51200
	ds_read_b128 v[198:201], v182 offset:52224
	ds_read_b128 v[202:205], v182 offset:53248
	ds_read_b128 v[206:209], v182 offset:54272
	ds_read_b128 v[210:213], v182 offset:55296
	ds_read_b128 v[214:217], v182 offset:56320
	global_load_lds_dwordx4 v162, s[36:37]
	s_add_i32 m0, s43, 0x2000
	s_add_u32 s8, s8, 0x44000
	global_load_lds_dwordx4 v166, s[36:37]
	s_addc_u32 s9, s9, 0
	s_add_i32 s36, s83, s5
	s_mov_b32 m0, s36
	s_nop 0
	global_load_lds_dwordx4 v162, s[8:9]
	s_add_i32 m0, s36, 0x2000
	s_nop 0
	global_load_lds_dwordx4 v166, s[8:9]
	s_mov_b32 m0, s55
	s_nop 0
	global_load_lds_dwordx4 v160, s[6:7]
	s_mov_b32 m0, s56
	s_nop 0
	global_load_lds_dwordx4 v164, s[6:7]
	s_waitcnt vmcnt(8)
	s_waitcnt lgkmcnt(0)
	s_setprio 1
	s_barrier
	v_mfma_f32_16x16x32_bf16 v[116:119], v[128:131], v[186:189], v[116:119]
	v_mfma_f32_16x16x32_bf16 v[112:115], v[136:139], v[186:189], v[112:115]
	v_mfma_f32_16x16x32_bf16 v[124:127], v[128:131], v[194:197], v[124:127]
	v_mfma_f32_16x16x32_bf16 v[120:123], v[136:139], v[194:197], v[120:123]
	v_mfma_f32_16x16x32_bf16 v[76:79], v[128:131], v[202:205], v[76:79]
	v_mfma_f32_16x16x32_bf16 v[72:75], v[136:139], v[202:205], v[72:75]
	v_mfma_f32_16x16x32_bf16 v[68:71], v[128:131], v[210:213], v[68:71]
	v_mfma_f32_16x16x32_bf16 v[64:67], v[136:139], v[210:213], v[64:67]
	v_mfma_f32_16x16x32_bf16 v[116:119], v[132:135], v[190:193], v[116:119]
	v_mfma_f32_16x16x32_bf16 v[112:115], v[140:143], v[190:193], v[112:115]
	v_mfma_f32_16x16x32_bf16 v[124:127], v[132:135], v[198:201], v[124:127]
	v_mfma_f32_16x16x32_bf16 v[120:123], v[140:143], v[198:201], v[120:123]
	v_mfma_f32_16x16x32_bf16 v[76:79], v[132:135], v[206:209], v[76:79]
	v_mfma_f32_16x16x32_bf16 v[72:75], v[140:143], v[206:209], v[72:75]
	v_mfma_f32_16x16x32_bf16 v[68:71], v[132:135], v[214:217], v[68:71]
	v_mfma_f32_16x16x32_bf16 v[64:67], v[140:143], v[214:217], v[64:67]
	v_mfma_f32_16x16x32_bf16 v[36:39], v[144:147], v[186:189], v[36:39]
	v_mfma_f32_16x16x32_bf16 v[32:35], v[152:155], v[186:189], v[32:35]
	v_mfma_f32_16x16x32_bf16 v[44:47], v[144:147], v[194:197], v[44:47]
	v_mfma_f32_16x16x32_bf16 v[40:43], v[152:155], v[194:197], v[40:43]
	v_mfma_f32_16x16x32_bf16 v[52:55], v[144:147], v[202:205], v[52:55]
	v_mfma_f32_16x16x32_bf16 v[48:51], v[152:155], v[202:205], v[48:51]
	v_mfma_f32_16x16x32_bf16 v[60:63], v[144:147], v[210:213], v[60:63]
	v_mfma_f32_16x16x32_bf16 v[56:59], v[152:155], v[210:213], v[56:59]
	v_mfma_f32_16x16x32_bf16 v[36:39], v[148:151], v[190:193], v[36:39]
	v_mfma_f32_16x16x32_bf16 v[32:35], v[156:159], v[190:193], v[32:35]
	v_mfma_f32_16x16x32_bf16 v[44:47], v[148:151], v[198:201], v[44:47]
	v_mfma_f32_16x16x32_bf16 v[40:43], v[156:159], v[198:201], v[40:43]
	v_mfma_f32_16x16x32_bf16 v[52:55], v[148:151], v[206:209], v[52:55]
	v_mfma_f32_16x16x32_bf16 v[48:51], v[156:159], v[206:209], v[48:51]
	v_mfma_f32_16x16x32_bf16 v[60:63], v[148:151], v[214:217], v[60:63]
	v_mfma_f32_16x16x32_bf16 v[56:59], v[156:159], v[214:217], v[56:59]
	s_barrier
	s_setprio 0
	s_add_i32 s42, s42, 2
	s_add_u32 s40, s40, 0x80000
	s_addc_u32 s41, s41, 0
	s_add_u32 s0, s0, 0x800000
	s_addc_u32 s1, s1, 0
	s_cmp_gt_u32 s42, 29
	s_cbranch_scc0 .LBB0_2542
	s_and_b64 vcc, exec, s[24:25]
	s_cbranch_vccz .LBB0_2545
	s_barrier

.LBB0_2664:
	ds_read_b128 v[152:155], v149
	ds_read_b128 v[156:159], v149 offset:1024
	ds_read_b128 v[160:163], v149 offset:2048
	ds_read_b128 v[164:167], v149 offset:3072
	ds_read_b128 v[168:171], v150
	ds_read_b128 v[172:175], v150 offset:1024
	ds_read_b128 v[176:179], v150 offset:2048
	ds_read_b128 v[180:183], v150 offset:3072
	s_add_u32 s24, s22, 0x3fc000
	s_addc_u32 s25, s23, 0
	s_cmp_eq_u32 s64, 28
	s_cselect_b32 s28, s15, s24
	s_cselect_b32 s29, s6, s25
	s_cselect_b32 s26, s54, s55
	s_cselect_b32 s27, s17, s56
	s_add_u32 s24, s28, 0x400000
	s_addc_u32 s25, s29, 0
	s_add_i32 m0, s30, 0xc000
	ds_read_b128 v[184:187], v151
	ds_read_b128 v[188:191], v151 offset:1024
	ds_read_b128 v[192:195], v151 offset:2048
	ds_read_b128 v[196:199], v151 offset:3072
	ds_read_b128 v[200:203], v151 offset:4096
	ds_read_b128 v[204:207], v151 offset:5120
	ds_read_b128 v[208:211], v151 offset:6144
	ds_read_b128 v[212:215], v151 offset:7168
	global_load_lds_dwordx4 v136, s[22:23]
	s_add_i32 m0, s30, 0xe000
	s_nop 0
	global_load_lds_dwordx4 v138, s[22:23]
	s_waitcnt vmcnt(8)
	s_waitcnt lgkmcnt(0)
	s_setprio 1
	s_barrier
	v_mfma_f32_16x16x32_bf16 v[124:127], v[152:155], v[184:187], v[124:127]
	v_mfma_f32_16x16x32_bf16 v[120:123], v[160:163], v[184:187], v[120:123]
	v_mfma_f32_16x16x32_bf16 v[108:111], v[152:155], v[192:195], v[108:111]
	v_mfma_f32_16x16x32_bf16 v[104:107], v[160:163], v[192:195], v[104:107]
	v_mfma_f32_16x16x32_bf16 v[92:95], v[152:155], v[200:203], v[92:95]
	v_mfma_f32_16x16x32_bf16 v[88:91], v[160:163], v[200:203], v[88:91]
	v_mfma_f32_16x16x32_bf16 v[76:79], v[152:155], v[208:211], v[76:79]
	v_mfma_f32_16x16x32_bf16 v[72:75], v[160:163], v[208:211], v[72:75]
	v_mfma_f32_16x16x32_bf16 v[124:127], v[156:159], v[188:191], v[124:127]
	v_mfma_f32_16x16x32_bf16 v[120:123], v[164:167], v[188:191], v[120:123]
	v_mfma_f32_16x16x32_bf16 v[108:111], v[156:159], v[196:199], v[108:111]
	v_mfma_f32_16x16x32_bf16 v[104:107], v[164:167], v[196:199], v[104:107]
	v_mfma_f32_16x16x32_bf16 v[92:95], v[156:159], v[204:207], v[92:95]
	v_mfma_f32_16x16x32_bf16 v[88:91], v[164:167], v[204:207], v[88:91]
	v_mfma_f32_16x16x32_bf16 v[76:79], v[156:159], v[212:215], v[76:79]
	v_mfma_f32_16x16x32_bf16 v[72:75], v[164:167], v[212:215], v[72:75]
	v_mfma_f32_16x16x32_bf16 v[116:119], v[168:171], v[184:187], v[116:119]
	v_mfma_f32_16x16x32_bf16 v[112:115], v[176:179], v[184:187], v[112:115]
	v_mfma_f32_16x16x32_bf16 v[100:103], v[168:171], v[192:195], v[100:103]
	v_mfma_f32_16x16x32_bf16 v[96:99], v[176:179], v[192:195], v[96:99]
	v_mfma_f32_16x16x32_bf16 v[84:87], v[168:171], v[200:203], v[84:87]
	v_mfma_f32_16x16x32_bf16 v[80:83], v[176:179], v[200:203], v[80:83]
	v_mfma_f32_16x16x32_bf16 v[68:71], v[168:171], v[208:211], v[68:71]
	v_mfma_f32_16x16x32_bf16 v[64:67], v[176:179], v[208:211], v[64:67]
	v_mfma_f32_16x16x32_bf16 v[116:119], v[172:175], v[188:191], v[116:119]
	v_mfma_f32_16x16x32_bf16 v[112:115], v[180:183], v[188:191], v[112:115]
	v_mfma_f32_16x16x32_bf16 v[100:103], v[172:175], v[196:199], v[100:103]
	v_mfma_f32_16x16x32_bf16 v[96:99], v[180:183], v[196:199], v[96:99]
	v_mfma_f32_16x16x32_bf16 v[84:87], v[172:175], v[204:207], v[84:87]
	v_mfma_f32_16x16x32_bf16 v[80:83], v[180:183], v[204:207], v[80:83]
	v_mfma_f32_16x16x32_bf16 v[68:71], v[172:175], v[212:215], v[68:71]
	v_mfma_f32_16x16x32_bf16 v[64:67], v[180:183], v[212:215], v[64:67]
	s_barrier
	s_setprio 0
	s_add_i32 s65, s57, s5
	v_lshl_add_u64 v[144:145], s[26:27], 0, v[130:131]
	s_mov_b32 m0, s65
	ds_read_b128 v[184:187], v151 offset:16384
	ds_read_b128 v[188:191], v151 offset:17408
	ds_read_b128 v[192:195], v151 offset:18432
	ds_read_b128 v[196:199], v151 offset:19456
	ds_read_b128 v[200:203], v151 offset:20480
	ds_read_b128 v[204:207], v151 offset:21504
	ds_read_b128 v[208:211], v151 offset:22528
	ds_read_b128 v[212:215], v151 offset:23552
	global_load_lds_dwordx4 v[144:145], off
	s_add_i32 m0, s65, 0x2000
	s_add_u32 s66, s26, 0x80000
	v_lshl_add_u64 v[216:217], s[26:27], 0, v[134:135]
	s_addc_u32 s67, s27, 0
	s_add_i32 s65, s81, s5
	global_load_lds_dwordx4 v[216:217], off
	s_mov_b32 m0, s65
	s_nop 0
	global_load_lds_dwordx4 v130, s[66:67]
	s_add_i32 m0, s65, 0x2000
	s_nop 0
	global_load_lds_dwordx4 v134, s[66:67]
	s_mov_b32 m0, s30
	s_nop 0
	global_load_lds_dwordx4 v128, s[28:29]
	s_mov_b32 m0, s31
	s_nop 0
	global_load_lds_dwordx4 v132, s[28:29]
	s_waitcnt vmcnt(8)
	s_waitcnt lgkmcnt(0)
	s_setprio 1
	s_barrier
	v_mfma_f32_16x16x32_bf16 v[60:63], v[152:155], v[184:187], v[60:63]
	v_mfma_f32_16x16x32_bf16 v[56:59], v[160:163], v[184:187], v[56:59]
	v_mfma_f32_16x16x32_bf16 v[44:47], v[152:155], v[192:195], v[44:47]
	v_mfma_f32_16x16x32_bf16 v[40:43], v[160:163], v[192:195], v[40:43]
	v_mfma_f32_16x16x32_bf16 v[28:31], v[152:155], v[200:203], v[28:31]
	v_mfma_f32_16x16x32_bf16 v[24:27], v[160:163], v[200:203], v[24:27]
	v_mfma_f32_16x16x32_bf16 v[12:15], v[152:155], v[208:211], v[12:15]
	v_mfma_f32_16x16x32_bf16 v[8:11], v[160:163], v[208:211], v[8:11]
	v_mfma_f32_16x16x32_bf16 v[60:63], v[156:159], v[188:191], v[60:63]
	v_mfma_f32_16x16x32_bf16 v[56:59], v[164:167], v[188:191], v[56:59]
	v_mfma_f32_16x16x32_bf16 v[44:47], v[156:159], v[196:199], v[44:47]
	v_mfma_f32_16x16x32_bf16 v[40:43], v[164:167], v[196:199], v[40:43]
	v_mfma_f32_16x16x32_bf16 v[28:31], v[156:159], v[204:207], v[28:31]
	v_mfma_f32_16x16x32_bf16 v[24:27], v[164:167], v[204:207], v[24:27]
	v_mfma_f32_16x16x32_bf16 v[12:15], v[156:159], v[212:215], v[12:15]
	v_mfma_f32_16x16x32_bf16 v[8:11], v[164:167], v[212:215], v[8:11]
	v_mfma_f32_16x16x32_bf16 v[52:55], v[168:171], v[184:187], v[52:55]
	v_mfma_f32_16x16x32_bf16 v[48:51], v[176:179], v[184:187], v[48:51]
	v_mfma_f32_16x16x32_bf16 v[36:39], v[168:171], v[192:195], v[36:39]
	v_mfma_f32_16x16x32_bf16 v[32:35], v[176:179], v[192:195], v[32:35]
	v_mfma_f32_16x16x32_bf16 v[20:23], v[168:171], v[200:203], v[20:23]
	v_mfma_f32_16x16x32_bf16 v[16:19], v[176:179], v[200:203], v[16:19]
	v_mfma_f32_16x16x32_bf16 v[4:7], v[168:171], v[208:211], v[4:7]
	v_mfma_f32_16x16x32_bf16 v[0:3], v[176:179], v[208:211], v[0:3]
	v_mfma_f32_16x16x32_bf16 v[52:55], v[172:175], v[188:191], v[52:55]
	v_mfma_f32_16x16x32_bf16 v[48:51], v[180:183], v[188:191], v[48:51]
	v_mfma_f32_16x16x32_bf16 v[36:39], v[172:175], v[196:199], v[36:39]
	v_mfma_f32_16x16x32_bf16 v[32:35], v[180:183], v[196:199], v[32:35]
	v_mfma_f32_16x16x32_bf16 v[20:23], v[172:175], v[204:207], v[20:23]
	v_mfma_f32_16x16x32_bf16 v[16:19], v[180:183], v[204:207], v[16:19]
	v_mfma_f32_16x16x32_bf16 v[4:7], v[172:175], v[212:215], v[4:7]
	v_mfma_f32_16x16x32_bf16 v[0:3], v[180:183], v[212:215], v[0:3]
	s_barrier
	s_setprio 0
	v_add_u32_e32 v164, s82, v148
	v_add_u32_e32 v180, s83, v148
	ds_read_b128 v[152:155], v164
	ds_read_b128 v[156:159], v164 offset:1024
	ds_read_b128 v[160:163], v164 offset:2048
	ds_read_b128 v[164:167], v164 offset:3072
	ds_read_b128 v[168:171], v180
	ds_read_b128 v[172:175], v180 offset:1024
	ds_read_b128 v[176:179], v180 offset:2048
	ds_read_b128 v[180:183], v180 offset:3072
	s_add_u32 s28, s28, 0x4000
	s_addc_u32 s29, s29, 0
	s_mov_b32 m0, s33
	ds_read_b128 v[184:187], v151 offset:32768
	ds_read_b128 v[188:191], v151 offset:33792
	ds_read_b128 v[192:195], v151 offset:34816
	ds_read_b128 v[196:199], v151 offset:35840
	ds_read_b128 v[200:203], v151 offset:36864
	ds_read_b128 v[204:207], v151 offset:37888
	ds_read_b128 v[208:211], v151 offset:38912
	ds_read_b128 v[212:215], v151 offset:39936
	global_load_lds_dwordx4 v128, s[28:29]
	v_lshl_add_u64 v[218:219], s[28:29], 0, v[132:133]
	s_mov_b32 m0, s34
	s_nop 0
	global_load_lds_dwordx4 v[218:219], off
	s_waitcnt vmcnt(8)
	s_waitcnt lgkmcnt(0)
	s_setprio 1
	s_barrier
	v_mfma_f32_16x16x32_bf16 v[124:127], v[152:155], v[184:187], v[124:127]
	v_mfma_f32_16x16x32_bf16 v[120:123], v[160:163], v[184:187], v[120:123]
	v_mfma_f32_16x16x32_bf16 v[108:111], v[152:155], v[192:195], v[108:111]
	v_mfma_f32_16x16x32_bf16 v[104:107], v[160:163], v[192:195], v[104:107]
	v_mfma_f32_16x16x32_bf16 v[92:95], v[152:155], v[200:203], v[92:95]
	v_mfma_f32_16x16x32_bf16 v[88:91], v[160:163], v[200:203], v[88:91]
	v_mfma_f32_16x16x32_bf16 v[76:79], v[152:155], v[208:211], v[76:79]
	v_mfma_f32_16x16x32_bf16 v[72:75], v[160:163], v[208:211], v[72:75]
	v_mfma_f32_16x16x32_bf16 v[124:127], v[156:159], v[188:191], v[124:127]
	v_mfma_f32_16x16x32_bf16 v[120:123], v[164:167], v[188:191], v[120:123]
	v_mfma_f32_16x16x32_bf16 v[108:111], v[156:159], v[196:199], v[108:111]
	v_mfma_f32_16x16x32_bf16 v[104:107], v[164:167], v[196:199], v[104:107]
	v_mfma_f32_16x16x32_bf16 v[92:95], v[156:159], v[204:207], v[92:95]
	v_mfma_f32_16x16x32_bf16 v[88:91], v[164:167], v[204:207], v[88:91]
	v_mfma_f32_16x16x32_bf16 v[76:79], v[156:159], v[212:215], v[76:79]
	v_mfma_f32_16x16x32_bf16 v[72:75], v[164:167], v[212:215], v[72:75]
	v_mfma_f32_16x16x32_bf16 v[116:119], v[168:171], v[184:187], v[116:119]
	v_mfma_f32_16x16x32_bf16 v[112:115], v[176:179], v[184:187], v[112:115]
	v_mfma_f32_16x16x32_bf16 v[100:103], v[168:171], v[192:195], v[100:103]
	v_mfma_f32_16x16x32_bf16 v[96:99], v[176:179], v[192:195], v[96:99]
	v_mfma_f32_16x16x32_bf16 v[84:87], v[168:171], v[200:203], v[84:87]
	v_mfma_f32_16x16x32_bf16 v[80:83], v[176:179], v[200:203], v[80:83]
	v_mfma_f32_16x16x32_bf16 v[68:71], v[168:171], v[208:211], v[68:71]
	v_mfma_f32_16x16x32_bf16 v[64:67], v[176:179], v[208:211], v[64:67]
	v_mfma_f32_16x16x32_bf16 v[116:119], v[172:175], v[188:191], v[116:119]
	v_mfma_f32_16x16x32_bf16 v[112:115], v[180:183], v[188:191], v[112:115]
	v_mfma_f32_16x16x32_bf16 v[100:103], v[172:175], v[196:199], v[100:103]
	v_mfma_f32_16x16x32_bf16 v[96:99], v[180:183], v[196:199], v[96:99]
	v_mfma_f32_16x16x32_bf16 v[84:87], v[172:175], v[204:207], v[84:87]
	v_mfma_f32_16x16x32_bf16 v[80:83], v[180:183], v[204:207], v[80:83]
	v_mfma_f32_16x16x32_bf16 v[68:71], v[172:175], v[212:215], v[68:71]
	v_mfma_f32_16x16x32_bf16 v[64:67], v[180:183], v[212:215], v[64:67]
	s_barrier
	s_setprio 0
	s_add_i32 s28, s82, s5
	v_lshl_add_u64 v[144:145], v[144:145], 0, s[10:11]
	s_mov_b32 m0, s28
	ds_read_b128 v[184:187], v151 offset:49152
	ds_read_b128 v[188:191], v151 offset:50176
	ds_read_b128 v[192:195], v151 offset:51200
	ds_read_b128 v[196:199], v151 offset:52224
	ds_read_b128 v[200:203], v151 offset:53248
	ds_read_b128 v[204:207], v151 offset:54272
	ds_read_b128 v[208:211], v151 offset:55296
	ds_read_b128 v[212:215], v151 offset:56320
	global_load_lds_dwordx4 v[144:145], off
	s_add_i32 m0, s28, 0x2000
	s_add_u32 s26, s26, 0x80080
	v_lshl_add_u64 v[144:145], v[216:217], 0, s[10:11]
	s_addc_u32 s27, s27, 0
	s_add_i32 s28, s83, s5
	global_load_lds_dwordx4 v[144:145], off
	s_mov_b32 m0, s28
	s_nop 0
	global_load_lds_dwordx4 v130, s[26:27]
	s_add_i32 m0, s28, 0x2000
	s_nop 0
	global_load_lds_dwordx4 v134, s[26:27]
	s_mov_b32 m0, s37
	s_nop 0
	global_load_lds_dwordx4 v128, s[24:25]
	s_mov_b32 m0, s38
	s_nop 0
	global_load_lds_dwordx4 v132, s[24:25]
	s_waitcnt vmcnt(8)
	s_waitcnt lgkmcnt(0)
	s_setprio 1
	s_barrier
	v_mfma_f32_16x16x32_bf16 v[60:63], v[152:155], v[184:187], v[60:63]
	v_mfma_f32_16x16x32_bf16 v[56:59], v[160:163], v[184:187], v[56:59]
	v_mfma_f32_16x16x32_bf16 v[44:47], v[152:155], v[192:195], v[44:47]
	v_mfma_f32_16x16x32_bf16 v[40:43], v[160:163], v[192:195], v[40:43]
	v_mfma_f32_16x16x32_bf16 v[28:31], v[152:155], v[200:203], v[28:31]
	v_mfma_f32_16x16x32_bf16 v[24:27], v[160:163], v[200:203], v[24:27]
	v_mfma_f32_16x16x32_bf16 v[12:15], v[152:155], v[208:211], v[12:15]
	v_mfma_f32_16x16x32_bf16 v[8:11], v[160:163], v[208:211], v[8:11]
	v_mfma_f32_16x16x32_bf16 v[60:63], v[156:159], v[188:191], v[60:63]
	v_mfma_f32_16x16x32_bf16 v[56:59], v[164:167], v[188:191], v[56:59]
	v_mfma_f32_16x16x32_bf16 v[44:47], v[156:159], v[196:199], v[44:47]
	v_mfma_f32_16x16x32_bf16 v[40:43], v[164:167], v[196:199], v[40:43]
	v_mfma_f32_16x16x32_bf16 v[28:31], v[156:159], v[204:207], v[28:31]
	v_mfma_f32_16x16x32_bf16 v[24:27], v[164:167], v[204:207], v[24:27]
	v_mfma_f32_16x16x32_bf16 v[12:15], v[156:159], v[212:215], v[12:15]
	v_mfma_f32_16x16x32_bf16 v[8:11], v[164:167], v[212:215], v[8:11]
	v_mfma_f32_16x16x32_bf16 v[52:55], v[168:171], v[184:187], v[52:55]
	v_mfma_f32_16x16x32_bf16 v[48:51], v[176:179], v[184:187], v[48:51]
	v_mfma_f32_16x16x32_bf16 v[36:39], v[168:171], v[192:195], v[36:39]
	v_mfma_f32_16x16x32_bf16 v[32:35], v[176:179], v[192:195], v[32:35]
	v_mfma_f32_16x16x32_bf16 v[20:23], v[168:171], v[200:203], v[20:23]
	v_mfma_f32_16x16x32_bf16 v[16:19], v[176:179], v[200:203], v[16:19]
	v_mfma_f32_16x16x32_bf16 v[4:7], v[168:171], v[208:211], v[4:7]
	v_mfma_f32_16x16x32_bf16 v[0:3], v[176:179], v[208:211], v[0:3]
	v_mfma_f32_16x16x32_bf16 v[52:55], v[172:175], v[188:191], v[52:55]
	v_mfma_f32_16x16x32_bf16 v[48:51], v[180:183], v[188:191], v[48:51]
	v_mfma_f32_16x16x32_bf16 v[36:39], v[172:175], v[196:199], v[36:39]
	v_mfma_f32_16x16x32_bf16 v[32:35], v[180:183], v[196:199], v[32:35]
	v_mfma_f32_16x16x32_bf16 v[20:23], v[172:175], v[204:207], v[20:23]
	v_mfma_f32_16x16x32_bf16 v[16:19], v[180:183], v[204:207], v[16:19]
	v_mfma_f32_16x16x32_bf16 v[4:7], v[172:175], v[212:215], v[4:7]
	v_mfma_f32_16x16x32_bf16 v[0:3], v[180:183], v[212:215], v[0:3]
	s_barrier
	s_setprio 0
	s_add_i32 s64, s64, 2
	s_add_u32 s55, s55, 0x100
	s_addc_u32 s56, s56, 0
	s_add_u32 s22, s22, 0x800000
	s_addc_u32 s23, s23, 0
	s_cmp_gt_u32 s64, 29
	s_cbranch_scc0 .LBB0_2664
	s_and_b64 vcc, exec, s[12:13]
	s_cbranch_vccz .LBB0_2667
	s_barrier

.LBB0_2772:
	ds_read_b128 v[128:131], v180
	ds_read_b128 v[132:135], v180 offset:1024
	ds_read_b128 v[136:139], v180 offset:2048
	ds_read_b128 v[140:143], v180 offset:3072
	ds_read_b128 v[144:147], v181
	ds_read_b128 v[148:151], v181 offset:1024
	ds_read_b128 v[152:155], v181 offset:2048
	ds_read_b128 v[156:159], v181 offset:3072
	s_add_u32 s6, s0, 0x3fc000
	s_addc_u32 s7, s1, 0
	s_cmp_eq_u32 s41, 12
	s_cselect_b32 s36, s13, s6
	s_cselect_b32 s37, s10, s7
	s_cselect_b32 s8, s29, s39
	s_cselect_b32 s9, s27, s40
	s_add_u32 s6, s36, 0x400000
	s_addc_u32 s7, s37, 0
	s_add_i32 m0, s25, 0xc000
	ds_read_b128 v[186:189], v182
	ds_read_b128 v[190:193], v182 offset:1024
	ds_read_b128 v[194:197], v182 offset:2048
	ds_read_b128 v[198:201], v182 offset:3072
	ds_read_b128 v[202:205], v182 offset:4096
	ds_read_b128 v[206:209], v182 offset:5120
	ds_read_b128 v[210:213], v182 offset:6144
	ds_read_b128 v[214:217], v182 offset:7168
	global_load_lds_dwordx4 v168, s[0:1]
	s_add_i32 m0, s25, 0xe000
	s_nop 0
	global_load_lds_dwordx4 v170, s[0:1]
	s_waitcnt vmcnt(8)
	s_waitcnt lgkmcnt(0)
	s_setprio 1
	s_barrier
	v_mfma_f32_16x16x32_bf16 v[104:107], v[128:131], v[186:189], v[104:107]
	v_mfma_f32_16x16x32_bf16 v[96:99], v[136:139], v[186:189], v[96:99]
	v_mfma_f32_16x16x32_bf16 v[84:87], v[128:131], v[194:197], v[84:87]
	v_mfma_f32_16x16x32_bf16 v[80:83], v[136:139], v[194:197], v[80:83]
	v_mfma_f32_16x16x32_bf16 v[92:95], v[128:131], v[202:205], v[92:95]
	v_mfma_f32_16x16x32_bf16 v[88:91], v[136:139], v[202:205], v[88:91]
	v_mfma_f32_16x16x32_bf16 v[108:111], v[128:131], v[210:213], v[108:111]
	v_mfma_f32_16x16x32_bf16 v[100:103], v[136:139], v[210:213], v[100:103]
	v_mfma_f32_16x16x32_bf16 v[104:107], v[132:135], v[190:193], v[104:107]
	v_mfma_f32_16x16x32_bf16 v[96:99], v[140:143], v[190:193], v[96:99]
	v_mfma_f32_16x16x32_bf16 v[84:87], v[132:135], v[198:201], v[84:87]
	v_mfma_f32_16x16x32_bf16 v[80:83], v[140:143], v[198:201], v[80:83]
	v_mfma_f32_16x16x32_bf16 v[92:95], v[132:135], v[206:209], v[92:95]
	v_mfma_f32_16x16x32_bf16 v[88:91], v[140:143], v[206:209], v[88:91]
	v_mfma_f32_16x16x32_bf16 v[108:111], v[132:135], v[214:217], v[108:111]
	v_mfma_f32_16x16x32_bf16 v[100:103], v[140:143], v[214:217], v[100:103]
	v_mfma_f32_16x16x32_bf16 v[28:31], v[144:147], v[186:189], v[28:31]
	v_mfma_f32_16x16x32_bf16 v[16:19], v[152:155], v[186:189], v[16:19]
	v_mfma_f32_16x16x32_bf16 v[4:7], v[144:147], v[194:197], v[4:7]
	v_mfma_f32_16x16x32_bf16 v[0:3], v[152:155], v[194:197], v[0:3]
	v_mfma_f32_16x16x32_bf16 v[12:15], v[144:147], v[202:205], v[12:15]
	v_mfma_f32_16x16x32_bf16 v[8:11], v[152:155], v[202:205], v[8:11]
	v_mfma_f32_16x16x32_bf16 v[24:27], v[144:147], v[210:213], v[24:27]
	v_mfma_f32_16x16x32_bf16 v[20:23], v[152:155], v[210:213], v[20:23]
	v_mfma_f32_16x16x32_bf16 v[28:31], v[148:151], v[190:193], v[28:31]
	v_mfma_f32_16x16x32_bf16 v[16:19], v[156:159], v[190:193], v[16:19]
	v_mfma_f32_16x16x32_bf16 v[4:7], v[148:151], v[198:201], v[4:7]
	v_mfma_f32_16x16x32_bf16 v[0:3], v[156:159], v[198:201], v[0:3]
	v_mfma_f32_16x16x32_bf16 v[12:15], v[148:151], v[206:209], v[12:15]
	v_mfma_f32_16x16x32_bf16 v[8:11], v[156:159], v[206:209], v[8:11]
	v_mfma_f32_16x16x32_bf16 v[24:27], v[148:151], v[214:217], v[24:27]
	v_mfma_f32_16x16x32_bf16 v[20:23], v[156:159], v[214:217], v[20:23]
	s_barrier
	s_setprio 0
	s_add_i32 s42, s57, s3
	v_lshl_add_u64 v[174:175], s[8:9], 0, v[162:163]
	s_mov_b32 m0, s42
	ds_read_b128 v[186:189], v182 offset:16384
	ds_read_b128 v[190:193], v182 offset:17408
	ds_read_b128 v[194:197], v182 offset:18432
	ds_read_b128 v[198:201], v182 offset:19456
	ds_read_b128 v[202:205], v182 offset:20480
	ds_read_b128 v[206:209], v182 offset:21504
	ds_read_b128 v[210:213], v182 offset:22528
	ds_read_b128 v[214:217], v182 offset:23552
	global_load_lds_dwordx4 v[174:175], off
	s_add_i32 m0, s42, 0x2000
	s_add_u32 s42, s8, 0x40000
	v_lshl_add_u64 v[218:219], s[8:9], 0, v[166:167]
	s_addc_u32 s43, s9, 0
	s_add_i32 s44, s81, s3
	global_load_lds_dwordx4 v[218:219], off
	s_mov_b32 m0, s44
	s_nop 0
	global_load_lds_dwordx4 v162, s[42:43]
	s_add_i32 m0, s44, 0x2000
	s_nop 0
	global_load_lds_dwordx4 v166, s[42:43]
	s_mov_b32 m0, s25
	s_nop 0
	global_load_lds_dwordx4 v160, s[36:37]
	s_mov_b32 m0, s33
	s_nop 0
	global_load_lds_dwordx4 v164, s[36:37]
	s_waitcnt vmcnt(8)
	s_waitcnt lgkmcnt(0)
	s_setprio 1
	s_barrier
	v_mfma_f32_16x16x32_bf16 v[116:119], v[128:131], v[186:189], v[116:119]
	v_mfma_f32_16x16x32_bf16 v[112:115], v[136:139], v[186:189], v[112:115]
	v_mfma_f32_16x16x32_bf16 v[124:127], v[128:131], v[194:197], v[124:127]
	v_mfma_f32_16x16x32_bf16 v[120:123], v[136:139], v[194:197], v[120:123]
	v_mfma_f32_16x16x32_bf16 v[76:79], v[128:131], v[202:205], v[76:79]
	v_mfma_f32_16x16x32_bf16 v[72:75], v[136:139], v[202:205], v[72:75]
	v_mfma_f32_16x16x32_bf16 v[68:71], v[128:131], v[210:213], v[68:71]
	v_mfma_f32_16x16x32_bf16 v[64:67], v[136:139], v[210:213], v[64:67]
	v_mfma_f32_16x16x32_bf16 v[116:119], v[132:135], v[190:193], v[116:119]
	v_mfma_f32_16x16x32_bf16 v[112:115], v[140:143], v[190:193], v[112:115]
	v_mfma_f32_16x16x32_bf16 v[124:127], v[132:135], v[198:201], v[124:127]
	v_mfma_f32_16x16x32_bf16 v[120:123], v[140:143], v[198:201], v[120:123]
	v_mfma_f32_16x16x32_bf16 v[76:79], v[132:135], v[206:209], v[76:79]
	v_mfma_f32_16x16x32_bf16 v[72:75], v[140:143], v[206:209], v[72:75]
	v_mfma_f32_16x16x32_bf16 v[68:71], v[132:135], v[214:217], v[68:71]
	v_mfma_f32_16x16x32_bf16 v[64:67], v[140:143], v[214:217], v[64:67]
	v_mfma_f32_16x16x32_bf16 v[36:39], v[144:147], v[186:189], v[36:39]
	v_mfma_f32_16x16x32_bf16 v[32:35], v[152:155], v[186:189], v[32:35]
	v_mfma_f32_16x16x32_bf16 v[44:47], v[144:147], v[194:197], v[44:47]
	v_mfma_f32_16x16x32_bf16 v[40:43], v[152:155], v[194:197], v[40:43]
	v_mfma_f32_16x16x32_bf16 v[52:55], v[144:147], v[202:205], v[52:55]
	v_mfma_f32_16x16x32_bf16 v[48:51], v[152:155], v[202:205], v[48:51]
	v_mfma_f32_16x16x32_bf16 v[60:63], v[144:147], v[210:213], v[60:63]
	v_mfma_f32_16x16x32_bf16 v[56:59], v[152:155], v[210:213], v[56:59]
	v_mfma_f32_16x16x32_bf16 v[36:39], v[148:151], v[190:193], v[36:39]
	v_mfma_f32_16x16x32_bf16 v[32:35], v[156:159], v[190:193], v[32:35]
	v_mfma_f32_16x16x32_bf16 v[44:47], v[148:151], v[198:201], v[44:47]
	v_mfma_f32_16x16x32_bf16 v[40:43], v[156:159], v[198:201], v[40:43]
	v_mfma_f32_16x16x32_bf16 v[52:55], v[148:151], v[206:209], v[52:55]
	v_mfma_f32_16x16x32_bf16 v[48:51], v[156:159], v[206:209], v[48:51]
	v_mfma_f32_16x16x32_bf16 v[60:63], v[148:151], v[214:217], v[60:63]
	v_mfma_f32_16x16x32_bf16 v[56:59], v[156:159], v[214:217], v[56:59]
	s_barrier
	s_setprio 0
	v_add_u32_e32 v140, s82, v179
	v_add_u32_e32 v156, s83, v179
	ds_read_b128 v[128:131], v140
	ds_read_b128 v[132:135], v140 offset:1024
	ds_read_b128 v[136:139], v140 offset:2048
	ds_read_b128 v[140:143], v140 offset:3072
	ds_read_b128 v[144:147], v156
	ds_read_b128 v[148:151], v156 offset:1024
	ds_read_b128 v[152:155], v156 offset:2048
	ds_read_b128 v[156:159], v156 offset:3072
	s_add_u32 s36, s36, 0x4000
	s_addc_u32 s37, s37, 0
	s_mov_b32 m0, s46
	ds_read_b128 v[186:189], v182 offset:32768
	ds_read_b128 v[190:193], v182 offset:33792
	ds_read_b128 v[194:197], v182 offset:34816
	ds_read_b128 v[198:201], v182 offset:35840
	ds_read_b128 v[202:205], v182 offset:36864
	ds_read_b128 v[206:209], v182 offset:37888
	ds_read_b128 v[210:213], v182 offset:38912
	ds_read_b128 v[214:217], v182 offset:39936
	global_load_lds_dwordx4 v160, s[36:37]
	v_lshl_add_u64 v[220:221], s[36:37], 0, v[164:165]
	s_mov_b32 m0, s47
	s_nop 0
	global_load_lds_dwordx4 v[220:221], off
	s_waitcnt vmcnt(8)
	s_waitcnt lgkmcnt(0)
	s_setprio 1
	s_barrier
	v_mfma_f32_16x16x32_bf16 v[104:107], v[128:131], v[186:189], v[104:107]
	v_mfma_f32_16x16x32_bf16 v[96:99], v[136:139], v[186:189], v[96:99]
	v_mfma_f32_16x16x32_bf16 v[84:87], v[128:131], v[194:197], v[84:87]
	v_mfma_f32_16x16x32_bf16 v[80:83], v[136:139], v[194:197], v[80:83]
	v_mfma_f32_16x16x32_bf16 v[92:95], v[128:131], v[202:205], v[92:95]
	v_mfma_f32_16x16x32_bf16 v[88:91], v[136:139], v[202:205], v[88:91]
	v_mfma_f32_16x16x32_bf16 v[108:111], v[128:131], v[210:213], v[108:111]
	v_mfma_f32_16x16x32_bf16 v[100:103], v[136:139], v[210:213], v[100:103]
	v_mfma_f32_16x16x32_bf16 v[104:107], v[132:135], v[190:193], v[104:107]
	v_mfma_f32_16x16x32_bf16 v[96:99], v[140:143], v[190:193], v[96:99]
	v_mfma_f32_16x16x32_bf16 v[84:87], v[132:135], v[198:201], v[84:87]
	v_mfma_f32_16x16x32_bf16 v[80:83], v[140:143], v[198:201], v[80:83]
	v_mfma_f32_16x16x32_bf16 v[92:95], v[132:135], v[206:209], v[92:95]
	v_mfma_f32_16x16x32_bf16 v[88:91], v[140:143], v[206:209], v[88:91]
	v_mfma_f32_16x16x32_bf16 v[108:111], v[132:135], v[214:217], v[108:111]
	v_mfma_f32_16x16x32_bf16 v[100:103], v[140:143], v[214:217], v[100:103]
	v_mfma_f32_16x16x32_bf16 v[28:31], v[144:147], v[186:189], v[28:31]
	v_mfma_f32_16x16x32_bf16 v[16:19], v[152:155], v[186:189], v[16:19]
	v_mfma_f32_16x16x32_bf16 v[4:7], v[144:147], v[194:197], v[4:7]
	v_mfma_f32_16x16x32_bf16 v[0:3], v[152:155], v[194:197], v[0:3]
	v_mfma_f32_16x16x32_bf16 v[12:15], v[144:147], v[202:205], v[12:15]
	v_mfma_f32_16x16x32_bf16 v[8:11], v[152:155], v[202:205], v[8:11]
	v_mfma_f32_16x16x32_bf16 v[24:27], v[144:147], v[210:213], v[24:27]
	v_mfma_f32_16x16x32_bf16 v[20:23], v[152:155], v[210:213], v[20:23]
	v_mfma_f32_16x16x32_bf16 v[28:31], v[148:151], v[190:193], v[28:31]
	v_mfma_f32_16x16x32_bf16 v[16:19], v[156:159], v[190:193], v[16:19]
	v_mfma_f32_16x16x32_bf16 v[4:7], v[148:151], v[198:201], v[4:7]
	v_mfma_f32_16x16x32_bf16 v[0:3], v[156:159], v[198:201], v[0:3]
	v_mfma_f32_16x16x32_bf16 v[12:15], v[148:151], v[206:209], v[12:15]
	v_mfma_f32_16x16x32_bf16 v[8:11], v[156:159], v[206:209], v[8:11]
	v_mfma_f32_16x16x32_bf16 v[24:27], v[148:151], v[214:217], v[24:27]
	v_mfma_f32_16x16x32_bf16 v[20:23], v[156:159], v[214:217], v[20:23]
	s_barrier
	s_setprio 0
	s_add_i32 s36, s82, s3
	v_lshl_add_u64 v[174:175], v[174:175], 0, s[20:21]
	s_mov_b32 m0, s36
	ds_read_b128 v[186:189], v182 offset:49152
	ds_read_b128 v[190:193], v182 offset:50176
	ds_read_b128 v[194:197], v182 offset:51200
	ds_read_b128 v[198:201], v182 offset:52224
	ds_read_b128 v[202:205], v182 offset:53248
	ds_read_b128 v[206:209], v182 offset:54272
	ds_read_b128 v[210:213], v182 offset:55296
	ds_read_b128 v[214:217], v182 offset:56320
	global_load_lds_dwordx4 v[174:175], off
	s_add_i32 m0, s36, 0x2000
	s_add_u32 s8, s8, 0x40080
	v_lshl_add_u64 v[174:175], v[218:219], 0, s[20:21]
	s_addc_u32 s9, s9, 0
	s_add_i32 s36, s83, s3
	global_load_lds_dwordx4 v[174:175], off
	s_mov_b32 m0, s36
	s_nop 0
	global_load_lds_dwordx4 v162, s[8:9]
	s_add_i32 m0, s36, 0x2000
	s_nop 0
	global_load_lds_dwordx4 v166, s[8:9]
	s_mov_b32 m0, s54
	s_nop 0
	global_load_lds_dwordx4 v160, s[6:7]
	s_mov_b32 m0, s55
	s_nop 0
	global_load_lds_dwordx4 v164, s[6:7]
	s_waitcnt vmcnt(8)
	s_waitcnt lgkmcnt(0)
	s_setprio 1
	s_barrier
	v_mfma_f32_16x16x32_bf16 v[116:119], v[128:131], v[186:189], v[116:119]
	v_mfma_f32_16x16x32_bf16 v[112:115], v[136:139], v[186:189], v[112:115]
	v_mfma_f32_16x16x32_bf16 v[124:127], v[128:131], v[194:197], v[124:127]
	v_mfma_f32_16x16x32_bf16 v[120:123], v[136:139], v[194:197], v[120:123]
	v_mfma_f32_16x16x32_bf16 v[76:79], v[128:131], v[202:205], v[76:79]
	v_mfma_f32_16x16x32_bf16 v[72:75], v[136:139], v[202:205], v[72:75]
	v_mfma_f32_16x16x32_bf16 v[68:71], v[128:131], v[210:213], v[68:71]
	v_mfma_f32_16x16x32_bf16 v[64:67], v[136:139], v[210:213], v[64:67]
	v_mfma_f32_16x16x32_bf16 v[116:119], v[132:135], v[190:193], v[116:119]
	v_mfma_f32_16x16x32_bf16 v[112:115], v[140:143], v[190:193], v[112:115]
	v_mfma_f32_16x16x32_bf16 v[124:127], v[132:135], v[198:201], v[124:127]
	v_mfma_f32_16x16x32_bf16 v[120:123], v[140:143], v[198:201], v[120:123]
	v_mfma_f32_16x16x32_bf16 v[76:79], v[132:135], v[206:209], v[76:79]
	v_mfma_f32_16x16x32_bf16 v[72:75], v[140:143], v[206:209], v[72:75]
	v_mfma_f32_16x16x32_bf16 v[68:71], v[132:135], v[214:217], v[68:71]
	v_mfma_f32_16x16x32_bf16 v[64:67], v[140:143], v[214:217], v[64:67]
	v_mfma_f32_16x16x32_bf16 v[36:39], v[144:147], v[186:189], v[36:39]
	v_mfma_f32_16x16x32_bf16 v[32:35], v[152:155], v[186:189], v[32:35]
	v_mfma_f32_16x16x32_bf16 v[44:47], v[144:147], v[194:197], v[44:47]
	v_mfma_f32_16x16x32_bf16 v[40:43], v[152:155], v[194:197], v[40:43]
	v_mfma_f32_16x16x32_bf16 v[52:55], v[144:147], v[202:205], v[52:55]
	v_mfma_f32_16x16x32_bf16 v[48:51], v[152:155], v[202:205], v[48:51]
	v_mfma_f32_16x16x32_bf16 v[60:63], v[144:147], v[210:213], v[60:63]
	v_mfma_f32_16x16x32_bf16 v[56:59], v[152:155], v[210:213], v[56:59]
	v_mfma_f32_16x16x32_bf16 v[36:39], v[148:151], v[190:193], v[36:39]
	v_mfma_f32_16x16x32_bf16 v[32:35], v[156:159], v[190:193], v[32:35]
	v_mfma_f32_16x16x32_bf16 v[44:47], v[148:151], v[198:201], v[44:47]
	v_mfma_f32_16x16x32_bf16 v[40:43], v[156:159], v[198:201], v[40:43]
	v_mfma_f32_16x16x32_bf16 v[52:55], v[148:151], v[206:209], v[52:55]
	v_mfma_f32_16x16x32_bf16 v[48:51], v[156:159], v[206:209], v[48:51]
	v_mfma_f32_16x16x32_bf16 v[60:63], v[148:151], v[214:217], v[60:63]
	v_mfma_f32_16x16x32_bf16 v[56:59], v[156:159], v[214:217], v[56:59]
	s_barrier
	s_setprio 0
	s_add_i32 s41, s41, 2
	s_add_u32 s39, s39, 0x100
	s_addc_u32 s40, s40, 0
	s_add_u32 s0, s0, 0x800000
	s_addc_u32 s1, s1, 0
	s_cmp_gt_u32 s41, 13
	s_cbranch_scc0 .LBB0_2772
	s_and_b64 vcc, exec, s[22:23]
	s_cbranch_vccz .LBB0_2775
	s_barrier

.LBB0_2888:
	ds_read_b128 v[152:155], v149
	ds_read_b128 v[156:159], v149 offset:1024
	ds_read_b128 v[160:163], v149 offset:2048
	ds_read_b128 v[164:167], v149 offset:3072
	ds_read_b128 v[168:171], v150
	ds_read_b128 v[172:175], v150 offset:1024
	ds_read_b128 v[176:179], v150 offset:2048
	ds_read_b128 v[180:183], v150 offset:3072
	s_add_u32 s24, s22, 0x3fc000
	s_addc_u32 s25, s23, 0
	s_cmp_eq_u32 s54, 28
	s_cselect_b32 s28, s50, s24
	s_cselect_b32 s29, s15, s25
	s_cselect_b32 s26, s51, s52
	s_cselect_b32 s27, s17, s53
	s_add_u32 s24, s28, 0x400000
	s_addc_u32 s25, s29, 0
	s_add_i32 m0, s31, 0xc000
	ds_read_b128 v[184:187], v151
	ds_read_b128 v[188:191], v151 offset:1024
	ds_read_b128 v[192:195], v151 offset:2048
	ds_read_b128 v[196:199], v151 offset:3072
	ds_read_b128 v[200:203], v151 offset:4096
	ds_read_b128 v[204:207], v151 offset:5120
	ds_read_b128 v[208:211], v151 offset:6144
	ds_read_b128 v[212:215], v151 offset:7168
	global_load_lds_dwordx4 v136, s[22:23]
	s_add_i32 m0, s31, 0xe000
	s_nop 0
	global_load_lds_dwordx4 v138, s[22:23]
	s_waitcnt vmcnt(8)
	s_waitcnt lgkmcnt(0)
	s_setprio 1
	s_barrier
	v_mfma_f32_16x16x32_bf16 v[124:127], v[152:155], v[184:187], v[124:127]
	v_mfma_f32_16x16x32_bf16 v[120:123], v[160:163], v[184:187], v[120:123]
	v_mfma_f32_16x16x32_bf16 v[108:111], v[152:155], v[192:195], v[108:111]
	v_mfma_f32_16x16x32_bf16 v[104:107], v[160:163], v[192:195], v[104:107]
	v_mfma_f32_16x16x32_bf16 v[92:95], v[152:155], v[200:203], v[92:95]
	v_mfma_f32_16x16x32_bf16 v[88:91], v[160:163], v[200:203], v[88:91]
	v_mfma_f32_16x16x32_bf16 v[76:79], v[152:155], v[208:211], v[76:79]
	v_mfma_f32_16x16x32_bf16 v[72:75], v[160:163], v[208:211], v[72:75]
	v_mfma_f32_16x16x32_bf16 v[124:127], v[156:159], v[188:191], v[124:127]
	v_mfma_f32_16x16x32_bf16 v[120:123], v[164:167], v[188:191], v[120:123]
	v_mfma_f32_16x16x32_bf16 v[108:111], v[156:159], v[196:199], v[108:111]
	v_mfma_f32_16x16x32_bf16 v[104:107], v[164:167], v[196:199], v[104:107]
	v_mfma_f32_16x16x32_bf16 v[92:95], v[156:159], v[204:207], v[92:95]
	v_mfma_f32_16x16x32_bf16 v[88:91], v[164:167], v[204:207], v[88:91]
	v_mfma_f32_16x16x32_bf16 v[76:79], v[156:159], v[212:215], v[76:79]
	v_mfma_f32_16x16x32_bf16 v[72:75], v[164:167], v[212:215], v[72:75]
	v_mfma_f32_16x16x32_bf16 v[116:119], v[168:171], v[184:187], v[116:119]
	v_mfma_f32_16x16x32_bf16 v[112:115], v[176:179], v[184:187], v[112:115]
	v_mfma_f32_16x16x32_bf16 v[100:103], v[168:171], v[192:195], v[100:103]
	v_mfma_f32_16x16x32_bf16 v[96:99], v[176:179], v[192:195], v[96:99]
	v_mfma_f32_16x16x32_bf16 v[84:87], v[168:171], v[200:203], v[84:87]
	v_mfma_f32_16x16x32_bf16 v[80:83], v[176:179], v[200:203], v[80:83]
	v_mfma_f32_16x16x32_bf16 v[68:71], v[168:171], v[208:211], v[68:71]
	v_mfma_f32_16x16x32_bf16 v[64:67], v[176:179], v[208:211], v[64:67]
	v_mfma_f32_16x16x32_bf16 v[116:119], v[172:175], v[188:191], v[116:119]
	v_mfma_f32_16x16x32_bf16 v[112:115], v[180:183], v[188:191], v[112:115]
	v_mfma_f32_16x16x32_bf16 v[100:103], v[172:175], v[196:199], v[100:103]
	v_mfma_f32_16x16x32_bf16 v[96:99], v[180:183], v[196:199], v[96:99]
	v_mfma_f32_16x16x32_bf16 v[84:87], v[172:175], v[204:207], v[84:87]
	v_mfma_f32_16x16x32_bf16 v[80:83], v[180:183], v[204:207], v[80:83]
	v_mfma_f32_16x16x32_bf16 v[68:71], v[172:175], v[212:215], v[68:71]
	v_mfma_f32_16x16x32_bf16 v[64:67], v[180:183], v[212:215], v[64:67]
	s_barrier
	s_setprio 0
	s_add_i32 s55, s57, s30
	s_mov_b32 m0, s55
	ds_read_b128 v[184:187], v151 offset:16384
	ds_read_b128 v[188:191], v151 offset:17408
	ds_read_b128 v[192:195], v151 offset:18432
	ds_read_b128 v[196:199], v151 offset:19456
	ds_read_b128 v[200:203], v151 offset:20480
	ds_read_b128 v[204:207], v151 offset:21504
	ds_read_b128 v[208:211], v151 offset:22528
	ds_read_b128 v[212:215], v151 offset:23552
	global_load_lds_dwordx4 v132, s[26:27]
	s_add_i32 m0, s55, 0x2000
	s_add_u32 s64, s26, 0x4000
	s_addc_u32 s65, s27, 0
	s_add_i32 s55, s81, s30
	global_load_lds_dwordx4 v128, s[26:27]
	s_mov_b32 m0, s55
	s_nop 0
	global_load_lds_dwordx4 v132, s[64:65]
	s_add_i32 m0, s55, 0x2000
	s_nop 0
	global_load_lds_dwordx4 v128, s[64:65]
	s_mov_b32 m0, s31
	s_nop 0
	global_load_lds_dwordx4 v134, s[28:29]
	s_mov_b32 m0, s33
	s_nop 0
	global_load_lds_dwordx4 v130, s[28:29]
	s_waitcnt vmcnt(8)
	s_waitcnt lgkmcnt(0)
	s_setprio 1
	s_barrier
	v_mfma_f32_16x16x32_bf16 v[60:63], v[152:155], v[184:187], v[60:63]
	v_mfma_f32_16x16x32_bf16 v[56:59], v[160:163], v[184:187], v[56:59]
	v_mfma_f32_16x16x32_bf16 v[44:47], v[152:155], v[192:195], v[44:47]
	v_mfma_f32_16x16x32_bf16 v[40:43], v[160:163], v[192:195], v[40:43]
	v_mfma_f32_16x16x32_bf16 v[28:31], v[152:155], v[200:203], v[28:31]
	v_mfma_f32_16x16x32_bf16 v[24:27], v[160:163], v[200:203], v[24:27]
	v_mfma_f32_16x16x32_bf16 v[12:15], v[152:155], v[208:211], v[12:15]
	v_mfma_f32_16x16x32_bf16 v[8:11], v[160:163], v[208:211], v[8:11]
	v_mfma_f32_16x16x32_bf16 v[60:63], v[156:159], v[188:191], v[60:63]
	v_mfma_f32_16x16x32_bf16 v[56:59], v[164:167], v[188:191], v[56:59]
	v_mfma_f32_16x16x32_bf16 v[44:47], v[156:159], v[196:199], v[44:47]
	v_mfma_f32_16x16x32_bf16 v[40:43], v[164:167], v[196:199], v[40:43]
	v_mfma_f32_16x16x32_bf16 v[28:31], v[156:159], v[204:207], v[28:31]
	v_mfma_f32_16x16x32_bf16 v[24:27], v[164:167], v[204:207], v[24:27]
	v_mfma_f32_16x16x32_bf16 v[12:15], v[156:159], v[212:215], v[12:15]
	v_mfma_f32_16x16x32_bf16 v[8:11], v[164:167], v[212:215], v[8:11]
	v_mfma_f32_16x16x32_bf16 v[52:55], v[168:171], v[184:187], v[52:55]
	v_mfma_f32_16x16x32_bf16 v[48:51], v[176:179], v[184:187], v[48:51]
	v_mfma_f32_16x16x32_bf16 v[36:39], v[168:171], v[192:195], v[36:39]
	v_mfma_f32_16x16x32_bf16 v[32:35], v[176:179], v[192:195], v[32:35]
	v_mfma_f32_16x16x32_bf16 v[20:23], v[168:171], v[200:203], v[20:23]
	v_mfma_f32_16x16x32_bf16 v[16:19], v[176:179], v[200:203], v[16:19]
	v_mfma_f32_16x16x32_bf16 v[4:7], v[168:171], v[208:211], v[4:7]
	v_mfma_f32_16x16x32_bf16 v[0:3], v[176:179], v[208:211], v[0:3]
	v_mfma_f32_16x16x32_bf16 v[52:55], v[172:175], v[188:191], v[52:55]
	v_mfma_f32_16x16x32_bf16 v[48:51], v[180:183], v[188:191], v[48:51]
	v_mfma_f32_16x16x32_bf16 v[36:39], v[172:175], v[196:199], v[36:39]
	v_mfma_f32_16x16x32_bf16 v[32:35], v[180:183], v[196:199], v[32:35]
	v_mfma_f32_16x16x32_bf16 v[20:23], v[172:175], v[204:207], v[20:23]
	v_mfma_f32_16x16x32_bf16 v[16:19], v[180:183], v[204:207], v[16:19]
	v_mfma_f32_16x16x32_bf16 v[4:7], v[172:175], v[212:215], v[4:7]
	v_mfma_f32_16x16x32_bf16 v[0:3], v[180:183], v[212:215], v[0:3]
	s_barrier
	s_setprio 0
	v_add_u32_e32 v144, s82, v148
	ds_read_b128 v[152:155], v144
	ds_read_b128 v[156:159], v144 offset:1024
	ds_read_b128 v[160:163], v144 offset:2048
	ds_read_b128 v[164:167], v144 offset:3072
	v_add_u32_e32 v144, s83, v148
	ds_read_b128 v[168:171], v144
	ds_read_b128 v[172:175], v144 offset:1024
	ds_read_b128 v[176:179], v144 offset:2048
	ds_read_b128 v[180:183], v144 offset:3072
	s_add_u32 s28, s28, 0x4000
	s_addc_u32 s29, s29, 0
	s_mov_b32 m0, s34
	ds_read_b128 v[184:187], v151 offset:32768
	ds_read_b128 v[188:191], v151 offset:33792
	ds_read_b128 v[192:195], v151 offset:34816
	ds_read_b128 v[196:199], v151 offset:35840
	ds_read_b128 v[200:203], v151 offset:36864
	ds_read_b128 v[204:207], v151 offset:37888
	ds_read_b128 v[208:211], v151 offset:38912
	ds_read_b128 v[212:215], v151 offset:39936
	global_load_lds_dwordx4 v134, s[28:29]
	s_mov_b32 m0, s35
	s_nop 0
	global_load_lds_dwordx4 v130, s[28:29]
	s_waitcnt vmcnt(8)
	s_waitcnt lgkmcnt(0)
	s_setprio 1
	s_barrier
	v_mfma_f32_16x16x32_bf16 v[124:127], v[152:155], v[184:187], v[124:127]
	v_mfma_f32_16x16x32_bf16 v[120:123], v[160:163], v[184:187], v[120:123]
	v_mfma_f32_16x16x32_bf16 v[108:111], v[152:155], v[192:195], v[108:111]
	v_mfma_f32_16x16x32_bf16 v[104:107], v[160:163], v[192:195], v[104:107]
	v_mfma_f32_16x16x32_bf16 v[92:95], v[152:155], v[200:203], v[92:95]
	v_mfma_f32_16x16x32_bf16 v[88:91], v[160:163], v[200:203], v[88:91]
	v_mfma_f32_16x16x32_bf16 v[76:79], v[152:155], v[208:211], v[76:79]
	v_mfma_f32_16x16x32_bf16 v[72:75], v[160:163], v[208:211], v[72:75]
	v_mfma_f32_16x16x32_bf16 v[124:127], v[156:159], v[188:191], v[124:127]
	v_mfma_f32_16x16x32_bf16 v[120:123], v[164:167], v[188:191], v[120:123]
	v_mfma_f32_16x16x32_bf16 v[108:111], v[156:159], v[196:199], v[108:111]
	v_mfma_f32_16x16x32_bf16 v[104:107], v[164:167], v[196:199], v[104:107]
	v_mfma_f32_16x16x32_bf16 v[92:95], v[156:159], v[204:207], v[92:95]
	v_mfma_f32_16x16x32_bf16 v[88:91], v[164:167], v[204:207], v[88:91]
	v_mfma_f32_16x16x32_bf16 v[76:79], v[156:159], v[212:215], v[76:79]
	v_mfma_f32_16x16x32_bf16 v[72:75], v[164:167], v[212:215], v[72:75]
	v_mfma_f32_16x16x32_bf16 v[116:119], v[168:171], v[184:187], v[116:119]
	v_mfma_f32_16x16x32_bf16 v[112:115], v[176:179], v[184:187], v[112:115]
	v_mfma_f32_16x16x32_bf16 v[100:103], v[168:171], v[192:195], v[100:103]
	v_mfma_f32_16x16x32_bf16 v[96:99], v[176:179], v[192:195], v[96:99]
	v_mfma_f32_16x16x32_bf16 v[84:87], v[168:171], v[200:203], v[84:87]
	v_mfma_f32_16x16x32_bf16 v[80:83], v[176:179], v[200:203], v[80:83]
	v_mfma_f32_16x16x32_bf16 v[68:71], v[168:171], v[208:211], v[68:71]
	v_mfma_f32_16x16x32_bf16 v[64:67], v[176:179], v[208:211], v[64:67]
	v_mfma_f32_16x16x32_bf16 v[116:119], v[172:175], v[188:191], v[116:119]
	v_mfma_f32_16x16x32_bf16 v[112:115], v[180:183], v[188:191], v[112:115]
	v_mfma_f32_16x16x32_bf16 v[100:103], v[172:175], v[196:199], v[100:103]
	v_mfma_f32_16x16x32_bf16 v[96:99], v[180:183], v[196:199], v[96:99]
	v_mfma_f32_16x16x32_bf16 v[84:87], v[172:175], v[204:207], v[84:87]
	v_mfma_f32_16x16x32_bf16 v[80:83], v[180:183], v[204:207], v[80:83]
	v_mfma_f32_16x16x32_bf16 v[68:71], v[172:175], v[212:215], v[68:71]
	v_mfma_f32_16x16x32_bf16 v[64:67], v[180:183], v[212:215], v[64:67]
	s_barrier
	s_setprio 0
	s_add_u32 s28, s26, 0x160000
	s_addc_u32 s29, s27, 0
	s_add_i32 s55, s82, s30
	s_mov_b32 m0, s55
	ds_read_b128 v[184:187], v151 offset:49152
	ds_read_b128 v[188:191], v151 offset:50176
	ds_read_b128 v[192:195], v151 offset:51200
	ds_read_b128 v[196:199], v151 offset:52224
	ds_read_b128 v[200:203], v151 offset:53248
	ds_read_b128 v[204:207], v151 offset:54272
	ds_read_b128 v[208:211], v151 offset:55296
	ds_read_b128 v[212:215], v151 offset:56320
	global_load_lds_dwordx4 v132, s[28:29]
	s_add_i32 m0, s55, 0x2000
	s_add_u32 s26, s26, 0x164000
	global_load_lds_dwordx4 v128, s[28:29]
	s_addc_u32 s27, s27, 0
	s_add_i32 s28, s83, s30
	s_mov_b32 m0, s28
	s_nop 0
	global_load_lds_dwordx4 v132, s[26:27]
	s_add_i32 m0, s28, 0x2000
	s_nop 0
	global_load_lds_dwordx4 v128, s[26:27]
	s_mov_b32 m0, s38
	s_nop 0
	global_load_lds_dwordx4 v134, s[24:25]
	s_mov_b32 m0, s39
	s_nop 0
	global_load_lds_dwordx4 v130, s[24:25]
	s_waitcnt vmcnt(8)
	s_waitcnt lgkmcnt(0)
	s_setprio 1
	s_barrier
	v_mfma_f32_16x16x32_bf16 v[60:63], v[152:155], v[184:187], v[60:63]
	v_mfma_f32_16x16x32_bf16 v[56:59], v[160:163], v[184:187], v[56:59]
	v_mfma_f32_16x16x32_bf16 v[44:47], v[152:155], v[192:195], v[44:47]
	v_mfma_f32_16x16x32_bf16 v[40:43], v[160:163], v[192:195], v[40:43]
	v_mfma_f32_16x16x32_bf16 v[28:31], v[152:155], v[200:203], v[28:31]
	v_mfma_f32_16x16x32_bf16 v[24:27], v[160:163], v[200:203], v[24:27]
	v_mfma_f32_16x16x32_bf16 v[12:15], v[152:155], v[208:211], v[12:15]
	v_mfma_f32_16x16x32_bf16 v[8:11], v[160:163], v[208:211], v[8:11]
	v_mfma_f32_16x16x32_bf16 v[60:63], v[156:159], v[188:191], v[60:63]
	v_mfma_f32_16x16x32_bf16 v[56:59], v[164:167], v[188:191], v[56:59]
	v_mfma_f32_16x16x32_bf16 v[44:47], v[156:159], v[196:199], v[44:47]
	v_mfma_f32_16x16x32_bf16 v[40:43], v[164:167], v[196:199], v[40:43]
	v_mfma_f32_16x16x32_bf16 v[28:31], v[156:159], v[204:207], v[28:31]
	v_mfma_f32_16x16x32_bf16 v[24:27], v[164:167], v[204:207], v[24:27]
	v_mfma_f32_16x16x32_bf16 v[12:15], v[156:159], v[212:215], v[12:15]
	v_mfma_f32_16x16x32_bf16 v[8:11], v[164:167], v[212:215], v[8:11]
	v_mfma_f32_16x16x32_bf16 v[52:55], v[168:171], v[184:187], v[52:55]
	v_mfma_f32_16x16x32_bf16 v[48:51], v[176:179], v[184:187], v[48:51]
	v_mfma_f32_16x16x32_bf16 v[36:39], v[168:171], v[192:195], v[36:39]
	v_mfma_f32_16x16x32_bf16 v[32:35], v[176:179], v[192:195], v[32:35]
	v_mfma_f32_16x16x32_bf16 v[20:23], v[168:171], v[200:203], v[20:23]
	v_mfma_f32_16x16x32_bf16 v[16:19], v[176:179], v[200:203], v[16:19]
	v_mfma_f32_16x16x32_bf16 v[4:7], v[168:171], v[208:211], v[4:7]
	v_mfma_f32_16x16x32_bf16 v[0:3], v[176:179], v[208:211], v[0:3]
	v_mfma_f32_16x16x32_bf16 v[52:55], v[172:175], v[188:191], v[52:55]
	v_mfma_f32_16x16x32_bf16 v[48:51], v[180:183], v[188:191], v[48:51]
	v_mfma_f32_16x16x32_bf16 v[36:39], v[172:175], v[196:199], v[36:39]
	v_mfma_f32_16x16x32_bf16 v[32:35], v[180:183], v[196:199], v[32:35]
	v_mfma_f32_16x16x32_bf16 v[20:23], v[172:175], v[204:207], v[20:23]
	v_mfma_f32_16x16x32_bf16 v[16:19], v[180:183], v[204:207], v[16:19]
	v_mfma_f32_16x16x32_bf16 v[4:7], v[172:175], v[212:215], v[4:7]
	v_mfma_f32_16x16x32_bf16 v[0:3], v[180:183], v[212:215], v[0:3]
	s_barrier
	s_setprio 0
	s_add_i32 s54, s54, 2
	s_add_u32 s52, s52, 0x2c0000
	s_addc_u32 s53, s53, 0
	s_add_u32 s22, s22, 0x800000
	s_addc_u32 s23, s23, 0
	s_cmp_gt_u32 s54, 29
	s_cbranch_scc0 .LBB0_2888
	s_and_b64 vcc, exec, s[10:11]
	s_cbranch_vccz .LBB0_2891
	s_barrier

.LBB0_2966:
	ds_read_b128 v[128:131], v186
	ds_read_b128 v[132:135], v186 offset:1024
	ds_read_b128 v[136:139], v186 offset:2048
	ds_read_b128 v[140:143], v186 offset:3072
	ds_read_b128 v[144:147], v187
	ds_read_b128 v[148:151], v187 offset:1024
	ds_read_b128 v[152:155], v187 offset:2048
	ds_read_b128 v[156:159], v187 offset:3072
	s_add_u32 s2, s0, 0x3fc000
	s_addc_u32 s3, s1, 0
	s_cmpk_eq_i32 s39, 0x54
	s_cselect_b32 s34, s9, s2
	s_cselect_b32 s35, s6, s3
	s_cselect_b32 s4, s36, s37
	s_cselect_b32 s5, s25, s38
	s_add_u32 s2, s34, 0x400000
	s_addc_u32 s3, s35, 0
	s_add_i32 m0, s52, 0xc000
	ds_read_b128 v[174:177], v188
	ds_read_b128 v[178:181], v188 offset:1024
	ds_read_b128 v[192:195], v188 offset:2048
	ds_read_b128 v[196:199], v188 offset:3072
	ds_read_b128 v[200:203], v188 offset:4096
	ds_read_b128 v[204:207], v188 offset:5120
	ds_read_b128 v[208:211], v188 offset:6144
	ds_read_b128 v[212:215], v188 offset:7168
	global_load_lds_dwordx4 v168, s[0:1]
	s_add_i32 m0, s52, 0xe000
	s_nop 0
	global_load_lds_dwordx4 v170, s[0:1]
	s_waitcnt vmcnt(8)
	s_waitcnt lgkmcnt(0)
	s_setprio 1
	s_barrier
	v_mfma_f32_16x16x32_bf16 v[52:55], v[128:131], v[174:177], v[52:55]
	v_mfma_f32_16x16x32_bf16 v[48:51], v[136:139], v[174:177], v[48:51]
	v_mfma_f32_16x16x32_bf16 v[12:15], v[128:131], v[192:195], v[12:15]
	v_mfma_f32_16x16x32_bf16 v[0:3], v[136:139], v[192:195], v[0:3]
	v_mfma_f32_16x16x32_bf16 v[64:67], v[128:131], v[200:203], v[64:67]
	v_mfma_f32_16x16x32_bf16 v[68:71], v[136:139], v[200:203], v[68:71]
	v_mfma_f32_16x16x32_bf16 v[80:83], v[128:131], v[208:211], v[80:83]
	v_mfma_f32_16x16x32_bf16 v[84:87], v[136:139], v[208:211], v[84:87]
	v_mfma_f32_16x16x32_bf16 v[52:55], v[132:135], v[178:181], v[52:55]
	v_mfma_f32_16x16x32_bf16 v[48:51], v[140:143], v[178:181], v[48:51]
	v_mfma_f32_16x16x32_bf16 v[12:15], v[132:135], v[196:199], v[12:15]
	v_mfma_f32_16x16x32_bf16 v[0:3], v[140:143], v[196:199], v[0:3]
	v_mfma_f32_16x16x32_bf16 v[64:67], v[132:135], v[204:207], v[64:67]
	v_mfma_f32_16x16x32_bf16 v[68:71], v[140:143], v[204:207], v[68:71]
	v_mfma_f32_16x16x32_bf16 v[80:83], v[132:135], v[212:215], v[80:83]
	v_mfma_f32_16x16x32_bf16 v[84:87], v[140:143], v[212:215], v[84:87]
	v_mfma_f32_16x16x32_bf16 v[44:47], v[144:147], v[174:177], v[44:47]
	v_mfma_f32_16x16x32_bf16 v[40:43], v[152:155], v[174:177], v[40:43]
	v_mfma_f32_16x16x32_bf16 v[4:7], v[144:147], v[192:195], v[4:7]
	v_mfma_f32_16x16x32_bf16 v[8:11], v[152:155], v[192:195], v[8:11]
	v_mfma_f32_16x16x32_bf16 v[16:19], v[144:147], v[200:203], v[16:19]
	v_mfma_f32_16x16x32_bf16 v[20:23], v[152:155], v[200:203], v[20:23]
	v_mfma_f32_16x16x32_bf16 v[24:27], v[144:147], v[208:211], v[24:27]
	v_mfma_f32_16x16x32_bf16 v[28:31], v[152:155], v[208:211], v[28:31]
	v_mfma_f32_16x16x32_bf16 v[44:47], v[148:151], v[178:181], v[44:47]
	v_mfma_f32_16x16x32_bf16 v[40:43], v[156:159], v[178:181], v[40:43]
	v_mfma_f32_16x16x32_bf16 v[4:7], v[148:151], v[196:199], v[4:7]
	v_mfma_f32_16x16x32_bf16 v[8:11], v[156:159], v[196:199], v[8:11]
	v_mfma_f32_16x16x32_bf16 v[16:19], v[148:151], v[204:207], v[16:19]
	v_mfma_f32_16x16x32_bf16 v[20:23], v[156:159], v[204:207], v[20:23]
	v_mfma_f32_16x16x32_bf16 v[24:27], v[148:151], v[212:215], v[24:27]
	v_mfma_f32_16x16x32_bf16 v[28:31], v[156:159], v[212:215], v[28:31]
	s_barrier
	s_setprio 0
	s_add_i32 s40, s57, s46
	s_mov_b32 m0, s40
	ds_read_b128 v[174:177], v188 offset:16384
	ds_read_b128 v[178:181], v188 offset:17408
	ds_read_b128 v[192:195], v188 offset:18432
	ds_read_b128 v[196:199], v188 offset:19456
	ds_read_b128 v[200:203], v188 offset:20480
	ds_read_b128 v[204:207], v188 offset:21504
	ds_read_b128 v[208:211], v188 offset:22528
	ds_read_b128 v[212:215], v188 offset:23552
	global_load_lds_dwordx4 v162, s[4:5]
	s_add_i32 m0, s40, 0x2000
	s_add_u32 s40, s4, 0x4000
	s_addc_u32 s41, s5, 0
	s_add_i32 s42, s81, s46
	global_load_lds_dwordx4 v166, s[4:5]
	s_mov_b32 m0, s42
	s_nop 0
	global_load_lds_dwordx4 v162, s[40:41]
	s_add_i32 m0, s42, 0x2000
	s_nop 0
	global_load_lds_dwordx4 v166, s[40:41]
	s_mov_b32 m0, s52
	s_nop 0
	global_load_lds_dwordx4 v160, s[34:35]
	s_mov_b32 m0, s53
	s_nop 0
	global_load_lds_dwordx4 v164, s[34:35]
	s_waitcnt vmcnt(8)
	s_waitcnt lgkmcnt(0)
	s_setprio 1
	s_barrier
	v_mfma_f32_16x16x32_bf16 v[104:107], v[128:131], v[174:177], v[104:107]
	v_mfma_f32_16x16x32_bf16 v[108:111], v[136:139], v[174:177], v[108:111]
	v_mfma_f32_16x16x32_bf16 v[120:123], v[128:131], v[192:195], v[120:123]
	v_mfma_f32_16x16x32_bf16 v[124:127], v[136:139], v[192:195], v[124:127]
	v_mfma_f32_16x16x32_bf16 v[116:119], v[128:131], v[200:203], v[116:119]
	v_mfma_f32_16x16x32_bf16 v[112:115], v[136:139], v[200:203], v[112:115]
	v_mfma_f32_16x16x32_bf16 v[100:103], v[128:131], v[208:211], v[100:103]
	v_mfma_f32_16x16x32_bf16 v[96:99], v[136:139], v[208:211], v[96:99]
	v_mfma_f32_16x16x32_bf16 v[104:107], v[132:135], v[178:181], v[104:107]
	v_mfma_f32_16x16x32_bf16 v[108:111], v[140:143], v[178:181], v[108:111]
	v_mfma_f32_16x16x32_bf16 v[120:123], v[132:135], v[196:199], v[120:123]
	v_mfma_f32_16x16x32_bf16 v[124:127], v[140:143], v[196:199], v[124:127]
	v_mfma_f32_16x16x32_bf16 v[116:119], v[132:135], v[204:207], v[116:119]
	v_mfma_f32_16x16x32_bf16 v[112:115], v[140:143], v[204:207], v[112:115]
	v_mfma_f32_16x16x32_bf16 v[100:103], v[132:135], v[212:215], v[100:103]
	v_mfma_f32_16x16x32_bf16 v[96:99], v[140:143], v[212:215], v[96:99]
	v_mfma_f32_16x16x32_bf16 v[32:35], v[144:147], v[174:177], v[32:35]
	v_mfma_f32_16x16x32_bf16 v[36:39], v[152:155], v[174:177], v[36:39]
	v_mfma_f32_16x16x32_bf16 v[56:59], v[144:147], v[192:195], v[56:59]
	v_mfma_f32_16x16x32_bf16 v[60:63], v[152:155], v[192:195], v[60:63]
	v_mfma_f32_16x16x32_bf16 v[72:75], v[144:147], v[200:203], v[72:75]
	v_mfma_f32_16x16x32_bf16 v[76:79], v[152:155], v[200:203], v[76:79]
	v_mfma_f32_16x16x32_bf16 v[92:95], v[144:147], v[208:211], v[92:95]
	v_mfma_f32_16x16x32_bf16 v[88:91], v[152:155], v[208:211], v[88:91]
	v_mfma_f32_16x16x32_bf16 v[32:35], v[148:151], v[178:181], v[32:35]
	v_mfma_f32_16x16x32_bf16 v[36:39], v[156:159], v[178:181], v[36:39]
	v_mfma_f32_16x16x32_bf16 v[56:59], v[148:151], v[196:199], v[56:59]
	v_mfma_f32_16x16x32_bf16 v[60:63], v[156:159], v[196:199], v[60:63]
	v_mfma_f32_16x16x32_bf16 v[72:75], v[148:151], v[204:207], v[72:75]
	v_mfma_f32_16x16x32_bf16 v[76:79], v[156:159], v[204:207], v[76:79]
	v_mfma_f32_16x16x32_bf16 v[92:95], v[148:151], v[212:215], v[92:95]
	v_mfma_f32_16x16x32_bf16 v[88:91], v[156:159], v[212:215], v[88:91]
	s_barrier
	s_setprio 0
	v_add_u32_e32 v140, s82, v185
	v_add_u32_e32 v156, s83, v185
	ds_read_b128 v[128:131], v140
	ds_read_b128 v[132:135], v140 offset:1024
	ds_read_b128 v[136:139], v140 offset:2048
	ds_read_b128 v[140:143], v140 offset:3072
	ds_read_b128 v[144:147], v156
	ds_read_b128 v[148:151], v156 offset:1024
	ds_read_b128 v[152:155], v156 offset:2048
	ds_read_b128 v[156:159], v156 offset:3072
	s_add_u32 s34, s34, 0x4000
	s_addc_u32 s35, s35, 0
	s_mov_b32 m0, s54
	ds_read_b128 v[174:177], v188 offset:32768
	ds_read_b128 v[178:181], v188 offset:33792
	ds_read_b128 v[192:195], v188 offset:34816
	ds_read_b128 v[196:199], v188 offset:35840
	ds_read_b128 v[200:203], v188 offset:36864
	ds_read_b128 v[204:207], v188 offset:37888
	ds_read_b128 v[208:211], v188 offset:38912
	ds_read_b128 v[212:215], v188 offset:39936
	global_load_lds_dwordx4 v160, s[34:35]
	s_mov_b32 m0, s55
	s_nop 0
	global_load_lds_dwordx4 v164, s[34:35]
	s_waitcnt vmcnt(8)
	s_waitcnt lgkmcnt(0)
	s_setprio 1
	s_barrier
	v_mfma_f32_16x16x32_bf16 v[52:55], v[128:131], v[174:177], v[52:55]
	v_mfma_f32_16x16x32_bf16 v[48:51], v[136:139], v[174:177], v[48:51]
	v_mfma_f32_16x16x32_bf16 v[12:15], v[128:131], v[192:195], v[12:15]
	v_mfma_f32_16x16x32_bf16 v[0:3], v[136:139], v[192:195], v[0:3]
	v_mfma_f32_16x16x32_bf16 v[64:67], v[128:131], v[200:203], v[64:67]
	v_mfma_f32_16x16x32_bf16 v[68:71], v[136:139], v[200:203], v[68:71]
	v_mfma_f32_16x16x32_bf16 v[80:83], v[128:131], v[208:211], v[80:83]
	v_mfma_f32_16x16x32_bf16 v[84:87], v[136:139], v[208:211], v[84:87]
	v_mfma_f32_16x16x32_bf16 v[52:55], v[132:135], v[178:181], v[52:55]
	v_mfma_f32_16x16x32_bf16 v[48:51], v[140:143], v[178:181], v[48:51]
	v_mfma_f32_16x16x32_bf16 v[12:15], v[132:135], v[196:199], v[12:15]
	v_mfma_f32_16x16x32_bf16 v[0:3], v[140:143], v[196:199], v[0:3]
	v_mfma_f32_16x16x32_bf16 v[64:67], v[132:135], v[204:207], v[64:67]
	v_mfma_f32_16x16x32_bf16 v[68:71], v[140:143], v[204:207], v[68:71]
	v_mfma_f32_16x16x32_bf16 v[80:83], v[132:135], v[212:215], v[80:83]
	v_mfma_f32_16x16x32_bf16 v[84:87], v[140:143], v[212:215], v[84:87]
	v_mfma_f32_16x16x32_bf16 v[44:47], v[144:147], v[174:177], v[44:47]
	v_mfma_f32_16x16x32_bf16 v[40:43], v[152:155], v[174:177], v[40:43]
	v_mfma_f32_16x16x32_bf16 v[4:7], v[144:147], v[192:195], v[4:7]
	v_mfma_f32_16x16x32_bf16 v[8:11], v[152:155], v[192:195], v[8:11]
	v_mfma_f32_16x16x32_bf16 v[16:19], v[144:147], v[200:203], v[16:19]
	v_mfma_f32_16x16x32_bf16 v[20:23], v[152:155], v[200:203], v[20:23]
	v_mfma_f32_16x16x32_bf16 v[24:27], v[144:147], v[208:211], v[24:27]
	v_mfma_f32_16x16x32_bf16 v[28:31], v[152:155], v[208:211], v[28:31]
	v_mfma_f32_16x16x32_bf16 v[44:47], v[148:151], v[178:181], v[44:47]
	v_mfma_f32_16x16x32_bf16 v[40:43], v[156:159], v[178:181], v[40:43]
	v_mfma_f32_16x16x32_bf16 v[4:7], v[148:151], v[196:199], v[4:7]
	v_mfma_f32_16x16x32_bf16 v[8:11], v[156:159], v[196:199], v[8:11]
	v_mfma_f32_16x16x32_bf16 v[16:19], v[148:151], v[204:207], v[16:19]
	v_mfma_f32_16x16x32_bf16 v[20:23], v[156:159], v[204:207], v[20:23]
	v_mfma_f32_16x16x32_bf16 v[24:27], v[148:151], v[212:215], v[24:27]
	v_mfma_f32_16x16x32_bf16 v[28:31], v[156:159], v[212:215], v[28:31]
	s_barrier
	s_setprio 0
	s_add_u32 s34, s4, 0x40000
	s_addc_u32 s35, s5, 0
	s_add_i32 s40, s82, s46
	s_mov_b32 m0, s40
	ds_read_b128 v[174:177], v188 offset:49152
	ds_read_b128 v[178:181], v188 offset:50176
	ds_read_b128 v[192:195], v188 offset:51200
	ds_read_b128 v[196:199], v188 offset:52224
	ds_read_b128 v[200:203], v188 offset:53248
	ds_read_b128 v[204:207], v188 offset:54272
	ds_read_b128 v[208:211], v188 offset:55296
	ds_read_b128 v[212:215], v188 offset:56320
	global_load_lds_dwordx4 v162, s[34:35]
	s_add_i32 m0, s40, 0x2000
	s_add_u32 s4, s4, 0x44000
	global_load_lds_dwordx4 v166, s[34:35]
	s_addc_u32 s5, s5, 0
	s_add_i32 s34, s83, s46
	s_mov_b32 m0, s34
	s_nop 0
	global_load_lds_dwordx4 v162, s[4:5]
	s_add_i32 m0, s34, 0x2000
	s_nop 0
	global_load_lds_dwordx4 v166, s[4:5]
	s_mov_b32 m0, s68
	s_nop 0
	global_load_lds_dwordx4 v160, s[2:3]
	v_lshl_add_u64 v[216:217], s[2:3], 0, v[164:165]
	s_mov_b32 m0, s69
	s_nop 0
	global_load_lds_dwordx4 v[216:217], off
	s_waitcnt vmcnt(8)
	s_waitcnt lgkmcnt(0)
	s_setprio 1
	s_barrier
	v_mfma_f32_16x16x32_bf16 v[104:107], v[128:131], v[174:177], v[104:107]
	v_mfma_f32_16x16x32_bf16 v[108:111], v[136:139], v[174:177], v[108:111]
	v_mfma_f32_16x16x32_bf16 v[120:123], v[128:131], v[192:195], v[120:123]
	v_mfma_f32_16x16x32_bf16 v[124:127], v[136:139], v[192:195], v[124:127]
	v_mfma_f32_16x16x32_bf16 v[116:119], v[128:131], v[200:203], v[116:119]
	v_mfma_f32_16x16x32_bf16 v[112:115], v[136:139], v[200:203], v[112:115]
	v_mfma_f32_16x16x32_bf16 v[100:103], v[128:131], v[208:211], v[100:103]
	v_mfma_f32_16x16x32_bf16 v[96:99], v[136:139], v[208:211], v[96:99]
	v_mfma_f32_16x16x32_bf16 v[104:107], v[132:135], v[178:181], v[104:107]
	v_mfma_f32_16x16x32_bf16 v[108:111], v[140:143], v[178:181], v[108:111]
	v_mfma_f32_16x16x32_bf16 v[120:123], v[132:135], v[196:199], v[120:123]
	v_mfma_f32_16x16x32_bf16 v[124:127], v[140:143], v[196:199], v[124:127]
	v_mfma_f32_16x16x32_bf16 v[116:119], v[132:135], v[204:207], v[116:119]
	v_mfma_f32_16x16x32_bf16 v[112:115], v[140:143], v[204:207], v[112:115]
	v_mfma_f32_16x16x32_bf16 v[100:103], v[132:135], v[212:215], v[100:103]
	v_mfma_f32_16x16x32_bf16 v[96:99], v[140:143], v[212:215], v[96:99]
	v_mfma_f32_16x16x32_bf16 v[32:35], v[144:147], v[174:177], v[32:35]
	v_mfma_f32_16x16x32_bf16 v[36:39], v[152:155], v[174:177], v[36:39]
	v_mfma_f32_16x16x32_bf16 v[56:59], v[144:147], v[192:195], v[56:59]
	v_mfma_f32_16x16x32_bf16 v[60:63], v[152:155], v[192:195], v[60:63]
	v_mfma_f32_16x16x32_bf16 v[72:75], v[144:147], v[200:203], v[72:75]
	v_mfma_f32_16x16x32_bf16 v[76:79], v[152:155], v[200:203], v[76:79]
	v_mfma_f32_16x16x32_bf16 v[92:95], v[144:147], v[208:211], v[92:95]
	v_mfma_f32_16x16x32_bf16 v[88:91], v[152:155], v[208:211], v[88:91]
	v_mfma_f32_16x16x32_bf16 v[32:35], v[148:151], v[178:181], v[32:35]
	v_mfma_f32_16x16x32_bf16 v[36:39], v[156:159], v[178:181], v[36:39]
	v_mfma_f32_16x16x32_bf16 v[56:59], v[148:151], v[196:199], v[56:59]
	v_mfma_f32_16x16x32_bf16 v[60:63], v[156:159], v[196:199], v[60:63]
	v_mfma_f32_16x16x32_bf16 v[72:75], v[148:151], v[204:207], v[72:75]
	v_mfma_f32_16x16x32_bf16 v[76:79], v[156:159], v[204:207], v[76:79]
	v_mfma_f32_16x16x32_bf16 v[92:95], v[148:151], v[212:215], v[92:95]
	v_mfma_f32_16x16x32_bf16 v[88:91], v[156:159], v[212:215], v[88:91]
	s_barrier
	s_setprio 0
	s_add_i32 s39, s39, 2
	s_add_u32 s37, s37, 0x80000
	s_addc_u32 s38, s38, 0
	s_add_u32 s0, s0, 0x800000
	s_addc_u32 s1, s1, 0
	s_cmpk_gt_u32 s39, 0x55
	s_cbranch_scc0 .LBB0_2966
	s_and_b64 vcc, exec, s[20:21]
	s_cbranch_vccz .LBB0_2969
	s_barrier
